# all flat_* memory ops converted to global_* (same addresses)
# speedup vs baseline: 1.0041x; 1.0041x over previous
; #define MOD ((float*)(wsb(a.ws) + WS_MOD))
; __global__ void __launch_bounds__(NTHR, 2) fwd_mega(Args a) {
;     ...
;         for (int item = bx; item < 384; item += G) {
;             const int l = item / 96, cgi = item % 96, ks = tid >> 6, jl = tid & 63, col = cgi * 64 + jl;
;             const float* w = wmod + ((size_t)l * 1024 + ks * 128) * 6144 + col;
;             float a0 = 0.f, a1 = 0.f, a2 = 0.f, a3 = 0.f, a4 = 0.f;
; #pragma unroll 8
;             for (int k = 0; k < 128; ++k) { const float wv = w[(size_t)k * 6144]; const int kk = ks * 128 + k;
;                 a0 += S[kk] * wv; a1 += S[1024 + kk] * wv; a2 += S[2048 + kk] * wv; a3 += S[3072 + kk] * wv; a4 += S[4096 + kk] * wv; }
;             RED[(ks * 5 + 0) * 64 + jl] = a0; RED[(ks * 5 + 1) * 64 + jl] = a1; RED[(ks * 5 + 2) * 64 + jl] = a2; RED[(ks * 5 + 3) * 64 + jl] = a3; RED[(ks * 5 + 4) * 64 + jl] = a4;
;             __syncthreads();
;             if (tid < 320) { const int bi = tid >> 6, j = tid & 63; float s = bmod[l * 6144 + cgi * 64 + j];
; #pragma unroll
;                 for (int k2 = 0; k2 < 8; ++k2) s += RED[(k2 * 5 + bi) * 64 + j];
;                 MOD[((size_t)l * 5 + bi) * 6144 + cgi * 64 + j] = s; }
;             __syncthreads();
.LBB0_24:
	v_lshl_add_u64 v[24:25], v[16:17], 0, s[18:19]
	v_add_co_u32_e32 v26, vcc, s13, v24
	global_load_dword v64, v[24:25], off
	s_nop 0
	v_addc_co_u32_e32 v27, vcc, 0, v25, vcc
	v_add_co_u32_e32 v28, vcc, s20, v24
	s_add_u32 s18, s18, 0x30000
	s_nop 0
	v_addc_co_u32_e32 v29, vcc, 0, v25, vcc
	v_add_co_u32_e32 v30, vcc, s21, v24
	s_addc_u32 s19, s19, 0
	s_nop 0
	v_addc_co_u32_e32 v31, vcc, 0, v25, vcc
	v_add_co_u32_e32 v32, vcc, s22, v24
	s_cmp_eq_u32 s18, 0x300000
	s_nop 0
	v_addc_co_u32_e32 v33, vcc, 0, v25, vcc
	v_add_co_u32_e32 v34, vcc, s23, v24
	s_nop 1
	v_addc_co_u32_e32 v35, vcc, 0, v25, vcc
	v_add_co_u32_e32 v36, vcc, s24, v24
	s_nop 1
	v_addc_co_u32_e32 v37, vcc, 0, v25, vcc
	v_add_co_u32_e32 v24, vcc, s25, v24
	s_nop 1
	v_addc_co_u32_e32 v25, vcc, 0, v25, vcc
	global_load_dword v66, v[26:27], off
	global_load_dword v68, v[28:29], off
	global_load_dword v70, v[30:31], off
	global_load_dword v72, v[32:33], off
	global_load_dword v74, v[34:35], off
	global_load_dword v76, v[36:37], off
	global_load_dword v78, v[24:25], off
	ds_read_b128 v[24:27], v22
	ds_read_b128 v[28:31], v22 offset:16
	ds_read_b128 v[32:35], v22 offset:4096
	ds_read_b128 v[36:39], v22 offset:4112
	ds_read_b128 v[40:43], v22 offset:8192
	ds_read_b128 v[44:47], v22 offset:8208
	ds_read_b128 v[48:51], v22 offset:12288
	ds_read_b128 v[52:55], v22 offset:12304
	ds_read_b128 v[56:59], v22 offset:16384
	ds_read_b128 v[60:63], v22 offset:16400
	s_waitcnt lgkmcnt(0)
	v_mov_b32_e32 v80, v24
	s_waitcnt lgkmcnt(7)
	v_mov_b32_e32 v81, v32
	v_mov_b32_e32 v32, v25
	v_mov_b32_e32 v24, v26
	v_mov_b32_e32 v25, v34
	v_mov_b32_e32 v34, v27
	s_waitcnt lgkmcnt(5)
	v_mov_b32_e32 v26, v40
	s_waitcnt lgkmcnt(3)
	v_mov_b32_e32 v27, v48
	v_mov_b32_e32 v48, v41
	v_mov_b32_e32 v40, v42
	v_mov_b32_e32 v41, v50
	v_mov_b32_e32 v50, v43
	v_mov_b32_e32 v42, v28
	v_mov_b32_e32 v43, v36
	v_mov_b32_e32 v36, v29
	v_mov_b32_e32 v28, v30
	v_mov_b32_e32 v29, v38
	v_mov_b32_e32 v38, v31
	v_mov_b32_e32 v30, v44
	s_waitcnt lgkmcnt(2)
	v_mov_b32_e32 v31, v52
	v_mov_b32_e32 v52, v45
	v_mov_b32_e32 v44, v46
	v_mov_b32_e32 v45, v54
	v_mov_b32_e32 v54, v47
	v_add_u32_e32 v22, 32, v22
	s_waitcnt vmcnt(0)
	v_pk_fma_f32 v[18:19], v[64:65], v[80:81], v[18:19] op_sel_hi:[0,1,1]
	v_pk_fma_f32 v[20:21], v[64:65], v[26:27], v[20:21] op_sel_hi:[0,1,1]
	s_waitcnt lgkmcnt(1)
	v_fmac_f32_e32 v11, v64, v56
	s_waitcnt vmcnt(6)
	v_pk_fma_f32 v[18:19], v[66:67], v[32:33], v[18:19] op_sel_hi:[0,1,1]
	v_pk_fma_f32 v[20:21], v[66:67], v[48:49], v[20:21] op_sel_hi:[0,1,1]
	v_fmac_f32_e32 v11, v66, v57
	s_waitcnt vmcnt(5)
	v_pk_fma_f32 v[18:19], v[68:69], v[24:25], v[18:19] op_sel_hi:[0,1,1]
	v_pk_fma_f32 v[20:21], v[68:69], v[40:41], v[20:21] op_sel_hi:[0,1,1]
	v_fmac_f32_e32 v11, v68, v58
	s_waitcnt vmcnt(4)
	v_pk_fma_f32 v[18:19], v[70:71], v[34:35], v[18:19] op_sel_hi:[0,1,1]
	v_pk_fma_f32 v[20:21], v[70:71], v[50:51], v[20:21] op_sel_hi:[0,1,1]
	v_fmac_f32_e32 v11, v70, v59
	s_waitcnt vmcnt(3)
	v_pk_fma_f32 v[18:19], v[72:73], v[42:43], v[18:19] op_sel_hi:[0,1,1]
	v_pk_fma_f32 v[20:21], v[72:73], v[30:31], v[20:21] op_sel_hi:[0,1,1]
	s_waitcnt lgkmcnt(0)
	v_fmac_f32_e32 v11, v72, v60
	s_waitcnt vmcnt(2)
	v_pk_fma_f32 v[18:19], v[74:75], v[36:37], v[18:19] op_sel_hi:[0,1,1]
	v_pk_fma_f32 v[20:21], v[74:75], v[52:53], v[20:21] op_sel_hi:[0,1,1]
	v_fmac_f32_e32 v11, v74, v61
	s_waitcnt vmcnt(1)
	v_pk_fma_f32 v[18:19], v[76:77], v[28:29], v[18:19] op_sel_hi:[0,1,1]
	v_pk_fma_f32 v[20:21], v[76:77], v[44:45], v[20:21] op_sel_hi:[0,1,1]
	v_fmac_f32_e32 v11, v76, v62
	s_waitcnt vmcnt(0)
	v_pk_fma_f32 v[18:19], v[78:79], v[38:39], v[18:19] op_sel_hi:[0,1,1]
	v_pk_fma_f32 v[20:21], v[78:79], v[54:55], v[20:21] op_sel_hi:[0,1,1]
	v_fmac_f32_e32 v11, v78, v63
	s_cbranch_scc0 .LBB0_24
	ds_write2st64_b32 v10, v18, v19 offset0:80 offset1:81
	ds_write2st64_b32 v10, v20, v21 offset0:82 offset1:83
	ds_write_b32 v10, v11 offset:21504
	s_waitcnt lgkmcnt(0)
	s_barrier
	s_and_saveexec_b64 s[18:19], s[4:5]
	s_cbranch_execz .LBB0_22
	s_mul_i32 s15, s16, 0x1800
	s_add_i32 s15, s15, s14
	v_or_b32_e32 v16, s15, v6
	v_ashrrev_i32_e32 v17, 31, v16
	v_lshl_add_u64 v[16:17], v[16:17], 2, s[8:9]
	global_load_dword v11, v[16:17], off
	ds_read2st64_b32 v[16:17], v7 offset0:80 offset1:85
	ds_read2st64_b32 v[18:19], v7 offset0:90 offset1:95
	ds_read2st64_b32 v[20:21], v7 offset0:100 offset1:105
	ds_read2st64_b32 v[22:23], v7 offset0:110 offset1:115
	s_mov_b64 s[28:29], s[10:11]
	v_mad_i64_i32 v[24:25], s[16:17], s16, 5, v[4:5]
	s_ashr_i32 s15, s14, 31
	v_mov_b64_e32 v[26:27], s[28:29]
	v_mad_u64_u32 v[26:27], s[16:17], v24, s13, v[26:27]
	v_mad_i32_i24 v27, v25, s13, v27
	v_lshl_add_u64 v[24:25], s[14:15], 2, v[26:27]
	v_lshl_add_u64 v[24:25], v[24:25], 0, v[12:13]
	v_add_co_u32_e32 v24, vcc, 0x100000, v24
	s_waitcnt vmcnt(0) lgkmcnt(3)
	v_add_f32_e32 v11, v11, v16
	v_add_f32_e32 v11, v11, v17
	s_waitcnt lgkmcnt(2)
	v_add_f32_e32 v11, v11, v18
	v_add_f32_e32 v11, v11, v19
	s_waitcnt lgkmcnt(1)
	v_add_f32_e32 v11, v11, v20
	v_add_f32_e32 v11, v11, v21
	s_waitcnt lgkmcnt(0)
	v_add_f32_e32 v11, v11, v22
	v_add_f32_e32 v11, v11, v23
	v_addc_co_u32_e32 v25, vcc, 0, v25, vcc
	global_store_dword v[24:25], v11, off
	s_branch .LBB0_22
; __device__ __forceinline__ int opq(int i) { asm volatile("" : "+s"(i)); return i; }
; #define LAM ((float*)(wsb(a.ws) + WS_LAM))
; __global__ void __launch_bounds__(NTHR, 2) fwd_mega(Args a) {
;     ...
;         if (bx == 0 && wave < 4) { const int l = wave;
;             const float s1 = wave_sum(a.in[opq(13)][l * 64 + lane] * a.in[opq(14)][l * 64 + lane]), s2 = wave_sum(a.in[opq(15)][l * 64 + lane] * a.in[opq(16)][l * 64 + lane]);
;             if (lane == 0) LAM[l] = expf(s1) - expf(s2) + (0.8f - 0.6f * expf(-0.3f * (float)l)); }
.LBB0_27:
	v_readlane_b32 s4, v253, 0
	s_cmp_eq_u32 s4, 0
	s_cselect_b64 s[4:5], -1, 0
	s_cmp_lt_i32 s12, 4
	s_cselect_b64 s[8:9], -1, 0
	s_and_b64 s[4:5], s[4:5], s[8:9]
	s_and_b64 vcc, exec, s[4:5]
	s_cbranch_vccz .LBB0_31
	s_mov_b32 s4, 13
	s_ashr_i32 s5, s4, 31
	s_lshl_b64 s[4:5], s[4:5], 3
	s_add_u32 s4, s90, s4
	s_addc_u32 s5, s91, s5
	s_load_dwordx2 s[4:5], s[4:5], 0x0
	v_lshl_or_b32 v4, s12, 6, v6
	v_ashrrev_i32_e32 v5, 31, v4
	v_lshlrev_b64 v[4:5], 2, v[4:5]
	s_mov_b32 s8, 14
	s_waitcnt lgkmcnt(0)
	v_lshl_add_u64 v[8:9], s[4:5], 0, v[4:5]
	global_load_dword v3, v[8:9], off
	s_ashr_i32 s9, s8, 31
	s_lshl_b64 s[4:5], s[8:9], 3
	s_add_u32 s4, s90, s4
	s_addc_u32 s5, s91, s5
	s_load_dwordx2 s[4:5], s[4:5], 0x0
	s_mov_b32 s8, 15
	v_cmp_eq_u32_e32 vcc, 0, v6
	s_waitcnt lgkmcnt(0)
	v_lshl_add_u64 v[8:9], s[4:5], 0, v[4:5]
	global_load_dword v7, v[8:9], off
	s_ashr_i32 s9, s8, 31
	s_lshl_b64 s[4:5], s[8:9], 3
	s_add_u32 s4, s90, s4
	s_addc_u32 s5, s91, s5
	s_load_dwordx2 s[4:5], s[4:5], 0x0
	s_mov_b32 s8, 16
	s_waitcnt lgkmcnt(0)
	v_lshl_add_u64 v[8:9], s[4:5], 0, v[4:5]
	global_load_dword v8, v[8:9], off
	s_ashr_i32 s9, s8, 31
	s_lshl_b64 s[4:5], s[8:9], 3
	s_add_u32 s4, s90, s4
	s_addc_u32 s5, s91, s5
	s_load_dwordx2 s[4:5], s[4:5], 0x0
	v_mov_b32_e32 v9, 0
	s_waitcnt lgkmcnt(0)
	v_lshl_add_u64 v[4:5], s[4:5], 0, v[4:5]
	global_load_dword v5, v[4:5], off
	v_mov_b32_e32 v4, 0
	s_waitcnt vmcnt(0)
	v_mul_f32_e32 v10, v3, v7
	s_nop 1
	v_mov_b32_dpp v4, v10 quad_perm:[1,0,3,2] row_mask:0xf bank_mask:0xf
	v_fmac_f32_e32 v4, v3, v7
	v_mul_f32_e32 v7, v8, v5
	s_nop 1
	v_mov_b32_dpp v9, v7 quad_perm:[1,0,3,2] row_mask:0xf bank_mask:0xf
	v_fmac_f32_e32 v9, v8, v5
	v_add_f32_dpp v3, v4, v4 quad_perm:[2,3,0,1] row_mask:0xf bank_mask:0xf bound_ctrl:1
	s_nop 0
	v_add_f32_dpp v5, v9, v9 quad_perm:[2,3,0,1] row_mask:0xf bank_mask:0xf bound_ctrl:1
	v_add_f32_dpp v3, v3, v3 row_half_mirror row_mask:0xf bank_mask:0xf bound_ctrl:1
	s_nop 0
	v_add_f32_dpp v5, v5, v5 row_half_mirror row_mask:0xf bank_mask:0xf bound_ctrl:1
	v_add_f32_dpp v3, v3, v3 row_mirror row_mask:0xf bank_mask:0xf bound_ctrl:1
	v_mov_b32_e32 v4, v3
	v_add_f32_dpp v5, v5, v5 row_mirror row_mask:0xf bank_mask:0xf bound_ctrl:1
	v_mov_b32_e32 v7, v5
	v_permlane16_swap_b32_e32 v3, v4
	s_nop 0
	v_permlane16_swap_b32_e32 v5, v7
	v_add_f32_e32 v3, v3, v4
	v_add_f32_e32 v5, v5, v7
	v_mov_b32_e32 v4, v3
	v_mov_b32_e32 v7, v5
	s_nop 0
	v_permlane32_swap_b32_e32 v3, v4
	v_permlane32_swap_b32_e32 v5, v7
	s_and_saveexec_b64 s[4:5], vcc
	s_cbranch_execz .LBB0_30
	v_add_f32_e32 v3, v3, v4
	s_mov_b32 s8, 0x3fb8aa3b
	v_mul_f32_e32 v4, 0x3fb8aa3b, v3
	v_fma_f32 v6, v3, s8, -v4
	v_rndne_f32_e32 v8, v4
	v_fmac_f32_e32 v6, 0x32a5705f, v3
	v_sub_f32_e32 v4, v4, v8
	v_add_f32_e32 v4, v4, v6
	v_exp_f32_e32 v4, v4
	v_cvt_i32_f32_e32 v6, v8
	v_add_f32_e32 v5, v5, v7
	s_mov_b32 s9, 0xc2ce8ed0
	v_mul_f32_e32 v7, 0x3fb8aa3b, v5
	v_ldexp_f32 v4, v4, v6
	v_cmp_ngt_f32_e32 vcc, s9, v3
	s_mov_b32 s10, 0x42b17218
	v_fma_f32 v8, v5, s8, -v7
	v_rndne_f32_e32 v9, v7
	v_cndmask_b32_e32 v4, 0, v4, vcc
	v_mov_b32_e32 v6, 0x7f800000
	v_fmac_f32_e32 v8, 0x32a5705f, v5
	v_sub_f32_e32 v7, v7, v9
	v_cmp_nlt_f32_e32 vcc, s10, v3
	v_add_f32_e32 v7, v7, v8
	v_exp_f32_e32 v7, v7
	v_cndmask_b32_e32 v3, v6, v4, vcc
	v_cvt_f32_i32_e32 v4, s12
	v_cvt_i32_f32_e32 v8, v9
	v_cmp_ngt_f32_e32 vcc, s9, v5
	s_ashr_i32 s13, s12, 31
	v_mul_f32_e32 v4, 0xbe99999a, v4
	v_ldexp_f32 v7, v7, v8
	v_mul_f32_e32 v8, 0x3fb8aa3b, v4
	v_fma_f32 v9, v4, s8, -v8
	v_rndne_f32_e32 v10, v8
	v_fmac_f32_e32 v9, 0x32a5705f, v4
	v_sub_f32_e32 v8, v8, v10
	v_add_f32_e32 v8, v8, v9
	v_exp_f32_e32 v8, v8
	v_cvt_i32_f32_e32 v9, v10
	v_cndmask_b32_e32 v7, 0, v7, vcc
	v_cmp_nlt_f32_e32 vcc, s10, v5
	s_nop 1
	v_cndmask_b32_e32 v5, v6, v7, vcc
	v_sub_f32_e32 v3, v3, v5
	v_ldexp_f32 v5, v8, v9
	v_cmp_ngt_f32_e32 vcc, s9, v4
	s_load_dwordx2 s[8:9], s[90:91], 0x110
	s_waitcnt lgkmcnt(0)
	v_cndmask_b32_e32 v5, 0, v5, vcc
	v_cmp_nlt_f32_e32 vcc, s10, v4
	s_lshl_b64 s[10:11], s[12:13], 2
	s_add_u32 s8, s8, s10
	v_cndmask_b32_e32 v4, v6, v5, vcc
	v_mov_b32_e32 v5, 0x3f4ccccd
	v_fmac_f32_e32 v5, 0xbf19999a, v4
	s_addc_u32 s9, s9, s11
	v_mov_b32_e32 v4, s8
	v_add_f32_e32 v3, v5, v3
	v_add_co_u32_e32 v4, vcc, 0x180000, v4
	v_mov_b32_e32 v5, s9
	s_nop 0
	v_addc_co_u32_e32 v5, vcc, 0, v5, vcc
	global_store_dword v[4:5], v3, off

; #define ROPE ((cf*)(wsb(a.ws) + WS_ROPE))
; __global__ void __launch_bounds__(NTHR, 2) fwd_mega(Args a) {
;     ...
;         const int gt = bx * NTHR + tid;
;         if (gt < 2048) { const int p = gt >> 4, f = gt & 15; const float inv = powf(10000.0f, -(float)f / 16.0f); float sn, cs; sincosf((float)p * inv, &sn, &cs); ROPE[gt] = mk2(cs, sn); }
.LBB0_36:
	s_or_b64 exec, exec, s[4:5]
	v_mul_f32_e32 v7, v5, v5
	v_mov_b32_e32 v8, 0x3c0881c4
	v_fmac_f32_e32 v8, 0xb94c1982, v7
	v_fmaak_f32 v8, v7, v8, 0xbe2aaa9d
	v_mul_f32_e32 v8, v7, v8
	v_fmac_f32_e32 v5, v5, v8
	v_mov_b32_e32 v8, 0xbab64f3b
	v_fmac_f32_e32 v8, 0x37d75334, v7
	v_fmaak_f32 v8, v7, v8, 0x3d2aabf7
	v_fmaak_f32 v8, v7, v8, 0xbf000004
	v_fma_f32 v7, v7, v8, 1.0
	v_lshlrev_b32_e32 v8, 30, v6
	v_and_b32_e32 v6, 1, v6
	v_cmp_eq_u32_e32 vcc, 0, v6
	s_brev_b32 s4, 1
	v_xor_b32_e32 v3, v3, v2
	v_cndmask_b32_e32 v6, v7, v5, vcc
	v_xor_b32_e32 v5, 0x80000000, v5
	v_cndmask_b32_e32 v5, v5, v7, vcc
	s_movk_i32 s8, 0x1f8
	v_and_b32_e32 v9, 0x80000000, v8
	v_xor_b32_e32 v3, v3, v6
	v_bitop3_b32 v5, v5, v8, s4 bitop3:0x78
	v_mov_b32_e32 v6, 0x7fc00000
	v_cmp_class_f32_e64 vcc, v2, s8
	v_xor_b32_e32 v3, v3, v9
	s_load_dwordx2 s[4:5], s[90:91], 0x110
	v_cndmask_b32_e32 v2, v6, v5, vcc
	v_ashrrev_i32_e32 v5, 31, v4
	v_cndmask_b32_e32 v3, v6, v3, vcc
	s_waitcnt lgkmcnt(0)
	s_nop 0
	v_lshl_add_u64 v[6:7], v[4:5], 3, s[4:5]
	v_add_co_u32_e32 v6, vcc, 0x180000, v6
	s_nop 1
	v_addc_co_u32_e32 v7, vcc, 0, v7, vcc
	global_store_dwordx2 v[6:7], v[2:3], off offset:256

; #define TW ((cf*)(wsb(a.ws) + WS_TW))
; __global__ void __launch_bounds__(NTHR, 2) fwd_mega(Args a) {
;     ...
;         for (int m = gt; m < FFTN; m += G * NTHR) { float sn, cs; sincospif((float)m / 8192.0f, &sn, &cs); TW[m] = mk2(cs, -sn); }
.LBB0_39:
	v_cvt_f32_i32_e32 v9, v4
	v_add_u32_e32 v4, s10, v4
	s_waitcnt lgkmcnt(0)
	s_mov_b64 s[20:21], s[8:9]
	v_cmp_lt_i32_e32 vcc, s18, v4
	v_mul_f32_e32 v9, 0x39000000, v9
	v_mul_f32_e64 v13, |v9|, 0.5
	v_fract_f32_e32 v14, v13
	s_or_b64 s[14:15], vcc, s[14:15]
	v_add_f32_e32 v14, v14, v14
	v_cmp_neq_f32_e32 vcc, s11, v13
	v_lshl_add_u64 v[10:11], s[20:21], 0, v[2:3]
	v_cmp_gt_f32_e64 s[20:21], |v9|, 1.0
	v_cndmask_b32_e32 v13, 0, v14, vcc
	v_and_b32_e32 v12, 0x7fffffff, v9
	v_cndmask_b32_e64 v13, |v9|, v13, s[20:21]
	v_add_f32_e32 v14, v13, v13
	v_rndne_f32_e32 v14, v14
	v_fmac_f32_e32 v13, -0.5, v14
	v_cvt_i32_f32_e32 v14, v14
	v_mul_f32_e32 v15, v13, v13
	v_fmamk_f32 v16, v15, 0x3e75aa41, v5
	v_fmamk_f32 v18, v15, 0x3d4be544, v6
	v_fmaak_f32 v16, v15, v16, 0x40234736
	v_fmaak_f32 v18, v15, v18, 0xbfaad1da
	v_mul_f32_e32 v17, v13, v15
	v_fmaak_f32 v16, v15, v16, 0xc0a55e0e
	v_fmaak_f32 v18, v15, v18, 0x4081e0d3
	v_lshlrev_b32_e32 v19, 30, v14
	v_and_b32_e32 v14, 1, v14
	v_mul_f32_e32 v16, v17, v16
	v_fmaak_f32 v17, v15, v18, 0xc09de9e6
	v_fmac_f32_e32 v16, 0x40490fdb, v13
	v_fma_f32 v13, v15, v17, 1.0
	v_cmp_eq_u32_e32 vcc, 0, v14
	v_xor_b32_e32 v12, v12, v9
	v_xor_b32_e32 v15, 0x80000000, v16
	v_cndmask_b32_e32 v14, v13, v16, vcc
	v_and_b32_e32 v18, 0x80000000, v19
	v_xor_b32_e32 v12, v12, v14
	v_cndmask_b32_e32 v13, v15, v13, vcc
	v_xor_b32_e32 v14, v12, v18
	v_bitop3_b32 v12, v13, v19, s16 bitop3:0x78
	v_cmp_class_f32_e64 vcc, v9, s17
	v_lshl_add_u64 v[2:3], v[2:3], 0, s[12:13]
	s_nop 0
	v_cndmask_b32_e32 v12, v7, v12, vcc
	v_cndmask_b32_e64 v13, v8, -v14, vcc
	global_store_dwordx2 v[10:11], v[12:13], off
	s_andn2_b64 exec, exec, s[14:15]
	s_cbranch_execnz .LBB0_39

;     const int nblk = N / 32, kb = item / nblk, nb = item % nblk, k0 = 64 * kb, n0 = 32 * nb;
; #pragma unroll 8
;     for (int i = 0; i < 32; ++i) { const int kk = 2 * i + (lane >> 5); scr[kk * 33 + (lane & 31)] = W[(size_t)(k0 + kk) * N + n0 + (lane & 31)]; }
;     asm volatile("s_waitcnt lgkmcnt(0)" ::: "memory");
.LBB0_90:
	s_lshl_b32 s44, s42, 1
	s_lshl_b32 s43, s40, 1
	v_or_b32_e32 v15, s44, v6
	v_or_b32_e32 v13, s43, v1
	v_add_lshl_u32 v17, v15, s39, 10
	v_add_lshl_u32 v16, v13, s41, 10
	v_or_b32_e32 v208, v14, v17
	v_or_b32_e32 v16, v3, v16
	v_lshl_add_u64 v[18:19], v[208:209], 2, s[10:11]
	v_mov_b32_e32 v17, v209
	v_lshl_add_u64 v[16:17], v[16:17], 2, s[10:11]
	global_load_dword v21, v[18:19], off
	global_load_dword v22, v[16:17], off
	v_mad_u64_u32 v[16:17], s[46:47], v15, s33, v[10:11]
	v_mad_u64_u32 v[18:19], s[46:47], v13, s33, v[10:11]
	s_add_i32 s46, s44, 4
	s_add_i32 s45, s43, 4
	v_or_b32_e32 v15, s46, v6
	v_or_b32_e32 v13, s45, v1
	v_add_lshl_u32 v17, v15, s39, 10
	v_or_b32_e32 v208, v14, v17
	v_mov_b32_e32 v17, v209
	s_add_i32 s45, s43, 8
	s_add_i32 s42, s42, 16
	s_add_i32 s40, s40, 16
	s_add_i32 s38, s38, -16
	s_waitcnt vmcnt(0)
	ds_write_b32 v16, v21
	ds_write_b32 v18, v22
	v_add_lshl_u32 v16, v13, s41, 10
	v_or_b32_e32 v16, v3, v16
	v_lshl_add_u64 v[18:19], v[208:209], 2, s[10:11]
	v_lshl_add_u64 v[16:17], v[16:17], 2, s[10:11]
	global_load_dword v21, v[18:19], off
	global_load_dword v22, v[16:17], off
	v_mad_u64_u32 v[16:17], s[46:47], v15, s33, v[10:11]
	v_mad_u64_u32 v[18:19], s[46:47], v13, s33, v[10:11]
	s_add_i32 s46, s44, 8
	s_nop 0
	v_or_b32_e32 v15, s46, v6
	v_or_b32_e32 v13, s45, v1
	v_add_lshl_u32 v17, v15, s39, 10
	v_or_b32_e32 v208, v14, v17
	v_mov_b32_e32 v17, v209
	s_add_i32 s45, s43, 12
	s_waitcnt vmcnt(1)
	ds_write_b32 v16, v21
	s_waitcnt vmcnt(0)
	ds_write_b32 v18, v22
	v_add_lshl_u32 v16, v13, s41, 10
	v_or_b32_e32 v16, v3, v16
	v_lshl_add_u64 v[18:19], v[208:209], 2, s[10:11]
	v_lshl_add_u64 v[16:17], v[16:17], 2, s[10:11]
	global_load_dword v21, v[18:19], off
	global_load_dword v22, v[16:17], off
	v_mad_u64_u32 v[16:17], s[46:47], v15, s33, v[10:11]
	v_mad_u64_u32 v[18:19], s[46:47], v13, s33, v[10:11]
	s_add_i32 s46, s44, 12
	s_nop 0
	v_or_b32_e32 v15, s46, v6
	v_or_b32_e32 v13, s45, v1
	v_add_lshl_u32 v17, v15, s39, 10
	v_or_b32_e32 v208, v14, v17
	v_mov_b32_e32 v17, v209
	s_add_i32 s45, s43, 16
	s_waitcnt vmcnt(1)
	ds_write_b32 v16, v21
	s_waitcnt vmcnt(0)
	ds_write_b32 v18, v22
	v_add_lshl_u32 v16, v13, s41, 10
	v_or_b32_e32 v16, v3, v16
	v_lshl_add_u64 v[18:19], v[208:209], 2, s[10:11]
	v_lshl_add_u64 v[16:17], v[16:17], 2, s[10:11]
	global_load_dword v21, v[18:19], off
	global_load_dword v22, v[16:17], off
	v_mad_u64_u32 v[16:17], s[46:47], v15, s33, v[10:11]
	v_mad_u64_u32 v[18:19], s[46:47], v13, s33, v[10:11]
	s_add_i32 s46, s44, 16
	s_nop 0
	v_or_b32_e32 v15, s46, v6
	v_or_b32_e32 v13, s45, v1
	v_add_lshl_u32 v17, v15, s39, 10
	v_or_b32_e32 v208, v14, v17
	v_mov_b32_e32 v17, v209
	s_add_i32 s45, s43, 20
	s_waitcnt vmcnt(1)
	ds_write_b32 v16, v21
	s_waitcnt vmcnt(0)
	ds_write_b32 v18, v22
	v_add_lshl_u32 v16, v13, s41, 10
	v_or_b32_e32 v16, v3, v16
	v_lshl_add_u64 v[18:19], v[208:209], 2, s[10:11]
	v_lshl_add_u64 v[16:17], v[16:17], 2, s[10:11]
	global_load_dword v21, v[18:19], off
	global_load_dword v22, v[16:17], off
	v_mad_u64_u32 v[16:17], s[46:47], v15, s33, v[10:11]
	v_mad_u64_u32 v[18:19], s[46:47], v13, s33, v[10:11]
	s_add_i32 s46, s44, 20
	s_nop 0
	v_or_b32_e32 v15, s46, v6
	v_or_b32_e32 v13, s45, v1
	v_add_lshl_u32 v17, v15, s39, 10
	v_or_b32_e32 v208, v14, v17
	v_mov_b32_e32 v17, v209
	s_add_i32 s45, s43, 24
	s_add_i32 s43, s43, 28
	s_waitcnt vmcnt(1)
	ds_write_b32 v16, v21
	s_waitcnt vmcnt(0)
	ds_write_b32 v18, v22
	v_add_lshl_u32 v16, v13, s41, 10
	v_or_b32_e32 v16, v3, v16
	v_lshl_add_u64 v[18:19], v[208:209], 2, s[10:11]
	v_lshl_add_u64 v[16:17], v[16:17], 2, s[10:11]
	global_load_dword v21, v[18:19], off
	global_load_dword v22, v[16:17], off
	v_mad_u64_u32 v[16:17], s[46:47], v15, s33, v[10:11]
	v_mad_u64_u32 v[18:19], s[46:47], v13, s33, v[10:11]
	s_add_i32 s46, s44, 24
	s_nop 0
	v_or_b32_e32 v15, s46, v6
	v_or_b32_e32 v13, s45, v1
	v_add_lshl_u32 v17, v15, s39, 10
	v_or_b32_e32 v208, v14, v17
	v_mov_b32_e32 v17, v209
	s_add_i32 s44, s44, 28
	s_cmp_lg_u32 s38, 0
	s_waitcnt vmcnt(1)
	ds_write_b32 v16, v21
	s_waitcnt vmcnt(0)
	ds_write_b32 v18, v22
	v_add_lshl_u32 v16, v13, s41, 10
	v_or_b32_e32 v16, v3, v16
	v_lshl_add_u64 v[18:19], v[208:209], 2, s[10:11]
	v_lshl_add_u64 v[16:17], v[16:17], 2, s[10:11]
	global_load_dword v21, v[18:19], off
	global_load_dword v22, v[16:17], off
	v_mad_u64_u32 v[16:17], s[46:47], v15, s33, v[10:11]
	v_or_b32_e32 v15, s44, v6
	v_mad_u64_u32 v[18:19], s[46:47], v13, s33, v[10:11]
	v_or_b32_e32 v13, s43, v1
	v_add_lshl_u32 v17, v15, s39, 10
	v_or_b32_e32 v208, v14, v17
	v_mov_b32_e32 v19, v209
	s_waitcnt vmcnt(1)
	ds_write_b32 v16, v21
	s_waitcnt vmcnt(0)
	ds_write_b32 v18, v22
	v_add_lshl_u32 v16, v13, s41, 10
	v_or_b32_e32 v18, v3, v16
	v_lshl_add_u64 v[16:17], v[208:209], 2, s[10:11]
	v_lshl_add_u64 v[18:19], v[18:19], 2, s[10:11]
	global_load_dword v21, v[16:17], off
	global_load_dword v22, v[18:19], off
	v_mad_u64_u32 v[16:17], s[44:45], v15, s33, v[10:11]
	v_mad_u64_u32 v[18:19], s[44:45], v13, s33, v[10:11]
	s_waitcnt vmcnt(1)
	ds_write_b32 v16, v21
	s_waitcnt vmcnt(0)
	ds_write_b32 v18, v22
	s_cbranch_scc1 .LBB0_90
; #define LAS __attribute__((address_space(3)))
; __device__ __forceinline__ unsigned pk2(float lo, float hi) { const f32x2_cv v = {lo, hi}; const bf16x2_cv b = __builtin_convertvector(v, bf16x2_cv); return __builtin_bit_cast(unsigned, b); }
;     ...
;     const int c = lane & 7;
; #pragma unroll
;     for (int j = 0; j < 4; ++j) { const int n = (lane >> 3) + 8 * j; const LAS float* s = scr + (8 * c) * 33 + n;
;         v4u o; o.x = pk2(s[0 * 33], s[1 * 33]); o.y = pk2(s[2 * 33], s[3 * 33]); o.z = pk2(s[4 * 33], s[5 * 33]); o.w = pk2(s[6 * 33], s[7 * 33]);
;         int row = n0 + n; if (PERM_UP == 2) { const int nl = row & 255; row = (row & ~255) + 128 * ((nl >> 5) & 1) + 32 * (nl >> 6) + (nl & 31); }
;         if (PERM_UP == 1) { const bool isv = row >= DFF; const int ch = isv ? row - DFF : row; row = (ch >> 7) * 256 + (isv ? 128 : 0) + (ch & 127); }
;         *(v4u*)(WT + (size_t)row * K + k0 + 8 * c) = o; }
;     asm volatile("s_waitcnt lgkmcnt(0)" ::: "memory");
	s_lshl_b32 s10, s39, 1
	s_add_u32 s10, s36, s10
	s_waitcnt lgkmcnt(0)
	s_addc_u32 s11, s37, 0
	v_mov_b32_e32 v13, v209
	v_lshl_add_u64 v[14:15], s[10:11], 0, v[12:13]
	ds_read_b32 v3, v7
	ds_read_b32 v13, v7 offset:132
	s_mov_b64 s[10:11], 0x1480000
	v_lshl_add_u64 v[18:19], v[14:15], 0, s[10:11]
	s_mov_b64 s[10:11], 0
	s_waitcnt lgkmcnt(0)
	v_cvt_pk_bf16_f32 v14, v3, v13
	ds_read_b32 v3, v7 offset:264
	ds_read_b32 v13, v7 offset:396
	s_waitcnt lgkmcnt(0)
	v_cvt_pk_bf16_f32 v15, v3, v13
	ds_read_b32 v3, v7 offset:528
	ds_read_b32 v13, v7 offset:660
	s_waitcnt lgkmcnt(0)
	v_cvt_pk_bf16_f32 v16, v3, v13
	ds_read_b32 v3, v7 offset:792
	ds_read_b32 v13, v7 offset:924
	s_waitcnt lgkmcnt(0)
	v_cvt_pk_bf16_f32 v17, v3, v13
	v_or_b32_e32 v3, s35, v5
	v_mul_u32_u24_e32 v3, 0xb00, v3
	v_lshlrev_b32_e32 v208, 1, v3
	v_lshl_add_u64 v[22:23], v[18:19], 0, v[208:209]
	global_store_dwordx4 v[22:23], v[14:17], off
	ds_read_b32 v3, v7 offset:32
	ds_read_b32 v13, v7 offset:164
	s_waitcnt lgkmcnt(0)
	v_cvt_pk_bf16_f32 v14, v3, v13
	ds_read_b32 v3, v7 offset:296
	ds_read_b32 v13, v7 offset:428
	s_waitcnt lgkmcnt(0)
	v_cvt_pk_bf16_f32 v15, v3, v13
	ds_read_b32 v3, v7 offset:560
	ds_read_b32 v13, v7 offset:692
	s_waitcnt lgkmcnt(0)
	v_cvt_pk_bf16_f32 v16, v3, v13
	ds_read_b32 v3, v7 offset:824
	ds_read_b32 v13, v7 offset:956
	s_waitcnt lgkmcnt(0)
	v_cvt_pk_bf16_f32 v17, v3, v13
	v_or_b32_e32 v3, s35, v9
	v_mul_u32_u24_e32 v3, 0xb00, v3
	v_lshlrev_b32_e32 v208, 1, v3
	v_lshl_add_u64 v[22:23], v[18:19], 0, v[208:209]
	global_store_dwordx4 v[22:23], v[14:17], off
	ds_read_b32 v3, v7 offset:64
	ds_read_b32 v13, v7 offset:196
	s_waitcnt lgkmcnt(0)
	v_cvt_pk_bf16_f32 v14, v3, v13
	ds_read_b32 v3, v7 offset:328
	ds_read_b32 v13, v7 offset:460
	s_waitcnt lgkmcnt(0)
	v_cvt_pk_bf16_f32 v15, v3, v13
	ds_read_b32 v3, v7 offset:592
	ds_read_b32 v13, v7 offset:724
	s_waitcnt lgkmcnt(0)
	v_cvt_pk_bf16_f32 v16, v3, v13
	ds_read_b32 v3, v7 offset:856
	ds_read_b32 v13, v7 offset:988
	s_waitcnt lgkmcnt(0)
	v_cvt_pk_bf16_f32 v17, v3, v13
	v_or_b32_e32 v3, s35, v11
	v_mul_u32_u24_e32 v3, 0xb00, v3
	v_lshlrev_b32_e32 v208, 1, v3
	v_lshl_add_u64 v[22:23], v[18:19], 0, v[208:209]
	global_store_dwordx4 v[22:23], v[14:17], off
	ds_read_b32 v3, v7 offset:96
	ds_read_b32 v13, v7 offset:228
	s_waitcnt lgkmcnt(0)
	v_cvt_pk_bf16_f32 v14, v3, v13
	ds_read_b32 v3, v7 offset:360
	ds_read_b32 v13, v7 offset:492
	s_waitcnt lgkmcnt(0)
	v_cvt_pk_bf16_f32 v15, v3, v13
	ds_read_b32 v3, v7 offset:624
	ds_read_b32 v13, v7 offset:756
	s_waitcnt lgkmcnt(0)
	v_cvt_pk_bf16_f32 v16, v3, v13
	ds_read_b32 v3, v7 offset:888
	ds_read_b32 v13, v7 offset:1020
	s_waitcnt lgkmcnt(0)
	v_cvt_pk_bf16_f32 v17, v3, v13
	v_or_b32_e32 v3, s35, v20
	v_mul_u32_u24_e32 v3, 0xb00, v3
	v_lshlrev_b32_e32 v208, 1, v3
	v_lshl_add_u64 v[18:19], v[18:19], 0, v[208:209]
	global_store_dwordx4 v[18:19], v[14:17], off
	s_waitcnt lgkmcnt(0)

;     const int nblk = N / 32, kb = item / nblk, nb = item % nblk, k0 = 64 * kb, n0 = 32 * nb;
; #pragma unroll 8
;     for (int i = 0; i < 32; ++i) { const int kk = 2 * i + (lane >> 5); scr[kk * 33 + (lane & 31)] = W[(size_t)(k0 + kk) * N + n0 + (lane & 31)]; }
;     asm volatile("s_waitcnt lgkmcnt(0)" ::: "memory");
.LBB0_94:
	s_lshl_b32 s45, s42, 1
	s_lshl_b32 s44, s41, 1
	v_or_b32_e32 v13, s45, v6
	v_or_b32_e32 v3, s44, v1
	v_add_u32_e32 v15, s39, v13
	v_add_u32_e32 v16, s40, v3
	v_mad_u64_u32 v[18:19], s[46:47], v15, s1, v[14:15]
	v_mad_u64_u32 v[16:17], s[46:47], v16, s1, v[14:15]
	v_mov_b32_e32 v19, v209
	v_lshl_add_u64 v[18:19], v[18:19], 2, s[10:11]
	v_mov_b32_e32 v17, v209
	v_lshl_add_u64 v[16:17], v[16:17], 2, s[10:11]
	global_load_dword v15, v[18:19], off
	global_load_dword v21, v[16:17], off
	v_mad_u64_u32 v[16:17], s[46:47], v13, s33, v[10:11]
	v_mad_u64_u32 v[18:19], s[46:47], v3, s33, v[10:11]
	s_add_i32 s47, s45, 4
	s_add_i32 s46, s44, 4
	v_or_b32_e32 v13, s47, v6
	v_or_b32_e32 v3, s46, v1
	s_add_i32 s42, s42, 16
	s_add_i32 s41, s41, 16
	s_add_i32 s43, s43, -16
	s_waitcnt vmcnt(0)
	ds_write_b32 v16, v15
	ds_write_b32 v18, v21
	v_add_u32_e32 v15, s39, v13
	v_add_u32_e32 v16, s40, v3
	v_mad_u64_u32 v[18:19], s[46:47], v15, s1, v[14:15]
	v_mad_u64_u32 v[16:17], s[46:47], v16, s1, v[14:15]
	v_mov_b32_e32 v19, v209
	v_lshl_add_u64 v[18:19], v[18:19], 2, s[10:11]
	v_mov_b32_e32 v17, v209
	v_lshl_add_u64 v[16:17], v[16:17], 2, s[10:11]
	global_load_dword v15, v[18:19], off
	global_load_dword v21, v[16:17], off
	v_mad_u64_u32 v[16:17], s[46:47], v13, s33, v[10:11]
	v_mad_u64_u32 v[18:19], s[46:47], v3, s33, v[10:11]
	s_add_i32 s47, s45, 8
	s_add_i32 s46, s44, 8
	v_or_b32_e32 v13, s47, v6
	v_or_b32_e32 v3, s46, v1
	s_waitcnt vmcnt(1)
	ds_write_b32 v16, v15
	s_waitcnt vmcnt(0)
	ds_write_b32 v18, v21
	v_add_u32_e32 v15, s39, v13
	v_add_u32_e32 v16, s40, v3
	v_mad_u64_u32 v[18:19], s[46:47], v15, s1, v[14:15]
	v_mad_u64_u32 v[16:17], s[46:47], v16, s1, v[14:15]
	v_mov_b32_e32 v19, v209
	v_lshl_add_u64 v[18:19], v[18:19], 2, s[10:11]
	v_mov_b32_e32 v17, v209
	v_lshl_add_u64 v[16:17], v[16:17], 2, s[10:11]
	global_load_dword v15, v[18:19], off
	global_load_dword v21, v[16:17], off
	v_mad_u64_u32 v[16:17], s[46:47], v13, s33, v[10:11]
	v_mad_u64_u32 v[18:19], s[46:47], v3, s33, v[10:11]
	s_add_i32 s47, s45, 12
	s_add_i32 s46, s44, 12
	v_or_b32_e32 v13, s47, v6
	v_or_b32_e32 v3, s46, v1
	s_waitcnt vmcnt(1)
	ds_write_b32 v16, v15
	s_waitcnt vmcnt(0)
	ds_write_b32 v18, v21
	v_add_u32_e32 v15, s39, v13
	v_add_u32_e32 v16, s40, v3
	v_mad_u64_u32 v[18:19], s[46:47], v15, s1, v[14:15]
	v_mad_u64_u32 v[16:17], s[46:47], v16, s1, v[14:15]
	v_mov_b32_e32 v19, v209
	v_lshl_add_u64 v[18:19], v[18:19], 2, s[10:11]
	v_mov_b32_e32 v17, v209
	v_lshl_add_u64 v[16:17], v[16:17], 2, s[10:11]
	global_load_dword v15, v[18:19], off
	global_load_dword v21, v[16:17], off
	v_mad_u64_u32 v[16:17], s[46:47], v13, s33, v[10:11]
	v_mad_u64_u32 v[18:19], s[46:47], v3, s33, v[10:11]
	s_add_i32 s47, s45, 16
	s_add_i32 s46, s44, 16
	v_or_b32_e32 v13, s47, v6
	v_or_b32_e32 v3, s46, v1
	s_waitcnt vmcnt(1)
	ds_write_b32 v16, v15
	s_waitcnt vmcnt(0)
	ds_write_b32 v18, v21
	v_add_u32_e32 v15, s39, v13
	v_add_u32_e32 v16, s40, v3
	v_mad_u64_u32 v[18:19], s[46:47], v15, s1, v[14:15]
	v_mad_u64_u32 v[16:17], s[46:47], v16, s1, v[14:15]
	v_mov_b32_e32 v19, v209
	v_lshl_add_u64 v[18:19], v[18:19], 2, s[10:11]
	v_mov_b32_e32 v17, v209
	v_lshl_add_u64 v[16:17], v[16:17], 2, s[10:11]
	global_load_dword v15, v[18:19], off
	global_load_dword v21, v[16:17], off
	v_mad_u64_u32 v[16:17], s[46:47], v13, s33, v[10:11]
	v_mad_u64_u32 v[18:19], s[46:47], v3, s33, v[10:11]
	s_add_i32 s47, s45, 20
	s_add_i32 s46, s44, 20
	v_or_b32_e32 v13, s47, v6
	v_or_b32_e32 v3, s46, v1
	s_waitcnt vmcnt(1)
	ds_write_b32 v16, v15
	s_waitcnt vmcnt(0)
	ds_write_b32 v18, v21
	v_add_u32_e32 v15, s39, v13
	v_add_u32_e32 v16, s40, v3
	v_mad_u64_u32 v[18:19], s[46:47], v15, s1, v[14:15]
	v_mad_u64_u32 v[16:17], s[46:47], v16, s1, v[14:15]
	v_mov_b32_e32 v19, v209
	v_lshl_add_u64 v[18:19], v[18:19], 2, s[10:11]
	v_mov_b32_e32 v17, v209
	v_lshl_add_u64 v[16:17], v[16:17], 2, s[10:11]
	global_load_dword v15, v[18:19], off
	global_load_dword v21, v[16:17], off
	v_mad_u64_u32 v[16:17], s[46:47], v13, s33, v[10:11]
	v_mad_u64_u32 v[18:19], s[46:47], v3, s33, v[10:11]
	s_add_i32 s47, s45, 24
	s_add_i32 s46, s44, 24
	v_or_b32_e32 v13, s47, v6
	v_or_b32_e32 v3, s46, v1
	s_add_i32 s45, s45, 28
	s_add_i32 s44, s44, 28
	s_cmp_lg_u32 s43, 0
	s_waitcnt vmcnt(1)
	ds_write_b32 v16, v15
	s_waitcnt vmcnt(0)
	ds_write_b32 v18, v21
	v_add_u32_e32 v15, s39, v13
	v_add_u32_e32 v16, s40, v3
	v_mad_u64_u32 v[18:19], s[46:47], v15, s1, v[14:15]
	v_mad_u64_u32 v[16:17], s[46:47], v16, s1, v[14:15]
	v_mov_b32_e32 v19, v209
	v_lshl_add_u64 v[18:19], v[18:19], 2, s[10:11]
	v_mov_b32_e32 v17, v209
	v_lshl_add_u64 v[16:17], v[16:17], 2, s[10:11]
	global_load_dword v15, v[18:19], off
	global_load_dword v21, v[16:17], off
	v_mad_u64_u32 v[16:17], s[46:47], v13, s33, v[10:11]
	v_or_b32_e32 v13, s45, v6
	v_mad_u64_u32 v[18:19], s[46:47], v3, s33, v[10:11]
	v_or_b32_e32 v3, s44, v1
	s_waitcnt vmcnt(1)
	ds_write_b32 v16, v15
	s_waitcnt vmcnt(0)
	ds_write_b32 v18, v21
	v_add_u32_e32 v15, s39, v13
	v_add_u32_e32 v16, s40, v3
	v_mad_u64_u32 v[18:19], s[44:45], v15, s1, v[14:15]
	v_mad_u64_u32 v[16:17], s[44:45], v16, s1, v[14:15]
	v_mov_b32_e32 v19, v209
	v_lshl_add_u64 v[18:19], v[18:19], 2, s[10:11]
	v_mov_b32_e32 v17, v209
	v_lshl_add_u64 v[16:17], v[16:17], 2, s[10:11]
	global_load_dword v15, v[18:19], off
	global_load_dword v21, v[16:17], off
	v_mad_u64_u32 v[16:17], s[44:45], v13, s33, v[10:11]
	v_mad_u64_u32 v[18:19], s[44:45], v3, s33, v[10:11]
	s_waitcnt vmcnt(1)
	ds_write_b32 v16, v15
	s_waitcnt vmcnt(0)
	ds_write_b32 v18, v21
	s_cbranch_scc1 .LBB0_94
; #define LAS __attribute__((address_space(3)))
; __device__ __forceinline__ unsigned pk2(float lo, float hi) { const f32x2_cv v = {lo, hi}; const bf16x2_cv b = __builtin_convertvector(v, bf16x2_cv); return __builtin_bit_cast(unsigned, b); }
;     ...
;     const int c = lane & 7;
; #pragma unroll
;     for (int j = 0; j < 4; ++j) { const int n = (lane >> 3) + 8 * j; const LAS float* s = scr + (8 * c) * 33 + n;
;         v4u o; o.x = pk2(s[0 * 33], s[1 * 33]); o.y = pk2(s[2 * 33], s[3 * 33]); o.z = pk2(s[4 * 33], s[5 * 33]); o.w = pk2(s[6 * 33], s[7 * 33]);
;         int row = n0 + n; if (PERM_UP == 2) { const int nl = row & 255; row = (row & ~255) + 128 * ((nl >> 5) & 1) + 32 * (nl >> 6) + (nl & 31); }
;         if (PERM_UP == 1) { const bool isv = row >= DFF; const int ch = isv ? row - DFF : row; row = (ch >> 7) * 256 + (isv ? 128 : 0) + (ch & 127); }
;         *(v4u*)(WT + (size_t)row * K + k0 + 8 * c) = o; }
;     asm volatile("s_waitcnt lgkmcnt(0)" ::: "memory");
	s_and_b32 s10, 0xffff, s39
	s_lshl_b32 s10, s10, 1
	s_add_u32 s10, s36, s10
	s_waitcnt lgkmcnt(0)
	s_addc_u32 s11, s37, 0
	v_mov_b32_e32 v13, v209
	v_lshl_add_u64 v[14:15], s[10:11], 0, v[12:13]
	ds_read_b32 v3, v7
	ds_read_b32 v13, v7 offset:132
	s_mov_b64 s[10:11], 0x980000
	v_lshl_add_u64 v[18:19], v[14:15], 0, s[10:11]
	s_and_b32 s10, 0xffff, s38
	s_cmpk_gt_u32 s10, 0x57
	s_waitcnt lgkmcnt(0)
	v_cvt_pk_bf16_f32 v14, v3, v13
	ds_read_b32 v3, v7 offset:264
	ds_read_b32 v13, v7 offset:396
	s_cselect_b64 vcc, -1, 0
	s_and_b64 s[10:11], vcc, exec
	s_cselect_b32 s10, 0x80, 0
	s_waitcnt lgkmcnt(0)
	v_cvt_pk_bf16_f32 v15, v3, v13
	ds_read_b32 v3, v7 offset:528
	ds_read_b32 v13, v7 offset:660
	s_waitcnt lgkmcnt(0)
	v_cvt_pk_bf16_f32 v16, v3, v13
	ds_read_b32 v3, v7 offset:792
	ds_read_b32 v13, v7 offset:924
	s_waitcnt lgkmcnt(0)
	v_cvt_pk_bf16_f32 v17, v3, v13
	v_or_b32_e32 v3, s35, v5
	v_add_u32_e32 v13, 0xfffff500, v3
	v_cndmask_b32_e32 v3, v3, v13, vcc
	v_lshlrev_b32_e32 v13, 1, v3
	v_and_b32_e32 v13, 0xffffff00, v13
	v_and_b32_e32 v3, 0x67, v3
	v_or3_b32 v22, v3, v13, s10
	v_ashrrev_i32_e32 v23, 31, v22
	v_lshlrev_b64 v[22:23], 11, v[22:23]
	v_lshl_add_u64 v[22:23], v[18:19], 0, v[22:23]
	global_store_dwordx4 v[22:23], v[14:17], off
	ds_read_b32 v3, v7 offset:32
	ds_read_b32 v13, v7 offset:164
	s_waitcnt lgkmcnt(0)
	v_cvt_pk_bf16_f32 v14, v3, v13
	ds_read_b32 v3, v7 offset:296
	ds_read_b32 v13, v7 offset:428
	s_waitcnt lgkmcnt(0)
	v_cvt_pk_bf16_f32 v15, v3, v13
	ds_read_b32 v3, v7 offset:560
	ds_read_b32 v13, v7 offset:692
	s_waitcnt lgkmcnt(0)
	v_cvt_pk_bf16_f32 v16, v3, v13
	ds_read_b32 v3, v7 offset:824
	ds_read_b32 v13, v7 offset:956
	s_waitcnt lgkmcnt(0)
	v_cvt_pk_bf16_f32 v17, v3, v13
	v_or_b32_e32 v3, s35, v9
	v_add_u32_e32 v13, 0xfffff500, v3
	v_cndmask_b32_e32 v3, v3, v13, vcc
	v_lshlrev_b32_e32 v13, 1, v3
	v_and_b32_e32 v13, 0xffffff00, v13
	v_and_b32_e32 v3, 0x6f, v3
	v_or3_b32 v22, v3, v13, s10
	v_ashrrev_i32_e32 v23, 31, v22
	v_lshlrev_b64 v[22:23], 11, v[22:23]
	v_lshl_add_u64 v[22:23], v[18:19], 0, v[22:23]
	global_store_dwordx4 v[22:23], v[14:17], off
	ds_read_b32 v3, v7 offset:64
	ds_read_b32 v13, v7 offset:196
	s_waitcnt lgkmcnt(0)
	v_cvt_pk_bf16_f32 v14, v3, v13
	ds_read_b32 v3, v7 offset:328
	ds_read_b32 v13, v7 offset:460
	s_waitcnt lgkmcnt(0)
	v_cvt_pk_bf16_f32 v15, v3, v13
	ds_read_b32 v3, v7 offset:592
	ds_read_b32 v13, v7 offset:724
	s_waitcnt lgkmcnt(0)
	v_cvt_pk_bf16_f32 v16, v3, v13
	ds_read_b32 v3, v7 offset:856
	ds_read_b32 v13, v7 offset:988
	s_waitcnt lgkmcnt(0)
	v_cvt_pk_bf16_f32 v17, v3, v13
	v_or_b32_e32 v3, s35, v11
	v_add_u32_e32 v13, 0xfffff500, v3
	v_cndmask_b32_e32 v3, v3, v13, vcc
	v_lshlrev_b32_e32 v13, 1, v3
	v_and_b32_e32 v13, 0xffffff00, v13
	v_and_b32_e32 v3, 0x77, v3
	v_or3_b32 v22, v3, v13, s10
	v_ashrrev_i32_e32 v23, 31, v22
	v_lshlrev_b64 v[22:23], 11, v[22:23]
	v_lshl_add_u64 v[22:23], v[18:19], 0, v[22:23]
	global_store_dwordx4 v[22:23], v[14:17], off
	ds_read_b32 v3, v7 offset:96
	ds_read_b32 v13, v7 offset:228
	s_waitcnt lgkmcnt(0)
	v_cvt_pk_bf16_f32 v14, v3, v13
	ds_read_b32 v3, v7 offset:360
	ds_read_b32 v13, v7 offset:492
	s_waitcnt lgkmcnt(0)
	v_cvt_pk_bf16_f32 v15, v3, v13
	ds_read_b32 v3, v7 offset:624
	ds_read_b32 v13, v7 offset:756
	s_waitcnt lgkmcnt(0)
	v_cvt_pk_bf16_f32 v16, v3, v13
	ds_read_b32 v3, v7 offset:888
	ds_read_b32 v13, v7 offset:1020
	s_waitcnt lgkmcnt(0)
	v_cvt_pk_bf16_f32 v17, v3, v13
	v_or_b32_e32 v3, s35, v20
	v_add_u32_e32 v13, 0xfffff500, v3
	v_cndmask_b32_e32 v3, v3, v13, vcc
	v_lshlrev_b32_e32 v13, 1, v3
	v_and_b32_e32 v13, 0xffffff00, v13
	v_and_b32_e32 v3, 0x7f, v3
	v_or3_b32 v22, v3, v13, s10
	v_ashrrev_i32_e32 v23, 31, v22
	v_lshlrev_b64 v[22:23], 11, v[22:23]
	v_lshl_add_u64 v[18:19], v[18:19], 0, v[22:23]
	global_store_dwordx4 v[18:19], v[14:17], off
	s_waitcnt lgkmcnt(0)

;     const int nblk = N / 32, kb = item / nblk, nb = item % nblk, k0 = 64 * kb, n0 = 32 * nb;
; #pragma unroll 8
;     for (int i = 0; i < 32; ++i) { const int kk = 2 * i + (lane >> 5); scr[kk * 33 + (lane & 31)] = W[(size_t)(k0 + kk) * N + n0 + (lane & 31)]; }
;     asm volatile("s_waitcnt lgkmcnt(0)" ::: "memory");
.LBB0_99:
	s_lshl_b32 s44, s41, 1
	s_lshl_b32 s43, s38, 1
	v_or_b32_e32 v15, s44, v6
	v_or_b32_e32 v13, s43, v1
	v_add_lshl_u32 v17, v15, s39, 10
	v_add_lshl_u32 v16, v13, s40, 10
	v_or_b32_e32 v208, v14, v17
	v_or_b32_e32 v16, v3, v16
	v_lshl_add_u64 v[18:19], v[208:209], 2, s[10:11]
	v_mov_b32_e32 v17, v209
	v_lshl_add_u64 v[16:17], v[16:17], 2, s[10:11]
	global_load_dword v21, v[18:19], off
	global_load_dword v22, v[16:17], off
	v_mad_u64_u32 v[16:17], s[46:47], v15, s33, v[10:11]
	v_mad_u64_u32 v[18:19], s[46:47], v13, s33, v[10:11]
	s_add_i32 s46, s44, 4
	s_add_i32 s45, s43, 4
	v_or_b32_e32 v15, s46, v6
	v_or_b32_e32 v13, s45, v1
	v_add_lshl_u32 v17, v15, s39, 10
	v_or_b32_e32 v208, v14, v17
	v_mov_b32_e32 v17, v209
	s_add_i32 s45, s43, 8
	s_add_i32 s41, s41, 16
	s_add_i32 s38, s38, 16
	s_add_i32 s42, s42, -16
	s_waitcnt vmcnt(0)
	ds_write_b32 v16, v21
	ds_write_b32 v18, v22
	v_add_lshl_u32 v16, v13, s40, 10
	v_or_b32_e32 v16, v3, v16
	v_lshl_add_u64 v[18:19], v[208:209], 2, s[10:11]
	v_lshl_add_u64 v[16:17], v[16:17], 2, s[10:11]
	global_load_dword v21, v[18:19], off
	global_load_dword v22, v[16:17], off
	v_mad_u64_u32 v[16:17], s[46:47], v15, s33, v[10:11]
	v_mad_u64_u32 v[18:19], s[46:47], v13, s33, v[10:11]
	s_add_i32 s46, s44, 8
	s_nop 0
	v_or_b32_e32 v15, s46, v6
	v_or_b32_e32 v13, s45, v1
	v_add_lshl_u32 v17, v15, s39, 10
	v_or_b32_e32 v208, v14, v17
	v_mov_b32_e32 v17, v209
	s_add_i32 s45, s43, 12
	s_waitcnt vmcnt(1)
	ds_write_b32 v16, v21
	s_waitcnt vmcnt(0)
	ds_write_b32 v18, v22
	v_add_lshl_u32 v16, v13, s40, 10
	v_or_b32_e32 v16, v3, v16
	v_lshl_add_u64 v[18:19], v[208:209], 2, s[10:11]
	v_lshl_add_u64 v[16:17], v[16:17], 2, s[10:11]
	global_load_dword v21, v[18:19], off
	global_load_dword v22, v[16:17], off
	v_mad_u64_u32 v[16:17], s[46:47], v15, s33, v[10:11]
	v_mad_u64_u32 v[18:19], s[46:47], v13, s33, v[10:11]
	s_add_i32 s46, s44, 12
	s_nop 0
	v_or_b32_e32 v15, s46, v6
	v_or_b32_e32 v13, s45, v1
	v_add_lshl_u32 v17, v15, s39, 10
	v_or_b32_e32 v208, v14, v17
	v_mov_b32_e32 v17, v209
	s_add_i32 s45, s43, 16
	s_waitcnt vmcnt(1)
	ds_write_b32 v16, v21
	s_waitcnt vmcnt(0)
	ds_write_b32 v18, v22
	v_add_lshl_u32 v16, v13, s40, 10
	v_or_b32_e32 v16, v3, v16
	v_lshl_add_u64 v[18:19], v[208:209], 2, s[10:11]
	v_lshl_add_u64 v[16:17], v[16:17], 2, s[10:11]
	global_load_dword v21, v[18:19], off
	global_load_dword v22, v[16:17], off
	v_mad_u64_u32 v[16:17], s[46:47], v15, s33, v[10:11]
	v_mad_u64_u32 v[18:19], s[46:47], v13, s33, v[10:11]
	s_add_i32 s46, s44, 16
	s_nop 0
	v_or_b32_e32 v15, s46, v6
	v_or_b32_e32 v13, s45, v1
	v_add_lshl_u32 v17, v15, s39, 10
	v_or_b32_e32 v208, v14, v17
	v_mov_b32_e32 v17, v209
	s_add_i32 s45, s43, 20
	s_waitcnt vmcnt(1)
	ds_write_b32 v16, v21
	s_waitcnt vmcnt(0)
	ds_write_b32 v18, v22
	v_add_lshl_u32 v16, v13, s40, 10
	v_or_b32_e32 v16, v3, v16
	v_lshl_add_u64 v[18:19], v[208:209], 2, s[10:11]
	v_lshl_add_u64 v[16:17], v[16:17], 2, s[10:11]
	global_load_dword v21, v[18:19], off
	global_load_dword v22, v[16:17], off
	v_mad_u64_u32 v[16:17], s[46:47], v15, s33, v[10:11]
	v_mad_u64_u32 v[18:19], s[46:47], v13, s33, v[10:11]
	s_add_i32 s46, s44, 20
	s_nop 0
	v_or_b32_e32 v15, s46, v6
	v_or_b32_e32 v13, s45, v1
	v_add_lshl_u32 v17, v15, s39, 10
	v_or_b32_e32 v208, v14, v17
	v_mov_b32_e32 v17, v209
	s_add_i32 s45, s43, 24
	s_add_i32 s43, s43, 28
	s_waitcnt vmcnt(1)
	ds_write_b32 v16, v21
	s_waitcnt vmcnt(0)
	ds_write_b32 v18, v22
	v_add_lshl_u32 v16, v13, s40, 10
	v_or_b32_e32 v16, v3, v16
	v_lshl_add_u64 v[18:19], v[208:209], 2, s[10:11]
	v_lshl_add_u64 v[16:17], v[16:17], 2, s[10:11]
	global_load_dword v21, v[18:19], off
	global_load_dword v22, v[16:17], off
	v_mad_u64_u32 v[16:17], s[46:47], v15, s33, v[10:11]
	v_mad_u64_u32 v[18:19], s[46:47], v13, s33, v[10:11]
	s_add_i32 s46, s44, 24
	s_nop 0
	v_or_b32_e32 v15, s46, v6
	v_or_b32_e32 v13, s45, v1
	v_add_lshl_u32 v17, v15, s39, 10
	v_or_b32_e32 v208, v14, v17
	v_mov_b32_e32 v17, v209
	s_add_i32 s44, s44, 28
	s_cmp_lg_u32 s42, 0
	s_waitcnt vmcnt(1)
	ds_write_b32 v16, v21
	s_waitcnt vmcnt(0)
	ds_write_b32 v18, v22
	v_add_lshl_u32 v16, v13, s40, 10
	v_or_b32_e32 v16, v3, v16
	v_lshl_add_u64 v[18:19], v[208:209], 2, s[10:11]
	v_lshl_add_u64 v[16:17], v[16:17], 2, s[10:11]
	global_load_dword v21, v[18:19], off
	global_load_dword v22, v[16:17], off
	v_mad_u64_u32 v[16:17], s[46:47], v15, s33, v[10:11]
	v_or_b32_e32 v15, s44, v6
	v_mad_u64_u32 v[18:19], s[46:47], v13, s33, v[10:11]
	v_or_b32_e32 v13, s43, v1
	v_add_lshl_u32 v17, v15, s39, 10
	v_or_b32_e32 v208, v14, v17
	v_mov_b32_e32 v19, v209
	s_waitcnt vmcnt(1)
	ds_write_b32 v16, v21
	s_waitcnt vmcnt(0)
	ds_write_b32 v18, v22
	v_add_lshl_u32 v16, v13, s40, 10
	v_or_b32_e32 v18, v3, v16
	v_lshl_add_u64 v[16:17], v[208:209], 2, s[10:11]
	v_lshl_add_u64 v[18:19], v[18:19], 2, s[10:11]
	global_load_dword v21, v[16:17], off
	global_load_dword v22, v[18:19], off
	v_mad_u64_u32 v[16:17], s[44:45], v15, s33, v[10:11]
	v_mad_u64_u32 v[18:19], s[44:45], v13, s33, v[10:11]
	s_waitcnt vmcnt(1)
	ds_write_b32 v16, v21
	s_waitcnt vmcnt(0)
	ds_write_b32 v18, v22
	s_cbranch_scc1 .LBB0_99
; #define LAS __attribute__((address_space(3)))
; __device__ __forceinline__ unsigned pk2(float lo, float hi) { const f32x2_cv v = {lo, hi}; const bf16x2_cv b = __builtin_convertvector(v, bf16x2_cv); return __builtin_bit_cast(unsigned, b); }
;     ...
;     const int c = lane & 7;
; #pragma unroll
;     for (int j = 0; j < 4; ++j) { const int n = (lane >> 3) + 8 * j; const LAS float* s = scr + (8 * c) * 33 + n;
;         v4u o; o.x = pk2(s[0 * 33], s[1 * 33]); o.y = pk2(s[2 * 33], s[3 * 33]); o.z = pk2(s[4 * 33], s[5 * 33]); o.w = pk2(s[6 * 33], s[7 * 33]);
;         int row = n0 + n; if (PERM_UP == 2) { const int nl = row & 255; row = (row & ~255) + 128 * ((nl >> 5) & 1) + 32 * (nl >> 6) + (nl & 31); }
;         if (PERM_UP == 1) { const bool isv = row >= DFF; const int ch = isv ? row - DFF : row; row = (ch >> 7) * 256 + (isv ? 128 : 0) + (ch & 127); }
;         *(v4u*)(WT + (size_t)row * K + k0 + 8 * c) = o; }
;     asm volatile("s_waitcnt lgkmcnt(0)" ::: "memory");
	s_lshl_b32 s10, s39, 1
	s_add_u32 s10, s36, s10
	s_waitcnt lgkmcnt(0)
	s_addc_u32 s11, s37, 0
	v_mov_b32_e32 v13, v209
	v_lshl_add_u64 v[14:15], s[10:11], 0, v[12:13]
	ds_read_b32 v3, v7
	ds_read_b32 v13, v7 offset:132
	s_mov_b64 s[10:11], 0x780000
	v_lshl_add_u64 v[18:19], v[14:15], 0, s[10:11]
	s_waitcnt lgkmcnt(0)
	v_cvt_pk_bf16_f32 v14, v3, v13
	ds_read_b32 v3, v7 offset:264
	ds_read_b32 v13, v7 offset:396
	s_waitcnt lgkmcnt(0)
	v_cvt_pk_bf16_f32 v15, v3, v13
	ds_read_b32 v3, v7 offset:528
	ds_read_b32 v13, v7 offset:660
	s_waitcnt lgkmcnt(0)
	v_cvt_pk_bf16_f32 v16, v3, v13
	ds_read_b32 v3, v7 offset:792
	ds_read_b32 v13, v7 offset:924
	s_waitcnt lgkmcnt(0)
	v_cvt_pk_bf16_f32 v17, v3, v13
	v_or_b32_e32 v3, s35, v5
	v_lshlrev_b32_e32 v208, 11, v3
	v_lshl_add_u64 v[22:23], v[18:19], 0, v[208:209]
	global_store_dwordx4 v[22:23], v[14:17], off
	ds_read_b32 v3, v7 offset:32
	ds_read_b32 v13, v7 offset:164
	s_waitcnt lgkmcnt(0)
	v_cvt_pk_bf16_f32 v14, v3, v13
	ds_read_b32 v3, v7 offset:296
	ds_read_b32 v13, v7 offset:428
	s_waitcnt lgkmcnt(0)
	v_cvt_pk_bf16_f32 v15, v3, v13
	ds_read_b32 v3, v7 offset:560
	ds_read_b32 v13, v7 offset:692
	s_waitcnt lgkmcnt(0)
	v_cvt_pk_bf16_f32 v16, v3, v13
	ds_read_b32 v3, v7 offset:824
	ds_read_b32 v13, v7 offset:956
	s_waitcnt lgkmcnt(0)
	v_cvt_pk_bf16_f32 v17, v3, v13
	v_or_b32_e32 v3, s35, v9
	v_lshlrev_b32_e32 v208, 11, v3
	v_lshl_add_u64 v[22:23], v[18:19], 0, v[208:209]
	global_store_dwordx4 v[22:23], v[14:17], off
	ds_read_b32 v3, v7 offset:64
	ds_read_b32 v13, v7 offset:196
	s_waitcnt lgkmcnt(0)
	v_cvt_pk_bf16_f32 v14, v3, v13
	ds_read_b32 v3, v7 offset:328
	ds_read_b32 v13, v7 offset:460
	s_waitcnt lgkmcnt(0)
	v_cvt_pk_bf16_f32 v15, v3, v13
	ds_read_b32 v3, v7 offset:592
	ds_read_b32 v13, v7 offset:724
	s_waitcnt lgkmcnt(0)
	v_cvt_pk_bf16_f32 v16, v3, v13
	ds_read_b32 v3, v7 offset:856
	ds_read_b32 v13, v7 offset:988
	s_waitcnt lgkmcnt(0)
	v_cvt_pk_bf16_f32 v17, v3, v13
	v_or_b32_e32 v3, s35, v11
	v_lshlrev_b32_e32 v208, 11, v3
	v_lshl_add_u64 v[22:23], v[18:19], 0, v[208:209]
	global_store_dwordx4 v[22:23], v[14:17], off
	ds_read_b32 v3, v7 offset:96
	ds_read_b32 v13, v7 offset:228
	s_waitcnt lgkmcnt(0)
	v_cvt_pk_bf16_f32 v14, v3, v13
	ds_read_b32 v3, v7 offset:360
	ds_read_b32 v13, v7 offset:492
	s_waitcnt lgkmcnt(0)
	v_cvt_pk_bf16_f32 v15, v3, v13
	ds_read_b32 v3, v7 offset:624
	ds_read_b32 v13, v7 offset:756
	s_waitcnt lgkmcnt(0)
	v_cvt_pk_bf16_f32 v16, v3, v13
	ds_read_b32 v3, v7 offset:888
	ds_read_b32 v13, v7 offset:1020
	s_waitcnt lgkmcnt(0)
	v_cvt_pk_bf16_f32 v17, v3, v13
	v_or_b32_e32 v3, s35, v20
	v_lshlrev_b32_e32 v208, 11, v3
	v_lshl_add_u64 v[18:19], v[18:19], 0, v[208:209]
	global_store_dwordx4 v[18:19], v[14:17], off
	s_waitcnt lgkmcnt(0)

;     const int nblk = N / 32, kb = item / nblk, nb = item % nblk, k0 = 64 * kb, n0 = 32 * nb;
; #pragma unroll 8
;     for (int i = 0; i < 32; ++i) { const int kk = 2 * i + (lane >> 5); scr[kk * 33 + (lane & 31)] = W[(size_t)(k0 + kk) * N + n0 + (lane & 31)]; }
;     asm volatile("s_waitcnt lgkmcnt(0)" ::: "memory");
.LBB0_104:
	s_lshl_b32 s42, s39, 1
	s_lshl_b32 s41, s37, 1
	v_or_b32_e32 v18, s42, v16
	v_or_b32_e32 v21, s41, v3
	v_mad_i64_i32 v[18:19], s[44:45], v18, s0, v[14:15]
	v_mad_i64_i32 v[22:23], s[44:45], v21, s0, v[14:15]
	global_load_dword v21, v[18:19], off
	global_load_dword v24, v[22:23], off
	v_or_b32_e32 v13, s41, v1
	v_or_b32_e32 v17, s42, v6
	v_mad_u64_u32 v[18:19], s[44:45], v17, s33, v[10:11]
	v_mad_u64_u32 v[22:23], s[44:45], v13, s33, v[10:11]
	s_add_i32 s44, s42, 4
	s_add_i32 s43, s41, 4
	v_or_b32_e32 v17, s44, v6
	v_or_b32_e32 v13, s43, v1
	s_add_i32 s39, s39, 16
	s_add_i32 s37, s37, 16
	s_add_i32 s40, s40, -16
	s_waitcnt vmcnt(0)
	ds_write_b32 v18, v21
	ds_write_b32 v22, v24
	v_or_b32_e32 v18, s44, v16
	v_or_b32_e32 v21, s43, v3
	v_mad_i64_i32 v[18:19], s[44:45], v18, s0, v[14:15]
	v_mad_i64_i32 v[22:23], s[44:45], v21, s0, v[14:15]
	global_load_dword v21, v[18:19], off
	global_load_dword v24, v[22:23], off
	v_mad_u64_u32 v[18:19], s[44:45], v17, s33, v[10:11]
	v_mad_u64_u32 v[22:23], s[44:45], v13, s33, v[10:11]
	s_add_i32 s44, s42, 8
	s_add_i32 s43, s41, 8
	v_or_b32_e32 v17, s44, v6
	v_or_b32_e32 v13, s43, v1
	s_waitcnt vmcnt(1)
	ds_write_b32 v18, v21
	s_waitcnt vmcnt(0)
	ds_write_b32 v22, v24
	v_or_b32_e32 v18, s44, v16
	v_or_b32_e32 v21, s43, v3
	v_mad_i64_i32 v[18:19], s[44:45], v18, s0, v[14:15]
	v_mad_i64_i32 v[22:23], s[44:45], v21, s0, v[14:15]
	global_load_dword v21, v[18:19], off
	global_load_dword v24, v[22:23], off
	v_mad_u64_u32 v[18:19], s[44:45], v17, s33, v[10:11]
	v_mad_u64_u32 v[22:23], s[44:45], v13, s33, v[10:11]
	s_add_i32 s44, s42, 12
	s_add_i32 s43, s41, 12
	v_or_b32_e32 v17, s44, v6
	v_or_b32_e32 v13, s43, v1
	s_waitcnt vmcnt(1)
	ds_write_b32 v18, v21
	s_waitcnt vmcnt(0)
	ds_write_b32 v22, v24
	v_or_b32_e32 v18, s44, v16
	v_or_b32_e32 v21, s43, v3
	v_mad_i64_i32 v[18:19], s[44:45], v18, s0, v[14:15]
	v_mad_i64_i32 v[22:23], s[44:45], v21, s0, v[14:15]
	global_load_dword v21, v[18:19], off
	global_load_dword v24, v[22:23], off
	v_mad_u64_u32 v[18:19], s[44:45], v17, s33, v[10:11]
	v_mad_u64_u32 v[22:23], s[44:45], v13, s33, v[10:11]
	s_add_i32 s44, s42, 16
	s_add_i32 s43, s41, 16
	v_or_b32_e32 v17, s44, v6
	v_or_b32_e32 v13, s43, v1
	s_waitcnt vmcnt(1)
	ds_write_b32 v18, v21
	s_waitcnt vmcnt(0)
	ds_write_b32 v22, v24
	v_or_b32_e32 v18, s44, v16
	v_or_b32_e32 v21, s43, v3
	v_mad_i64_i32 v[18:19], s[44:45], v18, s0, v[14:15]
	v_mad_i64_i32 v[22:23], s[44:45], v21, s0, v[14:15]
	global_load_dword v21, v[18:19], off
	global_load_dword v24, v[22:23], off
	v_mad_u64_u32 v[18:19], s[44:45], v17, s33, v[10:11]
	v_mad_u64_u32 v[22:23], s[44:45], v13, s33, v[10:11]
	s_add_i32 s44, s42, 20
	s_add_i32 s43, s41, 20
	v_or_b32_e32 v17, s44, v6
	v_or_b32_e32 v13, s43, v1
	s_waitcnt vmcnt(1)
	ds_write_b32 v18, v21
	s_waitcnt vmcnt(0)
	ds_write_b32 v22, v24
	v_or_b32_e32 v18, s44, v16
	v_or_b32_e32 v21, s43, v3
	v_mad_i64_i32 v[18:19], s[44:45], v18, s0, v[14:15]
	v_mad_i64_i32 v[22:23], s[44:45], v21, s0, v[14:15]
	global_load_dword v21, v[18:19], off
	global_load_dword v24, v[22:23], off
	v_mad_u64_u32 v[18:19], s[44:45], v17, s33, v[10:11]
	v_mad_u64_u32 v[22:23], s[44:45], v13, s33, v[10:11]
	s_add_i32 s44, s42, 24
	s_add_i32 s43, s41, 24
	v_or_b32_e32 v17, s44, v6
	v_or_b32_e32 v13, s43, v1
	s_add_i32 s42, s42, 28
	s_add_i32 s41, s41, 28
	s_cmp_lg_u32 s40, 0
	s_waitcnt vmcnt(1)
	ds_write_b32 v18, v21
	s_waitcnt vmcnt(0)
	ds_write_b32 v22, v24
	v_or_b32_e32 v18, s44, v16
	v_or_b32_e32 v21, s43, v3
	v_mad_i64_i32 v[18:19], s[44:45], v18, s0, v[14:15]
	v_mad_i64_i32 v[22:23], s[44:45], v21, s0, v[14:15]
	global_load_dword v21, v[18:19], off
	global_load_dword v24, v[22:23], off
	v_mad_u64_u32 v[18:19], s[44:45], v17, s33, v[10:11]
	v_mad_u64_u32 v[22:23], s[44:45], v13, s33, v[10:11]
	v_or_b32_e32 v17, s42, v6
	v_or_b32_e32 v13, s41, v1
	s_waitcnt vmcnt(1)
	ds_write_b32 v18, v21
	s_waitcnt vmcnt(0)
	ds_write_b32 v22, v24
	v_or_b32_e32 v18, s42, v16
	v_or_b32_e32 v21, s41, v3
	v_mad_i64_i32 v[18:19], s[42:43], v18, s0, v[14:15]
	v_mad_i64_i32 v[22:23], s[42:43], v21, s0, v[14:15]
	global_load_dword v21, v[18:19], off
	global_load_dword v24, v[22:23], off
	v_mad_u64_u32 v[18:19], s[42:43], v17, s33, v[10:11]
	v_mad_u64_u32 v[22:23], s[42:43], v13, s33, v[10:11]
	s_waitcnt vmcnt(1)
	ds_write_b32 v18, v21
	s_waitcnt vmcnt(0)
	ds_write_b32 v22, v24
	s_cbranch_scc1 .LBB0_104
; #define LAS __attribute__((address_space(3)))
; __device__ __forceinline__ unsigned pk2(float lo, float hi) { const f32x2_cv v = {lo, hi}; const bf16x2_cv b = __builtin_convertvector(v, bf16x2_cv); return __builtin_bit_cast(unsigned, b); }
;     ...
;     const int c = lane & 7;
; #pragma unroll
;     for (int j = 0; j < 4; ++j) { const int n = (lane >> 3) + 8 * j; const LAS float* s = scr + (8 * c) * 33 + n;
;         v4u o; o.x = pk2(s[0 * 33], s[1 * 33]); o.y = pk2(s[2 * 33], s[3 * 33]); o.z = pk2(s[4 * 33], s[5 * 33]); o.w = pk2(s[6 * 33], s[7 * 33]);
;         int row = n0 + n; if (PERM_UP == 2) { const int nl = row & 255; row = (row & ~255) + 128 * ((nl >> 5) & 1) + 32 * (nl >> 6) + (nl & 31); }
;         if (PERM_UP == 1) { const bool isv = row >= DFF; const int ch = isv ? row - DFF : row; row = (ch >> 7) * 256 + (isv ? 128 : 0) + (ch & 127); }
;         *(v4u*)(WT + (size_t)row * K + k0 + 8 * c) = o; }
;     asm volatile("s_waitcnt lgkmcnt(0)" ::: "memory");
	s_lshl_b32 s35, s35, 7
	s_and_b32 s37, s38, 0xffffff00
	s_and_b32 s35, s35, 0x80
	s_or_b32 s35, s37, s35
	s_lshr_b32 s37, s38, 1
	s_and_b32 s37, s37, 0x60
	s_or_b32 s35, s35, s37
	s_ashr_i32 s37, s36, 31
	s_lshl_b64 s[36:37], s[36:37], 1
	s_add_u32 s10, s10, s36
	s_waitcnt lgkmcnt(0)
	s_addc_u32 s11, s11, s37
	v_mov_b32_e32 v13, v209
	v_lshl_add_u64 v[14:15], s[10:11], 0, v[12:13]
	ds_read_b32 v3, v7
	ds_read_b32 v13, v7 offset:132
	s_mov_b64 s[10:11], 0x200000
	v_lshl_add_u64 v[18:19], v[14:15], 0, s[10:11]
	v_or_b32_e32 v22, s35, v5
	v_ashrrev_i32_e32 v23, 31, v22
	s_waitcnt lgkmcnt(0)
	v_cvt_pk_bf16_f32 v14, v3, v13
	ds_read_b32 v3, v7 offset:264
	ds_read_b32 v13, v7 offset:396
	v_lshlrev_b64 v[22:23], 11, v[22:23]
	v_lshl_add_u64 v[22:23], v[18:19], 0, v[22:23]
	s_waitcnt lgkmcnt(0)
	v_cvt_pk_bf16_f32 v15, v3, v13
	ds_read_b32 v3, v7 offset:528
	ds_read_b32 v13, v7 offset:660
	s_waitcnt lgkmcnt(0)
	v_cvt_pk_bf16_f32 v16, v3, v13
	ds_read_b32 v3, v7 offset:792
	ds_read_b32 v13, v7 offset:924
	s_waitcnt lgkmcnt(0)
	v_cvt_pk_bf16_f32 v17, v3, v13
	global_store_dwordx4 v[22:23], v[14:17], off
	ds_read_b32 v3, v7 offset:32
	ds_read_b32 v13, v7 offset:164
	v_or_b32_e32 v22, s35, v9
	v_ashrrev_i32_e32 v23, 31, v22
	v_lshlrev_b64 v[22:23], 11, v[22:23]
	v_lshl_add_u64 v[22:23], v[18:19], 0, v[22:23]
	s_waitcnt lgkmcnt(0)
	v_cvt_pk_bf16_f32 v14, v3, v13
	ds_read_b32 v3, v7 offset:296
	ds_read_b32 v13, v7 offset:428
	s_waitcnt lgkmcnt(0)
	v_cvt_pk_bf16_f32 v15, v3, v13
	ds_read_b32 v3, v7 offset:560
	ds_read_b32 v13, v7 offset:692
	s_waitcnt lgkmcnt(0)
	v_cvt_pk_bf16_f32 v16, v3, v13
	ds_read_b32 v3, v7 offset:824
	ds_read_b32 v13, v7 offset:956
	s_waitcnt lgkmcnt(0)
	v_cvt_pk_bf16_f32 v17, v3, v13
	global_store_dwordx4 v[22:23], v[14:17], off
	ds_read_b32 v3, v7 offset:64
	ds_read_b32 v13, v7 offset:196
	v_or_b32_e32 v22, s35, v11
	v_ashrrev_i32_e32 v23, 31, v22
	v_lshlrev_b64 v[22:23], 11, v[22:23]
	v_lshl_add_u64 v[22:23], v[18:19], 0, v[22:23]
	s_waitcnt lgkmcnt(0)
	v_cvt_pk_bf16_f32 v14, v3, v13
	ds_read_b32 v3, v7 offset:328
	ds_read_b32 v13, v7 offset:460
	s_waitcnt lgkmcnt(0)
	v_cvt_pk_bf16_f32 v15, v3, v13
	ds_read_b32 v3, v7 offset:592
	ds_read_b32 v13, v7 offset:724
	s_waitcnt lgkmcnt(0)
	v_cvt_pk_bf16_f32 v16, v3, v13
	ds_read_b32 v3, v7 offset:856
	ds_read_b32 v13, v7 offset:988
	s_waitcnt lgkmcnt(0)
	v_cvt_pk_bf16_f32 v17, v3, v13
	global_store_dwordx4 v[22:23], v[14:17], off
	ds_read_b32 v3, v7 offset:96
	ds_read_b32 v13, v7 offset:228
	v_or_b32_e32 v22, s35, v20
	v_ashrrev_i32_e32 v23, 31, v22
	v_lshlrev_b64 v[22:23], 11, v[22:23]
	v_lshl_add_u64 v[18:19], v[18:19], 0, v[22:23]
	s_waitcnt lgkmcnt(0)
	v_cvt_pk_bf16_f32 v14, v3, v13
	ds_read_b32 v3, v7 offset:360
	ds_read_b32 v13, v7 offset:492
	s_waitcnt lgkmcnt(0)
	v_cvt_pk_bf16_f32 v15, v3, v13
	ds_read_b32 v3, v7 offset:624
	ds_read_b32 v13, v7 offset:756
	s_waitcnt lgkmcnt(0)
	v_cvt_pk_bf16_f32 v16, v3, v13
	ds_read_b32 v3, v7 offset:888
	ds_read_b32 v13, v7 offset:1020
	s_waitcnt lgkmcnt(0)
	v_cvt_pk_bf16_f32 v17, v3, v13
	global_store_dwordx4 v[18:19], v[14:17], off
	s_waitcnt lgkmcnt(0)
	s_branch .LBB0_85

; #define FILT ((float*)(wsb(a.ws) + WS_FILT))
; #define FILTC ((float*)(wsb(a.ws) + WS_FILTC))
; __device__ __forceinline__ void prep_work(const Args& a, LAS unsigned char* lds, const int lp, const bool needc, const int widx, const int nwg, const bool do_main, const bool do_dn, const int tid, const int lane, const int wave) {
;     ...
;             for (int p = 0; p < npos; ++p) { float s = b3;
; #pragma unroll
;                 for (int e = 0; e < 64; ++e) s += H2[p * 64 + e] * w[e];
;                 const bool isc = p == 32; const int n = isc ? item : item * 32 + p; const float t = (float)n / (isc ? 255.0f : 8191.0f);
;                 float* dst = isc ? FILTC + (size_t)q * 256 : FILT + (size_t)q * 8192;
;                 dst[n] = s * expf(-t * adelta); }
.LBB0_176:
	s_waitcnt lgkmcnt(0)
	v_fma_f32 v74, v78, v74, v142
	v_fmac_f32_e32 v74, v79, v75
	v_fmac_f32_e32 v74, v80, v66
	v_fmac_f32_e32 v74, v81, v67
	v_fmac_f32_e32 v74, v82, v52
	v_fmac_f32_e32 v74, v83, v53
	v_fmac_f32_e32 v74, v84, v38
	v_fmac_f32_e32 v74, v85, v39
	v_fmac_f32_e32 v74, v86, v72
	v_fmac_f32_e32 v74, v87, v73
	v_fmac_f32_e32 v74, v88, v62
	v_fmac_f32_e32 v74, v89, v63
	v_fmac_f32_e32 v74, v90, v48
	v_fmac_f32_e32 v74, v91, v49
	v_fmac_f32_e32 v74, v92, v34
	v_fmac_f32_e32 v74, v93, v35
	v_fmac_f32_e32 v74, v94, v70
	v_fmac_f32_e32 v74, v95, v71
	v_fmac_f32_e32 v74, v96, v58
	v_fmac_f32_e32 v74, v97, v59
	v_fmac_f32_e32 v74, v98, v44
	v_fmac_f32_e32 v74, v99, v45
	v_fmac_f32_e32 v74, v100, v30
	v_fmac_f32_e32 v74, v101, v31
	v_fmac_f32_e32 v74, v102, v68
	v_fmac_f32_e32 v74, v103, v69
	v_fmac_f32_e32 v74, v104, v54
	v_fmac_f32_e32 v74, v105, v55
	v_fmac_f32_e32 v74, v106, v40
	v_fmac_f32_e32 v74, v107, v41
	v_fmac_f32_e32 v74, v108, v26
	v_fmac_f32_e32 v74, v109, v27
	v_fmac_f32_e32 v74, v110, v64
	v_fmac_f32_e32 v74, v111, v65
	v_fmac_f32_e32 v74, v112, v50
	v_fmac_f32_e32 v74, v113, v51
	s_waitcnt lgkmcnt(13)
	v_fmac_f32_e32 v74, v114, v36
	v_fmac_f32_e32 v74, v115, v37
	s_waitcnt lgkmcnt(12)
	v_fmac_f32_e32 v74, v116, v24
	v_fmac_f32_e32 v74, v117, v25
	s_waitcnt lgkmcnt(11)
	v_fmac_f32_e32 v74, v118, v60
	v_fmac_f32_e32 v74, v119, v61
	s_waitcnt lgkmcnt(10)
	v_fmac_f32_e32 v74, v120, v46
	v_fmac_f32_e32 v74, v121, v47
	s_waitcnt lgkmcnt(9)
	v_fmac_f32_e32 v74, v122, v32
	v_fmac_f32_e32 v74, v123, v33
	s_waitcnt lgkmcnt(8)
	v_fmac_f32_e32 v74, v124, v22
	v_fmac_f32_e32 v74, v125, v23
	s_waitcnt lgkmcnt(7)
	v_fmac_f32_e32 v74, v126, v56
	v_fmac_f32_e32 v74, v127, v57
	s_waitcnt lgkmcnt(6)
	v_fmac_f32_e32 v74, v128, v42
	v_fmac_f32_e32 v74, v129, v43
	s_waitcnt lgkmcnt(5)
	v_fmac_f32_e32 v74, v130, v28
	v_fmac_f32_e32 v74, v131, v29
	s_waitcnt lgkmcnt(4)
	v_fmac_f32_e32 v74, v132, v20
	s_and_b64 s[42:43], s[40:41], exec
	v_fmac_f32_e32 v74, v133, v21
	s_cselect_b32 s42, s23, s34
	s_waitcnt lgkmcnt(3)
	v_fmac_f32_e32 v74, v134, v18
	v_cvt_f32_i32_e32 v18, s42
	v_fmac_f32_e32 v74, v135, v19
	v_cndmask_b32_e64 v19, v230, v231, s[40:41]
	s_waitcnt lgkmcnt(2)
	v_fmac_f32_e32 v74, v136, v16
	v_div_scale_f32 v20, s[40:41], v19, v19, -v18
	v_rcp_f32_e32 v21, v20
	v_fmac_f32_e32 v74, v137, v17
	s_waitcnt lgkmcnt(1)
	v_fmac_f32_e32 v74, v138, v12
	v_fmac_f32_e32 v74, v139, v13
	v_fma_f32 v12, -v20, v21, 1.0
	v_fmac_f32_e32 v21, v12, v21
	v_div_scale_f32 v12, vcc, -v18, v19, -v18
	v_mul_f32_e32 v16, v12, v21
	v_fma_f32 v17, -v20, v16, v12
	v_fmac_f32_e32 v16, v17, v21
	v_fma_f32 v12, -v20, v16, v12
	v_div_fmas_f32 v12, v12, v21, v16
	v_div_fixup_f32 v12, v12, v19, -v18
	v_mul_f32_e32 v12, v1, v12
	v_mul_f32_e32 v16, 0x3fb8aa3b, v12
	v_fma_f32 v17, v12, s28, -v16
	v_rndne_f32_e32 v18, v16
	v_fmac_f32_e32 v17, 0x32a5705f, v12
	v_sub_f32_e32 v16, v16, v18
	v_add_f32_e32 v16, v16, v17
	v_exp_f32_e32 v16, v16
	v_cvt_i32_f32_e32 v17, v18
	s_waitcnt lgkmcnt(0)
	v_fmac_f32_e32 v74, v140, v10
	v_cmp_ngt_f32_e32 vcc, s24, v12
	v_fmac_f32_e32 v74, v141, v11
	v_ldexp_f32 v10, v16, v17
	v_cndmask_b32_e32 v10, 0, v10, vcc
	v_cmp_nlt_f32_e32 vcc, s25, v12
	s_ashr_i32 s43, s42, 31
	s_addk_i32 s35, 0x100
	v_cndmask_b32_e32 v10, v232, v10, vcc
	s_add_i32 s34, s34, 1
	v_mul_f32_e32 v12, v10, v74
	v_lshl_add_u64 v[10:11], s[42:43], 2, v[14:15]
	s_cmpk_eq_i32 s35, 0x2100
	global_store_dword v[10:11], v12, off
	s_cbranch_scc1 .LBB0_174

; __device__ __forceinline__ void norm_mod(const float* xl, const float* xc, const float* g, const float* mod, int shoff, int scoff, bf16_t* H, int nrows, int gw, int NGW, int lane) {
;     for (int r = gw; r < nrows; r += 4 * NGW) {
;         int rr[4]; const float* xp[4]; const float* mp[4];
; #pragma unroll
;         for (int k = 0; k < 4; ++k) { const int rk = r + k * NGW; rr[k] = rk < nrows ? rk : r; xp[k] = rr[k] < ML ? xl + (size_t)rr[k] * 1024 : xc + (size_t)(rr[k] - ML) * 1024; mp[k] = mod + (rr[k] < ML ? (rr[k] >> 13) : 4) * 6144; }
;         f32x4 v[4][4]; float ss[4];
; #pragma unroll
;         for (int k = 0; k < 4; ++k)
; #pragma unroll
;             for (int j = 0; j < 4; ++j) v[k][j] = ((const f32x4*)xp[k])[lane + 64 * j];
; #pragma unroll
;         for (int k = 0; k < 4; ++k) { ss[k] = 0.f;
; #pragma unroll
;             for (int j = 0; j < 4; ++j) ss[k] += (v[k][j].x * v[k][j].x + v[k][j].y * v[k][j].y) + (v[k][j].z * v[k][j].z + v[k][j].w * v[k][j].w); }
.LBB0_185:
	s_add_i32 s4, s12, 0xffff8000
	s_ashr_i32 s6, s12, 13
	s_cmp_lt_i32 s12, 0x8000
	s_cselect_b32 s5, s13, 0
	s_cselect_b32 s4, s12, s4
	s_mulk_i32 s6, 0x1800
	s_cselect_b32 s7, s53, s3
	s_cselect_b32 s10, s52, s2
	s_cselect_b32 s6, s6, 0x6000
	s_lshl_b64 s[4:5], s[4:5], 12
	s_add_u32 s10, s10, s4
	s_addc_u32 s11, s7, s5
	s_ashr_i32 s7, s6, 31
	s_lshl_b64 s[4:5], s[6:7], 2
	s_add_u32 s14, s81, s4
	s_addc_u32 s15, s66, s5
	s_add_u32 s4, s92, s12
	s_addc_u32 s5, 0, s13
	s_add_u32 s60, s92, s12
	s_cmp_lt_i32 s60, 0x8400
	s_cselect_b64 s[42:43], -1, 0
	s_and_b64 s[6:7], s[42:43], exec
	s_cselect_b32 s23, s60, s12
	s_cmp_lt_i32 s23, 0x8000
	s_cselect_b64 s[6:7], -1, 0
	s_ashr_i32 s36, s23, 31
	s_add_i32 s37, s23, 0xffff8000
	s_and_b64 s[34:35], s[6:7], exec
	s_cselect_b32 s35, s36, 0
	s_cselect_b32 s34, s23, s37
	s_cselect_b32 s37, s53, s3
	s_cselect_b32 s36, s52, s2
	s_lshl_b64 s[34:35], s[34:35], 12
	s_add_u32 s36, s36, s34
	s_addc_u32 s37, s37, s35
	s_ashr_i32 s23, s23, 13
	s_mulk_i32 s23, 0x1800
	s_and_b64 s[6:7], s[6:7], exec
	s_cselect_b32 s6, s23, 0x6000
	s_ashr_i32 s7, s6, 31
	s_lshl_b64 s[6:7], s[6:7], 2
	s_add_u32 s6, s81, s6
	s_addc_u32 s7, s66, s7
	s_add_u32 s23, s92, s60
	s_cmp_lt_i32 s23, 0x8400
	s_cselect_b64 s[38:39], -1, 0
	s_and_b64 s[34:35], s[38:39], exec
	s_cselect_b32 s35, s23, s12
	s_cmp_lt_i32 s35, 0x8000
	s_cselect_b64 s[44:45], -1, 0
	s_ashr_i32 s34, s35, 31
	s_add_i32 s46, s35, 0xffff8000
	s_and_b64 s[40:41], s[44:45], exec
	s_cselect_b32 s41, s34, 0
	s_cselect_b32 s40, s35, s46
	s_cselect_b32 s34, s53, s3
	s_cselect_b32 s46, s52, s2
	s_lshl_b64 s[40:41], s[40:41], 12
	s_add_u32 s46, s46, s40
	s_addc_u32 s47, s34, s41
	s_add_u32 s23, s92, s23
	s_cmp_lt_i32 s23, 0x8400
	s_cselect_b64 s[40:41], -1, 0
	s_and_b64 s[48:49], s[40:41], exec
	s_cselect_b32 s34, s23, s12
	s_cmp_lt_i32 s34, 0x8000
	v_mov_b32_e32 v87, v209
	s_cselect_b64 s[48:49], -1, 0
	s_ashr_i32 s61, s34, 31
	v_lshl_add_u64 v[4:5], s[10:11], 0, v[86:87]
	s_add_i32 s65, s34, 0xffff8000
	global_load_dwordx4 v[64:67], v[4:5], off
	global_load_dwordx4 v[44:47], v[4:5], off offset:1024
	s_and_b64 s[10:11], s[48:49], exec
	s_cselect_b32 s11, s61, 0
	s_cselect_b32 s10, s34, s65
	s_cselect_b32 s61, s53, s3
	s_cselect_b32 s65, s52, s2
	s_lshl_b64 s[10:11], s[10:11], 12
	s_add_u32 s10, s65, s10
	s_addc_u32 s11, s61, s11
	v_lshl_add_u64 v[0:1], s[10:11], 0, v[86:87]
	global_load_dwordx4 v[28:31], v[4:5], off offset:2048
	global_load_dwordx4 v[48:51], v[0:1], off
	global_load_dwordx4 v[32:35], v[0:1], off offset:1024
	global_load_dwordx4 v[16:19], v[0:1], off offset:2048
	s_nop 0
	global_load_dwordx4 v[0:3], v[0:1], off offset:3072
	s_nop 0
	global_load_dwordx4 v[12:15], v[4:5], off offset:3072
	v_lshl_add_u64 v[4:5], s[36:37], 0, v[86:87]
	global_load_dwordx4 v[60:63], v[4:5], off
	global_load_dwordx4 v[40:43], v[4:5], off offset:1024
	global_load_dwordx4 v[24:27], v[4:5], off offset:2048
	global_load_dwordx4 v[8:11], v[4:5], off offset:3072
	v_lshl_add_u64 v[4:5], s[46:47], 0, v[86:87]
	global_load_dwordx4 v[56:59], v[4:5], off
	global_load_dwordx4 v[36:39], v[4:5], off offset:1024
	global_load_dwordx4 v[20:23], v[4:5], off offset:2048
	s_nop 0
	global_load_dwordx4 v[4:7], v[4:5], off offset:3072
	s_add_u32 s10, s14, 0x1000
	s_addc_u32 s11, s15, 0
	s_cmp_gt_i32 s60, 0x83ff
	s_waitcnt vmcnt(0) lgkmcnt(0)
	v_mul_f32_e32 v52, v65, v65
	v_mul_f32_e32 v53, v67, v67
	v_mul_f32_e32 v54, v45, v45
	v_mul_f32_e32 v55, v47, v47
	v_fmac_f32_e32 v52, v64, v64
	v_fmac_f32_e32 v53, v66, v66
	v_fmac_f32_e32 v54, v44, v44
	v_fmac_f32_e32 v55, v46, v46
	v_add_f32_e32 v52, v52, v53
	v_add_f32_e32 v53, v54, v55
	v_add_f32_e32 v52, v52, v53
	v_mul_f32_e32 v53, v49, v49
	v_mul_f32_e32 v54, v51, v51
	v_mul_f32_e32 v55, v33, v33
	v_mul_f32_e32 v75, v35, v35
	v_mul_f32_e32 v77, v17, v17
	v_mul_f32_e32 v87, v19, v19
	v_fmac_f32_e32 v53, v48, v48
	v_fmac_f32_e32 v54, v50, v50
	v_fmac_f32_e32 v55, v32, v32
	v_fmac_f32_e32 v75, v34, v34
	v_mul_f32_e32 v88, v1, v1
	v_mul_f32_e32 v89, v3, v3
	v_fmac_f32_e32 v77, v16, v16
	v_fmac_f32_e32 v87, v18, v18
	v_add_f32_e32 v53, v53, v54
	v_add_f32_e32 v54, v55, v75
	v_fmac_f32_e32 v88, v0, v0
	v_fmac_f32_e32 v89, v2, v2
	v_add_f32_e32 v55, v77, v87
	v_add_f32_e32 v53, v53, v54
	v_add_f32_e32 v75, v88, v89
	v_add_f32_e32 v53, v53, v55
	v_mul_f32_e32 v73, v29, v29
	v_add_f32_e32 v75, v53, v75
	v_mul_f32_e32 v53, v31, v31
	v_fmac_f32_e32 v73, v28, v28
	v_fmac_f32_e32 v53, v30, v30
	v_add_f32_e32 v53, v73, v53
	v_add_f32_e32 v52, v52, v53
	v_mul_f32_e32 v53, v13, v13
	v_mul_f32_e32 v54, v15, v15
	v_fmac_f32_e32 v53, v12, v12
	v_fmac_f32_e32 v54, v14, v14
	v_add_f32_e32 v53, v53, v54
	v_add_f32_e32 v52, v52, v53
	v_mul_f32_e32 v53, v61, v61
	v_mul_f32_e32 v54, v63, v63
	v_fmac_f32_e32 v53, v60, v60
	v_fmac_f32_e32 v54, v62, v62
	v_add_f32_e32 v53, v53, v54
	v_mul_f32_e32 v54, v41, v41
	v_mul_f32_e32 v55, v43, v43
	v_fmac_f32_e32 v54, v40, v40
	v_fmac_f32_e32 v55, v42, v42
	v_add_f32_e32 v54, v54, v55
	v_add_f32_e32 v53, v53, v54
	v_mul_f32_e32 v54, v25, v25
	v_mul_f32_e32 v55, v27, v27
	v_fmac_f32_e32 v54, v24, v24
	v_fmac_f32_e32 v55, v26, v26
	v_add_f32_e32 v54, v54, v55
	v_add_f32_e32 v53, v53, v54
	v_mul_f32_e32 v54, v9, v9
	v_mul_f32_e32 v55, v11, v11
	v_fmac_f32_e32 v54, v8, v8
	v_fmac_f32_e32 v55, v10, v10
	v_add_f32_e32 v54, v54, v55
	v_add_f32_e32 v73, v53, v54
	v_mul_f32_e32 v53, v57, v57
	v_mul_f32_e32 v54, v59, v59
	v_fmac_f32_e32 v53, v56, v56
	v_fmac_f32_e32 v54, v58, v58
	v_add_f32_e32 v53, v53, v54
	v_mul_f32_e32 v54, v37, v37
	v_mul_f32_e32 v55, v39, v39
	v_fmac_f32_e32 v54, v36, v36
	v_fmac_f32_e32 v55, v38, v38
	v_add_f32_e32 v54, v54, v55
; __device__ __forceinline__ unsigned pk2(float lo, float hi) { const f32x2_cv v = {lo, hi}; const bf16x2_cv b = __builtin_convertvector(v, bf16x2_cv); return __builtin_bit_cast(unsigned, b); }
; __device__ __forceinline__ void norm_mod(const float* xl, const float* xc, const float* g, const float* mod, int shoff, int scoff, bf16_t* H, int nrows, int gw, int NGW, int lane) {
;     for (int r = gw; r < nrows; r += 4 * NGW) {
;         int rr[4]; const float* xp[4]; const float* mp[4];
; #pragma unroll
;         for (int k = 0; k < 4; ++k) { const int rk = r + k * NGW; rr[k] = rk < nrows ? rk : r; xp[k] = rr[k] < ML ? xl + (size_t)rr[k] * 1024 : xc + (size_t)(rr[k] - ML) * 1024; mp[k] = mod + (rr[k] < ML ? (rr[k] >> 13) : 4) * 6144; }
;         f32x4 v[4][4]; float ss[4];
; #pragma unroll
;         for (int k = 0; k < 4; ++k)
; #pragma unroll
;             for (int j = 0; j < 4; ++j) v[k][j] = ((const f32x4*)xp[k])[lane + 64 * j];
; #pragma unroll
;         for (int k = 0; k < 4; ++k) { ss[k] = 0.f;
; #pragma unroll
;             for (int j = 0; j < 4; ++j) ss[k] += (v[k][j].x * v[k][j].x + v[k][j].y * v[k][j].y) + (v[k][j].z * v[k][j].z + v[k][j].w * v[k][j].w); }
; #pragma unroll
;         for (int o = 1; o < 64; o <<= 1) {
; #pragma unroll
;             for (int k = 0; k < 4; ++k) { if (o == 1) ss[k] = wave_sum(ss[k]); } }
; #pragma unroll
;         for (int j = 0; j < 4; ++j) { const int col = 4 * lane + 256 * j;
;             const f32x4 g4 = *(const f32x4*)(g + col);
; #pragma unroll
;             for (int k = 0; k < 4; ++k) { if (k == 0 || r + k * NGW < nrows) {
;                 const float rinv = 1.0f / sqrtf(ss[k] * (1.0f / 1024.0f) + EPSF);
;                 const f32x4 sc4 = *(const f32x4*)(mp[k] + scoff + col), sh4 = *(const f32x4*)(mp[k] + shoff + col); const f32x4 o = (v[k][j] * rinv * g4) * (sc4 + 1.0f) + sh4;
;                 v2u w; w.x = pk2(o.x, o.y); w.y = pk2(o.z, o.w); *(v2u*)(H + (size_t)rr[k] * 1024 + col) = w; } }
;         }
;     }
; }
	v_add_f32_e32 v53, v53, v54
	v_mul_f32_e32 v54, v21, v21
	v_mul_f32_e32 v55, v23, v23
	v_fmac_f32_e32 v54, v20, v20
	v_fmac_f32_e32 v55, v22, v22
	v_add_f32_e32 v54, v54, v55
	v_add_f32_e32 v53, v53, v54
	v_mul_f32_e32 v54, v5, v5
	v_mul_f32_e32 v55, v7, v7
	v_add_f32_dpp v52, v52, v52 quad_perm:[1,0,3,2] row_mask:0xf bank_mask:0xf bound_ctrl:1
	v_fmac_f32_e32 v54, v4, v4
	v_fmac_f32_e32 v55, v6, v6
	v_add_f32_dpp v52, v52, v52 quad_perm:[2,3,0,1] row_mask:0xf bank_mask:0xf bound_ctrl:1
	v_add_f32_e32 v54, v54, v55
	v_lshl_add_u64 v[88:89], s[10:11], 0, v[208:209]
	v_add_f32_dpp v52, v52, v52 row_half_mirror row_mask:0xf bank_mask:0xf bound_ctrl:1
	v_add_f32_e32 v77, v53, v54
	global_load_dwordx4 v[92:95], v[88:89], off
	v_add_f32_dpp v87, v52, v52 row_mirror row_mask:0xf bank_mask:0xf bound_ctrl:1
	global_load_dwordx4 v[52:55], v[68:69], off
	v_lshl_add_u64 v[88:89], s[14:15], 0, v[208:209]
	global_load_dwordx4 v[96:99], v[88:89], off
	v_mov_b32_e32 v90, v87
	s_nop 1
	v_permlane16_swap_b32_e32 v87, v90
	v_add_f32_dpp v73, v73, v73 quad_perm:[1,0,3,2] row_mask:0xf bank_mask:0xf bound_ctrl:1
	v_add_f32_e32 v87, v87, v90
	v_mov_b32_e32 v90, v87
	v_add_f32_dpp v73, v73, v73 quad_perm:[2,3,0,1] row_mask:0xf bank_mask:0xf bound_ctrl:1
	s_nop 0
	v_permlane32_swap_b32_e32 v87, v90
	v_add_f32_dpp v73, v73, v73 row_half_mirror row_mask:0xf bank_mask:0xf bound_ctrl:1
	v_add_f32_e32 v90, v87, v90
	v_fmamk_f32 v90, v90, 0x3a800000, v220
	v_add_f32_dpp v73, v73, v73 row_mirror row_mask:0xf bank_mask:0xf bound_ctrl:1
	v_mov_b32_e32 v87, v73
	s_nop 1
	v_permlane16_swap_b32_e32 v73, v87
	v_add_f32_e32 v73, v73, v87
	v_mov_b32_e32 v87, v73
	s_nop 1
	v_permlane32_swap_b32_e32 v73, v87
	v_add_f32_e32 v91, v73, v87
	s_nop 0
	v_add_f32_dpp v73, v77, v77 quad_perm:[1,0,3,2] row_mask:0xf bank_mask:0xf bound_ctrl:1
	v_mul_f32_e32 v100, 0x4f800000, v90
	v_cmp_gt_f32_e32 vcc, s30, v90
	v_add_f32_dpp v73, v73, v73 quad_perm:[2,3,0,1] row_mask:0xf bank_mask:0xf bound_ctrl:1
	s_waitcnt vmcnt(0) lgkmcnt(0)
	v_pk_add_f32 v[94:95], v[94:95], 1.0 op_sel_hi:[1,0]
	v_add_f32_dpp v73, v73, v73 row_half_mirror row_mask:0xf bank_mask:0xf bound_ctrl:1
	v_cndmask_b32_e32 v90, v90, v100, vcc
	v_sqrt_f32_e32 v100, v90
	v_add_f32_dpp v73, v73, v73 row_mirror row_mask:0xf bank_mask:0xf bound_ctrl:1
	v_mov_b32_e32 v77, v73
	s_nop 1
	v_permlane16_swap_b32_e32 v73, v77
	v_add_f32_e32 v77, v73, v77
	s_nop 0
	v_add_f32_dpp v73, v75, v75 quad_perm:[1,0,3,2] row_mask:0xf bank_mask:0xf bound_ctrl:1
	v_pk_add_f32 v[92:93], v[92:93], 1.0 op_sel_hi:[1,0]
	v_mov_b32_e32 v87, v77
	v_add_f32_dpp v73, v73, v73 quad_perm:[2,3,0,1] row_mask:0xf bank_mask:0xf bound_ctrl:1
	s_nop 0
	v_permlane32_swap_b32_e32 v77, v87
	v_add_f32_dpp v73, v73, v73 row_half_mirror row_mask:0xf bank_mask:0xf bound_ctrl:1
	s_nop 1
	v_add_f32_dpp v73, v73, v73 row_mirror row_mask:0xf bank_mask:0xf bound_ctrl:1
	v_mov_b32_e32 v75, v73
	s_nop 1
	v_permlane16_swap_b32_e32 v73, v75
	v_add_f32_e32 v73, v73, v75
	v_add_u32_e32 v75, -1, v100
	v_fma_f32 v101, -v75, v100, v90
	v_cmp_ge_f32_e64 s[36:37], 0, v101
	v_add_u32_e32 v101, 1, v100
	s_nop 0
	v_cndmask_b32_e64 v75, v100, v75, s[36:37]
	v_fma_f32 v100, -v101, v100, v90
	v_cmp_lt_f32_e64 s[36:37], 0, v100
	s_nop 1
	v_cndmask_b32_e64 v75, v75, v101, s[36:37]
	v_mul_f32_e32 v100, 0x37800000, v75
	v_cndmask_b32_e32 v75, v75, v100, vcc
	v_cmp_class_f32_e32 vcc, v90, v221
	s_nop 1
	v_cndmask_b32_e32 v90, v75, v90, vcc
	v_div_scale_f32 v100, s[14:15], v90, v90, 1.0
	v_rcp_f32_e32 v101, v100
	v_mov_b32_e32 v75, v73
	s_nop 1
	v_permlane32_swap_b32_e32 v73, v75
	v_fma_f32 v102, -v100, v101, 1.0
	v_fmac_f32_e32 v101, v102, v101
	v_div_scale_f32 v102, vcc, 1.0, v90, 1.0
	v_mul_f32_e32 v103, v102, v101
	v_fma_f32 v104, -v100, v103, v102
	v_fmac_f32_e32 v103, v104, v101
	v_fma_f32 v100, -v100, v103, v102
	v_div_fmas_f32 v100, v100, v101, v103
	v_div_fixup_f32 v90, v100, v90, 1.0
	v_pk_mul_f32 v[66:67], v[66:67], v[90:91] op_sel_hi:[1,0]
	v_pk_mul_f32 v[64:65], v[64:65], v[90:91] op_sel_hi:[1,0]
	v_pk_mul_f32 v[66:67], v[66:67], v[54:55]
	v_pk_mul_f32 v[64:65], v[64:65], v[52:53]
	v_pk_fma_f32 v[66:67], v[66:67], v[94:95], v[98:99]
	v_pk_fma_f32 v[64:65], v[64:65], v[92:93], v[96:97]
	s_nop 0
	v_cvt_pk_bf16_f32 v64, v64, v65
	v_cvt_pk_bf16_f32 v65, v66, v67
	global_store_dwordx2 v[84:85], v[64:65], off
	v_fmamk_f32 v64, v91, 0x3a800000, v220
	v_cmp_gt_f32_e32 vcc, s30, v64
	v_mul_f32_e32 v65, 0x4f800000, v64
	s_cbranch_scc1 .LBB0_187
	v_cndmask_b32_e32 v66, v64, v65, vcc
	v_sqrt_f32_e32 v67, v66
	v_lshl_add_u64 v[96:97], s[6:7], 0, v[208:209]
	v_add_u32_e32 v91, -1, v67
	v_fma_f32 v92, -v91, v67, v66
	v_cmp_ge_f32_e64 s[36:37], 0, v92
	v_add_u32_e32 v92, 1, v67
	s_nop 0
	v_cndmask_b32_e64 v91, v67, v91, s[36:37]
	v_fma_f32 v67, -v92, v67, v66
	v_cmp_lt_f32_e64 s[36:37], 0, v67
	s_nop 1
	v_cndmask_b32_e64 v67, v91, v92, s[36:37]
	v_mul_f32_e32 v91, 0x37800000, v67
	v_cndmask_b32_e32 v67, v67, v91, vcc
	v_cmp_class_f32_e32 vcc, v66, v221
	s_nop 1
	v_cndmask_b32_e32 v66, v67, v66, vcc
	v_div_scale_f32 v67, s[14:15], v66, v66, 1.0
	v_rcp_f32_e32 v91, v67
	s_bfe_i64 s[14:15], s[4:5], 0x200000
	s_lshl_b64 s[14:15], s[14:15], 11
	v_fma_f32 v92, -v67, v91, 1.0
	v_fmac_f32_e32 v91, v92, v91
	v_div_scale_f32 v92, vcc, 1.0, v66, 1.0
	v_mul_f32_e32 v93, v92, v91
	v_fma_f32 v94, -v67, v93, v92
	v_fmac_f32_e32 v93, v94, v91
	v_fma_f32 v67, -v67, v93, v92
	v_div_fmas_f32 v67, v67, v91, v93
	v_add_co_u32_e32 v92, vcc, s96, v96
	v_div_fixup_f32 v66, v67, v66, 1.0
	s_nop 0
	v_addc_co_u32_e32 v93, vcc, 0, v97, vcc
	global_load_dwordx4 v[92:95], v[92:93], off
	s_nop 0
	global_load_dwordx4 v[96:99], v[96:97], off
	v_pk_mul_f32 v[62:63], v[62:63], v[66:67] op_sel_hi:[1,0]
	v_pk_mul_f32 v[60:61], v[60:61], v[66:67] op_sel_hi:[1,0]
	v_pk_mul_f32 v[62:63], v[62:63], v[54:55]
	v_pk_mul_f32 v[60:61], v[60:61], v[52:53]
	s_waitcnt vmcnt(0) lgkmcnt(0)
	v_pk_add_f32 v[66:67], v[94:95], 1.0 op_sel_hi:[1,0]
	v_pk_add_f32 v[92:93], v[92:93], 1.0 op_sel_hi:[1,0]
	v_pk_fma_f32 v[62:63], v[62:63], v[66:67], v[98:99]
	v_pk_fma_f32 v[60:61], v[60:61], v[92:93], v[96:97]
	s_nop 0
	v_cvt_pk_bf16_f32 v60, v60, v61
	v_cvt_pk_bf16_f32 v61, v62, v63
	v_lshl_add_u64 v[62:63], v[70:71], 0, s[14:15]
	global_store_dwordx2 v[62:63], v[60:61], off
; __device__ __forceinline__ unsigned pk2(float lo, float hi) { const f32x2_cv v = {lo, hi}; const bf16x2_cv b = __builtin_convertvector(v, bf16x2_cv); return __builtin_bit_cast(unsigned, b); }
; __device__ __forceinline__ void norm_mod(const float* xl, const float* xc, const float* g, const float* mod, int shoff, int scoff, bf16_t* H, int nrows, int gw, int NGW, int lane) {
;     for (int r = gw; r < nrows; r += 4 * NGW) {
;         int rr[4]; const float* xp[4]; const float* mp[4];
; #pragma unroll
;         for (int k = 0; k < 4; ++k) { const int rk = r + k * NGW; rr[k] = rk < nrows ? rk : r; xp[k] = rr[k] < ML ? xl + (size_t)rr[k] * 1024 : xc + (size_t)(rr[k] - ML) * 1024; mp[k] = mod + (rr[k] < ML ? (rr[k] >> 13) : 4) * 6144; }
;         f32x4 v[4][4]; float ss[4];
; #pragma unroll
;         for (int k = 0; k < 4; ++k)
; #pragma unroll
;             for (int j = 0; j < 4; ++j) v[k][j] = ((const f32x4*)xp[k])[lane + 64 * j];
; #pragma unroll
;         for (int k = 0; k < 4; ++k) { ss[k] = 0.f;
; #pragma unroll
;             for (int j = 0; j < 4; ++j) ss[k] += (v[k][j].x * v[k][j].x + v[k][j].y * v[k][j].y) + (v[k][j].z * v[k][j].z + v[k][j].w * v[k][j].w); }
; #pragma unroll
;         for (int o = 1; o < 64; o <<= 1) {
; #pragma unroll
;             for (int k = 0; k < 4; ++k) { if (o == 1) ss[k] = wave_sum(ss[k]); } }
; #pragma unroll
;         for (int j = 0; j < 4; ++j) { const int col = 4 * lane + 256 * j;
;             const f32x4 g4 = *(const f32x4*)(g + col);
; #pragma unroll
;             for (int k = 0; k < 4; ++k) { if (k == 0 || r + k * NGW < nrows) {
;                 const float rinv = 1.0f / sqrtf(ss[k] * (1.0f / 1024.0f) + EPSF);
;                 const f32x4 sc4 = *(const f32x4*)(mp[k] + scoff + col), sh4 = *(const f32x4*)(mp[k] + shoff + col); const f32x4 o = (v[k][j] * rinv * g4) * (sc4 + 1.0f) + sh4;
;                 v2u w; w.x = pk2(o.x, o.y); w.y = pk2(o.z, o.w); *(v2u*)(H + (size_t)rr[k] * 1024 + col) = w; } }
.LBB0_187:
	v_readlane_b32 s14, v254, 13
	s_add_u32 s14, s14, s12
	s_addc_u32 s15, 0, s13
	s_ashr_i32 s35, s35, 13
	s_mulk_i32 s35, 0x1800
	s_and_b64 s[36:37], s[44:45], exec
	s_cselect_b32 s36, s35, 0x6000
	s_ashr_i32 s37, s36, 31
	s_lshl_b64 s[36:37], s[36:37], 2
	v_add_f32_e32 v60, v77, v87
	s_add_u32 s46, s81, s36
	v_cndmask_b32_e64 v61, 0, 1, s[38:39]
	v_fmamk_f32 v60, v60, 0x3a800000, v220
	s_addc_u32 s47, s66, s37
	v_cmp_ne_u32_e64 s[36:37], 1, v61
	s_andn2_b64 vcc, exec, s[38:39]
	v_cmp_gt_f32_e64 s[38:39], s30, v60
	v_mul_f32_e32 v61, 0x4f800000, v60
	s_cbranch_vccnz .LBB0_189
	v_cndmask_b32_e64 v62, v60, v61, s[38:39]
	v_sqrt_f32_e32 v63, v62
	s_nop 0
	v_add_u32_e32 v66, -1, v63
	v_fma_f32 v67, -v66, v63, v62
	v_cmp_ge_f32_e32 vcc, 0, v67
	v_add_u32_e32 v67, 1, v63
	s_nop 0
	v_cndmask_b32_e32 v66, v63, v66, vcc
	v_fma_f32 v63, -v67, v63, v62
	v_cmp_lt_f32_e32 vcc, 0, v63
	s_nop 1
	v_cndmask_b32_e32 v63, v66, v67, vcc
	v_mul_f32_e32 v66, 0x37800000, v63
	v_cndmask_b32_e64 v63, v63, v66, s[38:39]
	v_cmp_class_f32_e32 vcc, v62, v221
	s_nop 1
	v_cndmask_b32_e32 v62, v63, v62, vcc
	v_div_scale_f32 v63, s[38:39], v62, v62, 1.0
	v_rcp_f32_e32 v66, v63
	s_bfe_i64 s[38:39], s[14:15], 0x200000
	s_lshl_b64 s[38:39], s[38:39], 11
	v_fma_f32 v67, -v63, v66, 1.0
	v_fmac_f32_e32 v66, v67, v66
	v_div_scale_f32 v67, vcc, 1.0, v62, 1.0
	v_mul_f32_e32 v77, v67, v66
	v_fma_f32 v87, -v63, v77, v67
	v_fmac_f32_e32 v77, v87, v66
	v_fma_f32 v63, -v63, v77, v67
	v_div_fmas_f32 v63, v63, v66, v77
	v_lshl_add_u64 v[66:67], s[46:47], 0, v[208:209]
	v_add_co_u32_e32 v92, vcc, s96, v66
	v_div_fixup_f32 v62, v63, v62, 1.0
	s_nop 0
	v_addc_co_u32_e32 v93, vcc, 0, v67, vcc
	global_load_dwordx4 v[92:95], v[92:93], off
	s_nop 0
	global_load_dwordx4 v[96:99], v[66:67], off
	v_pk_mul_f32 v[58:59], v[58:59], v[62:63] op_sel_hi:[1,0]
	v_pk_mul_f32 v[56:57], v[56:57], v[62:63] op_sel_hi:[1,0]
	v_pk_mul_f32 v[58:59], v[54:55], v[58:59]
	v_pk_mul_f32 v[56:57], v[52:53], v[56:57]
	s_waitcnt vmcnt(0) lgkmcnt(0)
	v_pk_add_f32 v[62:63], v[94:95], 1.0 op_sel_hi:[1,0]
	v_pk_add_f32 v[66:67], v[92:93], 1.0 op_sel_hi:[1,0]
	v_pk_fma_f32 v[58:59], v[58:59], v[62:63], v[98:99]
	v_pk_fma_f32 v[56:57], v[56:57], v[66:67], v[96:97]
	s_nop 0
	v_cvt_pk_bf16_f32 v56, v56, v57
	v_cvt_pk_bf16_f32 v57, v58, v59
	v_lshl_add_u64 v[58:59], v[70:71], 0, s[38:39]
	global_store_dwordx2 v[58:59], v[56:57], off
.LBB0_189:
	s_mul_i32 s35, s54, 24
	s_add_u32 s44, s35, s12
	s_addc_u32 s45, 0, s13
	s_ashr_i32 s34, s34, 13
	s_mul_i32 s38, s34, 0x1800
	s_and_b64 s[34:35], s[48:49], exec
	s_cselect_b32 s34, s38, 0x6000
	s_ashr_i32 s35, s34, 31
	s_lshl_b64 s[34:35], s[34:35], 2
	v_add_f32_e32 v56, v73, v75
	s_add_u32 s48, s81, s34
	v_cndmask_b32_e64 v57, 0, 1, s[40:41]
	v_fmamk_f32 v56, v56, 0x3a800000, v220
	s_addc_u32 s49, s66, s35
	v_cmp_ne_u32_e64 s[38:39], 1, v57
	s_andn2_b64 vcc, exec, s[40:41]
	v_cmp_gt_f32_e64 s[40:41], s30, v56
	v_mul_f32_e32 v57, 0x4f800000, v56
	s_cbranch_vccnz .LBB0_191
	v_cndmask_b32_e64 v58, v56, v57, s[40:41]
	v_sqrt_f32_e32 v59, v58
	s_nop 0
	v_add_u32_e32 v62, -1, v59
	v_fma_f32 v63, -v62, v59, v58
	v_cmp_ge_f32_e32 vcc, 0, v63
	v_add_u32_e32 v63, 1, v59
	s_nop 0
	v_cndmask_b32_e32 v62, v59, v62, vcc
	v_fma_f32 v59, -v63, v59, v58
	v_cmp_lt_f32_e32 vcc, 0, v59
	s_nop 1
	v_cndmask_b32_e32 v59, v62, v63, vcc
	v_mul_f32_e32 v62, 0x37800000, v59
	v_cndmask_b32_e64 v59, v59, v62, s[40:41]
	v_cmp_class_f32_e32 vcc, v58, v221
	s_nop 1
	v_cndmask_b32_e32 v58, v59, v58, vcc
	v_div_scale_f32 v59, s[34:35], v58, v58, 1.0
	v_rcp_f32_e32 v62, v59
	s_bfe_i64 s[34:35], s[44:45], 0x200000
	s_lshl_b64 s[34:35], s[34:35], 11
	v_fma_f32 v63, -v59, v62, 1.0
	v_fmac_f32_e32 v62, v63, v62
	v_div_scale_f32 v63, vcc, 1.0, v58, 1.0
	v_mul_f32_e32 v66, v63, v62
	v_fma_f32 v67, -v59, v66, v63
	v_fmac_f32_e32 v66, v67, v62
	v_fma_f32 v59, -v59, v66, v63
	v_div_fmas_f32 v59, v59, v62, v66
	v_lshl_add_u64 v[62:63], s[48:49], 0, v[208:209]
	v_add_co_u32_e32 v66, vcc, s96, v62
	v_div_fixup_f32 v58, v59, v58, 1.0
	s_nop 0
	v_addc_co_u32_e32 v67, vcc, 0, v63, vcc
	global_load_dwordx4 v[92:95], v[66:67], off
	global_load_dwordx4 v[96:99], v[62:63], off
	v_pk_mul_f32 v[50:51], v[50:51], v[58:59] op_sel_hi:[1,0]
	v_pk_mul_f32 v[48:49], v[48:49], v[58:59] op_sel_hi:[1,0]
	v_pk_mul_f32 v[50:51], v[54:55], v[50:51]
	v_pk_mul_f32 v[48:49], v[52:53], v[48:49]
	s_waitcnt vmcnt(0) lgkmcnt(0)
	v_pk_add_f32 v[52:53], v[94:95], 1.0 op_sel_hi:[1,0]
	v_pk_add_f32 v[54:55], v[92:93], 1.0 op_sel_hi:[1,0]
	v_pk_fma_f32 v[50:51], v[50:51], v[52:53], v[98:99]
	v_pk_fma_f32 v[48:49], v[48:49], v[54:55], v[96:97]
	s_nop 0
	v_cvt_pk_bf16_f32 v48, v48, v49
	v_cvt_pk_bf16_f32 v49, v50, v51
	v_lshl_add_u64 v[50:51], v[70:71], 0, s[34:35]
	global_store_dwordx2 v[50:51], v[48:49], off
; __device__ __forceinline__ unsigned pk2(float lo, float hi) { const f32x2_cv v = {lo, hi}; const bf16x2_cv b = __builtin_convertvector(v, bf16x2_cv); return __builtin_bit_cast(unsigned, b); }
; __device__ __forceinline__ void norm_mod(const float* xl, const float* xc, const float* g, const float* mod, int shoff, int scoff, bf16_t* H, int nrows, int gw, int NGW, int lane) {
;     ...
;         for (int j = 0; j < 4; ++j) { const int col = 4 * lane + 256 * j;
;             const f32x4 g4 = *(const f32x4*)(g + col);
; #pragma unroll
;             for (int k = 0; k < 4; ++k) { if (k == 0 || r + k * NGW < nrows) {
;                 const float rinv = 1.0f / sqrtf(ss[k] * (1.0f / 1024.0f) + EPSF);
;                 const f32x4 sc4 = *(const f32x4*)(mp[k] + scoff + col), sh4 = *(const f32x4*)(mp[k] + shoff + col); const f32x4 o = (v[k][j] * rinv * g4) * (sc4 + 1.0f) + sh4;
;                 v2u w; w.x = pk2(o.x, o.y); w.y = pk2(o.z, o.w); *(v2u*)(H + (size_t)rr[k] * 1024 + col) = w; } }
.LBB0_191:
	v_lshlrev_b32_e32 v52, 2, v72
	v_mov_b32_e32 v53, v209
	global_load_dwordx4 v[48:51], v[68:69], off offset:1024
	v_lshl_add_u64 v[54:55], s[10:11], 0, v[52:53]
	global_load_dwordx4 v[92:95], v[54:55], off
	global_load_dwordx4 v[96:99], v[88:89], off offset:1024
	v_mov_b32_e32 v91, v90
	v_mov_b32_e32 v54, v90
	v_mov_b32_e32 v55, v90
	v_pk_mul_f32 v[46:47], v[46:47], v[54:55]
	v_pk_mul_f32 v[44:45], v[44:45], v[90:91]
	s_andn2_b64 vcc, exec, s[42:43]
	s_waitcnt vmcnt(0)
	v_pk_mul_f32 v[46:47], v[46:47], v[50:51]
	v_pk_mul_f32 v[44:45], v[44:45], v[48:49]
	s_waitcnt lgkmcnt(0)
	v_pk_add_f32 v[54:55], v[94:95], 1.0 op_sel_hi:[1,0]
	v_pk_add_f32 v[58:59], v[92:93], 1.0 op_sel_hi:[1,0]
	v_pk_fma_f32 v[46:47], v[46:47], v[54:55], v[98:99]
	v_pk_fma_f32 v[44:45], v[44:45], v[58:59], v[96:97]
	s_nop 0
	v_cvt_pk_bf16_f32 v44, v44, v45
	v_cvt_pk_bf16_f32 v45, v46, v47
	global_store_dwordx2 v[84:85], v[44:45], off offset:512
	v_cndmask_b32_e64 v44, 0, 1, s[42:43]
	v_cmp_ne_u32_e64 s[40:41], 1, v44
	s_cbranch_vccnz .LBB0_202
	v_cmp_gt_f32_e32 vcc, s30, v64
	v_lshl_add_u64 v[58:59], s[6:7], 0, v[208:209]
	global_load_dwordx4 v[92:95], v[58:59], off offset:1024
	v_cndmask_b32_e32 v44, v64, v65, vcc
	v_sqrt_f32_e32 v45, v44
	s_nop 0
	v_add_u32_e32 v46, -1, v45
	v_fma_f32 v47, -v46, v45, v44
	v_cmp_ge_f32_e64 s[42:43], 0, v47
	v_add_u32_e32 v47, 1, v45
	s_nop 0
	v_cndmask_b32_e64 v46, v45, v46, s[42:43]
	v_fma_f32 v45, -v47, v45, v44
	v_cmp_lt_f32_e64 s[42:43], 0, v45
	s_nop 1
	v_cndmask_b32_e64 v45, v46, v47, s[42:43]
	v_mul_f32_e32 v46, 0x37800000, v45
	v_cndmask_b32_e32 v45, v45, v46, vcc
	v_cmp_class_f32_e32 vcc, v44, v221
	s_nop 1
	v_cndmask_b32_e32 v44, v45, v44, vcc
	v_div_scale_f32 v45, s[34:35], v44, v44, 1.0
	v_rcp_f32_e32 v46, v45
	s_bfe_i64 s[34:35], s[4:5], 0x200000
	s_lshl_b64 s[34:35], s[34:35], 11
	v_fma_f32 v47, -v45, v46, 1.0
	v_fmac_f32_e32 v46, v47, v46
	v_div_scale_f32 v47, vcc, 1.0, v44, 1.0
	v_mul_f32_e32 v54, v47, v46
	v_fma_f32 v55, -v45, v54, v47
	v_fmac_f32_e32 v54, v55, v46
	v_fma_f32 v45, -v45, v54, v47
	v_div_fmas_f32 v45, v45, v46, v54
	v_div_fixup_f32 v54, v45, v44, 1.0
	v_lshl_add_u64 v[44:45], s[6:7], 0, v[52:53]
	v_add_co_u32_e32 v44, vcc, s96, v44
	v_pk_mul_f32 v[42:43], v[42:43], v[54:55] op_sel_hi:[1,0]
	s_nop 0
	v_addc_co_u32_e32 v45, vcc, 0, v45, vcc
	global_load_dwordx4 v[44:47], v[44:45], off
	v_pk_mul_f32 v[40:41], v[40:41], v[54:55] op_sel_hi:[1,0]
	v_pk_mul_f32 v[42:43], v[42:43], v[50:51]
	v_pk_mul_f32 v[40:41], v[40:41], v[48:49]
	s_waitcnt vmcnt(0) lgkmcnt(0)
	v_pk_add_f32 v[46:47], v[46:47], 1.0 op_sel_hi:[1,0]
	v_pk_add_f32 v[44:45], v[44:45], 1.0 op_sel_hi:[1,0]
	v_pk_fma_f32 v[42:43], v[42:43], v[46:47], v[94:95]
	v_pk_fma_f32 v[40:41], v[40:41], v[44:45], v[92:93]
	s_nop 0
	v_cvt_pk_bf16_f32 v40, v40, v41
	v_cvt_pk_bf16_f32 v41, v42, v43
	v_lshl_add_u64 v[42:43], v[78:79], 0, s[34:35]
	global_store_dwordx2 v[42:43], v[40:41], off
	s_and_b64 vcc, exec, s[36:37]
	s_cbranch_vccz .LBB0_203

; __device__ __forceinline__ unsigned pk2(float lo, float hi) { const f32x2_cv v = {lo, hi}; const bf16x2_cv b = __builtin_convertvector(v, bf16x2_cv); return __builtin_bit_cast(unsigned, b); }
; __device__ __forceinline__ void norm_mod(const float* xl, const float* xc, const float* g, const float* mod, int shoff, int scoff, bf16_t* H, int nrows, int gw, int NGW, int lane) {
;     ...
;         for (int j = 0; j < 4; ++j) { const int col = 4 * lane + 256 * j;
;             const f32x4 g4 = *(const f32x4*)(g + col);
; #pragma unroll
;             for (int k = 0; k < 4; ++k) { if (k == 0 || r + k * NGW < nrows) {
;                 const float rinv = 1.0f / sqrtf(ss[k] * (1.0f / 1024.0f) + EPSF);
;                 const f32x4 sc4 = *(const f32x4*)(mp[k] + scoff + col), sh4 = *(const f32x4*)(mp[k] + shoff + col); const f32x4 o = (v[k][j] * rinv * g4) * (sc4 + 1.0f) + sh4;
;                 v2u w; w.x = pk2(o.x, o.y); w.y = pk2(o.z, o.w); *(v2u*)(H + (size_t)rr[k] * 1024 + col) = w; } }
.LBB0_194:
	v_cmp_gt_f32_e32 vcc, s30, v56
	v_mov_b32_e32 v53, v209
	s_nop 0
	v_cndmask_b32_e32 v36, v56, v57, vcc
	v_sqrt_f32_e32 v37, v36
	s_nop 0
	v_add_u32_e32 v38, -1, v37
	v_fma_f32 v39, -v38, v37, v36
	v_cmp_ge_f32_e64 s[42:43], 0, v39
	v_add_u32_e32 v39, 1, v37
	s_nop 0
	v_cndmask_b32_e64 v38, v37, v38, s[42:43]
	v_fma_f32 v37, -v39, v37, v36
	v_cmp_lt_f32_e64 s[42:43], 0, v37
	s_nop 1
	v_cndmask_b32_e64 v37, v38, v39, s[42:43]
	v_mul_f32_e32 v38, 0x37800000, v37
	v_cndmask_b32_e32 v37, v37, v38, vcc
	v_cmp_class_f32_e32 vcc, v36, v221
	s_nop 1
	v_cndmask_b32_e32 v36, v37, v36, vcc
	v_div_scale_f32 v37, s[34:35], v36, v36, 1.0
	v_rcp_f32_e32 v38, v37
	s_bfe_i64 s[34:35], s[44:45], 0x200000
	s_lshl_b64 s[34:35], s[34:35], 11
	v_fma_f32 v39, -v37, v38, 1.0
	v_fmac_f32_e32 v38, v39, v38
	v_div_scale_f32 v39, vcc, 1.0, v36, 1.0
	v_mul_f32_e32 v40, v39, v38
	v_fma_f32 v41, -v37, v40, v39
	v_fmac_f32_e32 v40, v41, v38
	v_fma_f32 v37, -v37, v40, v39
	v_div_fmas_f32 v37, v37, v38, v40
	v_div_fixup_f32 v44, v37, v36, 1.0
	v_lshl_add_u64 v[36:37], s[48:49], 0, v[52:53]
	v_add_co_u32_e32 v36, vcc, s96, v36
	v_lshl_add_u64 v[40:41], s[48:49], 0, v[208:209]
	s_nop 0
	v_addc_co_u32_e32 v37, vcc, 0, v37, vcc
	global_load_dwordx4 v[36:39], v[36:37], off
	v_pk_mul_f32 v[34:35], v[34:35], v[44:45] op_sel_hi:[1,0]
	global_load_dwordx4 v[40:43], v[40:41], off offset:1024
	v_pk_mul_f32 v[32:33], v[32:33], v[44:45] op_sel_hi:[1,0]
	v_pk_mul_f32 v[34:35], v[34:35], v[50:51]
	v_pk_mul_f32 v[32:33], v[32:33], v[48:49]
	s_waitcnt vmcnt(0) lgkmcnt(0)
	v_pk_add_f32 v[38:39], v[38:39], 1.0 op_sel_hi:[1,0]
	v_pk_add_f32 v[36:37], v[36:37], 1.0 op_sel_hi:[1,0]
	v_pk_fma_f32 v[34:35], v[34:35], v[38:39], v[42:43]
	v_pk_fma_f32 v[32:33], v[32:33], v[36:37], v[40:41]
	s_nop 0
	v_cvt_pk_bf16_f32 v32, v32, v33
	v_cvt_pk_bf16_f32 v33, v34, v35
	v_lshl_add_u64 v[34:35], v[78:79], 0, s[34:35]
	global_store_dwordx2 v[34:35], v[32:33], off
.LBB0_195:
	v_lshlrev_b32_e32 v36, 2, v74
	v_mov_b32_e32 v37, v209
	global_load_dwordx4 v[32:35], v[68:69], off offset:2048
	v_lshl_add_u64 v[38:39], s[10:11], 0, v[36:37]
	global_load_dwordx4 v[38:41], v[38:39], off
	s_nop 0
	global_load_dwordx4 v[42:45], v[88:89], off offset:2048
	v_mov_b32_e32 v46, v90
	v_mov_b32_e32 v47, v90
	v_pk_mul_f32 v[30:31], v[30:31], v[46:47]
	v_pk_mul_f32 v[28:29], v[28:29], v[90:91]
	s_and_b64 vcc, exec, s[40:41]
	s_waitcnt vmcnt(0)
	v_pk_mul_f32 v[30:31], v[30:31], v[34:35]
	v_pk_mul_f32 v[28:29], v[28:29], v[32:33]
	s_waitcnt lgkmcnt(0)
	v_pk_add_f32 v[40:41], v[40:41], 1.0 op_sel_hi:[1,0]
	v_pk_add_f32 v[38:39], v[38:39], 1.0 op_sel_hi:[1,0]
	v_pk_fma_f32 v[30:31], v[30:31], v[40:41], v[44:45]
	v_pk_fma_f32 v[28:29], v[28:29], v[38:39], v[42:43]
	s_nop 0
	v_cvt_pk_bf16_f32 v28, v28, v29
	v_cvt_pk_bf16_f32 v29, v30, v31
	global_store_dwordx2 v[84:85], v[28:29], off offset:1024
	s_cbranch_vccnz .LBB0_204
	v_cmp_gt_f32_e32 vcc, s30, v64
	s_nop 1
	v_cndmask_b32_e32 v28, v64, v65, vcc
	v_sqrt_f32_e32 v29, v28
	s_nop 0
	v_add_u32_e32 v30, -1, v29
	v_fma_f32 v31, -v30, v29, v28
	v_cmp_ge_f32_e64 s[42:43], 0, v31
	v_add_u32_e32 v31, 1, v29
	s_nop 0
	v_cndmask_b32_e64 v30, v29, v30, s[42:43]
	v_fma_f32 v29, -v31, v29, v28
	v_cmp_lt_f32_e64 s[42:43], 0, v29
	s_nop 1
	v_cndmask_b32_e64 v29, v30, v31, s[42:43]
	v_mul_f32_e32 v30, 0x37800000, v29
	v_cndmask_b32_e32 v29, v29, v30, vcc
	v_cmp_class_f32_e32 vcc, v28, v221
	s_nop 1
	v_cndmask_b32_e32 v28, v29, v28, vcc
	v_div_scale_f32 v29, s[34:35], v28, v28, 1.0
	v_rcp_f32_e32 v30, v29
	s_bfe_i64 s[34:35], s[4:5], 0x200000
	s_lshl_b64 s[34:35], s[34:35], 11
	v_fma_f32 v31, -v29, v30, 1.0
	v_fmac_f32_e32 v30, v31, v30
	v_div_scale_f32 v31, vcc, 1.0, v28, 1.0
	v_mul_f32_e32 v38, v31, v30
	v_fma_f32 v39, -v29, v38, v31
	v_fmac_f32_e32 v38, v39, v30
	v_fma_f32 v29, -v29, v38, v31
	v_div_fmas_f32 v29, v29, v30, v38
	v_div_fixup_f32 v42, v29, v28, 1.0
	v_lshl_add_u64 v[28:29], s[6:7], 0, v[36:37]
	v_add_co_u32_e32 v28, vcc, s96, v28
	v_lshl_add_u64 v[38:39], s[6:7], 0, v[208:209]
	s_nop 0
	v_addc_co_u32_e32 v29, vcc, 0, v29, vcc
	global_load_dwordx4 v[28:31], v[28:29], off
	v_pk_mul_f32 v[26:27], v[26:27], v[42:43] op_sel_hi:[1,0]
	global_load_dwordx4 v[38:41], v[38:39], off offset:2048
	v_pk_mul_f32 v[24:25], v[24:25], v[42:43] op_sel_hi:[1,0]
	v_pk_mul_f32 v[26:27], v[26:27], v[34:35]
	v_pk_mul_f32 v[24:25], v[24:25], v[32:33]
	s_waitcnt vmcnt(0) lgkmcnt(0)
	v_pk_add_f32 v[30:31], v[30:31], 1.0 op_sel_hi:[1,0]
	v_pk_add_f32 v[28:29], v[28:29], 1.0 op_sel_hi:[1,0]
	v_pk_fma_f32 v[26:27], v[26:27], v[30:31], v[40:41]
	v_pk_fma_f32 v[24:25], v[24:25], v[28:29], v[38:39]
	s_nop 0
	v_cvt_pk_bf16_f32 v24, v24, v25
	v_cvt_pk_bf16_f32 v25, v26, v27
	v_lshl_add_u64 v[26:27], v[80:81], 0, s[34:35]
	global_store_dwordx2 v[26:27], v[24:25], off
	s_and_b64 vcc, exec, s[36:37]
	s_cbranch_vccz .LBB0_205

; __device__ __forceinline__ unsigned pk2(float lo, float hi) { const f32x2_cv v = {lo, hi}; const bf16x2_cv b = __builtin_convertvector(v, bf16x2_cv); return __builtin_bit_cast(unsigned, b); }
; __device__ __forceinline__ void norm_mod(const float* xl, const float* xc, const float* g, const float* mod, int shoff, int scoff, bf16_t* H, int nrows, int gw, int NGW, int lane) {
;     ...
;         for (int j = 0; j < 4; ++j) { const int col = 4 * lane + 256 * j;
;             const f32x4 g4 = *(const f32x4*)(g + col);
; #pragma unroll
;             for (int k = 0; k < 4; ++k) { if (k == 0 || r + k * NGW < nrows) {
;                 const float rinv = 1.0f / sqrtf(ss[k] * (1.0f / 1024.0f) + EPSF);
;                 const f32x4 sc4 = *(const f32x4*)(mp[k] + scoff + col), sh4 = *(const f32x4*)(mp[k] + shoff + col); const f32x4 o = (v[k][j] * rinv * g4) * (sc4 + 1.0f) + sh4;
;                 v2u w; w.x = pk2(o.x, o.y); w.y = pk2(o.z, o.w); *(v2u*)(H + (size_t)rr[k] * 1024 + col) = w; } }
.LBB0_198:
	v_cmp_gt_f32_e32 vcc, s30, v56
	v_mov_b32_e32 v37, v209
	s_nop 0
	v_cndmask_b32_e32 v20, v56, v57, vcc
	v_sqrt_f32_e32 v21, v20
	s_nop 0
	v_add_u32_e32 v22, -1, v21
	v_fma_f32 v23, -v22, v21, v20
	v_cmp_ge_f32_e64 s[42:43], 0, v23
	v_add_u32_e32 v23, 1, v21
	s_nop 0
	v_cndmask_b32_e64 v22, v21, v22, s[42:43]
	v_fma_f32 v21, -v23, v21, v20
	v_cmp_lt_f32_e64 s[42:43], 0, v21
	s_nop 1
	v_cndmask_b32_e64 v21, v22, v23, s[42:43]
	v_mul_f32_e32 v22, 0x37800000, v21
	v_cndmask_b32_e32 v21, v21, v22, vcc
	v_cmp_class_f32_e32 vcc, v20, v221
	s_nop 1
	v_cndmask_b32_e32 v20, v21, v20, vcc
	v_div_scale_f32 v21, s[34:35], v20, v20, 1.0
	v_rcp_f32_e32 v22, v21
	s_bfe_i64 s[34:35], s[44:45], 0x200000
	s_lshl_b64 s[34:35], s[34:35], 11
	v_fma_f32 v23, -v21, v22, 1.0
	v_fmac_f32_e32 v22, v23, v22
	v_div_scale_f32 v23, vcc, 1.0, v20, 1.0
	v_mul_f32_e32 v24, v23, v22
	v_fma_f32 v25, -v21, v24, v23
	v_fmac_f32_e32 v24, v25, v22
	v_fma_f32 v21, -v21, v24, v23
	v_div_fmas_f32 v21, v21, v22, v24
	v_div_fixup_f32 v28, v21, v20, 1.0
	v_lshl_add_u64 v[20:21], s[48:49], 0, v[36:37]
	v_add_co_u32_e32 v20, vcc, s96, v20
	v_lshl_add_u64 v[24:25], s[48:49], 0, v[208:209]
	s_nop 0
	v_addc_co_u32_e32 v21, vcc, 0, v21, vcc
	global_load_dwordx4 v[20:23], v[20:21], off
	v_pk_mul_f32 v[18:19], v[18:19], v[28:29] op_sel_hi:[1,0]
	global_load_dwordx4 v[24:27], v[24:25], off offset:2048
	v_pk_mul_f32 v[16:17], v[16:17], v[28:29] op_sel_hi:[1,0]
	v_pk_mul_f32 v[18:19], v[18:19], v[34:35]
	v_pk_mul_f32 v[16:17], v[16:17], v[32:33]
	s_waitcnt vmcnt(0) lgkmcnt(0)
	v_pk_add_f32 v[22:23], v[22:23], 1.0 op_sel_hi:[1,0]
	v_pk_add_f32 v[20:21], v[20:21], 1.0 op_sel_hi:[1,0]
	v_pk_fma_f32 v[18:19], v[18:19], v[22:23], v[26:27]
	v_pk_fma_f32 v[16:17], v[16:17], v[20:21], v[24:25]
	s_nop 0
	v_cvt_pk_bf16_f32 v16, v16, v17
	v_cvt_pk_bf16_f32 v17, v18, v19
	v_lshl_add_u64 v[18:19], v[80:81], 0, s[34:35]
	global_store_dwordx2 v[18:19], v[16:17], off
.LBB0_199:
	v_lshlrev_b32_e32 v20, 2, v76
	v_mov_b32_e32 v21, v209
	global_load_dwordx4 v[16:19], v[68:69], off offset:3072
	v_lshl_add_u64 v[22:23], s[10:11], 0, v[20:21]
	global_load_dwordx4 v[22:25], v[22:23], off
	s_nop 0
	global_load_dwordx4 v[26:29], v[88:89], off offset:3072
	v_mov_b32_e32 v30, v90
	v_mov_b32_e32 v31, v90
	v_pk_mul_f32 v[12:13], v[12:13], v[90:91]
	v_pk_mul_f32 v[14:15], v[14:15], v[30:31]
	s_and_b64 vcc, exec, s[40:41]
	s_waitcnt vmcnt(0)
	v_pk_mul_f32 v[14:15], v[14:15], v[18:19]
	v_pk_mul_f32 v[12:13], v[12:13], v[16:17]
	s_waitcnt lgkmcnt(0)
	v_pk_add_f32 v[24:25], v[24:25], 1.0 op_sel_hi:[1,0]
	v_pk_add_f32 v[22:23], v[22:23], 1.0 op_sel_hi:[1,0]
	v_pk_fma_f32 v[14:15], v[14:15], v[24:25], v[28:29]
	v_pk_fma_f32 v[12:13], v[12:13], v[22:23], v[26:27]
	s_nop 0
	v_cvt_pk_bf16_f32 v12, v12, v13
	v_cvt_pk_bf16_f32 v13, v14, v15
	global_store_dwordx2 v[84:85], v[12:13], off offset:1536
	s_cbranch_vccnz .LBB0_206
	v_cmp_gt_f32_e32 vcc, s30, v64
	s_bfe_i64 s[4:5], s[4:5], 0x200000
	s_lshl_b64 s[4:5], s[4:5], 11
	v_cndmask_b32_e32 v12, v64, v65, vcc
	v_sqrt_f32_e32 v13, v12
	s_nop 0
	v_add_u32_e32 v14, -1, v13
	v_fma_f32 v15, -v14, v13, v12
	v_cmp_ge_f32_e64 s[40:41], 0, v15
	v_add_u32_e32 v15, 1, v13
	s_nop 0
	v_cndmask_b32_e64 v14, v13, v14, s[40:41]
	v_fma_f32 v13, -v15, v13, v12
	v_cmp_lt_f32_e64 s[40:41], 0, v13
	s_nop 1
	v_cndmask_b32_e64 v13, v14, v15, s[40:41]
	v_mul_f32_e32 v14, 0x37800000, v13
	v_cndmask_b32_e32 v13, v13, v14, vcc
	v_cmp_class_f32_e32 vcc, v12, v221
	s_nop 1
	v_cndmask_b32_e32 v12, v13, v12, vcc
	v_div_scale_f32 v13, s[10:11], v12, v12, 1.0
	v_rcp_f32_e32 v14, v13
	s_nop 0
	v_fma_f32 v15, -v13, v14, 1.0
	v_fmac_f32_e32 v14, v15, v14
	v_div_scale_f32 v15, vcc, 1.0, v12, 1.0
	v_mul_f32_e32 v22, v15, v14
	v_fma_f32 v23, -v13, v22, v15
	v_fmac_f32_e32 v22, v23, v14
	v_fma_f32 v13, -v13, v22, v15
	v_div_fmas_f32 v13, v13, v14, v22
	v_div_fixup_f32 v26, v13, v12, 1.0
	v_lshl_add_u64 v[12:13], s[6:7], 0, v[20:21]
	v_add_co_u32_e32 v12, vcc, s96, v12
	v_lshl_add_u64 v[22:23], s[6:7], 0, v[208:209]
	s_nop 0
	v_addc_co_u32_e32 v13, vcc, 0, v13, vcc
	global_load_dwordx4 v[12:15], v[12:13], off
	v_pk_mul_f32 v[10:11], v[10:11], v[26:27] op_sel_hi:[1,0]
	global_load_dwordx4 v[22:25], v[22:23], off offset:3072
	v_pk_mul_f32 v[8:9], v[8:9], v[26:27] op_sel_hi:[1,0]
	v_pk_mul_f32 v[10:11], v[10:11], v[18:19]
	v_pk_mul_f32 v[8:9], v[8:9], v[16:17]
	s_waitcnt vmcnt(0) lgkmcnt(0)
	v_pk_add_f32 v[14:15], v[14:15], 1.0 op_sel_hi:[1,0]
	v_pk_add_f32 v[12:13], v[12:13], 1.0 op_sel_hi:[1,0]
	v_pk_fma_f32 v[10:11], v[10:11], v[14:15], v[24:25]
	v_pk_fma_f32 v[8:9], v[8:9], v[12:13], v[22:23]
	s_nop 0
	v_cvt_pk_bf16_f32 v8, v8, v9
	v_cvt_pk_bf16_f32 v9, v10, v11
	v_lshl_add_u64 v[10:11], v[82:83], 0, s[4:5]
	global_store_dwordx2 v[10:11], v[8:9], off
	s_and_b64 vcc, exec, s[36:37]
	s_cbranch_vccz .LBB0_207

; __device__ __forceinline__ unsigned pk2(float lo, float hi) { const f32x2_cv v = {lo, hi}; const bf16x2_cv b = __builtin_convertvector(v, bf16x2_cv); return __builtin_bit_cast(unsigned, b); }
; __device__ __forceinline__ void norm_mod(const float* xl, const float* xc, const float* g, const float* mod, int shoff, int scoff, bf16_t* H, int nrows, int gw, int NGW, int lane) {
;     ...
; #pragma unroll
;             for (int k = 0; k < 4; ++k) { if (k == 0 || r + k * NGW < nrows) {
;                 const float rinv = 1.0f / sqrtf(ss[k] * (1.0f / 1024.0f) + EPSF);
;                 const f32x4 sc4 = *(const f32x4*)(mp[k] + scoff + col), sh4 = *(const f32x4*)(mp[k] + shoff + col); const f32x4 o = (v[k][j] * rinv * g4) * (sc4 + 1.0f) + sh4;
;                 v2u w; w.x = pk2(o.x, o.y); w.y = pk2(o.z, o.w); *(v2u*)(H + (size_t)rr[k] * 1024 + col) = w; } }
.LBB0_203:
	v_cmp_gt_f32_e32 vcc, s30, v60
	v_mov_b32_e32 v53, v209
	s_nop 0
	v_cndmask_b32_e32 v40, v60, v61, vcc
	v_sqrt_f32_e32 v41, v40
	s_nop 0
	v_add_u32_e32 v42, -1, v41
	v_fma_f32 v43, -v42, v41, v40
	v_cmp_ge_f32_e64 s[42:43], 0, v43
	v_add_u32_e32 v43, 1, v41
	s_nop 0
	v_cndmask_b32_e64 v42, v41, v42, s[42:43]
	v_fma_f32 v41, -v43, v41, v40
	v_cmp_lt_f32_e64 s[42:43], 0, v41
	s_nop 1
	v_cndmask_b32_e64 v41, v42, v43, s[42:43]
	v_mul_f32_e32 v42, 0x37800000, v41
	v_cndmask_b32_e32 v41, v41, v42, vcc
	v_cmp_class_f32_e32 vcc, v40, v221
	s_nop 1
	v_cndmask_b32_e32 v40, v41, v40, vcc
	v_div_scale_f32 v41, s[34:35], v40, v40, 1.0
	v_rcp_f32_e32 v42, v41
	s_bfe_i64 s[34:35], s[14:15], 0x200000
	s_lshl_b64 s[34:35], s[34:35], 11
	v_fma_f32 v43, -v41, v42, 1.0
	v_fmac_f32_e32 v42, v43, v42
	v_div_scale_f32 v43, vcc, 1.0, v40, 1.0
	v_mul_f32_e32 v44, v43, v42
	v_fma_f32 v45, -v41, v44, v43
	v_fmac_f32_e32 v44, v45, v42
	v_fma_f32 v41, -v41, v44, v43
	v_div_fmas_f32 v41, v41, v42, v44
	v_div_fixup_f32 v54, v41, v40, 1.0
	v_lshl_add_u64 v[40:41], s[46:47], 0, v[52:53]
	v_add_co_u32_e32 v40, vcc, s96, v40
	v_lshl_add_u64 v[44:45], s[46:47], 0, v[208:209]
	s_nop 0
	v_addc_co_u32_e32 v41, vcc, 0, v41, vcc
	global_load_dwordx4 v[40:43], v[40:41], off
	v_pk_mul_f32 v[38:39], v[38:39], v[54:55] op_sel_hi:[1,0]
	global_load_dwordx4 v[44:47], v[44:45], off offset:1024
	v_pk_mul_f32 v[36:37], v[36:37], v[54:55] op_sel_hi:[1,0]
	v_pk_mul_f32 v[38:39], v[38:39], v[50:51]
	v_pk_mul_f32 v[36:37], v[36:37], v[48:49]
	s_waitcnt vmcnt(0) lgkmcnt(0)
	v_pk_add_f32 v[42:43], v[42:43], 1.0 op_sel_hi:[1,0]
	v_pk_add_f32 v[40:41], v[40:41], 1.0 op_sel_hi:[1,0]
	v_pk_fma_f32 v[38:39], v[38:39], v[42:43], v[46:47]
	v_pk_fma_f32 v[36:37], v[36:37], v[40:41], v[44:45]
	s_nop 0
	v_cvt_pk_bf16_f32 v36, v36, v37
	v_cvt_pk_bf16_f32 v37, v38, v39
	v_lshl_add_u64 v[38:39], v[78:79], 0, s[34:35]
	global_store_dwordx2 v[38:39], v[36:37], off
	s_and_b64 vcc, exec, s[38:39]
	s_cbranch_vccz .LBB0_194
	s_branch .LBB0_195

; __device__ __forceinline__ unsigned pk2(float lo, float hi) { const f32x2_cv v = {lo, hi}; const bf16x2_cv b = __builtin_convertvector(v, bf16x2_cv); return __builtin_bit_cast(unsigned, b); }
; __device__ __forceinline__ void norm_mod(const float* xl, const float* xc, const float* g, const float* mod, int shoff, int scoff, bf16_t* H, int nrows, int gw, int NGW, int lane) {
;     ...
; #pragma unroll
;             for (int k = 0; k < 4; ++k) { if (k == 0 || r + k * NGW < nrows) {
;                 const float rinv = 1.0f / sqrtf(ss[k] * (1.0f / 1024.0f) + EPSF);
;                 const f32x4 sc4 = *(const f32x4*)(mp[k] + scoff + col), sh4 = *(const f32x4*)(mp[k] + shoff + col); const f32x4 o = (v[k][j] * rinv * g4) * (sc4 + 1.0f) + sh4;
;                 v2u w; w.x = pk2(o.x, o.y); w.y = pk2(o.z, o.w); *(v2u*)(H + (size_t)rr[k] * 1024 + col) = w; } }
.LBB0_205:
	v_cmp_gt_f32_e32 vcc, s30, v60
	v_mov_b32_e32 v37, v209
	s_nop 0
	v_cndmask_b32_e32 v24, v60, v61, vcc
	v_sqrt_f32_e32 v25, v24
	s_nop 0
	v_add_u32_e32 v26, -1, v25
	v_fma_f32 v27, -v26, v25, v24
	v_cmp_ge_f32_e64 s[42:43], 0, v27
	v_add_u32_e32 v27, 1, v25
	s_nop 0
	v_cndmask_b32_e64 v26, v25, v26, s[42:43]
	v_fma_f32 v25, -v27, v25, v24
	v_cmp_lt_f32_e64 s[42:43], 0, v25
	s_nop 1
	v_cndmask_b32_e64 v25, v26, v27, s[42:43]
	v_mul_f32_e32 v26, 0x37800000, v25
	v_cndmask_b32_e32 v25, v25, v26, vcc
	v_cmp_class_f32_e32 vcc, v24, v221
	s_nop 1
	v_cndmask_b32_e32 v24, v25, v24, vcc
	v_div_scale_f32 v25, s[34:35], v24, v24, 1.0
	v_rcp_f32_e32 v26, v25
	s_bfe_i64 s[34:35], s[14:15], 0x200000
	s_lshl_b64 s[34:35], s[34:35], 11
	v_fma_f32 v27, -v25, v26, 1.0
	v_fmac_f32_e32 v26, v27, v26
	v_div_scale_f32 v27, vcc, 1.0, v24, 1.0
	v_mul_f32_e32 v28, v27, v26
	v_fma_f32 v29, -v25, v28, v27
	v_fmac_f32_e32 v28, v29, v26
	v_fma_f32 v25, -v25, v28, v27
	v_div_fmas_f32 v25, v25, v26, v28
	v_div_fixup_f32 v38, v25, v24, 1.0
	v_lshl_add_u64 v[24:25], s[46:47], 0, v[36:37]
	v_add_co_u32_e32 v24, vcc, s96, v24
	v_lshl_add_u64 v[28:29], s[46:47], 0, v[208:209]
	s_nop 0
	v_addc_co_u32_e32 v25, vcc, 0, v25, vcc
	global_load_dwordx4 v[24:27], v[24:25], off
	v_pk_mul_f32 v[22:23], v[22:23], v[38:39] op_sel_hi:[1,0]
	global_load_dwordx4 v[28:31], v[28:29], off offset:2048
	v_pk_mul_f32 v[20:21], v[20:21], v[38:39] op_sel_hi:[1,0]
	v_pk_mul_f32 v[22:23], v[22:23], v[34:35]
	v_pk_mul_f32 v[20:21], v[20:21], v[32:33]
	s_waitcnt vmcnt(0) lgkmcnt(0)
	v_pk_add_f32 v[26:27], v[26:27], 1.0 op_sel_hi:[1,0]
	v_pk_add_f32 v[24:25], v[24:25], 1.0 op_sel_hi:[1,0]
	v_pk_fma_f32 v[22:23], v[22:23], v[26:27], v[30:31]
	v_pk_fma_f32 v[20:21], v[20:21], v[24:25], v[28:29]
	s_nop 0
	v_cvt_pk_bf16_f32 v20, v20, v21
	v_cvt_pk_bf16_f32 v21, v22, v23
	v_lshl_add_u64 v[22:23], v[80:81], 0, s[34:35]
	global_store_dwordx2 v[22:23], v[20:21], off
	s_and_b64 vcc, exec, s[38:39]
	s_cbranch_vccz .LBB0_198
	s_branch .LBB0_199

; __device__ __forceinline__ unsigned pk2(float lo, float hi) { const f32x2_cv v = {lo, hi}; const bf16x2_cv b = __builtin_convertvector(v, bf16x2_cv); return __builtin_bit_cast(unsigned, b); }
; __device__ __forceinline__ void norm_mod(const float* xl, const float* xc, const float* g, const float* mod, int shoff, int scoff, bf16_t* H, int nrows, int gw, int NGW, int lane) {
;     for (int r = gw; r < nrows; r += 4 * NGW) {
;         int rr[4]; const float* xp[4]; const float* mp[4];
; #pragma unroll
;         for (int k = 0; k < 4; ++k) { const int rk = r + k * NGW; rr[k] = rk < nrows ? rk : r; xp[k] = rr[k] < ML ? xl + (size_t)rr[k] * 1024 : xc + (size_t)(rr[k] - ML) * 1024; mp[k] = mod + (rr[k] < ML ? (rr[k] >> 13) : 4) * 6144; }
;         f32x4 v[4][4]; float ss[4];
; #pragma unroll
;         for (int k = 0; k < 4; ++k)
; #pragma unroll
;             for (int j = 0; j < 4; ++j) v[k][j] = ((const f32x4*)xp[k])[lane + 64 * j];
; #pragma unroll
;         for (int k = 0; k < 4; ++k) { ss[k] = 0.f;
; #pragma unroll
;             for (int j = 0; j < 4; ++j) ss[k] += (v[k][j].x * v[k][j].x + v[k][j].y * v[k][j].y) + (v[k][j].z * v[k][j].z + v[k][j].w * v[k][j].w); }
; #pragma unroll
;         for (int o = 1; o < 64; o <<= 1) {
; #pragma unroll
;             for (int k = 0; k < 4; ++k) { if (o == 1) ss[k] = wave_sum(ss[k]); } }
; #pragma unroll
;         for (int j = 0; j < 4; ++j) { const int col = 4 * lane + 256 * j;
;             const f32x4 g4 = *(const f32x4*)(g + col);
; #pragma unroll
;             for (int k = 0; k < 4; ++k) { if (k == 0 || r + k * NGW < nrows) {
;                 const float rinv = 1.0f / sqrtf(ss[k] * (1.0f / 1024.0f) + EPSF);
;                 const f32x4 sc4 = *(const f32x4*)(mp[k] + scoff + col), sh4 = *(const f32x4*)(mp[k] + shoff + col); const f32x4 o = (v[k][j] * rinv * g4) * (sc4 + 1.0f) + sh4;
;                 v2u w; w.x = pk2(o.x, o.y); w.y = pk2(o.z, o.w); *(v2u*)(H + (size_t)rr[k] * 1024 + col) = w; } }
.LBB0_207:
	v_cmp_gt_f32_e32 vcc, s30, v60
	v_mov_b32_e32 v21, v209
	s_nop 0
	v_cndmask_b32_e32 v8, v60, v61, vcc
	v_sqrt_f32_e32 v9, v8
	s_nop 0
	v_add_u32_e32 v10, -1, v9
	v_fma_f32 v11, -v10, v9, v8
	v_cmp_ge_f32_e64 s[36:37], 0, v11
	v_add_u32_e32 v11, 1, v9
	s_nop 0
	v_cndmask_b32_e64 v10, v9, v10, s[36:37]
	v_fma_f32 v9, -v11, v9, v8
	v_cmp_lt_f32_e64 s[36:37], 0, v9
	s_nop 1
	v_cndmask_b32_e64 v9, v10, v11, s[36:37]
	v_mul_f32_e32 v10, 0x37800000, v9
	v_cndmask_b32_e32 v9, v9, v10, vcc
	v_cmp_class_f32_e32 vcc, v8, v221
	s_nop 1
	v_cndmask_b32_e32 v8, v9, v8, vcc
	v_div_scale_f32 v9, s[4:5], v8, v8, 1.0
	v_rcp_f32_e32 v10, v9
	s_bfe_i64 s[4:5], s[14:15], 0x200000
	s_lshl_b64 s[4:5], s[4:5], 11
	v_fma_f32 v11, -v9, v10, 1.0
	v_fmac_f32_e32 v10, v11, v10
	v_div_scale_f32 v11, vcc, 1.0, v8, 1.0
	v_mul_f32_e32 v12, v11, v10
	v_fma_f32 v13, -v9, v12, v11
	v_fmac_f32_e32 v12, v13, v10
	v_fma_f32 v9, -v9, v12, v11
	v_div_fmas_f32 v9, v9, v10, v12
	v_div_fixup_f32 v22, v9, v8, 1.0
	v_lshl_add_u64 v[8:9], s[46:47], 0, v[20:21]
	v_add_co_u32_e32 v8, vcc, s96, v8
	v_lshl_add_u64 v[12:13], s[46:47], 0, v[208:209]
	s_nop 0
	v_addc_co_u32_e32 v9, vcc, 0, v9, vcc
	global_load_dwordx4 v[8:11], v[8:9], off
	v_pk_mul_f32 v[6:7], v[6:7], v[22:23] op_sel_hi:[1,0]
	global_load_dwordx4 v[12:15], v[12:13], off offset:3072
	v_pk_mul_f32 v[4:5], v[4:5], v[22:23] op_sel_hi:[1,0]
	v_pk_mul_f32 v[6:7], v[6:7], v[18:19]
	v_pk_mul_f32 v[4:5], v[4:5], v[16:17]
	s_waitcnt vmcnt(0) lgkmcnt(0)
	v_pk_add_f32 v[10:11], v[10:11], 1.0 op_sel_hi:[1,0]
	v_pk_add_f32 v[8:9], v[8:9], 1.0 op_sel_hi:[1,0]
	v_pk_fma_f32 v[6:7], v[6:7], v[10:11], v[14:15]
	v_pk_fma_f32 v[4:5], v[4:5], v[8:9], v[12:13]
	s_nop 0
	v_cvt_pk_bf16_f32 v4, v4, v5
	v_cvt_pk_bf16_f32 v5, v6, v7
	v_lshl_add_u64 v[6:7], v[82:83], 0, s[4:5]
	global_store_dwordx2 v[6:7], v[4:5], off
	s_and_b64 vcc, exec, s[38:39]
	s_cbranch_vccnz .LBB0_184
.LBB0_208:
	v_cmp_gt_f32_e32 vcc, s30, v56
	v_mov_b32_e32 v21, v209
	s_nop 0
	v_cndmask_b32_e32 v4, v56, v57, vcc
	v_sqrt_f32_e32 v5, v4
	s_nop 0
	v_add_u32_e32 v6, -1, v5
	v_fma_f32 v7, -v6, v5, v4
	v_cmp_ge_f32_e64 s[36:37], 0, v7
	v_add_u32_e32 v7, 1, v5
	s_nop 0
	v_cndmask_b32_e64 v6, v5, v6, s[36:37]
	v_fma_f32 v5, -v7, v5, v4
	v_cmp_lt_f32_e64 s[36:37], 0, v5
	s_nop 1
	v_cndmask_b32_e64 v5, v6, v7, s[36:37]
	v_mul_f32_e32 v6, 0x37800000, v5
	v_cndmask_b32_e32 v5, v5, v6, vcc
	v_cmp_class_f32_e32 vcc, v4, v221
	s_nop 1
	v_cndmask_b32_e32 v4, v5, v4, vcc
	v_div_scale_f32 v5, s[4:5], v4, v4, 1.0
	v_rcp_f32_e32 v6, v5
	s_bfe_i64 s[4:5], s[44:45], 0x200000
	s_lshl_b64 s[4:5], s[4:5], 11
	v_fma_f32 v7, -v5, v6, 1.0
	v_fmac_f32_e32 v6, v7, v6
	v_div_scale_f32 v7, vcc, 1.0, v4, 1.0
	v_mul_f32_e32 v8, v7, v6
	v_fma_f32 v9, -v5, v8, v7
	v_fmac_f32_e32 v8, v9, v6
	v_fma_f32 v5, -v5, v8, v7
	v_div_fmas_f32 v5, v5, v6, v8
	v_div_fixup_f32 v12, v5, v4, 1.0
	v_lshl_add_u64 v[4:5], s[48:49], 0, v[20:21]
	v_add_co_u32_e32 v4, vcc, s96, v4
	v_lshl_add_u64 v[8:9], s[48:49], 0, v[208:209]
	s_nop 0
	v_addc_co_u32_e32 v5, vcc, 0, v5, vcc
	global_load_dwordx4 v[4:7], v[4:5], off
	v_pk_mul_f32 v[2:3], v[2:3], v[12:13] op_sel_hi:[1,0]
	global_load_dwordx4 v[8:11], v[8:9], off offset:3072
	v_pk_mul_f32 v[0:1], v[0:1], v[12:13] op_sel_hi:[1,0]
	v_pk_mul_f32 v[2:3], v[2:3], v[18:19]
	v_pk_mul_f32 v[0:1], v[0:1], v[16:17]
	s_waitcnt vmcnt(0) lgkmcnt(0)
	v_pk_add_f32 v[6:7], v[6:7], 1.0 op_sel_hi:[1,0]
	v_pk_add_f32 v[4:5], v[4:5], 1.0 op_sel_hi:[1,0]
	v_pk_fma_f32 v[2:3], v[2:3], v[6:7], v[10:11]
	v_pk_fma_f32 v[0:1], v[0:1], v[4:5], v[8:9]
	s_nop 0
	v_cvt_pk_bf16_f32 v0, v0, v1
	v_cvt_pk_bf16_f32 v1, v2, v3
	v_lshl_add_u64 v[2:3], v[82:83], 0, s[4:5]
	global_store_dwordx2 v[2:3], v[0:1], off
	s_branch .LBB0_184

;     __device__ __forceinline__ void operator()(const pg8::f32x4 (&acc)[2][2][4][2], const pg8::Unit& u, int wr, int wc, int fr, int fq) const {
;     ...
;                     pg8::f32x4 y0 = acc[ai][bj][m][0], y1 = acc[ai][bj][m][1];
;                     if (normed) {
;                         y0 = y0 * rinv * gg[bj][0]; y1 = y1 * rinv * gg[bj][1];
;                         if (lat) { const int p = bj == 0 ? (t >> 6) : (t & 63); const pg8::f32x4* rp = (const pg8::f32x4*)(rope + p * 16 + 4 * fq); const pg8::f32x4 c01 = rp[0], c23 = rp[1];
;                             const pg8::f32x4 z0 = {y0[0] * c01[0] - y0[1] * c01[1], y0[0] * c01[1] + y0[1] * c01[0], y0[2] * c01[2] - y0[3] * c01[3], y0[2] * c01[3] + y0[3] * c01[2]};
;                             const pg8::f32x4 z1 = {y1[0] * c23[0] - y1[1] * c23[1], y1[0] * c23[1] + y1[1] * c23[0], y1[2] * c23[2] - y1[3] * c23[3], y1[2] * c23[3] + y1[3] * c23[2]};
;                             y0 = z0; y1 = z1; }
.LBB0_308:
	v_mov_b32_e32 v165, v164
	s_and_b64 vcc, exec, s[38:39]
	v_mov_b32_e32 v166, v140
	v_mov_b32_e32 v167, v141
	v_mov_b32_e32 v172, v142
	v_mov_b32_e32 v173, v143
	v_mov_b32_e32 v168, v136
	v_mov_b32_e32 v169, v137
	v_mov_b32_e32 v170, v138
	v_mov_b32_e32 v171, v139
	s_cbranch_vccnz .LBB0_312
	v_mov_b32_e32 v168, v164
	v_mov_b32_e32 v169, v164
	v_pk_mul_f32 v[166:167], v[142:143], v[168:169]
	v_pk_mul_f32 v[170:171], v[140:141], v[164:165]
	v_pk_mul_f32 v[168:169], v[138:139], v[168:169]
	v_pk_mul_f32 v[174:175], v[136:137], v[164:165]
	s_waitcnt vmcnt(0)
	v_pk_mul_f32 v[172:173], v[62:63], v[166:167]
	v_pk_mul_f32 v[166:167], v[60:61], v[170:171]
	v_pk_mul_f32 v[170:171], v[58:59], v[168:169]
	v_pk_mul_f32 v[168:169], v[56:57], v[174:175]
	s_and_saveexec_b64 s[4:5], s[40:41]
	s_cbranch_execz .LBB0_311
	v_lshlrev_b32_e32 v174, 1, v202
	v_and_b32_e32 v174, 0x3f80, v174
	v_mov_b32_e32 v175, v209
	v_lshl_add_u64 v[178:179], v[154:155], 0, v[174:175]
	global_load_dwordx4 v[174:177], v[178:179], off
	s_nop 0
	global_load_dwordx4 v[178:181], v[178:179], off offset:16
	s_waitcnt vmcnt(0) lgkmcnt(0)
	v_pk_mul_f32 v[184:185], v[166:167], v[174:175] op_sel:[1,1] op_sel_hi:[1,0]
	v_pk_mul_f32 v[182:183], v[166:167], v[174:175]
	v_pk_fma_f32 v[166:167], v[166:167], v[174:175], v[184:185] op_sel_hi:[0,1,1]
	v_mul_f32_e32 v166, v173, v177
	v_pk_fma_f32 v[174:175], v[172:173], v[176:177], v[166:167] op_sel_hi:[1,1,0] neg_lo:[0,0,1] neg_hi:[0,0,1]
	v_mul_f32_e32 v166, v173, v176
	v_pk_fma_f32 v[172:173], v[172:173], v[176:177], v[166:167] op_sel:[0,1,0] op_sel_hi:[1,0,0]
	v_pk_mul_f32 v[186:187], v[168:169], v[178:179] op_sel:[1,1] op_sel_hi:[1,0]
	v_mul_f32_e32 v166, v171, v181
	v_pk_mul_f32 v[176:177], v[168:169], v[178:179]
	v_pk_fma_f32 v[168:169], v[168:169], v[178:179], v[186:187] op_sel_hi:[0,1,1]
	v_pk_fma_f32 v[178:179], v[170:171], v[180:181], v[166:167] op_sel_hi:[1,1,0] neg_lo:[0,0,1] neg_hi:[0,0,1]
	v_mul_f32_e32 v166, v171, v180
	v_pk_fma_f32 v[170:171], v[170:171], v[180:181], v[166:167] op_sel:[0,1,0] op_sel_hi:[1,0,0]
	v_sub_f32_e32 v166, v182, v184
	v_sub_f32_e32 v168, v176, v186
	v_mov_b32_e32 v171, v170
	v_mov_b32_e32 v170, v178
	v_mov_b32_e32 v173, v172
	v_mov_b32_e32 v172, v174

; __device__ __forceinline__ unsigned pk2(float lo, float hi) { const f32x2_cv v = {lo, hi}; const bf16x2_cv b = __builtin_convertvector(v, bf16x2_cv); return __builtin_bit_cast(unsigned, b); }
;     __device__ __forceinline__ void operator()(const pg8::f32x4 (&acc)[2][2][4][2], const pg8::Unit& u, int wr, int wc, int fr, int fq) const {
;     ...
;                 for (int bj = 0; bj < 2; ++bj) {
;                     pg8::f32x4 y0 = acc[ai][bj][m][0], y1 = acc[ai][bj][m][1];
;                     if (normed) {
;                         y0 = y0 * rinv * gg[bj][0]; y1 = y1 * rinv * gg[bj][1];
;                         if (lat) { const int p = bj == 0 ? (t >> 6) : (t & 63); const pg8::f32x4* rp = (const pg8::f32x4*)(rope + p * 16 + 4 * fq); const pg8::f32x4 c01 = rp[0], c23 = rp[1];
;                             const pg8::f32x4 z0 = {y0[0] * c01[0] - y0[1] * c01[1], y0[0] * c01[1] + y0[1] * c01[0], y0[2] * c01[2] - y0[3] * c01[3], y0[2] * c01[3] + y0[3] * c01[2]};
;                             const pg8::f32x4 z1 = {y1[0] * c23[0] - y1[1] * c23[1], y1[0] * c23[1] + y1[1] * c23[0], y1[2] * c23[2] - y1[3] * c23[3], y1[2] * c23[3] + y1[3] * c23[2]};
;                             y0 = z0; y1 = z1; }
;                     }
;                     v4u o; o.x = pk2(y0[0], y0[1]); o.y = pk2(y0[2], y0[3]); o.z = pk2(y1[0], y1[1]); o.w = pk2(y1[2], y1[3]);
;                     *(v4u*)(dp + 32 * bj) = o;
.LBB0_312:
	v_and_b32_e32 v245, 63, v162
	v_mul_lo_u32 v174, v163, s94
	v_mul_lo_u32 v175, v162, s95
	v_mad_u64_u32 v[162:163], s[4:5], v162, s94, 0
	v_add3_u32 v163, v163, v175, v174
	v_lshl_add_u64 v[162:163], v[162:163], 1, v[160:161]
	v_mul_u32_u24_e32 v244, s100, v245
	v_sub_u32_e32 v244, 0, v244
	v_ashrrev_i32_e32 v245, 31, v244
	v_lshl_add_u64 v[162:163], v[162:163], 0, v[244:245]
	v_cvt_pk_bf16_f32 v166, v166, v167
	v_cvt_pk_bf16_f32 v167, v172, v173
	v_cvt_pk_bf16_f32 v168, v168, v169
	v_cvt_pk_bf16_f32 v169, v170, v171
	global_store_dwordx4 v[162:163], v[166:169], off
	s_and_b64 vcc, exec, s[38:39]
	v_mov_b32_e32 v172, v134
	v_mov_b32_e32 v166, v132
	v_mov_b32_e32 v167, v133
	v_mov_b32_e32 v173, v135
	v_mov_b32_e32 v168, v128
	v_mov_b32_e32 v169, v129
	v_mov_b32_e32 v170, v130
	v_mov_b32_e32 v171, v131
	s_cbranch_vccnz .LBB0_316
	v_mov_b32_e32 v168, v164
	v_mov_b32_e32 v169, v164
	v_pk_mul_f32 v[166:167], v[134:135], v[168:169]
	v_pk_mul_f32 v[170:171], v[132:133], v[164:165]
	v_pk_mul_f32 v[168:169], v[130:131], v[168:169]
	v_pk_mul_f32 v[164:165], v[128:129], v[164:165]
	s_waitcnt vmcnt(0)
	v_pk_mul_f32 v[172:173], v[54:55], v[166:167]
	v_pk_mul_f32 v[166:167], v[52:53], v[170:171]
	v_pk_mul_f32 v[170:171], v[50:51], v[168:169]
	v_pk_mul_f32 v[168:169], v[48:49], v[164:165]
	s_and_saveexec_b64 s[4:5], s[40:41]
	s_cbranch_execz .LBB0_315
	v_lshlrev_b32_e32 v164, 7, v202
	v_and_b32_e32 v164, 0x780, v164
	v_mov_b32_e32 v165, v209
	v_lshl_add_u64 v[164:165], v[154:155], 0, v[164:165]
	global_load_dwordx4 v[174:177], v[164:165], off
	global_load_dwordx4 v[178:181], v[164:165], off offset:16
	s_waitcnt vmcnt(0) lgkmcnt(0)
	v_pk_mul_f32 v[182:183], v[166:167], v[174:175] op_sel:[1,1] op_sel_hi:[1,0]
	v_pk_mul_f32 v[164:165], v[166:167], v[174:175]
	v_pk_fma_f32 v[166:167], v[166:167], v[174:175], v[182:183] op_sel_hi:[0,1,1]
	v_mul_f32_e32 v166, v173, v177
	v_pk_fma_f32 v[174:175], v[172:173], v[176:177], v[166:167] op_sel_hi:[1,1,0] neg_lo:[0,0,1] neg_hi:[0,0,1]
	v_mul_f32_e32 v166, v173, v176
	v_pk_fma_f32 v[172:173], v[172:173], v[176:177], v[166:167] op_sel:[0,1,0] op_sel_hi:[1,0,0]
	v_pk_mul_f32 v[184:185], v[168:169], v[178:179] op_sel:[1,1] op_sel_hi:[1,0]
	v_mul_f32_e32 v166, v171, v181
	v_pk_mul_f32 v[176:177], v[168:169], v[178:179]
	v_pk_fma_f32 v[168:169], v[168:169], v[178:179], v[184:185] op_sel_hi:[0,1,1]
	v_pk_fma_f32 v[178:179], v[170:171], v[180:181], v[166:167] op_sel_hi:[1,1,0] neg_lo:[0,0,1] neg_hi:[0,0,1]
	v_mul_f32_e32 v166, v171, v180
	v_pk_fma_f32 v[170:171], v[170:171], v[180:181], v[166:167] op_sel:[0,1,0] op_sel_hi:[1,0,0]
	v_sub_f32_e32 v166, v164, v182
	v_sub_f32_e32 v168, v176, v184
	v_mov_b32_e32 v171, v170
	v_mov_b32_e32 v170, v178
	v_mov_b32_e32 v173, v172
	v_mov_b32_e32 v172, v174

; __device__ __forceinline__ unsigned pk2(float lo, float hi) { const f32x2_cv v = {lo, hi}; const bf16x2_cv b = __builtin_convertvector(v, bf16x2_cv); return __builtin_bit_cast(unsigned, b); }
; __device__ __forceinline__ unsigned f2bf(float f) { return pk2(f, f) & 0xffffu; }
;     __device__ __forceinline__ void operator()(const pg8::f32x4 (&acc)[2][2][4][2], const pg8::Unit& u, int wr, int wc, int fr, int fq) const {
;     ...
;                 if (pn >= 2 && pn < 5) {
;                     bf16_t* cbp = lat ? hyr + (size_t)b * 768 * 8192 + t : hyrc + (size_t)b * 768 * 256 + t; const size_t cst = lat ? 8192 : 256;
; #pragma unroll
;                     for (int bj = 0; bj < 2; ++bj)
; #pragma unroll
;                         for (int n = 0; n < 2; ++n)
; #pragma unroll
;                             for (int e = 0; e < 4; ++e) cbp[(size_t)(dcol + 32 * bj + 8 * fq + 4 * n + e) * cst] = (bf16_t)f2bf(acc[ai][bj][m][n][e]);
;                     continue;
;                 }
;     ...
;                 for (int bj = 0; bj < 2; ++bj) {
;                     pg8::f32x4 y0 = acc[ai][bj][m][0], y1 = acc[ai][bj][m][1];
;                     if (normed) {
;                         y0 = y0 * rinv * gg[bj][0]; y1 = y1 * rinv * gg[bj][1];
;                         if (lat) { const int p = bj == 0 ? (t >> 6) : (t & 63); const pg8::f32x4* rp = (const pg8::f32x4*)(rope + p * 16 + 4 * fq); const pg8::f32x4 c01 = rp[0], c23 = rp[1];
;                             const pg8::f32x4 z0 = {y0[0] * c01[0] - y0[1] * c01[1], y0[0] * c01[1] + y0[1] * c01[0], y0[2] * c01[2] - y0[3] * c01[3], y0[2] * c01[3] + y0[3] * c01[2]};
;                             const pg8::f32x4 z1 = {y1[0] * c23[0] - y1[1] * c23[1], y1[0] * c23[1] + y1[1] * c23[0], y1[2] * c23[2] - y1[3] * c23[3], y1[2] * c23[3] + y1[3] * c23[2]};
;                             y0 = z0; y1 = z1; }
;                     }
;                     v4u o; o.x = pk2(y0[0], y0[1]); o.y = pk2(y0[2], y0[3]); o.z = pk2(y1[0], y1[1]); o.w = pk2(y1[2], y1[3]);
;                     *(v4u*)(dp + 32 * bj) = o;
.LBB0_316:
	v_cvt_pk_bf16_f32 v164, v166, v167
	v_cvt_pk_bf16_f32 v165, v172, v173
	v_cvt_pk_bf16_f32 v166, v168, v169
	v_cvt_pk_bf16_f32 v167, v170, v171
	s_mov_b64 s[4:5], 0
	v_lshl_add_u64 v[162:163], v[162:163], 0, v[246:247]
	global_store_dwordx4 v[162:163], v[164:167], off offset:64
.LBB0_317:
	v_add_u32_e32 v192, s42, v152
	v_add_u32_e32 v190, 1, v192
	v_add_u32_e32 v188, 2, v192
	v_add_u32_e32 v186, 3, v192
	v_add_u32_e32 v184, 4, v192
	v_add_u32_e32 v182, 5, v192
	v_add_u32_e32 v180, 6, v192
	v_add_u32_e32 v178, 7, v192
	v_add_u32_e32 v176, 32, v192
	v_add_u32_e32 v174, 33, v192
	v_add_u32_e32 v172, 34, v192
	v_add_u32_e32 v170, 35, v192
	v_add_u32_e32 v168, 36, v192
	v_add_u32_e32 v166, 37, v192
	v_add_u32_e32 v164, 38, v192
	v_add_u32_e32 v162, 39, v192
	s_and_b64 vcc, exec, s[4:5]
	v_ashrrev_i32_e32 v193, 31, v192
	v_ashrrev_i32_e32 v191, 31, v190
	v_ashrrev_i32_e32 v189, 31, v188
	v_ashrrev_i32_e32 v187, 31, v186
	v_ashrrev_i32_e32 v185, 31, v184
	v_ashrrev_i32_e32 v183, 31, v182
	v_ashrrev_i32_e32 v181, 31, v180
	v_ashrrev_i32_e32 v179, 31, v178
	v_ashrrev_i32_e32 v177, 31, v176
	v_ashrrev_i32_e32 v175, 31, v174
	v_ashrrev_i32_e32 v173, 31, v172
	v_ashrrev_i32_e32 v171, 31, v170
	v_ashrrev_i32_e32 v169, 31, v168
	v_ashrrev_i32_e32 v167, 31, v166
	v_ashrrev_i32_e32 v165, 31, v164
	v_ashrrev_i32_e32 v163, 31, v162
	s_cbranch_vccz .LBB0_319
	v_mov_b32_e32 v203, s46
	v_mov_b32_e32 v204, s85
	v_cndmask_b32_e64 v205, v203, v204, s[40:41]
	v_mov_b32_e32 v203, s89
	v_mov_b32_e32 v204, s84
	v_cndmask_b32_e64 v204, v203, v204, s[40:41]
	v_cndmask_b32_e64 v203, v235, v236, s[40:41]
	v_mad_i64_i32 v[204:205], s[4:5], v203, v201, v[204:205]
	v_lshlrev_b32_e32 v202, 1, v202
	v_mov_b32_e32 v203, v209
	v_cndmask_b32_e64 v201, 8, 13, s[40:41]
	v_lshl_add_u64 v[202:203], v[204:205], 0, v[202:203]
	v_lshlrev_b64 v[204:205], v201, v[192:193]
	v_cvt_pk_bf16_f32 v140, v140, s0
	v_lshl_add_u64 v[204:205], v[204:205], 1, v[202:203]
	global_store_short v[204:205], v140, off
	v_cvt_pk_bf16_f32 v204, v141, s0
	v_lshlrev_b64 v[140:141], v201, v[190:191]
	v_lshl_add_u64 v[140:141], v[140:141], 1, v[202:203]
	global_store_short v[140:141], v204, off
	v_lshlrev_b64 v[140:141], v201, v[188:189]
	v_cvt_pk_bf16_f32 v142, v142, s0
	v_lshl_add_u64 v[140:141], v[140:141], 1, v[202:203]
	global_store_short v[140:141], v142, off
	v_lshlrev_b64 v[140:141], v201, v[186:187]
	v_cvt_pk_bf16_f32 v142, v143, s0
	v_lshl_add_u64 v[140:141], v[140:141], 1, v[202:203]
	global_store_short v[140:141], v142, off
	v_lshlrev_b64 v[140:141], v201, v[184:185]
	v_cvt_pk_bf16_f32 v136, v136, s0
	v_lshl_add_u64 v[140:141], v[140:141], 1, v[202:203]
	global_store_short v[140:141], v136, off
	v_cvt_pk_bf16_f32 v140, v137, s0
	v_lshlrev_b64 v[136:137], v201, v[182:183]
	v_lshl_add_u64 v[136:137], v[136:137], 1, v[202:203]
	global_store_short v[136:137], v140, off
	v_lshlrev_b64 v[136:137], v201, v[180:181]
	v_cvt_pk_bf16_f32 v138, v138, s0
	v_lshl_add_u64 v[136:137], v[136:137], 1, v[202:203]
	global_store_short v[136:137], v138, off
	v_lshlrev_b64 v[136:137], v201, v[178:179]
	v_cvt_pk_bf16_f32 v138, v139, s0
	v_lshl_add_u64 v[136:137], v[136:137], 1, v[202:203]
	global_store_short v[136:137], v138, off
	v_lshlrev_b64 v[136:137], v201, v[176:177]
	v_cvt_pk_bf16_f32 v132, v132, s0
	v_lshl_add_u64 v[136:137], v[136:137], 1, v[202:203]
	global_store_short v[136:137], v132, off
	v_cvt_pk_bf16_f32 v136, v133, s0
	v_lshlrev_b64 v[132:133], v201, v[174:175]
	v_lshl_add_u64 v[132:133], v[132:133], 1, v[202:203]
	global_store_short v[132:133], v136, off
	v_lshlrev_b64 v[132:133], v201, v[172:173]
	v_cvt_pk_bf16_f32 v134, v134, s0
	v_lshl_add_u64 v[132:133], v[132:133], 1, v[202:203]
	global_store_short v[132:133], v134, off
	v_lshlrev_b64 v[132:133], v201, v[170:171]
	v_cvt_pk_bf16_f32 v134, v135, s0
	v_lshl_add_u64 v[132:133], v[132:133], 1, v[202:203]
	global_store_short v[132:133], v134, off
	v_lshlrev_b64 v[132:133], v201, v[168:169]
	v_cvt_pk_bf16_f32 v128, v128, s0
	v_lshl_add_u64 v[132:133], v[132:133], 1, v[202:203]
	global_store_short v[132:133], v128, off
	v_cvt_pk_bf16_f32 v132, v129, s0
	v_lshlrev_b64 v[128:129], v201, v[166:167]
	v_lshl_add_u64 v[128:129], v[128:129], 1, v[202:203]
	global_store_short v[128:129], v132, off
	v_lshlrev_b64 v[128:129], v201, v[164:165]
	v_cvt_pk_bf16_f32 v130, v130, s0
	v_lshl_add_u64 v[128:129], v[128:129], 1, v[202:203]
	global_store_short v[128:129], v130, off
	v_lshlrev_b64 v[128:129], v201, v[162:163]
	v_cvt_pk_bf16_f32 v130, v131, s0
	v_lshl_add_u64 v[128:129], v[128:129], 1, v[202:203]
	global_store_short v[128:129], v130, off

;     __device__ __forceinline__ void operator()(const pg8::f32x4 (&acc)[2][2][4][2], const pg8::Unit& u, int wr, int wc, int fr, int fq) const {
;     ...
;                     pg8::f32x4 y0 = acc[ai][bj][m][0], y1 = acc[ai][bj][m][1];
;                     if (normed) {
;                         y0 = y0 * rinv * gg[bj][0]; y1 = y1 * rinv * gg[bj][1];
;                         if (lat) { const int p = bj == 0 ? (t >> 6) : (t & 63); const pg8::f32x4* rp = (const pg8::f32x4*)(rope + p * 16 + 4 * fq); const pg8::f32x4 c01 = rp[0], c23 = rp[1];
;                             const pg8::f32x4 z0 = {y0[0] * c01[0] - y0[1] * c01[1], y0[0] * c01[1] + y0[1] * c01[0], y0[2] * c01[2] - y0[3] * c01[3], y0[2] * c01[3] + y0[3] * c01[2]};
;                             const pg8::f32x4 z1 = {y1[0] * c23[0] - y1[1] * c23[1], y1[0] * c23[1] + y1[1] * c23[0], y1[2] * c23[2] - y1[3] * c23[3], y1[2] * c23[3] + y1[3] * c23[2]};
;                             y0 = z0; y1 = z1; }
.LBB0_326:
	v_mov_b32_e32 v131, v130
	s_and_b64 vcc, exec, s[38:39]
	v_mov_b32_e32 v132, v124
	v_mov_b32_e32 v133, v125
	v_mov_b32_e32 v138, v126
	v_mov_b32_e32 v139, v127
	v_mov_b32_e32 v134, v120
	v_mov_b32_e32 v135, v121
	v_mov_b32_e32 v136, v122
	v_mov_b32_e32 v137, v123
	s_cbranch_vccnz .LBB0_330
	v_mov_b32_e32 v134, v130
	v_mov_b32_e32 v135, v130
	v_pk_mul_f32 v[132:133], v[126:127], v[134:135]
	v_pk_mul_f32 v[136:137], v[124:125], v[130:131]
	v_pk_mul_f32 v[134:135], v[122:123], v[134:135]
	v_pk_mul_f32 v[142:143], v[120:121], v[130:131]
	s_waitcnt vmcnt(0)
	v_pk_mul_f32 v[138:139], v[62:63], v[132:133]
	v_pk_mul_f32 v[132:133], v[60:61], v[136:137]
	v_pk_mul_f32 v[136:137], v[58:59], v[134:135]
	v_pk_mul_f32 v[134:135], v[56:57], v[142:143]
	s_and_saveexec_b64 s[4:5], s[44:45]
	s_cbranch_execz .LBB0_329
	v_lshlrev_b32_e32 v142, 1, v141
	v_and_b32_e32 v142, 0x3f80, v142
	v_mov_b32_e32 v143, v209
	v_lshl_add_u64 v[142:143], v[154:155], 0, v[142:143]
	global_load_dwordx4 v[202:205], v[142:143], off
	global_load_dwordx4 v[210:213], v[142:143], off offset:16
	s_waitcnt vmcnt(0) lgkmcnt(0)
	v_pk_mul_f32 v[206:207], v[132:133], v[202:203] op_sel:[1,1] op_sel_hi:[1,0]
	v_pk_mul_f32 v[142:143], v[132:133], v[202:203]
	v_pk_fma_f32 v[132:133], v[132:133], v[202:203], v[206:207] op_sel_hi:[0,1,1]
	v_mul_f32_e32 v132, v139, v205
	v_pk_fma_f32 v[202:203], v[138:139], v[204:205], v[132:133] op_sel_hi:[1,1,0] neg_lo:[0,0,1] neg_hi:[0,0,1]
	v_mul_f32_e32 v132, v139, v204
	v_pk_fma_f32 v[138:139], v[138:139], v[204:205], v[132:133] op_sel:[0,1,0] op_sel_hi:[1,0,0]
	v_pk_mul_f32 v[214:215], v[134:135], v[210:211] op_sel:[1,1] op_sel_hi:[1,0]
	v_mul_f32_e32 v132, v137, v213
	v_pk_mul_f32 v[204:205], v[134:135], v[210:211]
	v_pk_fma_f32 v[134:135], v[134:135], v[210:211], v[214:215] op_sel_hi:[0,1,1]
	v_pk_fma_f32 v[210:211], v[136:137], v[212:213], v[132:133] op_sel_hi:[1,1,0] neg_lo:[0,0,1] neg_hi:[0,0,1]
	v_mul_f32_e32 v132, v137, v212
	v_pk_fma_f32 v[136:137], v[136:137], v[212:213], v[132:133] op_sel:[0,1,0] op_sel_hi:[1,0,0]
	v_sub_f32_e32 v132, v142, v206
	v_sub_f32_e32 v134, v204, v214
	v_mov_b32_e32 v137, v136
	v_mov_b32_e32 v136, v210
	v_mov_b32_e32 v139, v138
	v_mov_b32_e32 v138, v202

; __device__ __forceinline__ unsigned pk2(float lo, float hi) { const f32x2_cv v = {lo, hi}; const bf16x2_cv b = __builtin_convertvector(v, bf16x2_cv); return __builtin_bit_cast(unsigned, b); }
;     __device__ __forceinline__ void operator()(const pg8::f32x4 (&acc)[2][2][4][2], const pg8::Unit& u, int wr, int wc, int fr, int fq) const {
;     ...
;                 for (int bj = 0; bj < 2; ++bj) {
;                     pg8::f32x4 y0 = acc[ai][bj][m][0], y1 = acc[ai][bj][m][1];
;                     if (normed) {
;                         y0 = y0 * rinv * gg[bj][0]; y1 = y1 * rinv * gg[bj][1];
;                         if (lat) { const int p = bj == 0 ? (t >> 6) : (t & 63); const pg8::f32x4* rp = (const pg8::f32x4*)(rope + p * 16 + 4 * fq); const pg8::f32x4 c01 = rp[0], c23 = rp[1];
;                             const pg8::f32x4 z0 = {y0[0] * c01[0] - y0[1] * c01[1], y0[0] * c01[1] + y0[1] * c01[0], y0[2] * c01[2] - y0[3] * c01[3], y0[2] * c01[3] + y0[3] * c01[2]};
;                             const pg8::f32x4 z1 = {y1[0] * c23[0] - y1[1] * c23[1], y1[0] * c23[1] + y1[1] * c23[0], y1[2] * c23[2] - y1[3] * c23[3], y1[2] * c23[3] + y1[3] * c23[2]};
;                             y0 = z0; y1 = z1; }
;                     }
;                     v4u o; o.x = pk2(y0[0], y0[1]); o.y = pk2(y0[2], y0[3]); o.z = pk2(y1[0], y1[1]); o.w = pk2(y1[2], y1[3]);
;                     *(v4u*)(dp + 32 * bj) = o;
.LBB0_330:
	v_and_b32_e32 v245, 63, v128
	v_mul_lo_u32 v142, v129, s94
	v_mul_lo_u32 v143, v128, s95
	v_mad_u64_u32 v[128:129], s[4:5], v128, s94, 0
	v_add3_u32 v129, v129, v143, v142
	v_lshl_add_u64 v[128:129], v[128:129], 1, v[160:161]
	v_mul_u32_u24_e32 v244, s100, v245
	v_sub_u32_e32 v244, 0, v244
	v_ashrrev_i32_e32 v245, 31, v244
	v_lshl_add_u64 v[128:129], v[128:129], 0, v[244:245]
	v_cvt_pk_bf16_f32 v132, v132, v133
	v_cvt_pk_bf16_f32 v133, v138, v139
	v_cvt_pk_bf16_f32 v134, v134, v135
	v_cvt_pk_bf16_f32 v135, v136, v137
	global_store_dwordx4 v[128:129], v[132:135], off
	s_and_b64 vcc, exec, s[38:39]
	v_mov_b32_e32 v138, v118
	v_mov_b32_e32 v132, v116
	v_mov_b32_e32 v133, v117
	v_mov_b32_e32 v139, v119
	v_mov_b32_e32 v134, v112
	v_mov_b32_e32 v135, v113
	v_mov_b32_e32 v136, v114
	v_mov_b32_e32 v137, v115
	s_cbranch_vccnz .LBB0_334
	v_mov_b32_e32 v134, v130
	v_mov_b32_e32 v135, v130
	v_pk_mul_f32 v[132:133], v[118:119], v[134:135]
	v_pk_mul_f32 v[136:137], v[116:117], v[130:131]
	v_pk_mul_f32 v[134:135], v[114:115], v[134:135]
	v_pk_mul_f32 v[130:131], v[112:113], v[130:131]
	s_waitcnt vmcnt(0)
	v_pk_mul_f32 v[138:139], v[54:55], v[132:133]
	v_pk_mul_f32 v[132:133], v[52:53], v[136:137]
	v_pk_mul_f32 v[136:137], v[50:51], v[134:135]
	v_pk_mul_f32 v[134:135], v[48:49], v[130:131]
	s_and_saveexec_b64 s[4:5], s[44:45]
	s_cbranch_execz .LBB0_333
	v_lshlrev_b32_e32 v130, 7, v141
	v_and_b32_e32 v130, 0xf80, v130
	v_mov_b32_e32 v131, v209
	v_lshl_add_u64 v[130:131], v[154:155], 0, v[130:131]
	global_load_dwordx4 v[202:205], v[130:131], off
	global_load_dwordx4 v[210:213], v[130:131], off offset:16
	s_waitcnt vmcnt(0) lgkmcnt(0)
	v_pk_mul_f32 v[142:143], v[132:133], v[202:203] op_sel:[1,1] op_sel_hi:[1,0]
	v_pk_mul_f32 v[130:131], v[132:133], v[202:203]
	v_pk_fma_f32 v[132:133], v[132:133], v[202:203], v[142:143] op_sel_hi:[0,1,1]
	v_mul_f32_e32 v132, v139, v205
	v_pk_fma_f32 v[202:203], v[138:139], v[204:205], v[132:133] op_sel_hi:[1,1,0] neg_lo:[0,0,1] neg_hi:[0,0,1]
	v_mul_f32_e32 v132, v139, v204
	v_pk_fma_f32 v[138:139], v[138:139], v[204:205], v[132:133] op_sel:[0,1,0] op_sel_hi:[1,0,0]
	v_pk_mul_f32 v[206:207], v[134:135], v[210:211] op_sel:[1,1] op_sel_hi:[1,0]
	v_mul_f32_e32 v132, v137, v213
	v_pk_mul_f32 v[204:205], v[134:135], v[210:211]
	v_pk_fma_f32 v[134:135], v[134:135], v[210:211], v[206:207] op_sel_hi:[0,1,1]
	v_pk_fma_f32 v[210:211], v[136:137], v[212:213], v[132:133] op_sel_hi:[1,1,0] neg_lo:[0,0,1] neg_hi:[0,0,1]
	v_mul_f32_e32 v132, v137, v212
	v_pk_fma_f32 v[136:137], v[136:137], v[212:213], v[132:133] op_sel:[0,1,0] op_sel_hi:[1,0,0]
	v_sub_f32_e32 v132, v130, v142
	v_sub_f32_e32 v134, v204, v206
	v_mov_b32_e32 v137, v136
	v_mov_b32_e32 v136, v210
	v_mov_b32_e32 v139, v138
	v_mov_b32_e32 v138, v202

; __device__ __forceinline__ unsigned pk2(float lo, float hi) { const f32x2_cv v = {lo, hi}; const bf16x2_cv b = __builtin_convertvector(v, bf16x2_cv); return __builtin_bit_cast(unsigned, b); }
; __device__ __forceinline__ unsigned f2bf(float f) { return pk2(f, f) & 0xffffu; }
;     __device__ __forceinline__ void operator()(const pg8::f32x4 (&acc)[2][2][4][2], const pg8::Unit& u, int wr, int wc, int fr, int fq) const {
;     ...
;                 if (pn >= 2 && pn < 5) {
;                     bf16_t* cbp = lat ? hyr + (size_t)b * 768 * 8192 + t : hyrc + (size_t)b * 768 * 256 + t; const size_t cst = lat ? 8192 : 256;
; #pragma unroll
;                     for (int bj = 0; bj < 2; ++bj)
; #pragma unroll
;                         for (int n = 0; n < 2; ++n)
; #pragma unroll
;                             for (int e = 0; e < 4; ++e) cbp[(size_t)(dcol + 32 * bj + 8 * fq + 4 * n + e) * cst] = (bf16_t)f2bf(acc[ai][bj][m][n][e]);
;                     continue;
;                 }
;     ...
;                     v4u o; o.x = pk2(y0[0], y0[1]); o.y = pk2(y0[2], y0[3]); o.z = pk2(y1[0], y1[1]); o.w = pk2(y1[2], y1[3]);
;                     *(v4u*)(dp + 32 * bj) = o;
.LBB0_334:
	v_cvt_pk_bf16_f32 v130, v132, v133
	v_cvt_pk_bf16_f32 v131, v138, v139
	v_cvt_pk_bf16_f32 v132, v134, v135
	v_cvt_pk_bf16_f32 v133, v136, v137
	s_mov_b64 s[4:5], 0
	v_lshl_add_u64 v[128:129], v[128:129], 0, v[246:247]
	global_store_dwordx4 v[128:129], v[130:133], off offset:64
.LBB0_335:
	s_and_b64 vcc, exec, s[4:5]
	s_cbranch_vccz .LBB0_337
	v_mov_b32_e32 v128, s46
	v_mov_b32_e32 v129, s85
	v_cndmask_b32_e64 v129, v128, v129, s[44:45]
	v_mov_b32_e32 v128, s89
	v_mov_b32_e32 v130, s84
	v_cndmask_b32_e64 v128, v128, v130, s[44:45]
	v_cndmask_b32_e64 v130, v235, v236, s[44:45]
	v_mad_i64_i32 v[128:129], s[4:5], v130, v140, v[128:129]
	v_lshlrev_b32_e32 v130, 1, v141
	v_mov_b32_e32 v131, v209
	v_cndmask_b32_e64 v132, 8, 13, s[44:45]
	v_lshl_add_u64 v[128:129], v[128:129], 0, v[130:131]
	v_lshlrev_b64 v[130:131], v132, v[192:193]
	v_cvt_pk_bf16_f32 v124, v124, s0
	v_lshl_add_u64 v[130:131], v[130:131], 1, v[128:129]
	global_store_short v[130:131], v124, off
	v_cvt_pk_bf16_f32 v130, v125, s0
	v_lshlrev_b64 v[124:125], v132, v[190:191]
	v_lshl_add_u64 v[124:125], v[124:125], 1, v[128:129]
	global_store_short v[124:125], v130, off
	v_lshlrev_b64 v[124:125], v132, v[188:189]
	v_cvt_pk_bf16_f32 v126, v126, s0
	v_lshl_add_u64 v[124:125], v[124:125], 1, v[128:129]
	global_store_short v[124:125], v126, off
	v_lshlrev_b64 v[124:125], v132, v[186:187]
	v_cvt_pk_bf16_f32 v126, v127, s0
	v_lshl_add_u64 v[124:125], v[124:125], 1, v[128:129]
	global_store_short v[124:125], v126, off
	v_lshlrev_b64 v[124:125], v132, v[184:185]
	v_cvt_pk_bf16_f32 v120, v120, s0
	v_lshl_add_u64 v[124:125], v[124:125], 1, v[128:129]
	global_store_short v[124:125], v120, off
	v_cvt_pk_bf16_f32 v124, v121, s0
	v_lshlrev_b64 v[120:121], v132, v[182:183]
	v_lshl_add_u64 v[120:121], v[120:121], 1, v[128:129]
	global_store_short v[120:121], v124, off
	v_lshlrev_b64 v[120:121], v132, v[180:181]
	v_cvt_pk_bf16_f32 v122, v122, s0
	v_lshl_add_u64 v[120:121], v[120:121], 1, v[128:129]
	global_store_short v[120:121], v122, off
	v_lshlrev_b64 v[120:121], v132, v[178:179]
	v_cvt_pk_bf16_f32 v122, v123, s0
	v_lshl_add_u64 v[120:121], v[120:121], 1, v[128:129]
	global_store_short v[120:121], v122, off
	v_lshlrev_b64 v[120:121], v132, v[176:177]
	v_cvt_pk_bf16_f32 v116, v116, s0
	v_lshl_add_u64 v[120:121], v[120:121], 1, v[128:129]
	global_store_short v[120:121], v116, off
	v_cvt_pk_bf16_f32 v120, v117, s0
	v_lshlrev_b64 v[116:117], v132, v[174:175]
	v_lshl_add_u64 v[116:117], v[116:117], 1, v[128:129]
	global_store_short v[116:117], v120, off
	v_lshlrev_b64 v[116:117], v132, v[172:173]
	v_cvt_pk_bf16_f32 v118, v118, s0
	v_lshl_add_u64 v[116:117], v[116:117], 1, v[128:129]
	global_store_short v[116:117], v118, off
	v_lshlrev_b64 v[116:117], v132, v[170:171]
	v_cvt_pk_bf16_f32 v118, v119, s0
	v_lshl_add_u64 v[116:117], v[116:117], 1, v[128:129]
	global_store_short v[116:117], v118, off
	v_lshlrev_b64 v[116:117], v132, v[168:169]
	v_cvt_pk_bf16_f32 v112, v112, s0
	v_lshl_add_u64 v[116:117], v[116:117], 1, v[128:129]
	global_store_short v[116:117], v112, off
	v_cvt_pk_bf16_f32 v116, v113, s0
	v_lshlrev_b64 v[112:113], v132, v[166:167]
	v_lshl_add_u64 v[112:113], v[112:113], 1, v[128:129]
	global_store_short v[112:113], v116, off
	v_lshlrev_b64 v[112:113], v132, v[164:165]
	v_cvt_pk_bf16_f32 v114, v114, s0
	v_lshl_add_u64 v[112:113], v[112:113], 1, v[128:129]
	global_store_short v[112:113], v114, off
	v_lshlrev_b64 v[112:113], v132, v[162:163]
	v_cvt_pk_bf16_f32 v114, v115, s0
	v_lshl_add_u64 v[112:113], v[112:113], 1, v[128:129]
	global_store_short v[112:113], v114, off

; __device__ __forceinline__ unsigned f2bf(float f) { return pk2(f, f) & 0xffffu; }
;     __device__ __forceinline__ void operator()(const pg8::f32x4 (&acc)[2][2][4][2], const pg8::Unit& u, int wr, int wc, int fr, int fq) const {
;     ...
;                 if (pn >= 2 && pn < 5) {
;                     bf16_t* cbp = lat ? hyr + (size_t)b * 768 * 8192 + t : hyrc + (size_t)b * 768 * 256 + t; const size_t cst = lat ? 8192 : 256;
; #pragma unroll
;                     for (int bj = 0; bj < 2; ++bj)
; #pragma unroll
;                         for (int n = 0; n < 2; ++n)
; #pragma unroll
;                             for (int e = 0; e < 4; ++e) cbp[(size_t)(dcol + 32 * bj + 8 * fq + 4 * n + e) * cst] = (bf16_t)f2bf(acc[ai][bj][m][n][e]);
;                     continue;
;                 }
.LBB0_341:
	s_and_b64 vcc, exec, s[4:5]
	s_cbranch_vccz .LBB0_343
	v_mov_b32_e32 v112, s46
	v_mov_b32_e32 v113, s85
	v_cndmask_b32_e64 v113, v112, v113, s[44:45]
	v_mov_b32_e32 v112, s89
	v_mov_b32_e32 v114, s84
	v_cndmask_b32_e64 v112, v112, v114, s[44:45]
	v_cndmask_b32_e64 v114, v235, v236, s[44:45]
	v_mad_i64_i32 v[112:113], s[4:5], v114, v124, v[112:113]
	v_lshlrev_b32_e32 v114, 1, v125
	v_mov_b32_e32 v115, v209
	v_cndmask_b32_e64 v116, 8, 13, s[44:45]
	v_lshl_add_u64 v[112:113], v[112:113], 0, v[114:115]
	v_lshlrev_b64 v[114:115], v116, v[192:193]
	v_cvt_pk_bf16_f32 v108, v108, s0
	v_lshl_add_u64 v[114:115], v[114:115], 1, v[112:113]
	global_store_short v[114:115], v108, off
	v_cvt_pk_bf16_f32 v114, v109, s0
	v_lshlrev_b64 v[108:109], v116, v[190:191]
	v_lshl_add_u64 v[108:109], v[108:109], 1, v[112:113]
	global_store_short v[108:109], v114, off
	v_lshlrev_b64 v[108:109], v116, v[188:189]
	v_cvt_pk_bf16_f32 v110, v110, s0
	v_lshl_add_u64 v[108:109], v[108:109], 1, v[112:113]
	global_store_short v[108:109], v110, off
	v_lshlrev_b64 v[108:109], v116, v[186:187]
	v_cvt_pk_bf16_f32 v110, v111, s0
	v_lshl_add_u64 v[108:109], v[108:109], 1, v[112:113]
	global_store_short v[108:109], v110, off
	v_lshlrev_b64 v[108:109], v116, v[184:185]
	v_cvt_pk_bf16_f32 v104, v104, s0
	v_lshl_add_u64 v[108:109], v[108:109], 1, v[112:113]
	global_store_short v[108:109], v104, off
	v_cvt_pk_bf16_f32 v108, v105, s0
	v_lshlrev_b64 v[104:105], v116, v[182:183]
	v_lshl_add_u64 v[104:105], v[104:105], 1, v[112:113]
	global_store_short v[104:105], v108, off
	v_lshlrev_b64 v[104:105], v116, v[180:181]
	v_cvt_pk_bf16_f32 v106, v106, s0
	v_lshl_add_u64 v[104:105], v[104:105], 1, v[112:113]
	global_store_short v[104:105], v106, off
	v_lshlrev_b64 v[104:105], v116, v[178:179]
	v_cvt_pk_bf16_f32 v106, v107, s0
	v_lshl_add_u64 v[104:105], v[104:105], 1, v[112:113]
	global_store_short v[104:105], v106, off
	v_lshlrev_b64 v[104:105], v116, v[176:177]
	v_cvt_pk_bf16_f32 v100, v100, s0
	v_lshl_add_u64 v[104:105], v[104:105], 1, v[112:113]
	global_store_short v[104:105], v100, off
	v_cvt_pk_bf16_f32 v104, v101, s0
	v_lshlrev_b64 v[100:101], v116, v[174:175]
	v_lshl_add_u64 v[100:101], v[100:101], 1, v[112:113]
	global_store_short v[100:101], v104, off
	v_lshlrev_b64 v[100:101], v116, v[172:173]
	v_cvt_pk_bf16_f32 v102, v102, s0
	v_lshl_add_u64 v[100:101], v[100:101], 1, v[112:113]
	global_store_short v[100:101], v102, off
	v_lshlrev_b64 v[100:101], v116, v[170:171]
	v_cvt_pk_bf16_f32 v102, v103, s0
	v_lshl_add_u64 v[100:101], v[100:101], 1, v[112:113]
	global_store_short v[100:101], v102, off
	v_lshlrev_b64 v[100:101], v116, v[168:169]
	v_cvt_pk_bf16_f32 v96, v96, s0
	v_lshl_add_u64 v[100:101], v[100:101], 1, v[112:113]
	global_store_short v[100:101], v96, off
	v_cvt_pk_bf16_f32 v100, v97, s0
	v_lshlrev_b64 v[96:97], v116, v[166:167]
	v_lshl_add_u64 v[96:97], v[96:97], 1, v[112:113]
	global_store_short v[96:97], v100, off
	v_lshlrev_b64 v[96:97], v116, v[164:165]
	v_cvt_pk_bf16_f32 v98, v98, s0
	v_lshl_add_u64 v[96:97], v[96:97], 1, v[112:113]
	global_store_short v[96:97], v98, off
	v_lshlrev_b64 v[96:97], v116, v[162:163]
	v_cvt_pk_bf16_f32 v98, v99, s0
	v_lshl_add_u64 v[96:97], v[96:97], 1, v[112:113]
	global_store_short v[96:97], v98, off

; __device__ __forceinline__ unsigned f2bf(float f) { return pk2(f, f) & 0xffffu; }
;     __device__ __forceinline__ void operator()(const pg8::f32x4 (&acc)[2][2][4][2], const pg8::Unit& u, int wr, int wc, int fr, int fq) const {
;     ...
;                 if (pn >= 2 && pn < 5) {
;                     bf16_t* cbp = lat ? hyr + (size_t)b * 768 * 8192 + t : hyrc + (size_t)b * 768 * 256 + t; const size_t cst = lat ? 8192 : 256;
; #pragma unroll
;                     for (int bj = 0; bj < 2; ++bj)
; #pragma unroll
;                         for (int n = 0; n < 2; ++n)
; #pragma unroll
;                             for (int e = 0; e < 4; ++e) cbp[(size_t)(dcol + 32 * bj + 8 * fq + 4 * n + e) * cst] = (bf16_t)f2bf(acc[ai][bj][m][n][e]);
;                     continue;
;                 }
.LBB0_347:
	s_and_b64 vcc, exec, s[4:5]
	s_cbranch_vccz .LBB0_349
	v_mov_b32_e32 v96, s46
	v_mov_b32_e32 v97, s85
	v_cndmask_b32_e64 v97, v96, v97, s[44:45]
	v_mov_b32_e32 v96, s89
	v_mov_b32_e32 v98, s84
	v_cndmask_b32_e64 v96, v96, v98, s[44:45]
	v_cndmask_b32_e64 v98, v235, v236, s[44:45]
	v_mad_i64_i32 v[96:97], s[4:5], v98, v108, v[96:97]
	v_lshlrev_b32_e32 v98, 1, v109
	v_mov_b32_e32 v99, v209
	v_cndmask_b32_e64 v100, 8, 13, s[44:45]
	v_lshl_add_u64 v[96:97], v[96:97], 0, v[98:99]
	v_lshlrev_b64 v[98:99], v100, v[192:193]
	v_cvt_pk_bf16_f32 v92, v92, s0
	v_lshl_add_u64 v[98:99], v[98:99], 1, v[96:97]
	global_store_short v[98:99], v92, off
	v_cvt_pk_bf16_f32 v98, v93, s0
	v_lshlrev_b64 v[92:93], v100, v[190:191]
	v_lshl_add_u64 v[92:93], v[92:93], 1, v[96:97]
	global_store_short v[92:93], v98, off
	v_lshlrev_b64 v[92:93], v100, v[188:189]
	v_cvt_pk_bf16_f32 v94, v94, s0
	v_lshl_add_u64 v[92:93], v[92:93], 1, v[96:97]
	global_store_short v[92:93], v94, off
	v_lshlrev_b64 v[92:93], v100, v[186:187]
	v_cvt_pk_bf16_f32 v94, v95, s0
	v_lshl_add_u64 v[92:93], v[92:93], 1, v[96:97]
	global_store_short v[92:93], v94, off
	v_lshlrev_b64 v[92:93], v100, v[184:185]
	v_cvt_pk_bf16_f32 v88, v88, s0
	v_lshl_add_u64 v[92:93], v[92:93], 1, v[96:97]
	global_store_short v[92:93], v88, off
	v_cvt_pk_bf16_f32 v92, v89, s0
	v_lshlrev_b64 v[88:89], v100, v[182:183]
	v_lshl_add_u64 v[88:89], v[88:89], 1, v[96:97]
	global_store_short v[88:89], v92, off
	v_lshlrev_b64 v[88:89], v100, v[180:181]
	v_cvt_pk_bf16_f32 v90, v90, s0
	v_lshl_add_u64 v[88:89], v[88:89], 1, v[96:97]
	global_store_short v[88:89], v90, off
	v_lshlrev_b64 v[88:89], v100, v[178:179]
	v_cvt_pk_bf16_f32 v90, v91, s0
	v_lshl_add_u64 v[88:89], v[88:89], 1, v[96:97]
	global_store_short v[88:89], v90, off
	v_lshlrev_b64 v[88:89], v100, v[176:177]
	v_cvt_pk_bf16_f32 v84, v84, s0
	v_lshl_add_u64 v[88:89], v[88:89], 1, v[96:97]
	global_store_short v[88:89], v84, off
	v_cvt_pk_bf16_f32 v88, v85, s0
	v_lshlrev_b64 v[84:85], v100, v[174:175]
	v_lshl_add_u64 v[84:85], v[84:85], 1, v[96:97]
	global_store_short v[84:85], v88, off
	v_lshlrev_b64 v[84:85], v100, v[172:173]
	v_cvt_pk_bf16_f32 v86, v86, s0
	v_lshl_add_u64 v[84:85], v[84:85], 1, v[96:97]
	global_store_short v[84:85], v86, off
	v_lshlrev_b64 v[84:85], v100, v[170:171]
	v_cvt_pk_bf16_f32 v86, v87, s0
	v_lshl_add_u64 v[84:85], v[84:85], 1, v[96:97]
	global_store_short v[84:85], v86, off
	v_lshlrev_b64 v[84:85], v100, v[168:169]
	v_cvt_pk_bf16_f32 v80, v80, s0
	v_lshl_add_u64 v[84:85], v[84:85], 1, v[96:97]
	global_store_short v[84:85], v80, off
	v_cvt_pk_bf16_f32 v84, v81, s0
	v_lshlrev_b64 v[80:81], v100, v[166:167]
	v_lshl_add_u64 v[80:81], v[80:81], 1, v[96:97]
	global_store_short v[80:81], v84, off
	v_lshlrev_b64 v[80:81], v100, v[164:165]
	v_cvt_pk_bf16_f32 v82, v82, s0
	v_lshl_add_u64 v[80:81], v[80:81], 1, v[96:97]
	global_store_short v[80:81], v82, off
	v_lshlrev_b64 v[80:81], v100, v[162:163]
	v_cvt_pk_bf16_f32 v82, v83, s0
	v_lshl_add_u64 v[80:81], v[80:81], 1, v[96:97]
	global_store_short v[80:81], v82, off

; __device__ __forceinline__ unsigned f2bf(float f) { return pk2(f, f) & 0xffffu; }
;     __device__ __forceinline__ void operator()(const pg8::f32x4 (&acc)[2][2][4][2], const pg8::Unit& u, int wr, int wc, int fr, int fq) const {
;     ...
;                 if (pn >= 2 && pn < 5) {
;                     bf16_t* cbp = lat ? hyr + (size_t)b * 768 * 8192 + t : hyrc + (size_t)b * 768 * 256 + t; const size_t cst = lat ? 8192 : 256;
; #pragma unroll
;                     for (int bj = 0; bj < 2; ++bj)
; #pragma unroll
;                         for (int n = 0; n < 2; ++n)
; #pragma unroll
;                             for (int e = 0; e < 4; ++e) cbp[(size_t)(dcol + 32 * bj + 8 * fq + 4 * n + e) * cst] = (bf16_t)f2bf(acc[ai][bj][m][n][e]);
;                     continue;
;                 }
.LBB0_353:
	s_and_b64 vcc, exec, s[4:5]
	s_cbranch_vccz .LBB0_355
	v_mov_b32_e32 v80, s46
	v_mov_b32_e32 v81, s85
	v_cndmask_b32_e64 v81, v80, v81, s[44:45]
	v_mov_b32_e32 v80, s89
	v_mov_b32_e32 v82, s84
	v_cndmask_b32_e64 v80, v80, v82, s[44:45]
	v_cndmask_b32_e64 v82, v235, v236, s[44:45]
	v_mad_i64_i32 v[80:81], s[4:5], v82, v92, v[80:81]
	v_lshlrev_b32_e32 v82, 1, v93
	v_mov_b32_e32 v83, v209
	v_cndmask_b32_e64 v84, 8, 13, s[44:45]
	v_lshl_add_u64 v[80:81], v[80:81], 0, v[82:83]
	v_lshlrev_b64 v[82:83], v84, v[192:193]
	v_cvt_pk_bf16_f32 v76, v76, s0
	v_lshl_add_u64 v[82:83], v[82:83], 1, v[80:81]
	global_store_short v[82:83], v76, off
	v_cvt_pk_bf16_f32 v82, v77, s0
	v_lshlrev_b64 v[76:77], v84, v[190:191]
	v_lshl_add_u64 v[76:77], v[76:77], 1, v[80:81]
	global_store_short v[76:77], v82, off
	v_lshlrev_b64 v[76:77], v84, v[188:189]
	v_cvt_pk_bf16_f32 v78, v78, s0
	v_lshl_add_u64 v[76:77], v[76:77], 1, v[80:81]
	global_store_short v[76:77], v78, off
	v_lshlrev_b64 v[76:77], v84, v[186:187]
	v_cvt_pk_bf16_f32 v78, v79, s0
	v_lshl_add_u64 v[76:77], v[76:77], 1, v[80:81]
	global_store_short v[76:77], v78, off
	v_lshlrev_b64 v[76:77], v84, v[184:185]
	v_cvt_pk_bf16_f32 v72, v72, s0
	v_lshl_add_u64 v[76:77], v[76:77], 1, v[80:81]
	global_store_short v[76:77], v72, off
	v_cvt_pk_bf16_f32 v76, v73, s0
	v_lshlrev_b64 v[72:73], v84, v[182:183]
	v_lshl_add_u64 v[72:73], v[72:73], 1, v[80:81]
	global_store_short v[72:73], v76, off
	v_lshlrev_b64 v[72:73], v84, v[180:181]
	v_cvt_pk_bf16_f32 v74, v74, s0
	v_lshl_add_u64 v[72:73], v[72:73], 1, v[80:81]
	global_store_short v[72:73], v74, off
	v_lshlrev_b64 v[72:73], v84, v[178:179]
	v_cvt_pk_bf16_f32 v74, v75, s0
	v_lshl_add_u64 v[72:73], v[72:73], 1, v[80:81]
	global_store_short v[72:73], v74, off
	v_lshlrev_b64 v[72:73], v84, v[176:177]
	v_cvt_pk_bf16_f32 v68, v68, s0
	v_lshl_add_u64 v[72:73], v[72:73], 1, v[80:81]
	global_store_short v[72:73], v68, off
	v_cvt_pk_bf16_f32 v72, v69, s0
	v_lshlrev_b64 v[68:69], v84, v[174:175]
	v_lshl_add_u64 v[68:69], v[68:69], 1, v[80:81]
	global_store_short v[68:69], v72, off
	v_lshlrev_b64 v[68:69], v84, v[172:173]
	v_cvt_pk_bf16_f32 v70, v70, s0
	v_lshl_add_u64 v[68:69], v[68:69], 1, v[80:81]
	global_store_short v[68:69], v70, off
	v_lshlrev_b64 v[68:69], v84, v[170:171]
	v_cvt_pk_bf16_f32 v70, v71, s0
	v_lshl_add_u64 v[68:69], v[68:69], 1, v[80:81]
	global_store_short v[68:69], v70, off
	v_lshlrev_b64 v[68:69], v84, v[168:169]
	v_cvt_pk_bf16_f32 v64, v64, s0
	v_lshl_add_u64 v[68:69], v[68:69], 1, v[80:81]
	global_store_short v[68:69], v64, off
	v_cvt_pk_bf16_f32 v68, v65, s0
	v_lshlrev_b64 v[64:65], v84, v[166:167]
	v_lshl_add_u64 v[64:65], v[64:65], 1, v[80:81]
	global_store_short v[64:65], v68, off
	v_lshlrev_b64 v[64:65], v84, v[164:165]
	v_cvt_pk_bf16_f32 v66, v66, s0
	v_lshl_add_u64 v[64:65], v[64:65], 1, v[80:81]
	global_store_short v[64:65], v66, off
	v_lshlrev_b64 v[64:65], v84, v[162:163]
	v_cvt_pk_bf16_f32 v66, v67, s0
	v_lshl_add_u64 v[64:65], v[64:65], 1, v[80:81]
	global_store_short v[64:65], v66, off

; __device__ __forceinline__ unsigned f2bf(float f) { return pk2(f, f) & 0xffffu; }
;     __device__ __forceinline__ void operator()(const pg8::f32x4 (&acc)[2][2][4][2], const pg8::Unit& u, int wr, int wc, int fr, int fq) const {
;     ...
;                 if (pn >= 2 && pn < 5) {
;                     bf16_t* cbp = lat ? hyr + (size_t)b * 768 * 8192 + t : hyrc + (size_t)b * 768 * 256 + t; const size_t cst = lat ? 8192 : 256;
; #pragma unroll
;                     for (int bj = 0; bj < 2; ++bj)
; #pragma unroll
;                         for (int n = 0; n < 2; ++n)
; #pragma unroll
;                             for (int e = 0; e < 4; ++e) cbp[(size_t)(dcol + 32 * bj + 8 * fq + 4 * n + e) * cst] = (bf16_t)f2bf(acc[ai][bj][m][n][e]);
;                     continue;
;                 }
.LBB0_359:
	s_and_b64 vcc, exec, s[4:5]
	s_cbranch_vccz .LBB0_361
	v_mov_b32_e32 v64, s46
	v_mov_b32_e32 v65, s85
	v_cndmask_b32_e64 v65, v64, v65, s[44:45]
	v_mov_b32_e32 v64, s89
	v_mov_b32_e32 v66, s84
	v_cndmask_b32_e64 v64, v64, v66, s[44:45]
	v_cndmask_b32_e64 v66, v235, v236, s[44:45]
	v_mad_i64_i32 v[64:65], s[4:5], v66, v76, v[64:65]
	v_lshlrev_b32_e32 v66, 1, v77
	v_mov_b32_e32 v67, v209
	v_cndmask_b32_e64 v68, 8, 13, s[44:45]
	v_lshl_add_u64 v[64:65], v[64:65], 0, v[66:67]
	v_lshlrev_b64 v[66:67], v68, v[192:193]
	v_cvt_pk_bf16_f32 v44, v44, s0
	v_lshl_add_u64 v[66:67], v[66:67], 1, v[64:65]
	global_store_short v[66:67], v44, off
	v_cvt_pk_bf16_f32 v66, v45, s0
	v_lshlrev_b64 v[44:45], v68, v[190:191]
	v_lshl_add_u64 v[44:45], v[44:45], 1, v[64:65]
	global_store_short v[44:45], v66, off
	v_lshlrev_b64 v[44:45], v68, v[188:189]
	v_cvt_pk_bf16_f32 v46, v46, s0
	v_lshl_add_u64 v[44:45], v[44:45], 1, v[64:65]
	global_store_short v[44:45], v46, off
	v_lshlrev_b64 v[44:45], v68, v[186:187]
	v_cvt_pk_bf16_f32 v46, v47, s0
	v_lshl_add_u64 v[44:45], v[44:45], 1, v[64:65]
	global_store_short v[44:45], v46, off
	v_lshlrev_b64 v[44:45], v68, v[184:185]
	v_cvt_pk_bf16_f32 v40, v40, s0
	v_lshl_add_u64 v[44:45], v[44:45], 1, v[64:65]
	global_store_short v[44:45], v40, off
	v_cvt_pk_bf16_f32 v44, v41, s0
	v_lshlrev_b64 v[40:41], v68, v[182:183]
	v_lshl_add_u64 v[40:41], v[40:41], 1, v[64:65]
	global_store_short v[40:41], v44, off
	v_lshlrev_b64 v[40:41], v68, v[180:181]
	v_cvt_pk_bf16_f32 v42, v42, s0
	v_lshl_add_u64 v[40:41], v[40:41], 1, v[64:65]
	global_store_short v[40:41], v42, off
	v_lshlrev_b64 v[40:41], v68, v[178:179]
	v_cvt_pk_bf16_f32 v42, v43, s0
	v_lshl_add_u64 v[40:41], v[40:41], 1, v[64:65]
	global_store_short v[40:41], v42, off
	v_lshlrev_b64 v[40:41], v68, v[176:177]
	v_cvt_pk_bf16_f32 v36, v36, s0
	v_lshl_add_u64 v[40:41], v[40:41], 1, v[64:65]
	global_store_short v[40:41], v36, off
	v_cvt_pk_bf16_f32 v40, v37, s0
	v_lshlrev_b64 v[36:37], v68, v[174:175]
	v_lshl_add_u64 v[36:37], v[36:37], 1, v[64:65]
	global_store_short v[36:37], v40, off
	v_lshlrev_b64 v[36:37], v68, v[172:173]
	v_cvt_pk_bf16_f32 v38, v38, s0
	v_lshl_add_u64 v[36:37], v[36:37], 1, v[64:65]
	global_store_short v[36:37], v38, off
	v_lshlrev_b64 v[36:37], v68, v[170:171]
	v_cvt_pk_bf16_f32 v38, v39, s0
	v_lshl_add_u64 v[36:37], v[36:37], 1, v[64:65]
	global_store_short v[36:37], v38, off
	v_lshlrev_b64 v[36:37], v68, v[168:169]
	v_cvt_pk_bf16_f32 v32, v32, s0
	v_lshl_add_u64 v[36:37], v[36:37], 1, v[64:65]
	global_store_short v[36:37], v32, off
	v_cvt_pk_bf16_f32 v36, v33, s0
	v_lshlrev_b64 v[32:33], v68, v[166:167]
	v_lshl_add_u64 v[32:33], v[32:33], 1, v[64:65]
	global_store_short v[32:33], v36, off
	v_lshlrev_b64 v[32:33], v68, v[164:165]
	v_cvt_pk_bf16_f32 v34, v34, s0
	v_lshl_add_u64 v[32:33], v[32:33], 1, v[64:65]
	global_store_short v[32:33], v34, off
	v_lshlrev_b64 v[32:33], v68, v[162:163]
	v_cvt_pk_bf16_f32 v34, v35, s0
	v_lshl_add_u64 v[32:33], v[32:33], 1, v[64:65]
	global_store_short v[32:33], v34, off

; __device__ __forceinline__ unsigned f2bf(float f) { return pk2(f, f) & 0xffffu; }
;     __device__ __forceinline__ void operator()(const pg8::f32x4 (&acc)[2][2][4][2], const pg8::Unit& u, int wr, int wc, int fr, int fq) const {
;     ...
;                 if (pn >= 2 && pn < 5) {
;                     bf16_t* cbp = lat ? hyr + (size_t)b * 768 * 8192 + t : hyrc + (size_t)b * 768 * 256 + t; const size_t cst = lat ? 8192 : 256;
; #pragma unroll
;                     for (int bj = 0; bj < 2; ++bj)
; #pragma unroll
;                         for (int n = 0; n < 2; ++n)
; #pragma unroll
;                             for (int e = 0; e < 4; ++e) cbp[(size_t)(dcol + 32 * bj + 8 * fq + 4 * n + e) * cst] = (bf16_t)f2bf(acc[ai][bj][m][n][e]);
;                     continue;
;                 }
.LBB0_365:
	s_and_b64 vcc, exec, s[4:5]
	s_cbranch_vccz .LBB0_367
	v_mov_b32_e32 v32, s46
	v_mov_b32_e32 v33, s85
	v_cndmask_b32_e64 v33, v32, v33, s[44:45]
	v_mov_b32_e32 v32, s89
	v_mov_b32_e32 v34, s84
	v_cndmask_b32_e64 v32, v32, v34, s[44:45]
	v_cndmask_b32_e64 v34, v235, v236, s[44:45]
	v_mad_i64_i32 v[32:33], s[4:5], v34, v44, v[32:33]
	v_lshlrev_b32_e32 v34, 1, v45
	v_mov_b32_e32 v35, v209
	v_cndmask_b32_e64 v36, 8, 13, s[44:45]
	v_lshl_add_u64 v[32:33], v[32:33], 0, v[34:35]
	v_lshlrev_b64 v[34:35], v36, v[192:193]
	v_cvt_pk_bf16_f32 v28, v28, s0
	v_lshl_add_u64 v[34:35], v[34:35], 1, v[32:33]
	global_store_short v[34:35], v28, off
	v_cvt_pk_bf16_f32 v34, v29, s0
	v_lshlrev_b64 v[28:29], v36, v[190:191]
	v_lshl_add_u64 v[28:29], v[28:29], 1, v[32:33]
	global_store_short v[28:29], v34, off
	v_lshlrev_b64 v[28:29], v36, v[188:189]
	v_cvt_pk_bf16_f32 v30, v30, s0
	v_lshl_add_u64 v[28:29], v[28:29], 1, v[32:33]
	global_store_short v[28:29], v30, off
	v_lshlrev_b64 v[28:29], v36, v[186:187]
	v_cvt_pk_bf16_f32 v30, v31, s0
	v_lshl_add_u64 v[28:29], v[28:29], 1, v[32:33]
	global_store_short v[28:29], v30, off
	v_lshlrev_b64 v[28:29], v36, v[184:185]
	v_cvt_pk_bf16_f32 v24, v24, s0
	v_lshl_add_u64 v[28:29], v[28:29], 1, v[32:33]
	global_store_short v[28:29], v24, off
	v_cvt_pk_bf16_f32 v28, v25, s0
	v_lshlrev_b64 v[24:25], v36, v[182:183]
	v_lshl_add_u64 v[24:25], v[24:25], 1, v[32:33]
	global_store_short v[24:25], v28, off
	v_lshlrev_b64 v[24:25], v36, v[180:181]
	v_cvt_pk_bf16_f32 v26, v26, s0
	v_lshl_add_u64 v[24:25], v[24:25], 1, v[32:33]
	global_store_short v[24:25], v26, off
	v_lshlrev_b64 v[24:25], v36, v[178:179]
	v_cvt_pk_bf16_f32 v26, v27, s0
	v_lshl_add_u64 v[24:25], v[24:25], 1, v[32:33]
	global_store_short v[24:25], v26, off
	v_lshlrev_b64 v[24:25], v36, v[176:177]
	v_cvt_pk_bf16_f32 v20, v20, s0
	v_lshl_add_u64 v[24:25], v[24:25], 1, v[32:33]
	global_store_short v[24:25], v20, off
	v_cvt_pk_bf16_f32 v24, v21, s0
	v_lshlrev_b64 v[20:21], v36, v[174:175]
	v_lshl_add_u64 v[20:21], v[20:21], 1, v[32:33]
	global_store_short v[20:21], v24, off
	v_lshlrev_b64 v[20:21], v36, v[172:173]
	v_cvt_pk_bf16_f32 v22, v22, s0
	v_lshl_add_u64 v[20:21], v[20:21], 1, v[32:33]
	global_store_short v[20:21], v22, off
	v_lshlrev_b64 v[20:21], v36, v[170:171]
	v_cvt_pk_bf16_f32 v22, v23, s0
	v_lshl_add_u64 v[20:21], v[20:21], 1, v[32:33]
	global_store_short v[20:21], v22, off
	v_lshlrev_b64 v[20:21], v36, v[168:169]
	v_cvt_pk_bf16_f32 v16, v16, s0
	v_lshl_add_u64 v[20:21], v[20:21], 1, v[32:33]
	global_store_short v[20:21], v16, off
	v_cvt_pk_bf16_f32 v20, v17, s0
	v_lshlrev_b64 v[16:17], v36, v[166:167]
	v_lshl_add_u64 v[16:17], v[16:17], 1, v[32:33]
	global_store_short v[16:17], v20, off
	v_lshlrev_b64 v[16:17], v36, v[164:165]
	v_cvt_pk_bf16_f32 v18, v18, s0
	v_lshl_add_u64 v[16:17], v[16:17], 1, v[32:33]
	global_store_short v[16:17], v18, off
	v_lshlrev_b64 v[16:17], v36, v[162:163]
	v_cvt_pk_bf16_f32 v18, v19, s0
	v_lshl_add_u64 v[16:17], v[16:17], 1, v[32:33]
	global_store_short v[16:17], v18, off

; __device__ __forceinline__ unsigned f2bf(float f) { return pk2(f, f) & 0xffffu; }
;     __device__ __forceinline__ void operator()(const pg8::f32x4 (&acc)[2][2][4][2], const pg8::Unit& u, int wr, int wc, int fr, int fq) const {
;     ...
;                 if (pn >= 2 && pn < 5) {
;                     bf16_t* cbp = lat ? hyr + (size_t)b * 768 * 8192 + t : hyrc + (size_t)b * 768 * 256 + t; const size_t cst = lat ? 8192 : 256;
; #pragma unroll
;                     for (int bj = 0; bj < 2; ++bj)
; #pragma unroll
;                         for (int n = 0; n < 2; ++n)
; #pragma unroll
;                             for (int e = 0; e < 4; ++e) cbp[(size_t)(dcol + 32 * bj + 8 * fq + 4 * n + e) * cst] = (bf16_t)f2bf(acc[ai][bj][m][n][e]);
;                     continue;
;                 }
.LBB0_371:
	s_and_b64 vcc, exec, s[4:5]
	s_cbranch_vccz .LBB0_373
	v_mov_b32_e32 v16, s46
	v_mov_b32_e32 v17, s85
	v_cndmask_b32_e64 v17, v16, v17, s[44:45]
	v_mov_b32_e32 v16, s89
	v_mov_b32_e32 v18, s84
	v_cndmask_b32_e64 v16, v16, v18, s[44:45]
	v_cndmask_b32_e64 v18, v235, v236, s[44:45]
	v_mad_i64_i32 v[16:17], s[4:5], v18, v28, v[16:17]
	v_lshlrev_b32_e32 v18, 1, v29
	v_mov_b32_e32 v19, v209
	v_cndmask_b32_e64 v20, 8, 13, s[44:45]
	v_lshl_add_u64 v[16:17], v[16:17], 0, v[18:19]
	v_lshlrev_b64 v[18:19], v20, v[192:193]
	v_cvt_pk_bf16_f32 v12, v12, s0
	v_lshl_add_u64 v[18:19], v[18:19], 1, v[16:17]
	global_store_short v[18:19], v12, off
	v_cvt_pk_bf16_f32 v18, v13, s0
	v_lshlrev_b64 v[12:13], v20, v[190:191]
	v_lshl_add_u64 v[12:13], v[12:13], 1, v[16:17]
	global_store_short v[12:13], v18, off
	v_lshlrev_b64 v[12:13], v20, v[188:189]
	v_cvt_pk_bf16_f32 v14, v14, s0
	v_lshl_add_u64 v[12:13], v[12:13], 1, v[16:17]
	global_store_short v[12:13], v14, off
	v_lshlrev_b64 v[12:13], v20, v[186:187]
	v_cvt_pk_bf16_f32 v14, v15, s0
	v_lshl_add_u64 v[12:13], v[12:13], 1, v[16:17]
	global_store_short v[12:13], v14, off
	v_lshlrev_b64 v[12:13], v20, v[184:185]
	v_cvt_pk_bf16_f32 v8, v8, s0
	v_lshl_add_u64 v[12:13], v[12:13], 1, v[16:17]
	global_store_short v[12:13], v8, off
	v_cvt_pk_bf16_f32 v12, v9, s0
	v_lshlrev_b64 v[8:9], v20, v[182:183]
	v_lshl_add_u64 v[8:9], v[8:9], 1, v[16:17]
	global_store_short v[8:9], v12, off
	v_lshlrev_b64 v[8:9], v20, v[180:181]
	v_cvt_pk_bf16_f32 v10, v10, s0
	v_lshl_add_u64 v[8:9], v[8:9], 1, v[16:17]
	global_store_short v[8:9], v10, off
	v_lshlrev_b64 v[8:9], v20, v[178:179]
	v_cvt_pk_bf16_f32 v10, v11, s0
	v_lshl_add_u64 v[8:9], v[8:9], 1, v[16:17]
	global_store_short v[8:9], v10, off
	v_lshlrev_b64 v[8:9], v20, v[176:177]
	v_cvt_pk_bf16_f32 v4, v4, s0
	v_lshl_add_u64 v[8:9], v[8:9], 1, v[16:17]
	global_store_short v[8:9], v4, off
	v_cvt_pk_bf16_f32 v8, v5, s0
	v_lshlrev_b64 v[4:5], v20, v[174:175]
	v_lshl_add_u64 v[4:5], v[4:5], 1, v[16:17]
	global_store_short v[4:5], v8, off
	v_lshlrev_b64 v[4:5], v20, v[172:173]
	v_cvt_pk_bf16_f32 v6, v6, s0
	v_lshl_add_u64 v[4:5], v[4:5], 1, v[16:17]
	global_store_short v[4:5], v6, off
	v_lshlrev_b64 v[4:5], v20, v[170:171]
	v_cvt_pk_bf16_f32 v6, v7, s0
	v_lshl_add_u64 v[4:5], v[4:5], 1, v[16:17]
	global_store_short v[4:5], v6, off
	v_lshlrev_b64 v[4:5], v20, v[168:169]
	v_cvt_pk_bf16_f32 v0, v0, s0
	v_lshl_add_u64 v[4:5], v[4:5], 1, v[16:17]
	global_store_short v[4:5], v0, off
	v_cvt_pk_bf16_f32 v4, v1, s0
	v_lshlrev_b64 v[0:1], v20, v[166:167]
	v_lshl_add_u64 v[0:1], v[0:1], 1, v[16:17]
	global_store_short v[0:1], v4, off
	v_lshlrev_b64 v[0:1], v20, v[164:165]
	v_cvt_pk_bf16_f32 v2, v2, s0
	v_lshl_add_u64 v[0:1], v[0:1], 1, v[16:17]
	global_store_short v[0:1], v2, off
	v_lshlrev_b64 v[0:1], v20, v[162:163]
	v_cvt_pk_bf16_f32 v2, v3, s0
	v_lshl_add_u64 v[0:1], v[0:1], 1, v[16:17]
	global_store_short v[0:1], v2, off

;     __device__ __forceinline__ void operator()(const pg8::f32x4 (&acc)[2][2][4][2], const pg8::Unit& u, int wr, int wc, int fr, int fq) const {
;     ...
;                     pg8::f32x4 y0 = acc[ai][bj][m][0], y1 = acc[ai][bj][m][1];
;                     if (normed) {
;                         y0 = y0 * rinv * gg[bj][0]; y1 = y1 * rinv * gg[bj][1];
;                         if (lat) { const int p = bj == 0 ? (t >> 6) : (t & 63); const pg8::f32x4* rp = (const pg8::f32x4*)(rope + p * 16 + 4 * fq); const pg8::f32x4 c01 = rp[0], c23 = rp[1];
;                             const pg8::f32x4 z0 = {y0[0] * c01[0] - y0[1] * c01[1], y0[0] * c01[1] + y0[1] * c01[0], y0[2] * c01[2] - y0[3] * c01[3], y0[2] * c01[3] + y0[3] * c01[2]};
;                             const pg8::f32x4 z1 = {y1[0] * c23[0] - y1[1] * c23[1], y1[0] * c23[1] + y1[1] * c23[0], y1[2] * c23[2] - y1[3] * c23[3], y1[2] * c23[3] + y1[3] * c23[2]};
;                             y0 = z0; y1 = z1; }
.LBB0_379:
	v_mov_b32_e32 v115, v114
	s_and_b64 vcc, exec, s[38:39]
	v_mov_b32_e32 v116, v108
	v_mov_b32_e32 v117, v109
	v_mov_b32_e32 v122, v110
	v_mov_b32_e32 v123, v111
	v_mov_b32_e32 v118, v104
	v_mov_b32_e32 v119, v105
	v_mov_b32_e32 v120, v106
	v_mov_b32_e32 v121, v107
	s_cbranch_vccnz .LBB0_383
	v_mov_b32_e32 v118, v114
	v_mov_b32_e32 v119, v114
	v_pk_mul_f32 v[116:117], v[110:111], v[118:119]
	v_pk_mul_f32 v[120:121], v[108:109], v[114:115]
	v_pk_mul_f32 v[118:119], v[106:107], v[118:119]
	v_pk_mul_f32 v[126:127], v[104:105], v[114:115]
	s_waitcnt vmcnt(0)
	v_pk_mul_f32 v[122:123], v[62:63], v[116:117]
	v_pk_mul_f32 v[116:117], v[60:61], v[120:121]
	v_pk_mul_f32 v[120:121], v[58:59], v[118:119]
	v_pk_mul_f32 v[118:119], v[56:57], v[126:127]
	s_and_saveexec_b64 s[4:5], s[44:45]
	s_cbranch_execz .LBB0_382
	v_lshlrev_b32_e32 v126, 1, v125
	v_and_b32_e32 v126, 0x3f80, v126
	v_mov_b32_e32 v127, v209
	v_lshl_add_u64 v[130:131], v[154:155], 0, v[126:127]
	global_load_dwordx4 v[126:129], v[130:131], off
	s_nop 0
	global_load_dwordx4 v[130:133], v[130:131], off offset:16
	s_waitcnt vmcnt(0) lgkmcnt(0)
	v_pk_mul_f32 v[136:137], v[116:117], v[126:127] op_sel:[1,1] op_sel_hi:[1,0]
	v_pk_mul_f32 v[134:135], v[116:117], v[126:127]
	v_pk_fma_f32 v[116:117], v[116:117], v[126:127], v[136:137] op_sel_hi:[0,1,1]
	v_mul_f32_e32 v116, v123, v129
	v_pk_fma_f32 v[126:127], v[122:123], v[128:129], v[116:117] op_sel_hi:[1,1,0] neg_lo:[0,0,1] neg_hi:[0,0,1]
	v_mul_f32_e32 v116, v123, v128
	v_pk_fma_f32 v[122:123], v[122:123], v[128:129], v[116:117] op_sel:[0,1,0] op_sel_hi:[1,0,0]
	v_pk_mul_f32 v[138:139], v[118:119], v[130:131] op_sel:[1,1] op_sel_hi:[1,0]
	v_mul_f32_e32 v116, v121, v133
	v_pk_mul_f32 v[128:129], v[118:119], v[130:131]
	v_pk_fma_f32 v[118:119], v[118:119], v[130:131], v[138:139] op_sel_hi:[0,1,1]
	v_pk_fma_f32 v[130:131], v[120:121], v[132:133], v[116:117] op_sel_hi:[1,1,0] neg_lo:[0,0,1] neg_hi:[0,0,1]
	v_mul_f32_e32 v116, v121, v132
	v_pk_fma_f32 v[120:121], v[120:121], v[132:133], v[116:117] op_sel:[0,1,0] op_sel_hi:[1,0,0]
	v_sub_f32_e32 v116, v134, v136
	v_sub_f32_e32 v118, v128, v138
	v_mov_b32_e32 v121, v120
	v_mov_b32_e32 v120, v130
	v_mov_b32_e32 v123, v122
	v_mov_b32_e32 v122, v126

; __device__ __forceinline__ unsigned pk2(float lo, float hi) { const f32x2_cv v = {lo, hi}; const bf16x2_cv b = __builtin_convertvector(v, bf16x2_cv); return __builtin_bit_cast(unsigned, b); }
;     __device__ __forceinline__ void operator()(const pg8::f32x4 (&acc)[2][2][4][2], const pg8::Unit& u, int wr, int wc, int fr, int fq) const {
;     ...
;                 for (int bj = 0; bj < 2; ++bj) {
;                     pg8::f32x4 y0 = acc[ai][bj][m][0], y1 = acc[ai][bj][m][1];
;                     if (normed) {
;                         y0 = y0 * rinv * gg[bj][0]; y1 = y1 * rinv * gg[bj][1];
;                         if (lat) { const int p = bj == 0 ? (t >> 6) : (t & 63); const pg8::f32x4* rp = (const pg8::f32x4*)(rope + p * 16 + 4 * fq); const pg8::f32x4 c01 = rp[0], c23 = rp[1];
;                             const pg8::f32x4 z0 = {y0[0] * c01[0] - y0[1] * c01[1], y0[0] * c01[1] + y0[1] * c01[0], y0[2] * c01[2] - y0[3] * c01[3], y0[2] * c01[3] + y0[3] * c01[2]};
;                             const pg8::f32x4 z1 = {y1[0] * c23[0] - y1[1] * c23[1], y1[0] * c23[1] + y1[1] * c23[0], y1[2] * c23[2] - y1[3] * c23[3], y1[2] * c23[3] + y1[3] * c23[2]};
;                             y0 = z0; y1 = z1; }
;                     }
;                     v4u o; o.x = pk2(y0[0], y0[1]); o.y = pk2(y0[2], y0[3]); o.z = pk2(y1[0], y1[1]); o.w = pk2(y1[2], y1[3]);
;                     *(v4u*)(dp + 32 * bj) = o;
.LBB0_383:
	v_and_b32_e32 v245, 63, v112
	v_mul_lo_u32 v126, v113, s94
	v_mul_lo_u32 v127, v112, s95
	v_mad_u64_u32 v[112:113], s[4:5], v112, s94, 0
	v_add3_u32 v113, v113, v127, v126
	v_lshl_add_u64 v[112:113], v[112:113], 1, v[160:161]
	v_mul_u32_u24_e32 v244, s100, v245
	v_sub_u32_e32 v244, 0, v244
	v_ashrrev_i32_e32 v245, 31, v244
	v_lshl_add_u64 v[112:113], v[112:113], 0, v[244:245]
	v_cvt_pk_bf16_f32 v116, v116, v117
	v_cvt_pk_bf16_f32 v117, v122, v123
	v_cvt_pk_bf16_f32 v118, v118, v119
	v_cvt_pk_bf16_f32 v119, v120, v121
	global_store_dwordx4 v[112:113], v[116:119], off
	s_and_b64 vcc, exec, s[38:39]
	v_mov_b32_e32 v122, v102
	v_mov_b32_e32 v116, v100
	v_mov_b32_e32 v117, v101
	v_mov_b32_e32 v123, v103
	v_mov_b32_e32 v118, v96
	v_mov_b32_e32 v119, v97
	v_mov_b32_e32 v120, v98
	v_mov_b32_e32 v121, v99
	s_cbranch_vccnz .LBB0_387
	v_mov_b32_e32 v118, v114
	v_mov_b32_e32 v119, v114
	v_pk_mul_f32 v[116:117], v[102:103], v[118:119]
	v_pk_mul_f32 v[120:121], v[100:101], v[114:115]
	v_pk_mul_f32 v[118:119], v[98:99], v[118:119]
	v_pk_mul_f32 v[114:115], v[96:97], v[114:115]
	s_waitcnt vmcnt(0)
	v_pk_mul_f32 v[122:123], v[54:55], v[116:117]
	v_pk_mul_f32 v[116:117], v[52:53], v[120:121]
	v_pk_mul_f32 v[120:121], v[50:51], v[118:119]
	v_pk_mul_f32 v[118:119], v[48:49], v[114:115]
	s_and_saveexec_b64 s[4:5], s[44:45]
	s_cbranch_execz .LBB0_386
	v_lshlrev_b32_e32 v114, 7, v125
	v_and_b32_e32 v114, 0x1780, v114
	v_mov_b32_e32 v115, v209
	v_lshl_add_u64 v[114:115], v[154:155], 0, v[114:115]
	global_load_dwordx4 v[126:129], v[114:115], off
	global_load_dwordx4 v[130:133], v[114:115], off offset:16
	s_waitcnt vmcnt(0) lgkmcnt(0)
	v_pk_mul_f32 v[134:135], v[116:117], v[126:127] op_sel:[1,1] op_sel_hi:[1,0]
	v_pk_mul_f32 v[114:115], v[116:117], v[126:127]
	v_pk_fma_f32 v[116:117], v[116:117], v[126:127], v[134:135] op_sel_hi:[0,1,1]
	v_mul_f32_e32 v116, v123, v129
	v_pk_fma_f32 v[126:127], v[122:123], v[128:129], v[116:117] op_sel_hi:[1,1,0] neg_lo:[0,0,1] neg_hi:[0,0,1]
	v_mul_f32_e32 v116, v123, v128
	v_pk_fma_f32 v[122:123], v[122:123], v[128:129], v[116:117] op_sel:[0,1,0] op_sel_hi:[1,0,0]
	v_pk_mul_f32 v[136:137], v[118:119], v[130:131] op_sel:[1,1] op_sel_hi:[1,0]
	v_mul_f32_e32 v116, v121, v133
	v_pk_mul_f32 v[128:129], v[118:119], v[130:131]
	v_pk_fma_f32 v[118:119], v[118:119], v[130:131], v[136:137] op_sel_hi:[0,1,1]
	v_pk_fma_f32 v[130:131], v[120:121], v[132:133], v[116:117] op_sel_hi:[1,1,0] neg_lo:[0,0,1] neg_hi:[0,0,1]
	v_mul_f32_e32 v116, v121, v132
	v_pk_fma_f32 v[120:121], v[120:121], v[132:133], v[116:117] op_sel:[0,1,0] op_sel_hi:[1,0,0]
	v_sub_f32_e32 v116, v114, v134
	v_sub_f32_e32 v118, v128, v136
	v_mov_b32_e32 v121, v120
	v_mov_b32_e32 v120, v130
	v_mov_b32_e32 v123, v122
	v_mov_b32_e32 v122, v126

; __device__ __forceinline__ unsigned pk2(float lo, float hi) { const f32x2_cv v = {lo, hi}; const bf16x2_cv b = __builtin_convertvector(v, bf16x2_cv); return __builtin_bit_cast(unsigned, b); }
;     __device__ __forceinline__ void operator()(const pg8::f32x4 (&acc)[2][2][4][2], const pg8::Unit& u, int wr, int wc, int fr, int fq) const {
;     ...
;                     v4u o; o.x = pk2(y0[0], y0[1]); o.y = pk2(y0[2], y0[3]); o.z = pk2(y1[0], y1[1]); o.w = pk2(y1[2], y1[3]);
;                     *(v4u*)(dp + 32 * bj) = o;
.LBB0_387:
	v_cvt_pk_bf16_f32 v114, v116, v117
	v_cvt_pk_bf16_f32 v115, v122, v123
	v_cvt_pk_bf16_f32 v116, v118, v119
	v_cvt_pk_bf16_f32 v117, v120, v121
	v_lshl_add_u64 v[112:113], v[112:113], 0, v[246:247]
	global_store_dwordx4 v[112:113], v[114:117], off offset:64
	s_branch .LBB0_343

;     __device__ __forceinline__ void operator()(const pg8::f32x4 (&acc)[2][2][4][2], const pg8::Unit& u, int wr, int wc, int fr, int fq) const {
;     ...
;                     pg8::f32x4 y0 = acc[ai][bj][m][0], y1 = acc[ai][bj][m][1];
;                     if (normed) {
;                         y0 = y0 * rinv * gg[bj][0]; y1 = y1 * rinv * gg[bj][1];
;                         if (lat) { const int p = bj == 0 ? (t >> 6) : (t & 63); const pg8::f32x4* rp = (const pg8::f32x4*)(rope + p * 16 + 4 * fq); const pg8::f32x4 c01 = rp[0], c23 = rp[1];
;                             const pg8::f32x4 z0 = {y0[0] * c01[0] - y0[1] * c01[1], y0[0] * c01[1] + y0[1] * c01[0], y0[2] * c01[2] - y0[3] * c01[3], y0[2] * c01[3] + y0[3] * c01[2]};
;                             const pg8::f32x4 z1 = {y1[0] * c23[0] - y1[1] * c23[1], y1[0] * c23[1] + y1[1] * c23[0], y1[2] * c23[2] - y1[3] * c23[3], y1[2] * c23[3] + y1[3] * c23[2]};
;                             y0 = z0; y1 = z1; }
.LBB0_391:
	v_mov_b32_e32 v99, v98
	s_and_b64 vcc, exec, s[38:39]
	v_mov_b32_e32 v100, v92
	v_mov_b32_e32 v101, v93
	v_mov_b32_e32 v106, v94
	v_mov_b32_e32 v107, v95
	v_mov_b32_e32 v102, v88
	v_mov_b32_e32 v103, v89
	v_mov_b32_e32 v104, v90
	v_mov_b32_e32 v105, v91
	s_cbranch_vccnz .LBB0_395
	v_mov_b32_e32 v102, v98
	v_mov_b32_e32 v103, v98
	v_pk_mul_f32 v[100:101], v[94:95], v[102:103]
	v_pk_mul_f32 v[104:105], v[92:93], v[98:99]
	v_pk_mul_f32 v[102:103], v[90:91], v[102:103]
	v_pk_mul_f32 v[110:111], v[88:89], v[98:99]
	s_waitcnt vmcnt(0)
	v_pk_mul_f32 v[106:107], v[62:63], v[100:101]
	v_pk_mul_f32 v[100:101], v[60:61], v[104:105]
	v_pk_mul_f32 v[104:105], v[58:59], v[102:103]
	v_pk_mul_f32 v[102:103], v[56:57], v[110:111]
	s_and_saveexec_b64 s[4:5], s[44:45]
	s_cbranch_execz .LBB0_394
	v_lshlrev_b32_e32 v110, 1, v109
	v_and_b32_e32 v110, 0x3f80, v110
	v_mov_b32_e32 v111, v209
	v_lshl_add_u64 v[114:115], v[154:155], 0, v[110:111]
	global_load_dwordx4 v[110:113], v[114:115], off
	s_nop 0
	global_load_dwordx4 v[114:117], v[114:115], off offset:16
	s_waitcnt vmcnt(0) lgkmcnt(0)
	v_pk_mul_f32 v[120:121], v[100:101], v[110:111] op_sel:[1,1] op_sel_hi:[1,0]
	v_pk_mul_f32 v[118:119], v[100:101], v[110:111]
	v_pk_fma_f32 v[100:101], v[100:101], v[110:111], v[120:121] op_sel_hi:[0,1,1]
	v_mul_f32_e32 v100, v107, v113
	v_pk_fma_f32 v[110:111], v[106:107], v[112:113], v[100:101] op_sel_hi:[1,1,0] neg_lo:[0,0,1] neg_hi:[0,0,1]
	v_mul_f32_e32 v100, v107, v112
	v_pk_fma_f32 v[106:107], v[106:107], v[112:113], v[100:101] op_sel:[0,1,0] op_sel_hi:[1,0,0]
	v_pk_mul_f32 v[122:123], v[102:103], v[114:115] op_sel:[1,1] op_sel_hi:[1,0]
	v_mul_f32_e32 v100, v105, v117
	v_pk_mul_f32 v[112:113], v[102:103], v[114:115]
	v_pk_fma_f32 v[102:103], v[102:103], v[114:115], v[122:123] op_sel_hi:[0,1,1]
	v_pk_fma_f32 v[114:115], v[104:105], v[116:117], v[100:101] op_sel_hi:[1,1,0] neg_lo:[0,0,1] neg_hi:[0,0,1]
	v_mul_f32_e32 v100, v105, v116
	v_pk_fma_f32 v[104:105], v[104:105], v[116:117], v[100:101] op_sel:[0,1,0] op_sel_hi:[1,0,0]
	v_sub_f32_e32 v100, v118, v120
	v_sub_f32_e32 v102, v112, v122
	v_mov_b32_e32 v105, v104
	v_mov_b32_e32 v104, v114
	v_mov_b32_e32 v107, v106
	v_mov_b32_e32 v106, v110

; __device__ __forceinline__ unsigned pk2(float lo, float hi) { const f32x2_cv v = {lo, hi}; const bf16x2_cv b = __builtin_convertvector(v, bf16x2_cv); return __builtin_bit_cast(unsigned, b); }
;     __device__ __forceinline__ void operator()(const pg8::f32x4 (&acc)[2][2][4][2], const pg8::Unit& u, int wr, int wc, int fr, int fq) const {
;     ...
;                 for (int bj = 0; bj < 2; ++bj) {
;                     pg8::f32x4 y0 = acc[ai][bj][m][0], y1 = acc[ai][bj][m][1];
;                     if (normed) {
;                         y0 = y0 * rinv * gg[bj][0]; y1 = y1 * rinv * gg[bj][1];
;                         if (lat) { const int p = bj == 0 ? (t >> 6) : (t & 63); const pg8::f32x4* rp = (const pg8::f32x4*)(rope + p * 16 + 4 * fq); const pg8::f32x4 c01 = rp[0], c23 = rp[1];
;                             const pg8::f32x4 z0 = {y0[0] * c01[0] - y0[1] * c01[1], y0[0] * c01[1] + y0[1] * c01[0], y0[2] * c01[2] - y0[3] * c01[3], y0[2] * c01[3] + y0[3] * c01[2]};
;                             const pg8::f32x4 z1 = {y1[0] * c23[0] - y1[1] * c23[1], y1[0] * c23[1] + y1[1] * c23[0], y1[2] * c23[2] - y1[3] * c23[3], y1[2] * c23[3] + y1[3] * c23[2]};
;                             y0 = z0; y1 = z1; }
;                     }
;                     v4u o; o.x = pk2(y0[0], y0[1]); o.y = pk2(y0[2], y0[3]); o.z = pk2(y1[0], y1[1]); o.w = pk2(y1[2], y1[3]);
;                     *(v4u*)(dp + 32 * bj) = o;
.LBB0_395:
	v_and_b32_e32 v245, 63, v96
	v_mul_lo_u32 v110, v97, s94
	v_mul_lo_u32 v111, v96, s95
	v_mad_u64_u32 v[96:97], s[4:5], v96, s94, 0
	v_add3_u32 v97, v97, v111, v110
	v_lshl_add_u64 v[96:97], v[96:97], 1, v[160:161]
	v_mul_u32_u24_e32 v244, s100, v245
	v_sub_u32_e32 v244, 0, v244
	v_ashrrev_i32_e32 v245, 31, v244
	v_lshl_add_u64 v[96:97], v[96:97], 0, v[244:245]
	v_cvt_pk_bf16_f32 v100, v100, v101
	v_cvt_pk_bf16_f32 v101, v106, v107
	v_cvt_pk_bf16_f32 v102, v102, v103
	v_cvt_pk_bf16_f32 v103, v104, v105
	global_store_dwordx4 v[96:97], v[100:103], off
	s_and_b64 vcc, exec, s[38:39]
	v_mov_b32_e32 v106, v86
	v_mov_b32_e32 v100, v84
	v_mov_b32_e32 v101, v85
	v_mov_b32_e32 v107, v87
	v_mov_b32_e32 v102, v80
	v_mov_b32_e32 v103, v81
	v_mov_b32_e32 v104, v82
	v_mov_b32_e32 v105, v83
	s_cbranch_vccnz .LBB0_399
	v_mov_b32_e32 v102, v98
	v_mov_b32_e32 v103, v98
	v_pk_mul_f32 v[100:101], v[86:87], v[102:103]
	v_pk_mul_f32 v[104:105], v[84:85], v[98:99]
	v_pk_mul_f32 v[102:103], v[82:83], v[102:103]
	v_pk_mul_f32 v[98:99], v[80:81], v[98:99]
	s_waitcnt vmcnt(0)
	v_pk_mul_f32 v[106:107], v[54:55], v[100:101]
	v_pk_mul_f32 v[100:101], v[52:53], v[104:105]
	v_pk_mul_f32 v[104:105], v[50:51], v[102:103]
	v_pk_mul_f32 v[102:103], v[48:49], v[98:99]
	s_and_saveexec_b64 s[4:5], s[44:45]
	s_cbranch_execz .LBB0_398
	v_lshlrev_b32_e32 v98, 7, v109
	v_and_b32_e32 v98, 0x1f80, v98
	v_mov_b32_e32 v99, v209
	v_lshl_add_u64 v[98:99], v[154:155], 0, v[98:99]
	global_load_dwordx4 v[110:113], v[98:99], off
	global_load_dwordx4 v[114:117], v[98:99], off offset:16
	s_waitcnt vmcnt(0) lgkmcnt(0)
	v_pk_mul_f32 v[118:119], v[100:101], v[110:111] op_sel:[1,1] op_sel_hi:[1,0]
	v_pk_mul_f32 v[98:99], v[100:101], v[110:111]
	v_pk_fma_f32 v[100:101], v[100:101], v[110:111], v[118:119] op_sel_hi:[0,1,1]
	v_mul_f32_e32 v100, v107, v113
	v_pk_fma_f32 v[110:111], v[106:107], v[112:113], v[100:101] op_sel_hi:[1,1,0] neg_lo:[0,0,1] neg_hi:[0,0,1]
	v_mul_f32_e32 v100, v107, v112
	v_pk_fma_f32 v[106:107], v[106:107], v[112:113], v[100:101] op_sel:[0,1,0] op_sel_hi:[1,0,0]
	v_pk_mul_f32 v[120:121], v[102:103], v[114:115] op_sel:[1,1] op_sel_hi:[1,0]
	v_mul_f32_e32 v100, v105, v117
	v_pk_mul_f32 v[112:113], v[102:103], v[114:115]
	v_pk_fma_f32 v[102:103], v[102:103], v[114:115], v[120:121] op_sel_hi:[0,1,1]
	v_pk_fma_f32 v[114:115], v[104:105], v[116:117], v[100:101] op_sel_hi:[1,1,0] neg_lo:[0,0,1] neg_hi:[0,0,1]
	v_mul_f32_e32 v100, v105, v116
	v_pk_fma_f32 v[104:105], v[104:105], v[116:117], v[100:101] op_sel:[0,1,0] op_sel_hi:[1,0,0]
	v_sub_f32_e32 v100, v98, v118
	v_sub_f32_e32 v102, v112, v120
	v_mov_b32_e32 v105, v104
	v_mov_b32_e32 v104, v114
	v_mov_b32_e32 v107, v106
	v_mov_b32_e32 v106, v110

; __device__ __forceinline__ unsigned pk2(float lo, float hi) { const f32x2_cv v = {lo, hi}; const bf16x2_cv b = __builtin_convertvector(v, bf16x2_cv); return __builtin_bit_cast(unsigned, b); }
;     __device__ __forceinline__ void operator()(const pg8::f32x4 (&acc)[2][2][4][2], const pg8::Unit& u, int wr, int wc, int fr, int fq) const {
;     ...
;                     v4u o; o.x = pk2(y0[0], y0[1]); o.y = pk2(y0[2], y0[3]); o.z = pk2(y1[0], y1[1]); o.w = pk2(y1[2], y1[3]);
;                     *(v4u*)(dp + 32 * bj) = o;
.LBB0_399:
	v_cvt_pk_bf16_f32 v98, v100, v101
	v_cvt_pk_bf16_f32 v99, v106, v107
	v_cvt_pk_bf16_f32 v100, v102, v103
	v_cvt_pk_bf16_f32 v101, v104, v105
	v_lshl_add_u64 v[96:97], v[96:97], 0, v[246:247]
	global_store_dwordx4 v[96:97], v[98:101], off offset:64
	s_branch .LBB0_349

;     __device__ __forceinline__ void operator()(const pg8::f32x4 (&acc)[2][2][4][2], const pg8::Unit& u, int wr, int wc, int fr, int fq) const {
;     ...
;                     pg8::f32x4 y0 = acc[ai][bj][m][0], y1 = acc[ai][bj][m][1];
;                     if (normed) {
;                         y0 = y0 * rinv * gg[bj][0]; y1 = y1 * rinv * gg[bj][1];
;                         if (lat) { const int p = bj == 0 ? (t >> 6) : (t & 63); const pg8::f32x4* rp = (const pg8::f32x4*)(rope + p * 16 + 4 * fq); const pg8::f32x4 c01 = rp[0], c23 = rp[1];
;                             const pg8::f32x4 z0 = {y0[0] * c01[0] - y0[1] * c01[1], y0[0] * c01[1] + y0[1] * c01[0], y0[2] * c01[2] - y0[3] * c01[3], y0[2] * c01[3] + y0[3] * c01[2]};
;                             const pg8::f32x4 z1 = {y1[0] * c23[0] - y1[1] * c23[1], y1[0] * c23[1] + y1[1] * c23[0], y1[2] * c23[2] - y1[3] * c23[3], y1[2] * c23[3] + y1[3] * c23[2]};
;                             y0 = z0; y1 = z1; }
.LBB0_403:
	v_mov_b32_e32 v83, v82
	s_and_b64 vcc, exec, s[38:39]
	v_mov_b32_e32 v84, v76
	v_mov_b32_e32 v85, v77
	v_mov_b32_e32 v90, v78
	v_mov_b32_e32 v91, v79
	v_mov_b32_e32 v86, v72
	v_mov_b32_e32 v87, v73
	v_mov_b32_e32 v88, v74
	v_mov_b32_e32 v89, v75
	s_cbranch_vccnz .LBB0_407
	v_mov_b32_e32 v86, v82
	v_mov_b32_e32 v87, v82
	v_pk_mul_f32 v[84:85], v[78:79], v[86:87]
	v_pk_mul_f32 v[88:89], v[76:77], v[82:83]
	v_pk_mul_f32 v[86:87], v[74:75], v[86:87]
	v_pk_mul_f32 v[94:95], v[72:73], v[82:83]
	s_waitcnt vmcnt(0)
	v_pk_mul_f32 v[90:91], v[62:63], v[84:85]
	v_pk_mul_f32 v[84:85], v[60:61], v[88:89]
	v_pk_mul_f32 v[88:89], v[58:59], v[86:87]
	v_pk_mul_f32 v[86:87], v[56:57], v[94:95]
	s_and_saveexec_b64 s[4:5], s[44:45]
	s_cbranch_execz .LBB0_406
	v_lshlrev_b32_e32 v94, 1, v93
	v_and_b32_e32 v94, 0x3f80, v94
	v_mov_b32_e32 v95, v209
	v_lshl_add_u64 v[98:99], v[154:155], 0, v[94:95]
	global_load_dwordx4 v[94:97], v[98:99], off
	s_nop 0
	global_load_dwordx4 v[98:101], v[98:99], off offset:16
	s_waitcnt vmcnt(0) lgkmcnt(0)
	v_pk_mul_f32 v[104:105], v[84:85], v[94:95] op_sel:[1,1] op_sel_hi:[1,0]
	v_pk_mul_f32 v[102:103], v[84:85], v[94:95]
	v_pk_fma_f32 v[84:85], v[84:85], v[94:95], v[104:105] op_sel_hi:[0,1,1]
	v_mul_f32_e32 v84, v91, v97
	v_pk_fma_f32 v[94:95], v[90:91], v[96:97], v[84:85] op_sel_hi:[1,1,0] neg_lo:[0,0,1] neg_hi:[0,0,1]
	v_mul_f32_e32 v84, v91, v96
	v_pk_fma_f32 v[90:91], v[90:91], v[96:97], v[84:85] op_sel:[0,1,0] op_sel_hi:[1,0,0]
	v_pk_mul_f32 v[106:107], v[86:87], v[98:99] op_sel:[1,1] op_sel_hi:[1,0]
	v_mul_f32_e32 v84, v89, v101
	v_pk_mul_f32 v[96:97], v[86:87], v[98:99]
	v_pk_fma_f32 v[86:87], v[86:87], v[98:99], v[106:107] op_sel_hi:[0,1,1]
	v_pk_fma_f32 v[98:99], v[88:89], v[100:101], v[84:85] op_sel_hi:[1,1,0] neg_lo:[0,0,1] neg_hi:[0,0,1]
	v_mul_f32_e32 v84, v89, v100
	v_pk_fma_f32 v[88:89], v[88:89], v[100:101], v[84:85] op_sel:[0,1,0] op_sel_hi:[1,0,0]
	v_sub_f32_e32 v84, v102, v104
	v_sub_f32_e32 v86, v96, v106
	v_mov_b32_e32 v89, v88
	v_mov_b32_e32 v88, v98
	v_mov_b32_e32 v91, v90
	v_mov_b32_e32 v90, v94

; __device__ __forceinline__ unsigned pk2(float lo, float hi) { const f32x2_cv v = {lo, hi}; const bf16x2_cv b = __builtin_convertvector(v, bf16x2_cv); return __builtin_bit_cast(unsigned, b); }
;     __device__ __forceinline__ void operator()(const pg8::f32x4 (&acc)[2][2][4][2], const pg8::Unit& u, int wr, int wc, int fr, int fq) const {
;     ...
;                 for (int bj = 0; bj < 2; ++bj) {
;                     pg8::f32x4 y0 = acc[ai][bj][m][0], y1 = acc[ai][bj][m][1];
;                     if (normed) {
;                         y0 = y0 * rinv * gg[bj][0]; y1 = y1 * rinv * gg[bj][1];
;                         if (lat) { const int p = bj == 0 ? (t >> 6) : (t & 63); const pg8::f32x4* rp = (const pg8::f32x4*)(rope + p * 16 + 4 * fq); const pg8::f32x4 c01 = rp[0], c23 = rp[1];
;                             const pg8::f32x4 z0 = {y0[0] * c01[0] - y0[1] * c01[1], y0[0] * c01[1] + y0[1] * c01[0], y0[2] * c01[2] - y0[3] * c01[3], y0[2] * c01[3] + y0[3] * c01[2]};
;                             const pg8::f32x4 z1 = {y1[0] * c23[0] - y1[1] * c23[1], y1[0] * c23[1] + y1[1] * c23[0], y1[2] * c23[2] - y1[3] * c23[3], y1[2] * c23[3] + y1[3] * c23[2]};
;                             y0 = z0; y1 = z1; }
;                     }
;                     v4u o; o.x = pk2(y0[0], y0[1]); o.y = pk2(y0[2], y0[3]); o.z = pk2(y1[0], y1[1]); o.w = pk2(y1[2], y1[3]);
;                     *(v4u*)(dp + 32 * bj) = o;
.LBB0_407:
	v_and_b32_e32 v245, 63, v80
	v_mul_lo_u32 v94, v81, s94
	v_mul_lo_u32 v95, v80, s95
	v_mad_u64_u32 v[80:81], s[4:5], v80, s94, 0
	v_add3_u32 v81, v81, v95, v94
	v_lshl_add_u64 v[80:81], v[80:81], 1, v[160:161]
	v_mul_u32_u24_e32 v244, s100, v245
	v_sub_u32_e32 v244, 0, v244
	v_ashrrev_i32_e32 v245, 31, v244
	v_lshl_add_u64 v[80:81], v[80:81], 0, v[244:245]
	v_cvt_pk_bf16_f32 v84, v84, v85
	v_cvt_pk_bf16_f32 v85, v90, v91
	v_cvt_pk_bf16_f32 v86, v86, v87
	v_cvt_pk_bf16_f32 v87, v88, v89
	global_store_dwordx4 v[80:81], v[84:87], off
	s_and_b64 vcc, exec, s[38:39]
	v_mov_b32_e32 v90, v70
	v_mov_b32_e32 v84, v68
	v_mov_b32_e32 v85, v69
	v_mov_b32_e32 v91, v71
	v_mov_b32_e32 v86, v64
	v_mov_b32_e32 v87, v65
	v_mov_b32_e32 v88, v66
	v_mov_b32_e32 v89, v67
	s_cbranch_vccnz .LBB0_411
	v_mov_b32_e32 v86, v82
	v_mov_b32_e32 v87, v82
	v_pk_mul_f32 v[84:85], v[70:71], v[86:87]
	v_pk_mul_f32 v[88:89], v[68:69], v[82:83]
	v_pk_mul_f32 v[86:87], v[66:67], v[86:87]
	v_pk_mul_f32 v[82:83], v[64:65], v[82:83]
	s_waitcnt vmcnt(0)
	v_pk_mul_f32 v[90:91], v[54:55], v[84:85]
	v_pk_mul_f32 v[84:85], v[52:53], v[88:89]
	v_pk_mul_f32 v[88:89], v[50:51], v[86:87]
	v_pk_mul_f32 v[86:87], v[48:49], v[82:83]
	s_and_saveexec_b64 s[4:5], s[44:45]
	s_cbranch_execz .LBB0_410
	v_lshlrev_b32_e32 v82, 7, v93
	v_and_b32_e32 v82, 0x780, v82
	v_mov_b32_e32 v83, v209
	v_lshl_add_u64 v[82:83], v[154:155], 0, v[82:83]
	global_load_dwordx4 v[94:97], v[82:83], off
	global_load_dwordx4 v[98:101], v[82:83], off offset:16
	s_waitcnt vmcnt(0) lgkmcnt(0)
	v_pk_mul_f32 v[102:103], v[84:85], v[94:95] op_sel:[1,1] op_sel_hi:[1,0]
	v_pk_mul_f32 v[82:83], v[84:85], v[94:95]
	v_pk_fma_f32 v[84:85], v[84:85], v[94:95], v[102:103] op_sel_hi:[0,1,1]
	v_mul_f32_e32 v84, v91, v97
	v_pk_fma_f32 v[94:95], v[90:91], v[96:97], v[84:85] op_sel_hi:[1,1,0] neg_lo:[0,0,1] neg_hi:[0,0,1]
	v_mul_f32_e32 v84, v91, v96
	v_pk_fma_f32 v[90:91], v[90:91], v[96:97], v[84:85] op_sel:[0,1,0] op_sel_hi:[1,0,0]
	v_pk_mul_f32 v[104:105], v[86:87], v[98:99] op_sel:[1,1] op_sel_hi:[1,0]
	v_mul_f32_e32 v84, v89, v101
	v_pk_mul_f32 v[96:97], v[86:87], v[98:99]
	v_pk_fma_f32 v[86:87], v[86:87], v[98:99], v[104:105] op_sel_hi:[0,1,1]
	v_pk_fma_f32 v[98:99], v[88:89], v[100:101], v[84:85] op_sel_hi:[1,1,0] neg_lo:[0,0,1] neg_hi:[0,0,1]
	v_mul_f32_e32 v84, v89, v100
	v_pk_fma_f32 v[88:89], v[88:89], v[100:101], v[84:85] op_sel:[0,1,0] op_sel_hi:[1,0,0]
	v_sub_f32_e32 v84, v82, v102
	v_sub_f32_e32 v86, v96, v104
	v_mov_b32_e32 v89, v88
	v_mov_b32_e32 v88, v98
	v_mov_b32_e32 v91, v90
	v_mov_b32_e32 v90, v94

; __device__ __forceinline__ unsigned pk2(float lo, float hi) { const f32x2_cv v = {lo, hi}; const bf16x2_cv b = __builtin_convertvector(v, bf16x2_cv); return __builtin_bit_cast(unsigned, b); }
;     __device__ __forceinline__ void operator()(const pg8::f32x4 (&acc)[2][2][4][2], const pg8::Unit& u, int wr, int wc, int fr, int fq) const {
;     ...
;                     v4u o; o.x = pk2(y0[0], y0[1]); o.y = pk2(y0[2], y0[3]); o.z = pk2(y1[0], y1[1]); o.w = pk2(y1[2], y1[3]);
;                     *(v4u*)(dp + 32 * bj) = o;
.LBB0_411:
	v_cvt_pk_bf16_f32 v82, v84, v85
	v_cvt_pk_bf16_f32 v83, v90, v91
	v_cvt_pk_bf16_f32 v84, v86, v87
	v_cvt_pk_bf16_f32 v85, v88, v89
	v_lshl_add_u64 v[80:81], v[80:81], 0, v[246:247]
	global_store_dwordx4 v[80:81], v[82:85], off offset:64
	s_branch .LBB0_355

;     __device__ __forceinline__ void operator()(const pg8::f32x4 (&acc)[2][2][4][2], const pg8::Unit& u, int wr, int wc, int fr, int fq) const {
;     ...
;                     pg8::f32x4 y0 = acc[ai][bj][m][0], y1 = acc[ai][bj][m][1];
;                     if (normed) {
;                         y0 = y0 * rinv * gg[bj][0]; y1 = y1 * rinv * gg[bj][1];
;                         if (lat) { const int p = bj == 0 ? (t >> 6) : (t & 63); const pg8::f32x4* rp = (const pg8::f32x4*)(rope + p * 16 + 4 * fq); const pg8::f32x4 c01 = rp[0], c23 = rp[1];
;                             const pg8::f32x4 z0 = {y0[0] * c01[0] - y0[1] * c01[1], y0[0] * c01[1] + y0[1] * c01[0], y0[2] * c01[2] - y0[3] * c01[3], y0[2] * c01[3] + y0[3] * c01[2]};
;                             const pg8::f32x4 z1 = {y1[0] * c23[0] - y1[1] * c23[1], y1[0] * c23[1] + y1[1] * c23[0], y1[2] * c23[2] - y1[3] * c23[3], y1[2] * c23[3] + y1[3] * c23[2]};
;                             y0 = z0; y1 = z1; }
.LBB0_415:
	v_mov_b32_e32 v67, v66
	s_and_b64 vcc, exec, s[38:39]
	v_mov_b32_e32 v68, v44
	v_mov_b32_e32 v69, v45
	v_mov_b32_e32 v74, v46
	v_mov_b32_e32 v75, v47
	v_mov_b32_e32 v70, v40
	v_mov_b32_e32 v71, v41
	v_mov_b32_e32 v72, v42
	v_mov_b32_e32 v73, v43
	s_cbranch_vccnz .LBB0_419
	v_mov_b32_e32 v70, v66
	v_mov_b32_e32 v71, v66
	v_pk_mul_f32 v[68:69], v[46:47], v[70:71]
	v_pk_mul_f32 v[72:73], v[44:45], v[66:67]
	v_pk_mul_f32 v[70:71], v[42:43], v[70:71]
	v_pk_mul_f32 v[78:79], v[40:41], v[66:67]
	s_waitcnt vmcnt(0)
	v_pk_mul_f32 v[74:75], v[62:63], v[68:69]
	v_pk_mul_f32 v[68:69], v[60:61], v[72:73]
	v_pk_mul_f32 v[72:73], v[58:59], v[70:71]
	v_pk_mul_f32 v[70:71], v[56:57], v[78:79]
	s_and_saveexec_b64 s[4:5], s[44:45]
	s_cbranch_execz .LBB0_418
	v_lshlrev_b32_e32 v78, 1, v77
	v_and_b32_e32 v78, 0x3f80, v78
	v_mov_b32_e32 v79, v209
	v_lshl_add_u64 v[82:83], v[154:155], 0, v[78:79]
	global_load_dwordx4 v[78:81], v[82:83], off
	s_nop 0
	global_load_dwordx4 v[82:85], v[82:83], off offset:16
	s_waitcnt vmcnt(0) lgkmcnt(0)
	v_pk_mul_f32 v[88:89], v[68:69], v[78:79] op_sel:[1,1] op_sel_hi:[1,0]
	v_pk_mul_f32 v[86:87], v[68:69], v[78:79]
	v_pk_fma_f32 v[68:69], v[68:69], v[78:79], v[88:89] op_sel_hi:[0,1,1]
	v_mul_f32_e32 v68, v75, v81
	v_pk_fma_f32 v[78:79], v[74:75], v[80:81], v[68:69] op_sel_hi:[1,1,0] neg_lo:[0,0,1] neg_hi:[0,0,1]
	v_mul_f32_e32 v68, v75, v80
	v_pk_fma_f32 v[74:75], v[74:75], v[80:81], v[68:69] op_sel:[0,1,0] op_sel_hi:[1,0,0]
	v_pk_mul_f32 v[90:91], v[70:71], v[82:83] op_sel:[1,1] op_sel_hi:[1,0]
	v_mul_f32_e32 v68, v73, v85
	v_pk_mul_f32 v[80:81], v[70:71], v[82:83]
	v_pk_fma_f32 v[70:71], v[70:71], v[82:83], v[90:91] op_sel_hi:[0,1,1]
	v_pk_fma_f32 v[82:83], v[72:73], v[84:85], v[68:69] op_sel_hi:[1,1,0] neg_lo:[0,0,1] neg_hi:[0,0,1]
	v_mul_f32_e32 v68, v73, v84
	v_pk_fma_f32 v[72:73], v[72:73], v[84:85], v[68:69] op_sel:[0,1,0] op_sel_hi:[1,0,0]
	v_sub_f32_e32 v68, v86, v88
	v_sub_f32_e32 v70, v80, v90
	v_mov_b32_e32 v73, v72
	v_mov_b32_e32 v72, v82
	v_mov_b32_e32 v75, v74
	v_mov_b32_e32 v74, v78

; __device__ __forceinline__ unsigned pk2(float lo, float hi) { const f32x2_cv v = {lo, hi}; const bf16x2_cv b = __builtin_convertvector(v, bf16x2_cv); return __builtin_bit_cast(unsigned, b); }
;     __device__ __forceinline__ void operator()(const pg8::f32x4 (&acc)[2][2][4][2], const pg8::Unit& u, int wr, int wc, int fr, int fq) const {
;     ...
;                 for (int bj = 0; bj < 2; ++bj) {
;                     pg8::f32x4 y0 = acc[ai][bj][m][0], y1 = acc[ai][bj][m][1];
;                     if (normed) {
;                         y0 = y0 * rinv * gg[bj][0]; y1 = y1 * rinv * gg[bj][1];
;                         if (lat) { const int p = bj == 0 ? (t >> 6) : (t & 63); const pg8::f32x4* rp = (const pg8::f32x4*)(rope + p * 16 + 4 * fq); const pg8::f32x4 c01 = rp[0], c23 = rp[1];
;                             const pg8::f32x4 z0 = {y0[0] * c01[0] - y0[1] * c01[1], y0[0] * c01[1] + y0[1] * c01[0], y0[2] * c01[2] - y0[3] * c01[3], y0[2] * c01[3] + y0[3] * c01[2]};
;                             const pg8::f32x4 z1 = {y1[0] * c23[0] - y1[1] * c23[1], y1[0] * c23[1] + y1[1] * c23[0], y1[2] * c23[2] - y1[3] * c23[3], y1[2] * c23[3] + y1[3] * c23[2]};
;                             y0 = z0; y1 = z1; }
;                     }
;                     v4u o; o.x = pk2(y0[0], y0[1]); o.y = pk2(y0[2], y0[3]); o.z = pk2(y1[0], y1[1]); o.w = pk2(y1[2], y1[3]);
;                     *(v4u*)(dp + 32 * bj) = o;
.LBB0_419:
	v_and_b32_e32 v245, 63, v64
	v_mul_lo_u32 v78, v65, s94
	v_mul_lo_u32 v79, v64, s95
	v_mad_u64_u32 v[64:65], s[4:5], v64, s94, 0
	v_add3_u32 v65, v65, v79, v78
	v_lshl_add_u64 v[64:65], v[64:65], 1, v[160:161]
	v_mul_u32_u24_e32 v244, s100, v245
	v_sub_u32_e32 v244, 0, v244
	v_ashrrev_i32_e32 v245, 31, v244
	v_lshl_add_u64 v[64:65], v[64:65], 0, v[244:245]
	v_cvt_pk_bf16_f32 v68, v68, v69
	v_cvt_pk_bf16_f32 v69, v74, v75
	v_cvt_pk_bf16_f32 v70, v70, v71
	v_cvt_pk_bf16_f32 v71, v72, v73
	global_store_dwordx4 v[64:65], v[68:71], off
	s_and_b64 vcc, exec, s[38:39]
	v_mov_b32_e32 v74, v38
	v_mov_b32_e32 v68, v36
	v_mov_b32_e32 v69, v37
	v_mov_b32_e32 v75, v39
	v_mov_b32_e32 v70, v32
	v_mov_b32_e32 v71, v33
	v_mov_b32_e32 v72, v34
	v_mov_b32_e32 v73, v35
	s_cbranch_vccnz .LBB0_423
	v_mov_b32_e32 v70, v66
	v_mov_b32_e32 v71, v66
	v_pk_mul_f32 v[68:69], v[38:39], v[70:71]
	v_pk_mul_f32 v[72:73], v[36:37], v[66:67]
	v_pk_mul_f32 v[70:71], v[34:35], v[70:71]
	v_pk_mul_f32 v[66:67], v[32:33], v[66:67]
	s_waitcnt vmcnt(0)
	v_pk_mul_f32 v[74:75], v[54:55], v[68:69]
	v_pk_mul_f32 v[68:69], v[52:53], v[72:73]
	v_pk_mul_f32 v[72:73], v[50:51], v[70:71]
	v_pk_mul_f32 v[70:71], v[48:49], v[66:67]
	s_and_saveexec_b64 s[4:5], s[44:45]
	s_cbranch_execz .LBB0_422
	v_lshlrev_b32_e32 v66, 7, v77
	v_and_b32_e32 v66, 0xf80, v66
	v_mov_b32_e32 v67, v209
	v_lshl_add_u64 v[66:67], v[154:155], 0, v[66:67]
	global_load_dwordx4 v[78:81], v[66:67], off
	global_load_dwordx4 v[82:85], v[66:67], off offset:16
	s_waitcnt vmcnt(0) lgkmcnt(0)
	v_pk_mul_f32 v[86:87], v[68:69], v[78:79] op_sel:[1,1] op_sel_hi:[1,0]
	v_pk_mul_f32 v[66:67], v[68:69], v[78:79]
	v_pk_fma_f32 v[68:69], v[68:69], v[78:79], v[86:87] op_sel_hi:[0,1,1]
	v_mul_f32_e32 v68, v75, v81
	v_pk_fma_f32 v[78:79], v[74:75], v[80:81], v[68:69] op_sel_hi:[1,1,0] neg_lo:[0,0,1] neg_hi:[0,0,1]
	v_mul_f32_e32 v68, v75, v80
	v_pk_fma_f32 v[74:75], v[74:75], v[80:81], v[68:69] op_sel:[0,1,0] op_sel_hi:[1,0,0]
	v_pk_mul_f32 v[88:89], v[70:71], v[82:83] op_sel:[1,1] op_sel_hi:[1,0]
	v_mul_f32_e32 v68, v73, v85
	v_pk_mul_f32 v[80:81], v[70:71], v[82:83]
	v_pk_fma_f32 v[70:71], v[70:71], v[82:83], v[88:89] op_sel_hi:[0,1,1]
	v_pk_fma_f32 v[82:83], v[72:73], v[84:85], v[68:69] op_sel_hi:[1,1,0] neg_lo:[0,0,1] neg_hi:[0,0,1]
	v_mul_f32_e32 v68, v73, v84
	v_pk_fma_f32 v[72:73], v[72:73], v[84:85], v[68:69] op_sel:[0,1,0] op_sel_hi:[1,0,0]
	v_sub_f32_e32 v68, v66, v86
	v_sub_f32_e32 v70, v80, v88
	v_mov_b32_e32 v73, v72
	v_mov_b32_e32 v72, v82
	v_mov_b32_e32 v75, v74
	v_mov_b32_e32 v74, v78

; __device__ __forceinline__ unsigned pk2(float lo, float hi) { const f32x2_cv v = {lo, hi}; const bf16x2_cv b = __builtin_convertvector(v, bf16x2_cv); return __builtin_bit_cast(unsigned, b); }
;     __device__ __forceinline__ void operator()(const pg8::f32x4 (&acc)[2][2][4][2], const pg8::Unit& u, int wr, int wc, int fr, int fq) const {
;     ...
;                     v4u o; o.x = pk2(y0[0], y0[1]); o.y = pk2(y0[2], y0[3]); o.z = pk2(y1[0], y1[1]); o.w = pk2(y1[2], y1[3]);
;                     *(v4u*)(dp + 32 * bj) = o;
.LBB0_423:
	v_cvt_pk_bf16_f32 v66, v68, v69
	v_cvt_pk_bf16_f32 v67, v74, v75
	v_cvt_pk_bf16_f32 v68, v70, v71
	v_cvt_pk_bf16_f32 v69, v72, v73
	v_lshl_add_u64 v[64:65], v[64:65], 0, v[246:247]
	global_store_dwordx4 v[64:65], v[66:69], off offset:64
	s_branch .LBB0_361

;     __device__ __forceinline__ void operator()(const pg8::f32x4 (&acc)[2][2][4][2], const pg8::Unit& u, int wr, int wc, int fr, int fq) const {
;     ...
;                     pg8::f32x4 y0 = acc[ai][bj][m][0], y1 = acc[ai][bj][m][1];
;                     if (normed) {
;                         y0 = y0 * rinv * gg[bj][0]; y1 = y1 * rinv * gg[bj][1];
;                         if (lat) { const int p = bj == 0 ? (t >> 6) : (t & 63); const pg8::f32x4* rp = (const pg8::f32x4*)(rope + p * 16 + 4 * fq); const pg8::f32x4 c01 = rp[0], c23 = rp[1];
;                             const pg8::f32x4 z0 = {y0[0] * c01[0] - y0[1] * c01[1], y0[0] * c01[1] + y0[1] * c01[0], y0[2] * c01[2] - y0[3] * c01[3], y0[2] * c01[3] + y0[3] * c01[2]};
;                             const pg8::f32x4 z1 = {y1[0] * c23[0] - y1[1] * c23[1], y1[0] * c23[1] + y1[1] * c23[0], y1[2] * c23[2] - y1[3] * c23[3], y1[2] * c23[3] + y1[3] * c23[2]};
;                             y0 = z0; y1 = z1; }
.LBB0_427:
	v_mov_b32_e32 v35, v34
	s_and_b64 vcc, exec, s[38:39]
	v_mov_b32_e32 v36, v28
	v_mov_b32_e32 v37, v29
	v_mov_b32_e32 v42, v30
	v_mov_b32_e32 v43, v31
	v_mov_b32_e32 v38, v24
	v_mov_b32_e32 v39, v25
	v_mov_b32_e32 v40, v26
	v_mov_b32_e32 v41, v27
	s_cbranch_vccnz .LBB0_431
	v_mov_b32_e32 v38, v34
	v_mov_b32_e32 v39, v34
	v_pk_mul_f32 v[36:37], v[30:31], v[38:39]
	v_pk_mul_f32 v[40:41], v[28:29], v[34:35]
	v_pk_mul_f32 v[38:39], v[26:27], v[38:39]
	v_pk_mul_f32 v[46:47], v[24:25], v[34:35]
	s_waitcnt vmcnt(0)
	v_pk_mul_f32 v[42:43], v[62:63], v[36:37]
	v_pk_mul_f32 v[36:37], v[60:61], v[40:41]
	v_pk_mul_f32 v[40:41], v[58:59], v[38:39]
	v_pk_mul_f32 v[38:39], v[56:57], v[46:47]
	s_and_saveexec_b64 s[4:5], s[44:45]
	s_cbranch_execz .LBB0_430
	v_lshlrev_b32_e32 v46, 1, v45
	v_and_b32_e32 v46, 0x3f80, v46
	v_mov_b32_e32 v47, v209
	v_lshl_add_u64 v[46:47], v[154:155], 0, v[46:47]
	global_load_dwordx4 v[64:67], v[46:47], off
	global_load_dwordx4 v[68:71], v[46:47], off offset:16
	s_waitcnt vmcnt(0) lgkmcnt(0)
	v_pk_mul_f32 v[72:73], v[36:37], v[64:65] op_sel:[1,1] op_sel_hi:[1,0]
	v_pk_mul_f32 v[46:47], v[36:37], v[64:65]
	v_pk_fma_f32 v[36:37], v[36:37], v[64:65], v[72:73] op_sel_hi:[0,1,1]
	v_mul_f32_e32 v36, v43, v67
	v_pk_fma_f32 v[64:65], v[42:43], v[66:67], v[36:37] op_sel_hi:[1,1,0] neg_lo:[0,0,1] neg_hi:[0,0,1]
	v_mul_f32_e32 v36, v43, v66
	v_pk_fma_f32 v[42:43], v[42:43], v[66:67], v[36:37] op_sel:[0,1,0] op_sel_hi:[1,0,0]
	v_pk_mul_f32 v[74:75], v[38:39], v[68:69] op_sel:[1,1] op_sel_hi:[1,0]
	v_mul_f32_e32 v36, v41, v71
	v_pk_mul_f32 v[66:67], v[38:39], v[68:69]
	v_pk_fma_f32 v[38:39], v[38:39], v[68:69], v[74:75] op_sel_hi:[0,1,1]
	v_pk_fma_f32 v[68:69], v[40:41], v[70:71], v[36:37] op_sel_hi:[1,1,0] neg_lo:[0,0,1] neg_hi:[0,0,1]
	v_mul_f32_e32 v36, v41, v70
	v_pk_fma_f32 v[40:41], v[40:41], v[70:71], v[36:37] op_sel:[0,1,0] op_sel_hi:[1,0,0]
	v_sub_f32_e32 v36, v46, v72
	v_sub_f32_e32 v38, v66, v74
	v_mov_b32_e32 v41, v40
	v_mov_b32_e32 v40, v68
	v_mov_b32_e32 v43, v42
	v_mov_b32_e32 v42, v64

; __device__ __forceinline__ unsigned pk2(float lo, float hi) { const f32x2_cv v = {lo, hi}; const bf16x2_cv b = __builtin_convertvector(v, bf16x2_cv); return __builtin_bit_cast(unsigned, b); }
;     __device__ __forceinline__ void operator()(const pg8::f32x4 (&acc)[2][2][4][2], const pg8::Unit& u, int wr, int wc, int fr, int fq) const {
;     ...
;                 for (int bj = 0; bj < 2; ++bj) {
;                     pg8::f32x4 y0 = acc[ai][bj][m][0], y1 = acc[ai][bj][m][1];
;                     if (normed) {
;                         y0 = y0 * rinv * gg[bj][0]; y1 = y1 * rinv * gg[bj][1];
;                         if (lat) { const int p = bj == 0 ? (t >> 6) : (t & 63); const pg8::f32x4* rp = (const pg8::f32x4*)(rope + p * 16 + 4 * fq); const pg8::f32x4 c01 = rp[0], c23 = rp[1];
;                             const pg8::f32x4 z0 = {y0[0] * c01[0] - y0[1] * c01[1], y0[0] * c01[1] + y0[1] * c01[0], y0[2] * c01[2] - y0[3] * c01[3], y0[2] * c01[3] + y0[3] * c01[2]};
;                             const pg8::f32x4 z1 = {y1[0] * c23[0] - y1[1] * c23[1], y1[0] * c23[1] + y1[1] * c23[0], y1[2] * c23[2] - y1[3] * c23[3], y1[2] * c23[3] + y1[3] * c23[2]};
;                             y0 = z0; y1 = z1; }
;                     }
;                     v4u o; o.x = pk2(y0[0], y0[1]); o.y = pk2(y0[2], y0[3]); o.z = pk2(y1[0], y1[1]); o.w = pk2(y1[2], y1[3]);
;                     *(v4u*)(dp + 32 * bj) = o;
.LBB0_431:
	v_and_b32_e32 v245, 63, v32
	v_mul_lo_u32 v46, v33, s94
	v_mul_lo_u32 v47, v32, s95
	v_mad_u64_u32 v[32:33], s[4:5], v32, s94, 0
	v_add3_u32 v33, v33, v47, v46
	v_lshl_add_u64 v[32:33], v[32:33], 1, v[160:161]
	v_mul_u32_u24_e32 v244, s100, v245
	v_sub_u32_e32 v244, 0, v244
	v_ashrrev_i32_e32 v245, 31, v244
	v_lshl_add_u64 v[32:33], v[32:33], 0, v[244:245]
	v_cvt_pk_bf16_f32 v36, v36, v37
	v_cvt_pk_bf16_f32 v37, v42, v43
	v_cvt_pk_bf16_f32 v38, v38, v39
	v_cvt_pk_bf16_f32 v39, v40, v41
	global_store_dwordx4 v[32:33], v[36:39], off
	s_and_b64 vcc, exec, s[38:39]
	v_mov_b32_e32 v42, v22
	v_mov_b32_e32 v36, v20
	v_mov_b32_e32 v37, v21
	v_mov_b32_e32 v43, v23
	v_mov_b32_e32 v38, v16
	v_mov_b32_e32 v39, v17
	v_mov_b32_e32 v40, v18
	v_mov_b32_e32 v41, v19
	s_cbranch_vccnz .LBB0_435
	v_mov_b32_e32 v38, v34
	v_mov_b32_e32 v39, v34
	v_pk_mul_f32 v[36:37], v[22:23], v[38:39]
	v_pk_mul_f32 v[40:41], v[20:21], v[34:35]
	v_pk_mul_f32 v[38:39], v[18:19], v[38:39]
	v_pk_mul_f32 v[34:35], v[16:17], v[34:35]
	s_waitcnt vmcnt(0)
	v_pk_mul_f32 v[42:43], v[54:55], v[36:37]
	v_pk_mul_f32 v[36:37], v[52:53], v[40:41]
	v_pk_mul_f32 v[40:41], v[50:51], v[38:39]
	v_pk_mul_f32 v[38:39], v[48:49], v[34:35]
	s_and_saveexec_b64 s[4:5], s[44:45]
	s_cbranch_execz .LBB0_434
	v_lshlrev_b32_e32 v34, 7, v45
	v_and_b32_e32 v34, 0x1780, v34
	v_mov_b32_e32 v35, v209
	v_lshl_add_u64 v[34:35], v[154:155], 0, v[34:35]
	global_load_dwordx4 v[64:67], v[34:35], off
	global_load_dwordx4 v[68:71], v[34:35], off offset:16
	s_waitcnt vmcnt(0) lgkmcnt(0)
	v_pk_mul_f32 v[46:47], v[36:37], v[64:65] op_sel:[1,1] op_sel_hi:[1,0]
	v_pk_mul_f32 v[34:35], v[36:37], v[64:65]
	v_pk_fma_f32 v[36:37], v[36:37], v[64:65], v[46:47] op_sel_hi:[0,1,1]
	v_mul_f32_e32 v36, v43, v67
	v_pk_fma_f32 v[64:65], v[42:43], v[66:67], v[36:37] op_sel_hi:[1,1,0] neg_lo:[0,0,1] neg_hi:[0,0,1]
	v_mul_f32_e32 v36, v43, v66
	v_pk_fma_f32 v[42:43], v[42:43], v[66:67], v[36:37] op_sel:[0,1,0] op_sel_hi:[1,0,0]
	v_pk_mul_f32 v[72:73], v[38:39], v[68:69] op_sel:[1,1] op_sel_hi:[1,0]
	v_mul_f32_e32 v36, v41, v71
	v_pk_mul_f32 v[66:67], v[38:39], v[68:69]
	v_pk_fma_f32 v[38:39], v[38:39], v[68:69], v[72:73] op_sel_hi:[0,1,1]
	v_pk_fma_f32 v[68:69], v[40:41], v[70:71], v[36:37] op_sel_hi:[1,1,0] neg_lo:[0,0,1] neg_hi:[0,0,1]
	v_mul_f32_e32 v36, v41, v70
	v_pk_fma_f32 v[40:41], v[40:41], v[70:71], v[36:37] op_sel:[0,1,0] op_sel_hi:[1,0,0]
	v_sub_f32_e32 v36, v34, v46
	v_sub_f32_e32 v38, v66, v72
	v_mov_b32_e32 v41, v40
	v_mov_b32_e32 v40, v68
	v_mov_b32_e32 v43, v42
	v_mov_b32_e32 v42, v64

; __device__ __forceinline__ unsigned pk2(float lo, float hi) { const f32x2_cv v = {lo, hi}; const bf16x2_cv b = __builtin_convertvector(v, bf16x2_cv); return __builtin_bit_cast(unsigned, b); }
;     __device__ __forceinline__ void operator()(const pg8::f32x4 (&acc)[2][2][4][2], const pg8::Unit& u, int wr, int wc, int fr, int fq) const {
;     ...
;                     v4u o; o.x = pk2(y0[0], y0[1]); o.y = pk2(y0[2], y0[3]); o.z = pk2(y1[0], y1[1]); o.w = pk2(y1[2], y1[3]);
;                     *(v4u*)(dp + 32 * bj) = o;
.LBB0_435:
	v_cvt_pk_bf16_f32 v34, v36, v37
	v_cvt_pk_bf16_f32 v35, v42, v43
	v_cvt_pk_bf16_f32 v36, v38, v39
	v_cvt_pk_bf16_f32 v37, v40, v41
	v_lshl_add_u64 v[32:33], v[32:33], 0, v[246:247]
	global_store_dwordx4 v[32:33], v[34:37], off offset:64
	s_branch .LBB0_367

;     __device__ __forceinline__ void operator()(const pg8::f32x4 (&acc)[2][2][4][2], const pg8::Unit& u, int wr, int wc, int fr, int fq) const {
;     ...
;                     pg8::f32x4 y0 = acc[ai][bj][m][0], y1 = acc[ai][bj][m][1];
;                     if (normed) {
;                         y0 = y0 * rinv * gg[bj][0]; y1 = y1 * rinv * gg[bj][1];
;                         if (lat) { const int p = bj == 0 ? (t >> 6) : (t & 63); const pg8::f32x4* rp = (const pg8::f32x4*)(rope + p * 16 + 4 * fq); const pg8::f32x4 c01 = rp[0], c23 = rp[1];
;                             const pg8::f32x4 z0 = {y0[0] * c01[0] - y0[1] * c01[1], y0[0] * c01[1] + y0[1] * c01[0], y0[2] * c01[2] - y0[3] * c01[3], y0[2] * c01[3] + y0[3] * c01[2]};
;                             const pg8::f32x4 z1 = {y1[0] * c23[0] - y1[1] * c23[1], y1[0] * c23[1] + y1[1] * c23[0], y1[2] * c23[2] - y1[3] * c23[3], y1[2] * c23[3] + y1[3] * c23[2]};
;                             y0 = z0; y1 = z1; }
.LBB0_439:
	v_mov_b32_e32 v19, v18
	s_and_b64 vcc, exec, s[38:39]
	v_mov_b32_e32 v20, v12
	v_mov_b32_e32 v21, v13
	v_mov_b32_e32 v26, v14
	v_mov_b32_e32 v27, v15
	v_mov_b32_e32 v22, v8
	v_mov_b32_e32 v23, v9
	v_mov_b32_e32 v24, v10
	v_mov_b32_e32 v25, v11
	s_cbranch_vccnz .LBB0_443
	v_mov_b32_e32 v22, v18
	v_mov_b32_e32 v23, v18
	v_pk_mul_f32 v[20:21], v[14:15], v[22:23]
	v_pk_mul_f32 v[24:25], v[12:13], v[18:19]
	v_pk_mul_f32 v[22:23], v[10:11], v[22:23]
	v_pk_mul_f32 v[30:31], v[8:9], v[18:19]
	s_waitcnt vmcnt(0)
	v_pk_mul_f32 v[26:27], v[62:63], v[20:21]
	v_pk_mul_f32 v[20:21], v[60:61], v[24:25]
	v_pk_mul_f32 v[24:25], v[58:59], v[22:23]
	v_pk_mul_f32 v[22:23], v[56:57], v[30:31]
	s_and_saveexec_b64 s[4:5], s[44:45]
	s_cbranch_execz .LBB0_442
	v_lshlrev_b32_e32 v30, 1, v29
	v_and_b32_e32 v30, 0x3f80, v30
	v_mov_b32_e32 v31, v209
	v_lshl_add_u64 v[34:35], v[154:155], 0, v[30:31]
	global_load_dwordx4 v[30:33], v[34:35], off
	s_nop 0
	global_load_dwordx4 v[34:37], v[34:35], off offset:16
	s_waitcnt vmcnt(0) lgkmcnt(0)
	v_pk_mul_f32 v[40:41], v[20:21], v[30:31] op_sel:[1,1] op_sel_hi:[1,0]
	v_pk_mul_f32 v[38:39], v[20:21], v[30:31]
	v_pk_fma_f32 v[20:21], v[20:21], v[30:31], v[40:41] op_sel_hi:[0,1,1]
	v_mul_f32_e32 v20, v27, v33
	v_pk_fma_f32 v[30:31], v[26:27], v[32:33], v[20:21] op_sel_hi:[1,1,0] neg_lo:[0,0,1] neg_hi:[0,0,1]
	v_mul_f32_e32 v20, v27, v32
	v_pk_fma_f32 v[26:27], v[26:27], v[32:33], v[20:21] op_sel:[0,1,0] op_sel_hi:[1,0,0]
	v_pk_mul_f32 v[42:43], v[22:23], v[34:35] op_sel:[1,1] op_sel_hi:[1,0]
	v_mul_f32_e32 v20, v25, v37
	v_pk_mul_f32 v[32:33], v[22:23], v[34:35]
	v_pk_fma_f32 v[22:23], v[22:23], v[34:35], v[42:43] op_sel_hi:[0,1,1]
	v_pk_fma_f32 v[34:35], v[24:25], v[36:37], v[20:21] op_sel_hi:[1,1,0] neg_lo:[0,0,1] neg_hi:[0,0,1]
	v_mul_f32_e32 v20, v25, v36
	v_pk_fma_f32 v[24:25], v[24:25], v[36:37], v[20:21] op_sel:[0,1,0] op_sel_hi:[1,0,0]
	v_sub_f32_e32 v20, v38, v40
	v_sub_f32_e32 v22, v32, v42
	v_mov_b32_e32 v25, v24
	v_mov_b32_e32 v24, v34
	v_mov_b32_e32 v27, v26
	v_mov_b32_e32 v26, v30

; __device__ __forceinline__ unsigned pk2(float lo, float hi) { const f32x2_cv v = {lo, hi}; const bf16x2_cv b = __builtin_convertvector(v, bf16x2_cv); return __builtin_bit_cast(unsigned, b); }
;     __device__ __forceinline__ void operator()(const pg8::f32x4 (&acc)[2][2][4][2], const pg8::Unit& u, int wr, int wc, int fr, int fq) const {
;     ...
;                 for (int bj = 0; bj < 2; ++bj) {
;                     pg8::f32x4 y0 = acc[ai][bj][m][0], y1 = acc[ai][bj][m][1];
;                     if (normed) {
;                         y0 = y0 * rinv * gg[bj][0]; y1 = y1 * rinv * gg[bj][1];
;                         if (lat) { const int p = bj == 0 ? (t >> 6) : (t & 63); const pg8::f32x4* rp = (const pg8::f32x4*)(rope + p * 16 + 4 * fq); const pg8::f32x4 c01 = rp[0], c23 = rp[1];
;                             const pg8::f32x4 z0 = {y0[0] * c01[0] - y0[1] * c01[1], y0[0] * c01[1] + y0[1] * c01[0], y0[2] * c01[2] - y0[3] * c01[3], y0[2] * c01[3] + y0[3] * c01[2]};
;                             const pg8::f32x4 z1 = {y1[0] * c23[0] - y1[1] * c23[1], y1[0] * c23[1] + y1[1] * c23[0], y1[2] * c23[2] - y1[3] * c23[3], y1[2] * c23[3] + y1[3] * c23[2]};
;                             y0 = z0; y1 = z1; }
;                     }
;                     v4u o; o.x = pk2(y0[0], y0[1]); o.y = pk2(y0[2], y0[3]); o.z = pk2(y1[0], y1[1]); o.w = pk2(y1[2], y1[3]);
;                     *(v4u*)(dp + 32 * bj) = o;
.LBB0_443:
	v_and_b32_e32 v245, 63, v16
	v_mul_lo_u32 v30, v17, s94
	v_mul_lo_u32 v31, v16, s95
	v_mad_u64_u32 v[16:17], s[4:5], v16, s94, 0
	v_add3_u32 v17, v17, v31, v30
	v_lshl_add_u64 v[16:17], v[16:17], 1, v[160:161]
	v_mul_u32_u24_e32 v244, s100, v245
	v_sub_u32_e32 v244, 0, v244
	v_ashrrev_i32_e32 v245, 31, v244
	v_lshl_add_u64 v[16:17], v[16:17], 0, v[244:245]
	v_cvt_pk_bf16_f32 v20, v20, v21
	v_cvt_pk_bf16_f32 v21, v26, v27
	v_cvt_pk_bf16_f32 v22, v22, v23
	v_cvt_pk_bf16_f32 v23, v24, v25
	global_store_dwordx4 v[16:17], v[20:23], off
	s_and_b64 vcc, exec, s[38:39]
	v_mov_b32_e32 v26, v6
	v_mov_b32_e32 v20, v4
	v_mov_b32_e32 v21, v5
	v_mov_b32_e32 v27, v7
	v_mov_b32_e32 v22, v0
	v_mov_b32_e32 v23, v1
	v_mov_b32_e32 v24, v2
	v_mov_b32_e32 v25, v3
	s_cbranch_vccnz .LBB0_447
	v_mov_b32_e32 v22, v18
	v_mov_b32_e32 v23, v18
	v_pk_mul_f32 v[20:21], v[6:7], v[22:23]
	v_pk_mul_f32 v[24:25], v[4:5], v[18:19]
	v_pk_mul_f32 v[22:23], v[2:3], v[22:23]
	v_pk_mul_f32 v[18:19], v[0:1], v[18:19]
	s_waitcnt vmcnt(0)
	v_pk_mul_f32 v[26:27], v[54:55], v[20:21]
	v_pk_mul_f32 v[20:21], v[52:53], v[24:25]
	v_pk_mul_f32 v[24:25], v[50:51], v[22:23]
	v_pk_mul_f32 v[22:23], v[48:49], v[18:19]
	s_and_saveexec_b64 s[4:5], s[44:45]
	s_cbranch_execz .LBB0_446
	v_lshlrev_b32_e32 v18, 7, v29
	v_and_b32_e32 v18, 0x1f80, v18
	v_mov_b32_e32 v19, v209
	v_lshl_add_u64 v[18:19], v[154:155], 0, v[18:19]
	global_load_dwordx4 v[30:33], v[18:19], off
	global_load_dwordx4 v[34:37], v[18:19], off offset:16
	s_waitcnt vmcnt(0) lgkmcnt(0)
	v_pk_mul_f32 v[38:39], v[20:21], v[30:31] op_sel:[1,1] op_sel_hi:[1,0]
	v_pk_mul_f32 v[18:19], v[20:21], v[30:31]
	v_pk_fma_f32 v[20:21], v[20:21], v[30:31], v[38:39] op_sel_hi:[0,1,1]
	v_mul_f32_e32 v20, v27, v33
	v_pk_fma_f32 v[30:31], v[26:27], v[32:33], v[20:21] op_sel_hi:[1,1,0] neg_lo:[0,0,1] neg_hi:[0,0,1]
	v_mul_f32_e32 v20, v27, v32
	v_pk_fma_f32 v[26:27], v[26:27], v[32:33], v[20:21] op_sel:[0,1,0] op_sel_hi:[1,0,0]
	v_pk_mul_f32 v[40:41], v[22:23], v[34:35] op_sel:[1,1] op_sel_hi:[1,0]
	v_mul_f32_e32 v20, v25, v37
	v_pk_mul_f32 v[32:33], v[22:23], v[34:35]
	v_pk_fma_f32 v[22:23], v[22:23], v[34:35], v[40:41] op_sel_hi:[0,1,1]
	v_pk_fma_f32 v[34:35], v[24:25], v[36:37], v[20:21] op_sel_hi:[1,1,0] neg_lo:[0,0,1] neg_hi:[0,0,1]
	v_mul_f32_e32 v20, v25, v36
	v_pk_fma_f32 v[24:25], v[24:25], v[36:37], v[20:21] op_sel:[0,1,0] op_sel_hi:[1,0,0]
	v_sub_f32_e32 v20, v18, v38
	v_sub_f32_e32 v22, v32, v40
	v_mov_b32_e32 v25, v24
	v_mov_b32_e32 v24, v34
	v_mov_b32_e32 v27, v26
	v_mov_b32_e32 v26, v30

; __device__ __forceinline__ unsigned pk2(float lo, float hi) { const f32x2_cv v = {lo, hi}; const bf16x2_cv b = __builtin_convertvector(v, bf16x2_cv); return __builtin_bit_cast(unsigned, b); }
;     __device__ __forceinline__ void operator()(const pg8::f32x4 (&acc)[2][2][4][2], const pg8::Unit& u, int wr, int wc, int fr, int fq) const {
;     ...
;                     v4u o; o.x = pk2(y0[0], y0[1]); o.y = pk2(y0[2], y0[3]); o.z = pk2(y1[0], y1[1]); o.w = pk2(y1[2], y1[3]);
;                     *(v4u*)(dp + 32 * bj) = o;
.LBB0_447:
	v_cvt_pk_bf16_f32 v18, v20, v21
	v_cvt_pk_bf16_f32 v19, v26, v27
	v_cvt_pk_bf16_f32 v20, v22, v23
	v_cvt_pk_bf16_f32 v21, v24, v25
	v_lshl_add_u64 v[16:17], v[16:17], 0, v[246:247]
	global_store_dwordx4 v[16:17], v[18:21], off offset:64
	s_branch .LBB0_373

; __global__ void __launch_bounds__(NTHR, 2) fwd_mega(Args a) {
;     ...
;                     float s = 0.f; for (int i = tid; i < 8192; i += NTHR) s += fabsf(hf[i]) + fabsf(hb[i]);
.LBB0_511:
	global_load_dword v9, v[6:7], off
	global_load_dword v10, v[4:5], off
	v_add_u32_e32 v8, 0x200, v8
	v_cmp_lt_i32_e32 vcc, s31, v8
	v_lshl_add_u64 v[4:5], v[4:5], 0, s[16:17]
	v_lshl_add_u64 v[6:7], v[6:7], 0, s[16:17]
	s_or_b64 s[10:11], vcc, s[10:11]
	s_waitcnt vmcnt(0) lgkmcnt(0)
	v_add_f32_e64 v9, |v9|, |v10|
	v_add_f32_e32 v1, v1, v9
	s_andn2_b64 exec, exec, s[10:11]
	s_cbranch_execnz .LBB0_511
	s_or_b64 exec, exec, s[10:11]

; __global__ void __launch_bounds__(NTHR, 2) fwd_mega(Args a) {
;     ...
;                     for (int i = tid; i < 8192; i += NTHR) { X[PX(i)] = mk2(hf[i] * inv, 0.f); X[PX(8192 + i)] = (i == 0) ? mk2(0.f, 0.f) : mk2(hb[8192 - i] * inv, 0.f); }
.LBB0_518:
	global_load_dword v5, v[2:3], off
	v_ashrrev_i32_e32 v8, 6, v7
	v_lshl_add_u32 v8, v8, 3, v6
	v_cmp_ne_u32_e32 vcc, 0, v7
	s_waitcnt vmcnt(0) lgkmcnt(0)
	v_mul_f32_e32 v208, v1, v5
	ds_write_b64 v8, v[208:209]
	v_mov_b32_e32 v208, 0
	s_and_saveexec_b64 s[60:61], vcc
	s_cbranch_execz .LBB0_517
	v_mov_b32_e32 v5, v209
	v_lshl_add_u64 v[8:9], v[4:5], 2, s[4:5]
	global_load_dword v5, v[8:9], off
	s_waitcnt vmcnt(0) lgkmcnt(0)
	v_mul_f32_e32 v208, v1, v5
	s_branch .LBB0_517

; #define LAS __attribute__((address_space(3)))
; __device__ __forceinline__ void fft_last_fwd(LAS cf* X, int tid, cf* KFW, float bias, float scale) {
; #pragma unroll 2
;     for (int i = 0; i < 8; ++i) { const int it = tid + 512 * i, g = it & 255, k = it >> 8, base = g * 64 + 4 * k;
;         cf e0 = X[PX(base)], e1 = X[PX(base + 1)], e2 = X[PX(base + 2)], e3 = X[PX(base + 3)];
;         bfly4_fwd(e0, e1, e2, e3);
;         if (KFW) { cf* o = KFW + (4 * k) * 256 + g; o[0] = mk2((e0.x + bias) * scale, e0.y * scale); o[256] = mk2((e1.x + bias) * scale, e1.y * scale); o[512] = mk2((e2.x + bias) * scale, e2.y * scale); o[768] = mk2((e3.x + bias) * scale, e3.y * scale); }
;         else { X[PX(base)] = e0; X[PX(base + 1)] = e1; X[PX(base + 2)] = e2; X[PX(base + 3)] = e3; } }
;     __syncthreads();
; }
; __global__ void __launch_bounds__(NTHR, 2) fwd_mega(Args a) {
;     ...
;                     fft_last_fwd(X, tid, KF + o * FFTN, o == 0 ? bias1 : bias2, 1.0f / FFTN);
;                 }
;                 __threadfence(); __syncthreads();
.LBB0_527:
	v_add_u32_e32 v1, s4, v16
	v_ashrrev_i32_e32 v3, 6, v1
	v_and_b32_e32 v3, -4, v3
	v_add_u32_e32 v6, v3, v157
	v_ashrrev_i32_e32 v7, 6, v6
	v_lshlrev_b32_e32 v7, 3, v7
	v_lshlrev_b32_e32 v6, 3, v6
	v_add3_u32 v10, 0, v7, v6
	ds_read2_b64 v[6:9], v10 offset1:1
	ds_read2_b64 v[10:13], v10 offset0:2 offset1:3
	v_lshlrev_b32_e32 v140, 8, v3
	v_ashrrev_i32_e32 v141, 31, v140
	v_lshl_add_u64 v[140:141], v[140:141], 3, v[4:5]
	v_add_u32_e32 v1, 0x200, v1
	s_waitcnt lgkmcnt(0)
	v_pk_add_f32 v[14:15], v[6:7], v[10:11]
	v_pk_add_f32 v[6:7], v[6:7], v[10:11] neg_lo:[0,1] neg_hi:[0,1]
	v_pk_add_f32 v[10:11], v[8:9], v[12:13]
	v_pk_add_f32 v[8:9], v[8:9], v[12:13] neg_lo:[0,1] neg_hi:[0,1]
	v_pk_add_f32 v[12:13], v[14:15], v[10:11]
	v_pk_add_f32 v[10:11], v[14:15], v[10:11] neg_lo:[0,1] neg_hi:[0,1]
	v_add_f32_e32 v12, v2, v12
	v_pk_add_f32 v[14:15], v[6:7], v[8:9] op_sel:[0,1] op_sel_hi:[1,0]
	v_pk_mul_f32 v[12:13], v[12:13], s[22:23] op_sel_hi:[1,0]
	v_mov_b32_e32 v3, v7
	v_pk_add_f32 v[138:139], v[6:7], v[8:9] op_sel:[0,1] op_sel_hi:[1,0] neg_lo:[0,1] neg_hi:[0,1]
	global_store_dwordx2 v[140:141], v[12:13], off
	v_pk_add_f32 v[12:13], v[2:3], v[14:15]
	v_pk_add_f32 v[6:7], v[6:7], v[8:9] op_sel_hi:[1,0] neg_lo:[0,1] neg_hi:[0,1]
	v_add_f32_e32 v10, v2, v10
	v_mov_b32_e32 v13, v7
	v_pk_mul_f32 v[6:7], v[12:13], s[22:23] op_sel_hi:[1,0]
	global_store_dwordx2 v[140:141], v[6:7], off offset:2048
	v_pk_mul_f32 v[6:7], v[10:11], s[22:23] op_sel_hi:[1,0]
	v_add_co_u32_e32 v10, vcc, s96, v140
	v_mov_b32_e32 v139, v8
	s_nop 0
	v_addc_co_u32_e32 v11, vcc, 0, v141, vcc
	v_ashrrev_i32_e32 v1, 6, v1
	global_store_dwordx2 v[10:11], v[6:7], off
	v_pk_add_f32 v[6:7], v[2:3], v[138:139]
	v_and_b32_e32 v1, -4, v1
	v_pk_mul_f32 v[6:7], v[6:7], s[22:23] op_sel_hi:[1,0]
	v_add_u32_e32 v3, v1, v157
	global_store_dwordx2 v[10:11], v[6:7], off offset:2048
	v_ashrrev_i32_e32 v6, 6, v3
	v_lshlrev_b32_e32 v6, 3, v6
	v_lshlrev_b32_e32 v3, 3, v3
	v_add3_u32 v3, 0, v6, v3
	ds_read2_b64 v[6:9], v3 offset1:1
	ds_read2_b64 v[10:13], v3 offset0:2 offset1:3
	v_lshlrev_b32_e32 v140, 8, v1
	v_ashrrev_i32_e32 v141, 31, v140
	v_lshl_add_u64 v[140:141], v[140:141], 3, v[4:5]
	s_addk_i32 s4, 0x400
	s_waitcnt lgkmcnt(0)
	v_pk_add_f32 v[14:15], v[6:7], v[10:11]
	v_pk_add_f32 v[6:7], v[6:7], v[10:11] neg_lo:[0,1] neg_hi:[0,1]
	v_pk_add_f32 v[10:11], v[8:9], v[12:13]
	v_pk_add_f32 v[8:9], v[8:9], v[12:13] neg_lo:[0,1] neg_hi:[0,1]
	v_pk_add_f32 v[12:13], v[14:15], v[10:11]
	v_pk_add_f32 v[10:11], v[14:15], v[10:11] neg_lo:[0,1] neg_hi:[0,1]
	v_add_f32_e32 v12, v2, v12
	v_pk_add_f32 v[14:15], v[6:7], v[8:9] op_sel:[0,1] op_sel_hi:[1,0]
	v_pk_mul_f32 v[12:13], v[12:13], s[22:23] op_sel_hi:[1,0]
	v_mov_b32_e32 v3, v7
	v_pk_add_f32 v[138:139], v[6:7], v[8:9] op_sel:[0,1] op_sel_hi:[1,0] neg_lo:[0,1] neg_hi:[0,1]
	global_store_dwordx2 v[140:141], v[12:13], off
	v_pk_add_f32 v[12:13], v[2:3], v[14:15]
	v_pk_add_f32 v[6:7], v[6:7], v[8:9] op_sel_hi:[1,0] neg_lo:[0,1] neg_hi:[0,1]
	v_add_f32_e32 v10, v2, v10
	v_mov_b32_e32 v13, v7
	v_pk_mul_f32 v[6:7], v[12:13], s[22:23] op_sel_hi:[1,0]
	global_store_dwordx2 v[140:141], v[6:7], off offset:2048
	v_pk_mul_f32 v[6:7], v[10:11], s[22:23] op_sel_hi:[1,0]
	v_add_co_u32_e32 v10, vcc, 0x1000, v140
	v_mov_b32_e32 v139, v8
	s_nop 0
	v_addc_co_u32_e32 v11, vcc, 0, v141, vcc
	global_store_dwordx2 v[10:11], v[6:7], off
	v_pk_add_f32 v[6:7], v[2:3], v[138:139]
	s_cmpk_lg_i32 s4, 0x1000
	v_pk_mul_f32 v[6:7], v[6:7], s[22:23] op_sel_hi:[1,0]
	global_store_dwordx2 v[10:11], v[6:7], off offset:2048
	s_cbranch_scc1 .LBB0_527
	s_mov_b32 s48, 1
	s_mov_b64 s[46:47], 0
	s_and_b64 vcc, exec, s[36:37]
	s_waitcnt lgkmcnt(0)
	s_barrier
	s_cbranch_vccz .LBB0_509
	v_mov_b32_e32 v1, v209
	v_lshl_add_u64 v[0:1], s[12:13], 0, v[0:1]
	s_mov_b32 s78, s81
	v_lshl_add_u64 v[142:143], v[0:1], 0, s[66:67]
	s_lshl_b64 s[48:49], s[14:15], 15
	v_mov_b32_e32 v132, v124
	v_mov_b32_e32 v138, v133
	v_mov_b32_e32 v139, v124
	v_mov_b32_e32 v140, v135
	v_mov_b32_e32 v141, v134
	v_mov_b32_e32 v131, v130
	v_mov_b32_e32 v144, v129
	v_mov_b32_e32 v145, v129
	v_mov_b32_e32 v127, v126
	v_mov_b32_e32 v146, v128
	v_mov_b32_e32 v147, v128
	v_mov_b32_e32 v148, v128
	v_mov_b32_e32 v149, v126
	s_mov_b32 s12, 0
	s_mov_b64 s[4:5], -1
	buffer_wbl2 sc1
	s_waitcnt vmcnt(0)
	buffer_inv sc1
	s_barrier
	s_branch .LBB0_531

; __device__ __forceinline__ float bf2f(bf16_t u) { return __uint_as_float((unsigned)u << 16); }
; __device__ __forceinline__ float bflo(unsigned w) { return __uint_as_float(w << 16); }
; __device__ __forceinline__ float bfhi(unsigned w) { return __uint_as_float(w & 0xffff0000u); }
; __device__ __forceinline__ void conv8(const bf16_t* p, int c, int n, float w0, float w1, float w2, float b, float (&o)[8]) {
;     const v4u v = *(const v4u*)(p + 8 * c);
;     const float um = c > 0 ? bf2f(p[8 * c - 1]) : 0.f, up = 8 * c + 8 < n ? bf2f(p[8 * c + 8]) : 0.f;
;     const float u0 = bflo(v.x), u1 = bfhi(v.x), u2 = bflo(v.y), u3 = bfhi(v.y), u4 = bflo(v.z), u5 = bfhi(v.z), u6 = bflo(v.w), u7 = bfhi(v.w);
;     o[0] = w0 * um + w1 * u0 + w2 * u1 + b; o[1] = w0 * u0 + w1 * u1 + w2 * u2 + b; o[2] = w0 * u1 + w1 * u2 + w2 * u3 + b; o[3] = w0 * u2 + w1 * u3 + w2 * u4 + b;
;     o[4] = w0 * u3 + w1 * u4 + w2 * u5 + b; o[5] = w0 * u4 + w1 * u5 + w2 * u6 + b; o[6] = w0 * u5 + w1 * u6 + w2 * u7 + b; o[7] = w0 * u6 + w1 * u7 + w2 * up + b;
; }
; __global__ void __launch_bounds__(NTHR, 2) fwd_mega(Args a) {
;     ...
;                     for (int k = 0; k < 2; ++k) { const int ch = 64 * (wave + 8 * k) + cw; float u0[8], u1[8];
;                         conv8(pv0, ch, 8192, wv0, wv1, wv2, bv, u0); conv8(pv1, ch, 8192, wv0, wv1, wv2, bv, u1);
; #pragma unroll
;                         for (int e = 0; e < 8; ++e) { X[PX(8 * ch + e)] = mk2(u0[e], u1[e]); X[PX(8192 + 8 * ch + e)] = mk2(0.f, 0.f); } }
.LBB0_533:
	v_add_u32_e32 v14, s10, v158
	v_lshlrev_b32_e32 v8, 3, v14
	v_ashrrev_i32_e32 v9, 31, v8
	v_lshl_add_u64 v[0:1], v[8:9], 1, s[36:37]
	global_load_dwordx4 v[4:7], v[0:1], off
	v_cmp_lt_i32_e32 vcc, 0, v14
	v_mov_b32_e32 v10, 0
	v_mov_b32_e32 v15, 0
	s_and_saveexec_b64 s[4:5], vcc
	s_cbranch_execz .LBB0_535
	v_add_co_u32_e64 v2, s[46:47], -2, v0
	s_nop 1
	v_addc_co_u32_e64 v3, s[46:47], -1, v1, s[46:47]
	global_load_ushort v2, v[2:3], off
	s_waitcnt vmcnt(0) lgkmcnt(0)
	v_lshlrev_b32_e32 v15, 16, v2
.LBB0_535:
	s_or_b64 exec, exec, s[4:5]
	v_cmp_gt_i32_e64 s[46:47], s57, v14
	s_and_saveexec_b64 s[4:5], s[46:47]
	s_cbranch_execz .LBB0_537
	global_load_ushort v0, v[0:1], off offset:16
	s_waitcnt vmcnt(0) lgkmcnt(0)
	v_lshlrev_b32_e32 v10, 16, v0
.LBB0_537:
	s_or_b64 exec, exec, s[4:5]
	v_lshl_add_u64 v[12:13], v[8:9], 1, s[80:81]
	global_load_dwordx4 v[0:3], v[12:13], off
	v_mov_b32_e32 v11, 0
	v_mov_b32_e32 v9, 0
	s_and_saveexec_b64 s[4:5], vcc
	s_cbranch_execz .LBB0_539
	v_add_co_u32_e32 v150, vcc, -2, v12
	s_nop 1
	v_addc_co_u32_e32 v151, vcc, -1, v13, vcc
	global_load_ushort v9, v[150:151], off
	s_waitcnt vmcnt(0) lgkmcnt(0)
	v_lshlrev_b32_e32 v9, 16, v9
.LBB0_539:
	s_or_b64 exec, exec, s[4:5]
	s_and_saveexec_b64 s[4:5], s[46:47]
	s_cbranch_execz .LBB0_532
	global_load_ushort v11, v[12:13], off offset:16
	s_waitcnt vmcnt(0) lgkmcnt(0)
	v_lshlrev_b32_e32 v11, 16, v11
	s_branch .LBB0_532

; #define LAS __attribute__((address_space(3)))
; __device__ __forceinline__ cf cmul(cf a, cf b) { return mk2(a.x * b.x - a.y * b.y, a.x * b.y + a.y * b.x); }
; __device__ __forceinline__ void fft_mid_mul(LAS cf* X, int tid, const cf* KFR) {
; #pragma unroll 2
;     for (int i = 0; i < 8; ++i) { const int it = tid + 512 * i, g = it & 255, k = it >> 8, base = g * 64 + 4 * k; const cf* q = KFR + (4 * k) * 256 + g;
;         cf e0 = X[PX(base)], e1 = X[PX(base + 1)], e2 = X[PX(base + 2)], e3 = X[PX(base + 3)];
;         const cf k0 = ld_f2_l2(q), k1 = ld_f2_l2(q + 256), k2 = ld_f2_l2(q + 512), k3 = ld_f2_l2(q + 768);
;         bfly4_fwd(e0, e1, e2, e3);
;         e0 = cmul(e0, k0); e1 = cmul(e1, k1); e2 = cmul(e2, k2); e3 = cmul(e3, k3);
;         bfly4_inv(e0, e1, e2, e3);
;         X[PX(base)] = e0; X[PX(base + 1)] = e1; X[PX(base + 2)] = e2; X[PX(base + 3)] = e3; }
;     __syncthreads();
; }
.LBB0_548:
	v_add_u32_e32 v170, s4, v16
	v_ashrrev_i32_e32 v0, 6, v170
	v_and_b32_e32 v0, -4, v0
	v_add_u32_e32 v2, v0, v157
	v_lshlrev_b32_e32 v0, 8, v0
	v_ashrrev_i32_e32 v1, 31, v0
	v_lshl_add_u64 v[8:9], v[0:1], 3, v[136:137]
	v_ashrrev_i32_e32 v0, 6, v2
	v_lshlrev_b32_e32 v0, 3, v0
	v_lshlrev_b32_e32 v1, 3, v2
	v_add3_u32 v171, 0, v0, v1
	ds_read2_b64 v[0:3], v171 offset1:1
	ds_read2_b64 v[4:7], v171 offset0:2 offset1:3
	global_load_dwordx2 v[10:11], v[8:9], off sc1
	global_load_dwordx2 v[12:13], v[8:9], off offset:2048 sc1
	v_add_co_u32_e32 v8, vcc, s96, v8
	s_addk_i32 s4, 0x400
	s_nop 0
	v_addc_co_u32_e32 v9, vcc, 0, v9, vcc
	global_load_dwordx2 v[14:15], v[8:9], off sc1
	s_nop 0
	global_load_dwordx2 v[8:9], v[8:9], off offset:2048 sc1
	s_waitcnt lgkmcnt(0)
	v_pk_add_f32 v[150:151], v[0:1], v[4:5]
	v_pk_add_f32 v[0:1], v[0:1], v[4:5] neg_lo:[0,1] neg_hi:[0,1]
	v_pk_add_f32 v[4:5], v[2:3], v[6:7]
	v_pk_add_f32 v[2:3], v[2:3], v[6:7] neg_lo:[0,1] neg_hi:[0,1]
	v_pk_add_f32 v[6:7], v[150:151], v[4:5]
	v_pk_add_f32 v[4:5], v[150:151], v[4:5] neg_lo:[0,1] neg_hi:[0,1]
	s_cmpk_lg_i32 s4, 0x1000
	s_waitcnt vmcnt(0)
	v_pk_mul_f32 v[150:151], v[6:7], v[10:11] op_sel:[1,1] op_sel_hi:[1,0]
	s_nop 0
	v_pk_fma_f32 v[152:153], v[6:7], v[10:11], v[150:151] neg_lo:[0,0,1] neg_hi:[0,0,1]
	v_pk_fma_f32 v[6:7], v[6:7], v[10:11], v[150:151] op_sel_hi:[0,1,1]
	v_pk_add_f32 v[10:11], v[0:1], v[2:3] op_sel:[1,0] op_sel_hi:[1,0] neg_lo:[0,1] neg_hi:[0,1]
	v_mov_b32_e32 v153, v7
	v_pk_add_f32 v[6:7], v[0:1], v[2:3] op_sel:[0,1] op_sel_hi:[0,1]
	v_pk_mul_f32 v[10:11], v[10:11], v[12:13] op_sel:[0,1] op_sel_hi:[1,0]
	s_nop 0
	v_pk_fma_f32 v[150:151], v[6:7], v[12:13], v[10:11] neg_lo:[0,0,1] neg_hi:[0,0,1]
	v_pk_fma_f32 v[6:7], v[6:7], v[12:13], v[10:11]
	s_nop 0
	v_mov_b32_e32 v151, v7
	v_pk_mul_f32 v[6:7], v[4:5], v[14:15] op_sel:[1,1] op_sel_hi:[1,0]
	s_nop 0
	v_pk_fma_f32 v[10:11], v[4:5], v[14:15], v[6:7] neg_lo:[0,0,1] neg_hi:[0,0,1]
	v_pk_fma_f32 v[4:5], v[4:5], v[14:15], v[6:7] op_sel_hi:[0,1,1]
	v_mov_b32_e32 v11, v5
	v_pk_add_f32 v[4:5], v[0:1], v[2:3] op_sel:[0,1] op_sel_hi:[0,1] neg_lo:[0,1] neg_hi:[0,1]
	v_pk_add_f32 v[0:1], v[0:1], v[2:3] op_sel:[1,0] op_sel_hi:[1,0]
	s_nop 0
	v_pk_mul_f32 v[0:1], v[0:1], v[8:9] op_sel:[0,1] op_sel_hi:[1,0]
	s_nop 0
	v_pk_fma_f32 v[2:3], v[4:5], v[8:9], v[0:1] neg_lo:[0,0,1] neg_hi:[0,0,1]
	v_pk_fma_f32 v[0:1], v[4:5], v[8:9], v[0:1]
	v_pk_add_f32 v[4:5], v[152:153], v[10:11] neg_lo:[0,1] neg_hi:[0,1]
	v_mov_b32_e32 v3, v1
	v_pk_add_f32 v[0:1], v[152:153], v[10:11]
	v_pk_add_f32 v[6:7], v[150:151], v[2:3]
	v_pk_add_f32 v[2:3], v[150:151], v[2:3] neg_lo:[0,1] neg_hi:[0,1]
	v_pk_add_f32 v[8:9], v[0:1], v[6:7]
	v_pk_add_f32 v[0:1], v[0:1], v[6:7] neg_lo:[0,1] neg_hi:[0,1]
	v_pk_add_f32 v[6:7], v[4:5], v[2:3] op_sel:[0,1] op_sel_hi:[1,0] neg_lo:[0,1] neg_hi:[0,1]
	v_pk_add_f32 v[10:11], v[4:5], v[2:3] op_sel_hi:[1,0]
	v_pk_add_f32 v[12:13], v[4:5], v[2:3] op_sel:[0,1] op_sel_hi:[1,0]
	v_pk_add_f32 v[2:3], v[4:5], v[2:3] op_sel_hi:[1,0] neg_lo:[0,1] neg_hi:[0,1]
	v_mov_b32_e32 v7, v11
	v_mov_b32_e32 v13, v3
	ds_write2_b64 v171, v[0:1], v[12:13] offset0:2 offset1:3
	v_add_u32_e32 v0, 0x200, v170
	v_ashrrev_i32_e32 v0, 6, v0
	v_and_b32_e32 v0, -4, v0
	v_add_u32_e32 v2, v0, v157
	v_lshlrev_b32_e32 v0, 8, v0
	v_ashrrev_i32_e32 v1, 31, v0
	ds_write2_b64 v171, v[8:9], v[6:7] offset1:1
	v_lshl_add_u64 v[8:9], v[0:1], 3, v[136:137]
	v_ashrrev_i32_e32 v0, 6, v2
	v_lshlrev_b32_e32 v0, 3, v0
	v_lshlrev_b32_e32 v1, 3, v2
	v_add3_u32 v170, 0, v0, v1
	ds_read2_b64 v[0:3], v170 offset1:1
	ds_read2_b64 v[4:7], v170 offset0:2 offset1:3
	global_load_dwordx2 v[10:11], v[8:9], off sc1
	global_load_dwordx2 v[12:13], v[8:9], off offset:2048 sc1
	v_add_co_u32_e32 v8, vcc, s96, v8
	s_waitcnt lgkmcnt(0)
	v_pk_add_f32 v[150:151], v[0:1], v[4:5]
	v_addc_co_u32_e32 v9, vcc, 0, v9, vcc
	global_load_dwordx2 v[14:15], v[8:9], off sc1
	s_nop 0
	global_load_dwordx2 v[8:9], v[8:9], off offset:2048 sc1
	v_pk_add_f32 v[0:1], v[0:1], v[4:5] neg_lo:[0,1] neg_hi:[0,1]
	v_pk_add_f32 v[4:5], v[2:3], v[6:7]
	v_pk_add_f32 v[2:3], v[2:3], v[6:7] neg_lo:[0,1] neg_hi:[0,1]
	v_pk_add_f32 v[6:7], v[150:151], v[4:5]
	v_pk_add_f32 v[4:5], v[150:151], v[4:5] neg_lo:[0,1] neg_hi:[0,1]
	s_waitcnt vmcnt(0)
	v_pk_mul_f32 v[150:151], v[6:7], v[10:11] op_sel:[1,1] op_sel_hi:[1,0]
	s_nop 0
	v_pk_fma_f32 v[152:153], v[6:7], v[10:11], v[150:151] neg_lo:[0,0,1] neg_hi:[0,0,1]
	v_pk_fma_f32 v[6:7], v[6:7], v[10:11], v[150:151] op_sel_hi:[0,1,1]
	v_pk_add_f32 v[10:11], v[0:1], v[2:3] op_sel:[1,0] op_sel_hi:[1,0] neg_lo:[0,1] neg_hi:[0,1]
	v_mov_b32_e32 v153, v7
	v_pk_add_f32 v[6:7], v[0:1], v[2:3] op_sel:[0,1] op_sel_hi:[0,1]
	v_pk_mul_f32 v[10:11], v[10:11], v[12:13] op_sel:[0,1] op_sel_hi:[1,0]
	s_nop 0
	v_pk_fma_f32 v[150:151], v[6:7], v[12:13], v[10:11] neg_lo:[0,0,1] neg_hi:[0,0,1]
	v_pk_fma_f32 v[6:7], v[6:7], v[12:13], v[10:11]
	s_nop 0
	v_mov_b32_e32 v151, v7
	s_waitcnt lgkmcnt(0)
	v_pk_mul_f32 v[6:7], v[4:5], v[14:15] op_sel:[1,1] op_sel_hi:[1,0]
	s_nop 0
	v_pk_fma_f32 v[10:11], v[4:5], v[14:15], v[6:7] neg_lo:[0,0,1] neg_hi:[0,0,1]
	v_pk_fma_f32 v[4:5], v[4:5], v[14:15], v[6:7] op_sel_hi:[0,1,1]
	v_mov_b32_e32 v11, v5
	v_pk_add_f32 v[4:5], v[0:1], v[2:3] op_sel:[0,1] op_sel_hi:[0,1] neg_lo:[0,1] neg_hi:[0,1]
	v_pk_add_f32 v[0:1], v[0:1], v[2:3] op_sel:[1,0] op_sel_hi:[1,0]
	s_nop 0
	v_pk_mul_f32 v[0:1], v[0:1], v[8:9] op_sel:[0,1] op_sel_hi:[1,0]
	s_nop 0
	v_pk_fma_f32 v[2:3], v[4:5], v[8:9], v[0:1] neg_lo:[0,0,1] neg_hi:[0,0,1]
	v_pk_fma_f32 v[0:1], v[4:5], v[8:9], v[0:1]
	v_pk_add_f32 v[4:5], v[152:153], v[10:11] neg_lo:[0,1] neg_hi:[0,1]
	v_mov_b32_e32 v3, v1
	v_pk_add_f32 v[0:1], v[152:153], v[10:11]
	v_pk_add_f32 v[6:7], v[150:151], v[2:3]
	v_pk_add_f32 v[2:3], v[150:151], v[2:3] neg_lo:[0,1] neg_hi:[0,1]
	v_pk_add_f32 v[8:9], v[0:1], v[6:7]
	v_pk_add_f32 v[0:1], v[0:1], v[6:7] neg_lo:[0,1] neg_hi:[0,1]
	v_pk_add_f32 v[6:7], v[4:5], v[2:3] op_sel:[0,1] op_sel_hi:[1,0] neg_lo:[0,1] neg_hi:[0,1]
	v_pk_add_f32 v[10:11], v[4:5], v[2:3] op_sel_hi:[1,0]
	v_pk_add_f32 v[12:13], v[4:5], v[2:3] op_sel:[0,1] op_sel_hi:[1,0]
	v_pk_add_f32 v[2:3], v[4:5], v[2:3] op_sel_hi:[1,0] neg_lo:[0,1] neg_hi:[0,1]
	v_mov_b32_e32 v7, v11
	v_mov_b32_e32 v13, v3
	ds_write2_b64 v170, v[8:9], v[6:7] offset1:1
	ds_write2_b64 v170, v[0:1], v[12:13] offset0:2 offset1:3
	s_cbranch_scc1 .LBB0_548
	s_mov_b32 s6, 0
	s_mov_b64 s[4:5], -1
	s_waitcnt lgkmcnt(0)
	s_barrier

; __device__ __forceinline__ float bf2f(bf16_t u) { return __uint_as_float((unsigned)u << 16); }
; __device__ __forceinline__ float bflo(unsigned w) { return __uint_as_float(w << 16); }
; __device__ __forceinline__ float bfhi(unsigned w) { return __uint_as_float(w & 0xffff0000u); }
; __device__ __forceinline__ void conv8(const bf16_t* p, int c, int n, float w0, float w1, float w2, float b, float (&o)[8]) {
;     const v4u v = *(const v4u*)(p + 8 * c);
;     const float um = c > 0 ? bf2f(p[8 * c - 1]) : 0.f, up = 8 * c + 8 < n ? bf2f(p[8 * c + 8]) : 0.f;
;     const float u0 = bflo(v.x), u1 = bfhi(v.x), u2 = bflo(v.y), u3 = bfhi(v.y), u4 = bflo(v.z), u5 = bfhi(v.z), u6 = bflo(v.w), u7 = bfhi(v.w);
;     o[0] = w0 * um + w1 * u0 + w2 * u1 + b; o[1] = w0 * u0 + w1 * u1 + w2 * u2 + b; o[2] = w0 * u1 + w1 * u2 + w2 * u3 + b; o[3] = w0 * u2 + w1 * u3 + w2 * u4 + b;
;     o[4] = w0 * u3 + w1 * u4 + w2 * u5 + b; o[5] = w0 * u4 + w1 * u5 + w2 * u6 + b; o[6] = w0 * u5 + w1 * u6 + w2 * u7 + b; o[7] = w0 * u6 + w1 * u7 + w2 * up + b;
; }
; __global__ void __launch_bounds__(NTHR, 2) fwd_mega(Args a) {
;     ...
;                     for (int k = 0; k < 2; ++k) { const int ch = 64 * (wave + 8 * k) + cw; float a0_[8], a1_[8];
;                         conv8(pv0 + 256 * 8192, ch, 8192, wa0, wa1, wa2, ba, a0_); conv8(pv1 + 256 * 8192, ch, 8192, wa0, wa1, wa2, ba, a1_);
; #pragma unroll
;                         for (int e = 0; e < 8; ++e) { const cf cv = X[PX(8 * ch + e)]; X[PX(8 * ch + e)] = mk2(a0_[e] * cv.x, a1_[e] * cv.y); X[PX(8192 + 8 * ch + e)] = mk2(0.f, 0.f); } }
.LBB0_557:
	v_add_u32_e32 v12, s13, v158
	v_lshlrev_b32_e32 v8, 3, v12
	v_ashrrev_i32_e32 v9, 31, v8
	v_lshl_add_u64 v[0:1], v[8:9], 1, s[4:5]
	global_load_dwordx4 v[4:7], v[0:1], off
	v_cmp_lt_i32_e32 vcc, 0, v12
	v_mov_b32_e32 v13, 0
	v_mov_b32_e32 v15, 0
	s_and_saveexec_b64 s[10:11], vcc
	s_cbranch_execz .LBB0_559
	v_add_co_u32_e64 v2, s[46:47], -2, v0
	s_nop 1
	v_addc_co_u32_e64 v3, s[46:47], -1, v1, s[46:47]
	global_load_ushort v2, v[2:3], off
	s_waitcnt vmcnt(0) lgkmcnt(0)
	v_lshlrev_b32_e32 v15, 16, v2
.LBB0_559:
	s_or_b64 exec, exec, s[10:11]
	v_cmp_gt_i32_e64 s[46:47], s57, v12
	s_and_saveexec_b64 s[10:11], s[46:47]
	s_cbranch_execz .LBB0_561
	global_load_ushort v0, v[0:1], off offset:16
	s_waitcnt vmcnt(0) lgkmcnt(0)
	v_lshlrev_b32_e32 v13, 16, v0
.LBB0_561:
	s_or_b64 exec, exec, s[10:11]
	v_lshl_add_u64 v[10:11], v[8:9], 1, s[6:7]
	global_load_dwordx4 v[0:3], v[10:11], off
	v_mov_b32_e32 v9, 0
	v_mov_b32_e32 v14, 0
	s_and_saveexec_b64 s[10:11], vcc
	s_cbranch_execz .LBB0_563
	v_add_co_u32_e32 v150, vcc, -2, v10
	s_nop 1
	v_addc_co_u32_e32 v151, vcc, -1, v11, vcc
	global_load_ushort v14, v[150:151], off
	s_waitcnt vmcnt(0) lgkmcnt(0)
	v_lshlrev_b32_e32 v14, 16, v14
.LBB0_563:
	s_or_b64 exec, exec, s[10:11]
	s_and_saveexec_b64 s[10:11], s[46:47]
	s_cbranch_execz .LBB0_556
	global_load_ushort v9, v[10:11], off offset:16
	s_waitcnt vmcnt(0) lgkmcnt(0)
	v_lshlrev_b32_e32 v9, 16, v9
	s_branch .LBB0_556

; #define LAS __attribute__((address_space(3)))
; __device__ __forceinline__ cf cmul(cf a, cf b) { return mk2(a.x * b.x - a.y * b.y, a.x * b.y + a.y * b.x); }
; __device__ __forceinline__ void fft_mid_mul(LAS cf* X, int tid, const cf* KFR) {
; #pragma unroll 2
;     for (int i = 0; i < 8; ++i) { const int it = tid + 512 * i, g = it & 255, k = it >> 8, base = g * 64 + 4 * k; const cf* q = KFR + (4 * k) * 256 + g;
;         cf e0 = X[PX(base)], e1 = X[PX(base + 1)], e2 = X[PX(base + 2)], e3 = X[PX(base + 3)];
;         const cf k0 = ld_f2_l2(q), k1 = ld_f2_l2(q + 256), k2 = ld_f2_l2(q + 512), k3 = ld_f2_l2(q + 768);
;         bfly4_fwd(e0, e1, e2, e3);
;         e0 = cmul(e0, k0); e1 = cmul(e1, k1); e2 = cmul(e2, k2); e3 = cmul(e3, k3);
;         bfly4_inv(e0, e1, e2, e3);
;         X[PX(base)] = e0; X[PX(base + 1)] = e1; X[PX(base + 2)] = e2; X[PX(base + 3)] = e3; }
;     __syncthreads();
; }
.LBB0_572:
	v_add_u32_e32 v170, s4, v16
	v_ashrrev_i32_e32 v0, 6, v170
	v_and_b32_e32 v0, -4, v0
	v_add_u32_e32 v2, v0, v157
	v_lshlrev_b32_e32 v0, 8, v0
	v_ashrrev_i32_e32 v1, 31, v0
	v_lshl_add_u64 v[8:9], v[0:1], 3, v[142:143]
	v_ashrrev_i32_e32 v0, 6, v2
	v_lshlrev_b32_e32 v0, 3, v0
	v_lshlrev_b32_e32 v1, 3, v2
	v_add3_u32 v171, 0, v0, v1
	ds_read2_b64 v[0:3], v171 offset1:1
	ds_read2_b64 v[4:7], v171 offset0:2 offset1:3
	global_load_dwordx2 v[10:11], v[8:9], off sc1
	global_load_dwordx2 v[12:13], v[8:9], off offset:2048 sc1
	v_add_co_u32_e32 v8, vcc, s96, v8
	s_addk_i32 s4, 0x400
	s_nop 0
	v_addc_co_u32_e32 v9, vcc, 0, v9, vcc
	global_load_dwordx2 v[14:15], v[8:9], off sc1
	s_nop 0
	global_load_dwordx2 v[8:9], v[8:9], off offset:2048 sc1
	s_waitcnt lgkmcnt(0)
	v_pk_add_f32 v[150:151], v[0:1], v[4:5]
	v_pk_add_f32 v[0:1], v[0:1], v[4:5] neg_lo:[0,1] neg_hi:[0,1]
	v_pk_add_f32 v[4:5], v[2:3], v[6:7]
	v_pk_add_f32 v[2:3], v[2:3], v[6:7] neg_lo:[0,1] neg_hi:[0,1]
	v_pk_add_f32 v[6:7], v[150:151], v[4:5]
	v_pk_add_f32 v[4:5], v[150:151], v[4:5] neg_lo:[0,1] neg_hi:[0,1]
	s_cmpk_lg_i32 s4, 0x1000
	s_waitcnt vmcnt(0)
	v_pk_mul_f32 v[150:151], v[6:7], v[10:11] op_sel:[1,1] op_sel_hi:[1,0]
	s_nop 0
	v_pk_fma_f32 v[152:153], v[6:7], v[10:11], v[150:151] neg_lo:[0,0,1] neg_hi:[0,0,1]
	v_pk_fma_f32 v[6:7], v[6:7], v[10:11], v[150:151] op_sel_hi:[0,1,1]
	v_pk_add_f32 v[10:11], v[0:1], v[2:3] op_sel:[1,0] op_sel_hi:[1,0] neg_lo:[0,1] neg_hi:[0,1]
	v_mov_b32_e32 v153, v7
	v_pk_add_f32 v[6:7], v[0:1], v[2:3] op_sel:[0,1] op_sel_hi:[0,1]
	v_pk_mul_f32 v[10:11], v[10:11], v[12:13] op_sel:[0,1] op_sel_hi:[1,0]
	s_nop 0
	v_pk_fma_f32 v[150:151], v[6:7], v[12:13], v[10:11] neg_lo:[0,0,1] neg_hi:[0,0,1]
	v_pk_fma_f32 v[6:7], v[6:7], v[12:13], v[10:11]
	s_nop 0
	v_mov_b32_e32 v151, v7
	v_pk_mul_f32 v[6:7], v[4:5], v[14:15] op_sel:[1,1] op_sel_hi:[1,0]
	s_nop 0
	v_pk_fma_f32 v[10:11], v[4:5], v[14:15], v[6:7] neg_lo:[0,0,1] neg_hi:[0,0,1]
	v_pk_fma_f32 v[4:5], v[4:5], v[14:15], v[6:7] op_sel_hi:[0,1,1]
	v_mov_b32_e32 v11, v5
	v_pk_add_f32 v[4:5], v[0:1], v[2:3] op_sel:[0,1] op_sel_hi:[0,1] neg_lo:[0,1] neg_hi:[0,1]
	v_pk_add_f32 v[0:1], v[0:1], v[2:3] op_sel:[1,0] op_sel_hi:[1,0]
	s_nop 0
	v_pk_mul_f32 v[0:1], v[0:1], v[8:9] op_sel:[0,1] op_sel_hi:[1,0]
	s_nop 0
	v_pk_fma_f32 v[2:3], v[4:5], v[8:9], v[0:1] neg_lo:[0,0,1] neg_hi:[0,0,1]
	v_pk_fma_f32 v[0:1], v[4:5], v[8:9], v[0:1]
	v_pk_add_f32 v[4:5], v[152:153], v[10:11] neg_lo:[0,1] neg_hi:[0,1]
	v_mov_b32_e32 v3, v1
	v_pk_add_f32 v[0:1], v[152:153], v[10:11]
	v_pk_add_f32 v[6:7], v[150:151], v[2:3]
	v_pk_add_f32 v[2:3], v[150:151], v[2:3] neg_lo:[0,1] neg_hi:[0,1]
	v_pk_add_f32 v[8:9], v[0:1], v[6:7]
	v_pk_add_f32 v[0:1], v[0:1], v[6:7] neg_lo:[0,1] neg_hi:[0,1]
	v_pk_add_f32 v[6:7], v[4:5], v[2:3] op_sel:[0,1] op_sel_hi:[1,0] neg_lo:[0,1] neg_hi:[0,1]
	v_pk_add_f32 v[10:11], v[4:5], v[2:3] op_sel_hi:[1,0]
	v_pk_add_f32 v[12:13], v[4:5], v[2:3] op_sel:[0,1] op_sel_hi:[1,0]
	v_pk_add_f32 v[2:3], v[4:5], v[2:3] op_sel_hi:[1,0] neg_lo:[0,1] neg_hi:[0,1]
	v_mov_b32_e32 v7, v11
	v_mov_b32_e32 v13, v3
	ds_write2_b64 v171, v[0:1], v[12:13] offset0:2 offset1:3
	v_add_u32_e32 v0, 0x200, v170
	v_ashrrev_i32_e32 v0, 6, v0
	v_and_b32_e32 v0, -4, v0
	v_add_u32_e32 v2, v0, v157
	v_lshlrev_b32_e32 v0, 8, v0
	v_ashrrev_i32_e32 v1, 31, v0
	ds_write2_b64 v171, v[8:9], v[6:7] offset1:1
	v_lshl_add_u64 v[8:9], v[0:1], 3, v[142:143]
	v_ashrrev_i32_e32 v0, 6, v2
	v_lshlrev_b32_e32 v0, 3, v0
	v_lshlrev_b32_e32 v1, 3, v2
	v_add3_u32 v170, 0, v0, v1
	ds_read2_b64 v[0:3], v170 offset1:1
	ds_read2_b64 v[4:7], v170 offset0:2 offset1:3
	global_load_dwordx2 v[10:11], v[8:9], off sc1
	global_load_dwordx2 v[12:13], v[8:9], off offset:2048 sc1
	v_add_co_u32_e32 v8, vcc, s96, v8
	s_waitcnt lgkmcnt(0)
	v_pk_add_f32 v[150:151], v[0:1], v[4:5]
	v_addc_co_u32_e32 v9, vcc, 0, v9, vcc
	global_load_dwordx2 v[14:15], v[8:9], off sc1
	s_nop 0
	global_load_dwordx2 v[8:9], v[8:9], off offset:2048 sc1
	v_pk_add_f32 v[0:1], v[0:1], v[4:5] neg_lo:[0,1] neg_hi:[0,1]
	v_pk_add_f32 v[4:5], v[2:3], v[6:7]
	v_pk_add_f32 v[2:3], v[2:3], v[6:7] neg_lo:[0,1] neg_hi:[0,1]
	v_pk_add_f32 v[6:7], v[150:151], v[4:5]
	v_pk_add_f32 v[4:5], v[150:151], v[4:5] neg_lo:[0,1] neg_hi:[0,1]
	s_waitcnt vmcnt(0)
	v_pk_mul_f32 v[150:151], v[6:7], v[10:11] op_sel:[1,1] op_sel_hi:[1,0]
	s_nop 0
	v_pk_fma_f32 v[152:153], v[6:7], v[10:11], v[150:151] neg_lo:[0,0,1] neg_hi:[0,0,1]
	v_pk_fma_f32 v[6:7], v[6:7], v[10:11], v[150:151] op_sel_hi:[0,1,1]
	v_pk_add_f32 v[10:11], v[0:1], v[2:3] op_sel:[1,0] op_sel_hi:[1,0] neg_lo:[0,1] neg_hi:[0,1]
	v_mov_b32_e32 v153, v7
	v_pk_add_f32 v[6:7], v[0:1], v[2:3] op_sel:[0,1] op_sel_hi:[0,1]
	v_pk_mul_f32 v[10:11], v[10:11], v[12:13] op_sel:[0,1] op_sel_hi:[1,0]
	s_nop 0
	v_pk_fma_f32 v[150:151], v[6:7], v[12:13], v[10:11] neg_lo:[0,0,1] neg_hi:[0,0,1]
	v_pk_fma_f32 v[6:7], v[6:7], v[12:13], v[10:11]
	s_nop 0
	v_mov_b32_e32 v151, v7
	s_waitcnt lgkmcnt(0)
	v_pk_mul_f32 v[6:7], v[4:5], v[14:15] op_sel:[1,1] op_sel_hi:[1,0]
	s_nop 0
	v_pk_fma_f32 v[10:11], v[4:5], v[14:15], v[6:7] neg_lo:[0,0,1] neg_hi:[0,0,1]
	v_pk_fma_f32 v[4:5], v[4:5], v[14:15], v[6:7] op_sel_hi:[0,1,1]
	v_mov_b32_e32 v11, v5
	v_pk_add_f32 v[4:5], v[0:1], v[2:3] op_sel:[0,1] op_sel_hi:[0,1] neg_lo:[0,1] neg_hi:[0,1]
	v_pk_add_f32 v[0:1], v[0:1], v[2:3] op_sel:[1,0] op_sel_hi:[1,0]
	s_nop 0
	v_pk_mul_f32 v[0:1], v[0:1], v[8:9] op_sel:[0,1] op_sel_hi:[1,0]
	s_nop 0
	v_pk_fma_f32 v[2:3], v[4:5], v[8:9], v[0:1] neg_lo:[0,0,1] neg_hi:[0,0,1]
	v_pk_fma_f32 v[0:1], v[4:5], v[8:9], v[0:1]
	v_pk_add_f32 v[4:5], v[152:153], v[10:11] neg_lo:[0,1] neg_hi:[0,1]
	v_mov_b32_e32 v3, v1
	v_pk_add_f32 v[0:1], v[152:153], v[10:11]
	v_pk_add_f32 v[6:7], v[150:151], v[2:3]
	v_pk_add_f32 v[2:3], v[150:151], v[2:3] neg_lo:[0,1] neg_hi:[0,1]
	v_pk_add_f32 v[8:9], v[0:1], v[6:7]
	v_pk_add_f32 v[0:1], v[0:1], v[6:7] neg_lo:[0,1] neg_hi:[0,1]
	v_pk_add_f32 v[6:7], v[4:5], v[2:3] op_sel:[0,1] op_sel_hi:[1,0] neg_lo:[0,1] neg_hi:[0,1]
	v_pk_add_f32 v[10:11], v[4:5], v[2:3] op_sel_hi:[1,0]
	v_pk_add_f32 v[12:13], v[4:5], v[2:3] op_sel:[0,1] op_sel_hi:[1,0]
	v_pk_add_f32 v[2:3], v[4:5], v[2:3] op_sel_hi:[1,0] neg_lo:[0,1] neg_hi:[0,1]
	v_mov_b32_e32 v7, v11
	v_mov_b32_e32 v13, v3
	ds_write2_b64 v170, v[8:9], v[6:7] offset1:1
	ds_write2_b64 v170, v[0:1], v[12:13] offset0:2 offset1:3
	s_cbranch_scc1 .LBB0_572
	s_mov_b32 s6, 0
	s_mov_b64 s[4:5], -1
	s_waitcnt lgkmcnt(0)
	s_barrier

; #define YH ((float*)(wsb(a.ws) + WS_YH))
; __global__ void __launch_bounds__(NTHR, 2) fwd_mega(Args a) {
;     ...
;                     for (int k = 0; k < 2; ++k) { const int ch = 64 * (wave + 8 * k) + cw; float x0_[8], x1_[8];
;                         conv8(pv0 + 512 * 8192, ch, 8192, wb0, wb1, wb2, bb, x0_); conv8(pv1 + 512 * 8192, ch, 8192, wb0, wb1, wb2, bb, x1_);
;                         f32x4 o0a, o0b, o1a, o1b;
; #pragma unroll
;                         for (int e = 0; e < 4; ++e) { const cf ca = X[PX(8 * ch + e)], cb2 = X[PX(8 * ch + 4 + e)]; o0a[e] = x0_[e] * ca.x; o1a[e] = x1_[e] * ca.y; o0b[e] = x0_[4 + e] * cb2.x; o1b[e] = x1_[4 + e] * cb2.y; }
;                         float* y0p = YH + ((size_t)b0 * 256 + c) * 8192 + 8 * ch; float* y1p = YH + ((size_t)b1 * 256 + c) * 8192 + 8 * ch;
;                         *(f32x4*)y0p = o0a; *(f32x4*)(y0p + 4) = o0b; *(f32x4*)y1p = o1a; *(f32x4*)(y1p + 4) = o1b; }
.LBB0_580:
	s_or_b64 exec, exec, s[36:37]
	s_waitcnt vmcnt(0) lgkmcnt(0)
	v_and_b32_e32 v170, 0xffff0000, v0
	v_mov_b32_e32 v14, v170
	v_lshlrev_b32_e32 v4, 16, v0
	v_pk_mul_f32 v[14:15], v[148:149], v[14:15]
	v_lshlrev_b32_e32 v171, 16, v1
	v_pk_fma_f32 v[14:15], v[148:149], v[4:5], v[14:15] op_sel:[0,0,1] op_sel_hi:[1,0,0]
	v_and_b32_e32 v153, 0xffff0000, v3
	v_pk_fma_f32 v[14:15], v[144:145], v[170:171], v[14:15]
	v_and_b32_e32 v173, 16, v3
	v_pk_add_f32 v[178:179], v[130:131], v[14:15]
	v_and_b32_e32 v15, 16, v2
	v_and_b32_e32 v14, 0xffff0000, v1
	v_lshlrev_b32_e32 v1, 16, v2
	v_mov_b32_e32 v0, v14
	v_and_b32_e32 v172, 0xffff0000, v2
	v_lshlrev_b32_e32 v175, 16, v3
	v_pk_mov_b32 v[2:3], v[170:171], v[14:15] op_sel:[1,0]
	v_mov_b32_e32 v174, v172
	v_pk_mov_b32 v[172:173], v[0:1], v[172:173] op_sel:[1,0]
	v_pk_mul_f32 v[2:3], v[146:147], v[2:3]
	v_pk_mul_f32 v[14:15], v[146:147], v[172:173]
	v_pk_fma_f32 v[2:3], v[126:127], v[170:171], v[2:3]
	v_mov_b32_e32 v152, v175
	v_pk_fma_f32 v[2:3], v[144:145], v[0:1], v[2:3]
	v_pk_fma_f32 v[0:1], v[126:127], v[0:1], v[14:15]
	v_mov_b32_e32 v4, v153
	v_pk_fma_f32 v[0:1], v[144:145], v[174:175], v[0:1]
	v_lshlrev_b32_e32 v183, 16, v9
	v_pk_add_f32 v[180:181], v[130:131], v[0:1]
	v_pk_mul_f32 v[0:1], v[146:147], v[152:153]
	v_and_b32_e32 v152, 0xffff0000, v6
	v_pk_fma_f32 v[0:1], v[126:127], v[174:175], v[0:1]
	v_lshlrev_b32_e32 v153, 16, v7
	v_pk_fma_f32 v[0:1], v[144:145], v[4:5], v[0:1]
	v_lshlrev_b32_e32 v4, 3, v150
	v_pk_add_f32 v[14:15], v[130:131], v[0:1]
	v_and_b32_e32 v1, -8, v12
	v_add3_u32 v184, 0, v1, v4
	ds_read2_b64 v[170:173], v184 offset1:1
	ds_read2_b64 v[174:177], v184 offset0:4 offset1:5
	v_mov_b32_e32 v12, v152
	v_lshlrev_b32_e32 v0, 16, v6
	v_pk_mul_f32 v[12:13], v[148:149], v[12:13]
	s_waitcnt lgkmcnt(1)
	v_mov_b32_e32 v4, v170
	v_mov_b32_e32 v5, v172
	v_pk_mul_f32 v[4:5], v[4:5], v[178:179]
	v_pk_fma_f32 v[0:1], v[148:149], v[0:1], v[12:13] op_sel:[0,0,1] op_sel_hi:[1,0,0]
	s_waitcnt lgkmcnt(0)
	v_mov_b32_e32 v12, v174
	v_mov_b32_e32 v13, v176
	v_and_b32_e32 v178, 0xffff0000, v7
	v_pk_mul_f32 v[12:13], v[12:13], v[180:181]
	v_lshlrev_b32_e32 v181, 16, v8
	v_mov_b32_e32 v180, v178
	v_and_b32_e32 v7, 16, v9
	v_and_b32_e32 v6, 0xffff0000, v8
	v_mov_b32_e32 v182, v6
	v_pk_mov_b32 v[6:7], v[180:181], v[6:7] op_sel:[1,0]
	v_pk_fma_f32 v[0:1], v[144:145], v[152:153], v[0:1]
	v_pk_mul_f32 v[6:7], v[146:147], v[6:7]
	v_pk_add_f32 v[0:1], v[130:131], v[0:1]
	v_pk_fma_f32 v[6:7], v[126:127], v[180:181], v[6:7]
	v_mov_b32_e32 v172, v171
	v_pk_fma_f32 v[6:7], v[144:145], v[182:183], v[6:7]
	v_mov_b32_e32 v176, v175
	v_pk_add_f32 v[6:7], v[130:131], v[6:7]
	v_and_b32_e32 v10, 0xffff0000, v9
	v_pk_mul_f32 v[0:1], v[172:173], v[0:1]
	v_and_b32_e32 v179, 16, v8
	v_pk_mul_f32 v[8:9], v[176:177], v[6:7]
	ds_read2_b64 v[170:173], v184 offset0:2 offset1:3
	ds_read2_b64 v[174:177], v184 offset0:6 offset1:7
	v_pk_add_f32 v[2:3], v[130:131], v[2:3]
	s_xor_b64 s[36:37], s[60:61], -1
	s_mov_b64 s[34:35], s[58:59]
	s_waitcnt lgkmcnt(1)
	v_mov_b32_e32 v6, v170
	v_mov_b32_e32 v7, v172
	v_pk_mul_f32 v[6:7], v[6:7], v[2:3]
	v_pk_mov_b32 v[2:3], v[152:153], v[178:179] op_sel:[1,0]
	s_add_u32 s23, s34, s10
	v_pk_mul_f32 v[2:3], v[146:147], v[2:3]
	s_addc_u32 s35, s35, s11
	v_pk_fma_f32 v[2:3], v[126:127], v[152:153], v[2:3]
	s_waitcnt lgkmcnt(0)
	v_mov_b32_e32 v152, v174
	v_mov_b32_e32 v153, v176
	v_pk_mul_f32 v[14:15], v[152:153], v[14:15]
	v_mov_b32_e32 v152, v183
	v_mov_b32_e32 v153, v10
	v_pk_mul_f32 v[152:153], v[146:147], v[152:153]
	s_add_u32 s34, s23, s48
	v_pk_fma_f32 v[152:153], v[126:127], v[182:183], v[152:153]
	s_addc_u32 s35, s35, s49
	v_lshlrev_b64 v[150:151], 2, v[150:151]
	v_pk_fma_f32 v[10:11], v[144:145], v[10:11], v[152:153]
	v_lshl_add_u64 v[152:153], s[34:35], 0, v[150:151]
	s_mov_b64 s[34:35], s[58:59]
	s_add_u32 s23, s34, s12
	s_addc_u32 s35, s35, s13
	s_add_u32 s34, s23, s48
	s_mov_b32 s23, 0xd500000
	v_mov_b32_e32 v172, v171
	v_lshl_add_u64 v[170:171], v[152:153], 0, s[26:27]
	s_addc_u32 s35, s35, s49
	v_add_co_u32_e32 v152, vcc, s23, v152
	v_lshl_add_u64 v[150:151], s[34:35], 0, v[150:151]
	s_nop 0
	v_addc_co_u32_e32 v153, vcc, 0, v153, vcc
	v_pk_fma_f32 v[2:3], v[144:145], v[180:181], v[2:3]
	global_store_dwordx4 v[152:153], v[4:7], off
	global_store_dwordx4 v[170:171], v[12:15], off offset:16
	v_pk_add_f32 v[2:3], v[130:131], v[2:3]
	v_add_co_u32_e32 v4, vcc, 0xd500000, v150
	v_pk_mul_f32 v[2:3], v[172:173], v[2:3]
	s_nop 0
	v_addc_co_u32_e32 v5, vcc, 0, v151, vcc
	v_pk_add_f32 v[10:11], v[130:131], v[10:11]
	v_mov_b32_e32 v176, v175
	s_movk_i32 s23, 0x200
	s_mov_b64 s[60:61], 0
	s_and_b64 vcc, exec, s[36:37]
	v_pk_mul_f32 v[10:11], v[176:177], v[10:11]
	v_lshl_add_u64 v[172:173], v[150:151], 0, s[26:27]
	global_store_dwordx4 v[4:5], v[0:3], off
	global_store_dwordx4 v[172:173], v[8:11], off offset:16
	s_cbranch_vccnz .LBB0_530
; __device__ __forceinline__ float bf2f(bf16_t u) { return __uint_as_float((unsigned)u << 16); }
; __device__ __forceinline__ float bflo(unsigned w) { return __uint_as_float(w << 16); }
; __device__ __forceinline__ float bfhi(unsigned w) { return __uint_as_float(w & 0xffff0000u); }
; #define FILTC ((float*)(wsb(a.ws) + WS_FILTC))
; __device__ __forceinline__ void conv8(const bf16_t* p, int c, int n, float w0, float w1, float w2, float b, float (&o)[8]) {
;     const v4u v = *(const v4u*)(p + 8 * c);
;     const float um = c > 0 ? bf2f(p[8 * c - 1]) : 0.f, up = 8 * c + 8 < n ? bf2f(p[8 * c + 8]) : 0.f;
;     const float u0 = bflo(v.x), u1 = bfhi(v.x), u2 = bflo(v.y), u3 = bfhi(v.y), u4 = bflo(v.z), u5 = bfhi(v.z), u6 = bflo(v.w), u7 = bfhi(v.w);
;     o[0] = w0 * um + w1 * u0 + w2 * u1 + b; o[1] = w0 * u0 + w1 * u1 + w2 * u2 + b; o[2] = w0 * u1 + w1 * u2 + w2 * u3 + b; o[3] = w0 * u2 + w1 * u3 + w2 * u4 + b;
;     o[4] = w0 * u3 + w1 * u4 + w2 * u5 + b; o[5] = w0 * u4 + w1 * u5 + w2 * u6 + b; o[6] = w0 * u5 + w1 * u6 + w2 * u7 + b; o[7] = w0 * u6 + w1 * u7 + w2 * up + b;
; }
; __global__ void __launch_bounds__(NTHR, 2) fwd_mega(Args a) {
;     ...
;                     for (int o = 0; o < 2; ++o) {
;                         const float* hf = FILTC + ((size_t)(0 * 2 + o) * 256 + c) * 256; const float* hb = FILTC + ((size_t)(1 * 2 + o) * 256 + c) * 256;
;                         const float f_ = tid < 256 ? hf[tid] : 0.f, b_ = tid < 256 ? hb[tid] : 0.f;
.LBB0_581:
	v_add_u32_e32 v12, s23, v158
	v_lshlrev_b32_e32 v150, 3, v12
	v_ashrrev_i32_e32 v151, 31, v150
	v_lshl_add_u64 v[6:7], v[150:151], 1, s[4:5]
	global_load_dwordx4 v[0:3], v[6:7], off
	v_cmp_lt_i32_e32 vcc, 0, v12
	v_mov_b32_e32 v5, 0
	v_mov_b32_e32 v15, 0
	s_and_saveexec_b64 s[36:37], vcc
	s_cbranch_execz .LBB0_583
	v_add_co_u32_e64 v8, s[46:47], -2, v6
	s_nop 1
	v_addc_co_u32_e64 v9, s[46:47], -1, v7, s[46:47]
	global_load_ushort v4, v[8:9], off
	s_waitcnt vmcnt(0) lgkmcnt(0)
	v_lshlrev_b32_e32 v15, 16, v4
.LBB0_583:
	s_or_b64 exec, exec, s[36:37]
	v_cmp_gt_i32_e64 s[46:47], s57, v12
	s_and_saveexec_b64 s[36:37], s[46:47]
	s_cbranch_execz .LBB0_585
	global_load_ushort v4, v[6:7], off offset:16
	s_waitcnt vmcnt(0) lgkmcnt(0)
	v_lshlrev_b32_e32 v5, 16, v4
.LBB0_585:
	s_or_b64 exec, exec, s[36:37]
	v_lshl_add_u64 v[152:153], v[150:151], 1, s[6:7]
	global_load_dwordx4 v[6:9], v[152:153], off
	v_mov_b32_e32 v11, 0
	v_mov_b32_e32 v13, 0
	s_and_saveexec_b64 s[36:37], vcc
	s_cbranch_execz .LBB0_587
	v_add_co_u32_e32 v170, vcc, -2, v152
	s_nop 1
	v_addc_co_u32_e32 v171, vcc, -1, v153, vcc
	global_load_ushort v4, v[170:171], off
	s_waitcnt vmcnt(0) lgkmcnt(0)
	v_lshlrev_b32_e32 v13, 16, v4
.LBB0_587:
	s_or_b64 exec, exec, s[36:37]
	s_and_saveexec_b64 s[36:37], s[46:47]
	s_cbranch_execz .LBB0_580
	global_load_ushort v4, v[152:153], off offset:16
	s_waitcnt vmcnt(0) lgkmcnt(0)
	v_lshlrev_b32_e32 v11, 16, v4
	s_branch .LBB0_580
.LBB0_589:
	v_readlane_b32 s4, v255, 10
	v_readlane_b32 s5, v255, 11
	s_and_b64 vcc, exec, s[4:5]
	s_movk_i32 s80, 0x4000
	s_mov_b64 s[84:85], 0x15202000
	s_mov_b32 s81, s78
	s_cbranch_vccz .LBB0_507
	v_mov_b32_e32 v1, v16
	s_mov_b64 s[12:13], s[58:59]
	s_mov_b64 s[6:7], s[58:59]
	s_lshl_b64 s[4:5], s[14:15], 10
	v_mov_b32_e32 v2, 0
	v_mov_b32_e32 v3, 0
	s_and_saveexec_b64 s[10:11], s[42:43]
	s_cbranch_execz .LBB0_592
	s_add_u32 s12, s12, s4
	s_addc_u32 s13, s13, s5
	v_lshl_add_u64 v[4:5], v[16:17], 2, s[12:13]
	v_add_co_u32_e32 v4, vcc, 0x3e00000, v4
	s_nop 1
	v_addc_co_u32_e32 v5, vcc, 0, v5, vcc
	global_load_dword v3, v[4:5], off
.LBB0_592:
	s_or_b64 exec, exec, s[10:11]
	s_and_saveexec_b64 s[10:11], s[42:43]
	s_cbranch_execz .LBB0_594
	s_add_u32 s6, s6, s4
	s_addc_u32 s7, s7, s5
	v_lshl_add_u64 v[4:5], v[16:17], 2, s[6:7]
	v_add_co_u32_e32 v4, vcc, 0x3e80000, v4
	s_nop 1
	v_addc_co_u32_e32 v5, vcc, 0, v5, vcc
	global_load_dword v2, v[4:5], off

; #define FILTC ((float*)(wsb(a.ws) + WS_FILTC))
; __global__ void __launch_bounds__(NTHR, 2) fwd_mega(Args a) {
;     ...
;                     for (int o = 0; o < 2; ++o) {
;                         const float* hf = FILTC + ((size_t)(0 * 2 + o) * 256 + c) * 256; const float* hb = FILTC + ((size_t)(1 * 2 + o) * 256 + c) * 256;
;                         const float f_ = tid < 256 ? hf[tid] : 0.f, b_ = tid < 256 ? hb[tid] : 0.f;
.LBB0_599:
	s_or_b64 exec, exec, s[6:7]
	s_mov_b64 s[12:13], s[58:59]
	s_mov_b64 s[6:7], s[58:59]
	v_mov_b32_e32 v2, 0
	v_mov_b32_e32 v3, 0
	s_and_saveexec_b64 s[10:11], s[42:43]
	s_cbranch_execz .LBB0_601
	s_add_u32 s12, s12, s4
	s_addc_u32 s13, s13, s5
	v_lshl_add_u64 v[4:5], v[16:17], 2, s[12:13]
	v_add_co_u32_e32 v4, vcc, 0x3e40000, v4
	s_nop 1
	v_addc_co_u32_e32 v5, vcc, 0, v5, vcc
	global_load_dword v3, v[4:5], off
.LBB0_601:
	s_or_b64 exec, exec, s[10:11]
	s_and_saveexec_b64 s[10:11], s[42:43]
	s_cbranch_execz .LBB0_603
	s_add_u32 s6, s6, s4
	s_addc_u32 s7, s7, s5
	v_lshl_add_u64 v[4:5], v[16:17], 2, s[6:7]
	v_add_co_u32_e32 v4, vcc, 0x3ec0000, v4
	s_nop 1
	v_addc_co_u32_e32 v5, vcc, 0, v5, vcc
	global_load_dword v2, v[4:5], off

; __device__ __forceinline__ float bf2f(bf16_t u) { return __uint_as_float((unsigned)u << 16); }
; __device__ __forceinline__ float hy_in(const bf16_t* p, int t, int n, float w0, float w1, float w2, float b) {
;     const float um = t > 0 ? bf2f(p[t - 1]) : 0.f, u0 = bf2f(p[t]), up = t < n - 1 ? bf2f(p[t + 1]) : 0.f;
;     return w0 * um + w1 * u0 + w2 * up + b;
; }
; __global__ void __launch_bounds__(NTHR, 2) fwd_mega(Args a) {
;     ...
;                     for (int k = 0; k < 2; ++k) { const int i = tidc + 512 * k, b = i >> 8, t = i & 255; const bf16_t* p = HYRC + ((size_t)b * 768 + c) * 256;
;                         U[i] = hy_in(p, t, 256, wv0, wv1, wv2, bv); XA[i] = hy_in(p + 256 * 256, t, 256, wa0, wa1, wa2, ba); XB[i] = hy_in(p + 512 * 256, t, 256, wb0, wb1, wb2, bb); }
.LBB0_610:
	v_add_u32_e32 v10, s10, v1
	v_lshrrev_b32_e32 v2, 8, v10
	v_mul_hi_i32_i24_e32 v3, 0x300, v2
	v_mul_i32_i24_e32 v2, 0x300, v2
	s_mov_b64 s[10:11], s[58:59]
	v_lshl_add_u64 v[2:3], v[2:3], 0, s[14:15]
	v_lshlrev_b64 v[2:3], 9, v[2:3]
	v_lshl_add_u64 v[2:3], s[10:11], 0, v[2:3]
	s_mov_b64 s[10:11], 0x1ee00000
	v_lshl_add_u64 v[4:5], v[2:3], 0, s[10:11]
	v_mov_b32_e32 v7, 0
	v_mov_b64_e32 v[8:9], 0
	v_lshlrev_b32_e32 v2, 1, v0
	v_mov_b32_e32 v6, 0
	s_and_saveexec_b64 s[10:11], s[46:47]
	s_cbranch_execz .LBB0_612
	v_mov_b32_e32 v3, v209
	v_lshl_add_u64 v[8:9], v[4:5], 0, v[2:3]
	v_add_co_u32_e32 v8, vcc, -2, v8
	s_nop 1
	v_addc_co_u32_e32 v9, vcc, -1, v9, vcc
	global_load_ushort v3, v[8:9], off
	v_mov_b64_e32 v[8:9], v[0:1]
	s_waitcnt vmcnt(0) lgkmcnt(0)
	v_lshlrev_b32_e32 v6, 16, v3
.LBB0_612:
	s_or_b64 exec, exec, s[10:11]
	v_lshlrev_b32_e32 v208, 1, v8
	v_lshl_add_u64 v[8:9], v[4:5], 0, v[208:209]
	global_load_ushort v3, v[8:9], off
	s_and_saveexec_b64 s[10:11], s[48:49]
	s_cbranch_execz .LBB0_614
	global_load_ushort v7, v[8:9], off offset:2
	s_waitcnt vmcnt(0) lgkmcnt(0)
	v_lshlrev_b32_e32 v7, 16, v7
.LBB0_614:
	s_or_b64 exec, exec, s[10:11]
	s_waitcnt vmcnt(0) lgkmcnt(0)
	v_lshlrev_b32_e32 v3, 16, v3
	v_pk_mul_f32 v[6:7], v[138:139], v[6:7]
	v_lshl_add_u32 v12, v10, 2, 0
	v_fma_f32 v3, v125, v3, v6
	v_add_f32_e32 v3, v3, v7
	v_add_f32_e32 v3, v166, v3
	ds_write_b32 v12, v3 offset:4096
	v_lshl_add_u64 v[8:9], v[4:5], 0, s[66:67]
	v_mov_b32_e32 v7, 0
	v_mov_b64_e32 v[10:11], 0
	v_mov_b32_e32 v3, 0
	s_and_saveexec_b64 s[10:11], s[46:47]
	s_cbranch_execz .LBB0_616
	v_mov_b32_e32 v3, v209
	v_lshl_add_u64 v[10:11], v[8:9], 0, v[2:3]
	v_add_co_u32_e32 v10, vcc, -2, v10
	s_nop 1
	v_addc_co_u32_e32 v11, vcc, -1, v11, vcc
	global_load_ushort v3, v[10:11], off
	v_mov_b64_e32 v[10:11], v[0:1]
	s_waitcnt vmcnt(0) lgkmcnt(0)
	v_lshlrev_b32_e32 v3, 16, v3
.LBB0_616:
	s_or_b64 exec, exec, s[10:11]
	v_lshlrev_b32_e32 v208, 1, v10
	v_lshl_add_u64 v[8:9], v[8:9], 0, v[208:209]
	global_load_ushort v6, v[8:9], off
	s_and_saveexec_b64 s[10:11], s[48:49]
	s_cbranch_execz .LBB0_618
	global_load_ushort v7, v[8:9], off offset:2
	s_waitcnt vmcnt(0) lgkmcnt(0)
	v_lshlrev_b32_e32 v7, 16, v7
.LBB0_618:
	s_or_b64 exec, exec, s[10:11]
	s_waitcnt vmcnt(0) lgkmcnt(0)
	v_lshlrev_b32_e32 v6, 16, v6
	v_pk_mul_f32 v[6:7], v[140:141], v[6:7]
	s_mov_b64 s[10:11], 0x40000
	v_fma_f32 v3, v167, v3, v6
	v_add_f32_e32 v3, v3, v7
	v_add_f32_e32 v3, v168, v3
	v_lshl_add_u64 v[6:7], v[4:5], 0, s[10:11]
	v_mov_b32_e32 v5, 0
	v_mov_b64_e32 v[8:9], 0
	v_mov_b32_e32 v10, 0
	ds_write_b32 v12, v3 offset:8192
	s_and_saveexec_b64 s[10:11], s[46:47]
	s_cbranch_execz .LBB0_620
	v_mov_b32_e32 v3, v209
	v_lshl_add_u64 v[2:3], v[6:7], 0, v[2:3]
	v_add_co_u32_e32 v2, vcc, -2, v2
	v_mov_b64_e32 v[8:9], v[0:1]
	s_nop 0
	v_addc_co_u32_e32 v3, vcc, -1, v3, vcc
	global_load_ushort v2, v[2:3], off
	s_waitcnt vmcnt(0) lgkmcnt(0)
	v_lshlrev_b32_e32 v10, 16, v2
.LBB0_620:
	s_or_b64 exec, exec, s[10:11]
	v_lshlrev_b32_e32 v208, 1, v8
	v_lshl_add_u64 v[2:3], v[6:7], 0, v[208:209]
	global_load_ushort v4, v[2:3], off
	s_and_saveexec_b64 s[10:11], s[48:49]
	s_cbranch_execz .LBB0_609
	global_load_ushort v2, v[2:3], off offset:2
	s_waitcnt vmcnt(0) lgkmcnt(0)
	v_lshlrev_b32_e32 v5, 16, v2
	s_branch .LBB0_609

; #define LAS __attribute__((address_space(3)))
; #define YHC ((float*)(wsb(a.ws) + WS_YHC))
; __global__ void __launch_bounds__(NTHR, 2) fwd_mega(Args a) {
;     ...
; #pragma unroll 1
;                     for (int k = 0; k < 2; ++k) { const int i = tidc + 512 * k, b = i >> 8, t = i & 255; float acc = 0.f; const LAS float* kp = KC + 512 + 255 + t; const LAS float* up = Z1 + b * 256;
; #pragma unroll 8
;                         for (int s = 0; s < 256; ++s) acc += kp[-s] * up[s];
;                         YHC[((size_t)b * 256 + c) * 256 + t] = XB[i] * (acc + bias2 * Z1[i]); }
.LBB0_628:
	ds_read2_b32 v[124:125], v6 offset0:6 offset1:7
	v_add_u32_e32 v7, s10, v5
	ds_read_b128 v[8:11], v7
	ds_read_b128 v[12:15], v7 offset:16
	s_add_i32 s10, s10, 32
	s_cmpk_eq_i32 s10, 0x400
	s_waitcnt lgkmcnt(0)
	v_fmac_f32_e32 v3, v125, v8
	v_fmac_f32_e32 v3, v124, v9
	ds_read2_b32 v[8:9], v6 offset0:4 offset1:5
	s_waitcnt lgkmcnt(0)
	v_fmac_f32_e32 v3, v9, v10
	v_fmac_f32_e32 v3, v8, v11
	ds_read2_b32 v[8:9], v6 offset0:2 offset1:3
	s_waitcnt lgkmcnt(0)
	v_fmac_f32_e32 v3, v9, v12
	v_fmac_f32_e32 v3, v8, v13
	ds_read2_b32 v[8:9], v6 offset1:1
	v_subrev_u32_e32 v6, 32, v6
	s_waitcnt lgkmcnt(0)
	v_fmac_f32_e32 v3, v9, v14
	v_fmac_f32_e32 v3, v8, v15
	s_cbranch_scc0 .LBB0_628
	v_lshl_add_u32 v5, v4, 2, 0
	v_ashrrev_i32_e32 v4, 8, v4
	ds_read2st64_b32 v[6:7], v5 offset0:48 offset1:64
	v_ashrrev_i32_e32 v5, 31, v4
	s_mov_b64 s[10:11], s[58:59]
	v_lshlrev_b64 v[4:5], 18, v[4:5]
	v_lshlrev_b32_e32 v208, 2, v0
	v_lshl_add_u64 v[4:5], s[10:11], 0, v[4:5]
	v_lshl_add_u64 v[4:5], v[4:5], 0, s[4:5]
	v_lshl_add_u64 v[4:5], v[4:5], 0, v[208:209]
	v_add_co_u32_e32 v4, vcc, 0xf500000, v4
	s_waitcnt lgkmcnt(0)
	v_fmac_f32_e32 v3, v164, v7
	v_addc_co_u32_e32 v5, vcc, 0, v5, vcc
	v_mul_f32_e32 v3, v6, v3
	s_movk_i32 s12, 0x200
	s_mov_b64 s[10:11], 0
	s_and_b64 vcc, exec, s[6:7]
	global_store_dword v[4:5], v3, off
	s_cbranch_vccz .LBB0_627
	s_waitcnt lgkmcnt(0)
	s_barrier
	s_branch .LBB0_507

; __device__ __forceinline__ int crow(int r,int hi){return (r&3)+8*(r>>2)+4*hi;}
; template<int THRL,bool DV128,int PQ,int PK,int PV,int PO> __device__ __forceinline__ void attn_unit(const bf16*Qb,const bf16*__restrict__ Kb,const bf16*__restrict__ Vb,bf16*Ob,const int NT,char*shm,const int wave0){
;     ...
;   for(int r=0;r<16;++r)rli[r]=__builtin_amdgcn_rcpf(wsf[32+crow(r,hi)]);
;   bf16*Ow=Ob+(long)(wid*QBLK)*PO;
;   { bf16*stg=(bf16*)(shm+L_OST)+wid*2048;
;     #pragma unroll
;     for(int hf=0;hf<VS;++hf){
;       #pragma unroll
;       for(int r=0;r<16;++r){const int orow=crow(r,hi);
;         #pragma unroll
;         for(int d0=0;d0<2;++d0)stg[orow*64+d0*32+r32]=__float2bfloat16(o[2*hf+d0][r]*rli[r]);}
;       asm volatile("s_waitcnt lgkmcnt(0)":::"memory");
;       #pragma unroll
;       for(int i=0;i<4;++i){const int row=i*8+(lane>>3),ch=lane&7; const u32x4 v=*(const u32x4*)(stg+row*64+ch*8); ATTN_STORE16(Ow+(long)row*PO+hf*64+ch*8,v);}
;       asm volatile("s_waitcnt lgkmcnt(0)":::"memory"); } }
;   asm volatile("s_waitcnt lgkmcnt(0)\n\ts_barrier":::"memory");
.LBB0_637:
	s_or_b64 exec, exec, s[12:13]
	s_waitcnt lgkmcnt(0)
	ds_read_b128 v[32:35], v48 offset:49280
	ds_read_b128 v[36:39], v48 offset:49312
	s_lshl_b32 s7, s46, 1
	s_add_u32 s7, s10, s7
	s_addc_u32 s10, s11, 0
	s_waitcnt lgkmcnt(1)
	v_rcp_f32_e32 v40, v32
	s_mul_hi_i32 s11, s4, 0xa00
	s_mulk_i32 s4, 0xa00
	s_add_u32 s4, s7, s4
	v_rcp_f32_e32 v41, v33
	s_addc_u32 s7, s10, s11
	s_lshl_b32 s5, s5, 12
	v_rcp_f32_e32 v42, v34
	v_rcp_f32_e32 v43, v35
	s_waitcnt lgkmcnt(0)
	v_rcp_f32_e32 v44, v36
	ds_read_b128 v[32:35], v48 offset:49344
	v_rcp_f32_e32 v45, v37
	v_rcp_f32_e32 v46, v38
	v_rcp_f32_e32 v47, v39
	ds_read_b128 v[36:39], v48 offset:49376
	s_add_i32 s11, s5, 0
	v_lshlrev_b32_e32 v48, 1, v197
	v_lshlrev_b32_e32 v49, 9, v198
	v_mul_f32_e32 v0, v0, v40
	v_add3_u32 v48, s11, v48, v49
	v_cvt_pk_bf16_f32 v0, v0, s0
	ds_write_b16 v48, v0 offset:51264
	v_mul_f32_e32 v0, v17, v41
	v_cvt_pk_bf16_f32 v0, v0, s0
	ds_write_b16 v48, v0 offset:51328
	v_mul_f32_e32 v0, v1, v41
	v_cvt_pk_bf16_f32 v0, v0, s0
	ds_write_b16 v48, v0 offset:51392
	v_mul_f32_e32 v0, v18, v42
	v_cvt_pk_bf16_f32 v0, v0, s0
	ds_write_b16 v48, v0 offset:51456
	v_mul_f32_e32 v0, v2, v42
	v_cvt_pk_bf16_f32 v0, v0, s0
	ds_write_b16 v48, v0 offset:51520
	v_mul_f32_e32 v0, v19, v43
	v_cvt_pk_bf16_f32 v0, v0, s0
	ds_write_b16 v48, v0 offset:51584
	v_mul_f32_e32 v0, v3, v43
	v_cvt_pk_bf16_f32 v0, v0, s0
	ds_write_b16 v48, v0 offset:51648
	v_mul_f32_e32 v0, v20, v44
	v_cvt_pk_bf16_f32 v0, v0, s0
	ds_write_b16 v48, v0 offset:52224
	v_mul_f32_e32 v0, v4, v44
	v_cvt_pk_bf16_f32 v0, v0, s0
	ds_write_b16 v48, v0 offset:52288
	v_mul_f32_e32 v0, v21, v45
	v_cvt_pk_bf16_f32 v0, v0, s0
	ds_write_b16 v48, v0 offset:52352
	v_mul_f32_e32 v0, v5, v45
	v_cvt_pk_bf16_f32 v0, v0, s0
	ds_write_b16 v48, v0 offset:52416
	v_mul_f32_e32 v0, v22, v46
	v_cvt_pk_bf16_f32 v0, v0, s0
	ds_write_b16 v48, v0 offset:52480
	v_mul_f32_e32 v0, v6, v46
	v_cvt_pk_bf16_f32 v0, v0, s0
	s_waitcnt lgkmcnt(13)
	v_rcp_f32_e32 v32, v32
	ds_write_b16 v48, v0 offset:52544
	v_mul_f32_e32 v0, v23, v47
	v_cvt_pk_bf16_f32 v0, v0, s0
	ds_write_b16 v48, v0 offset:52608
	v_mul_f32_e32 v0, v7, v47
	v_cvt_pk_bf16_f32 v0, v0, s0
	v_rcp_f32_e32 v33, v33
	ds_write_b16 v48, v0 offset:52672
	v_mul_f32_e32 v0, v24, v32
	v_cvt_pk_bf16_f32 v0, v0, s0
	ds_write_b16 v48, v0 offset:53248
	v_mul_f32_e32 v0, v8, v32
	v_cvt_pk_bf16_f32 v0, v0, s0
	v_rcp_f32_e32 v34, v34
	ds_write_b16 v48, v0 offset:53312
	v_mul_f32_e32 v0, v25, v33
	v_cvt_pk_bf16_f32 v0, v0, s0
	ds_write_b16 v48, v0 offset:53376
	v_mul_f32_e32 v0, v9, v33
	v_cvt_pk_bf16_f32 v0, v0, s0
	v_rcp_f32_e32 v35, v35
	ds_write_b16 v48, v0 offset:53440
	v_mul_f32_e32 v0, v26, v34
	v_cvt_pk_bf16_f32 v0, v0, s0
	ds_write_b16 v48, v0 offset:53504
	v_mul_f32_e32 v0, v10, v34
	v_cvt_pk_bf16_f32 v0, v0, s0
	s_waitcnt lgkmcnt(14)
	v_rcp_f32_e32 v36, v36
	ds_write_b16 v48, v0 offset:53568
	v_mul_f32_e32 v0, v27, v35
	v_cvt_pk_bf16_f32 v0, v0, s0
	ds_write_b16 v48, v0 offset:53632
	v_mul_f32_e32 v0, v11, v35
	v_cvt_pk_bf16_f32 v0, v0, s0
	v_rcp_f32_e32 v37, v37
	ds_write_b16 v48, v0 offset:53696
	v_mul_f32_e32 v0, v28, v36
	v_cvt_pk_bf16_f32 v0, v0, s0
	ds_write_b16 v48, v0 offset:54272
	v_mul_f32_e32 v0, v12, v36
	v_cvt_pk_bf16_f32 v0, v0, s0
	v_rcp_f32_e32 v38, v38
	ds_write_b16 v48, v0 offset:54336
	v_mul_f32_e32 v0, v29, v37
	v_cvt_pk_bf16_f32 v0, v0, s0
	ds_write_b16 v48, v0 offset:54400
	v_mul_f32_e32 v0, v13, v37
	v_cvt_pk_bf16_f32 v0, v0, s0
	v_rcp_f32_e32 v39, v39
	ds_write_b16 v48, v0 offset:54464
	v_mul_f32_e32 v0, v30, v38
	v_cvt_pk_bf16_f32 v0, v0, s0
	ds_write_b16 v48, v0 offset:54528
	v_mul_f32_e32 v0, v14, v38
	v_cvt_pk_bf16_f32 v0, v0, s0
	ds_write_b16 v48, v0 offset:54592
	v_mul_f32_e32 v0, v31, v39
	v_cvt_pk_bf16_f32 v0, v0, s0
	v_mul_f32_e32 v16, v16, v40
	ds_write_b16 v48, v0 offset:54656
	v_mul_f32_e32 v0, v15, v39
	v_lshlrev_b32_e32 v49, 1, v199
	v_cvt_pk_bf16_f32 v16, v16, s0
	v_cvt_pk_bf16_f32 v0, v0, s0
	v_lshrrev_b32_e32 v6, 3, v196
	s_mul_hi_i32 s10, s6, 0xa00
	s_mulk_i32 s6, 0xa00
	v_and_b32_e32 v208, 0x70, v49
	ds_write_b16 v48, v16 offset:51200
	ds_write_b16 v48, v0 offset:54720
	v_lshlrev_b32_e32 v0, 7, v6
	s_add_u32 s4, s4, s6
	s_waitcnt lgkmcnt(0)
	v_add3_u32 v8, s11, v208, v0
	s_addc_u32 s5, s7, s10
	ds_read_b128 v[0:3], v8 offset:51200
	v_mul_u32_u24_e32 v6, 0x500, v6
	v_lshl_add_u64 v[4:5], s[4:5], 0, v[208:209]
	v_lshlrev_b32_e32 v208, 1, v6
	v_lshl_add_u64 v[4:5], v[4:5], 0, v[208:209]
	s_mov_b32 s4, 0x8200000
	v_add_co_u32_e32 v6, vcc, s4, v4
	s_mov_b32 s4, 0x8205000
	s_nop 0
	v_addc_co_u32_e32 v7, vcc, 0, v5, vcc
	s_waitcnt lgkmcnt(0)
	global_store_dwordx4 v[6:7], v[0:3], off
	ds_read_b128 v[0:3], v8 offset:52224
	v_add_co_u32_e32 v6, vcc, s4, v4
	s_add_i32 s23, s23, s54
	s_nop 0
	v_addc_co_u32_e32 v7, vcc, 0, v5, vcc
	s_waitcnt lgkmcnt(0)
	global_store_dwordx4 v[6:7], v[0:3], off
	ds_read_b128 v[0:3], v8 offset:53248
	v_add_co_u32_e32 v6, vcc, 0x820a000, v4
	s_cmp_ge_i32 s23, s48
	s_nop 0
	v_addc_co_u32_e32 v7, vcc, 0, v5, vcc
	s_waitcnt lgkmcnt(0)
	global_store_dwordx4 v[6:7], v[0:3], off
	ds_read_b128 v[0:3], v8 offset:54272
	v_add_co_u32_e32 v4, vcc, 0x820f000, v4
	s_nop 1
	v_addc_co_u32_e32 v5, vcc, 0, v5, vcc
	s_waitcnt lgkmcnt(0)
	global_store_dwordx4 v[4:5], v[0:3], off
	s_waitcnt lgkmcnt(0)
	s_waitcnt lgkmcnt(0)
	s_barrier
	s_cbranch_scc1 .LBB0_632

; __device__ __forceinline__ int lane_id_v() { int l; asm volatile("v_mbcnt_lo_u32_b32 %0, -1, 0\n\tv_mbcnt_hi_u32_b32 %0, -1, %0" : "=v"(l)); return l; }
; #define WAIT_BAR(N) asm volatile("s_waitcnt vmcnt(" #N ") lgkmcnt(0)\n\ts_barrier":::"memory")
;   #define DMA_K(t,slot) glds16(ksrc+(long)(t)*KVBLK*PK,(unsigned)__builtin_amdgcn_readfirstlane(kdst+(slot)))
;   #define DMA_V(t,slot) do{ glds16(vsrc+(long)(t)*KVBLK*PV,(unsigned)__builtin_amdgcn_readfirstlane(vdst+VS*(slot))); if constexpr(DV128){ glds16(vsrc+64+(long)(t)*KVBLK*PV,(unsigned)__builtin_amdgcn_readfirstlane(vdst+VS*(slot)+8192)); } }while(0)
; template<int THRL,bool DV128,int PQ,int PK,int PV,int PO> __device__ __forceinline__ void attn_unit(const bf16*Qb,const bf16*__restrict__ Kb,const bf16*__restrict__ Vb,bf16*Ob,const int NT,char*shm,const int wave0){
;   int tid_o=wave0*64+lane_id_v(); asm volatile("":"+v"(tid_o)); const int tid=tid_o,lane=tid&63,r32=lane&31,hi=lane>>5; const int wid=__builtin_amdgcn_readfirstlane(tid>>6);
;   const bf16*Qw=Qb+(long)(wid*QBLK)*PQ;
;   const bf16*Kh=Kb,*Vh=Vb;
;   const unsigned lds0=(unsigned)(uintptr_t)shm;
;   constexpr int VS=DV128?2:1, L_WS=LDS_V+NSLOT*SLOTB*VS, L_OST=L_WS+NW*64*4;
;   float*wsf=(float*)(shm+L_WS)+wid*64;
;   const bf16*ksrc=Kh+(long)lane*PK+wid*8;
;   const bf16*vsrc=Vh+(long)(16*(wid&3)+(lane>>2))*PV+(wid>>2)*32+(lane&3)*8;
;   const unsigned kdst=lds0+LDS_K+wid*1024, vdst=lds0+LDS_V+wid*1024;
;     ...
;   const char*Kbase=shm+LDS_K; bf16x8 kf[8];
;   const lds_cptr shm3=(lds_cptr)shm; const lds_cptr kp0=shm3+LDS_K+hi*1024+r32*16; const lds_cptr vp0=shm3+LDS_V+((lane>>4)&1)*32+(lane&3)*8+(4*hi+((lane&15)>>2))*64;
;   DMA_K(0,0);DMA_V(0,0);DMA_K(1,SLOTB);
;   bf16x8 qr[4];
;   #pragma unroll
;   for(int d0=0;d0<4;++d0)qr[d0]=*reinterpret_cast<const bf16x8*>(&Qw[(long)r32*PQ+d0*16+hi*8]);
;   float mhat=0.f,l_reg=0.f;f32x16 o[4];o[0]=f32x16{};o[1]=f32x16{};o[2]=f32x16{};o[3]=f32x16{};f32x16 negm=f32x16{};asm volatile("":"+v"(negm));
;     ...
;   bool resc=false;
;     ...
;   f32x16 pA0,pA1,pB0,pB1;
;   int sl_prev=0,sl_cur=0,sl_next=SLOTB;
;     ...
;   DMA_K(2,2*SLOTB);
;   WAIT_BAR(3);
.LBB0_642:
	s_and_b32 s61, s10, 3
	s_mov_b64 s[6:7], s[58:59]
	s_lshl_b32 s5, s61, 7
	s_add_u32 s12, s6, s5
	s_addc_u32 s13, s7, 0
	s_ashr_i32 s5, s4, 31
	s_lshl_b64 s[6:7], s[4:5], 9
	s_add_u32 s35, s12, s6
	s_addc_u32 s44, s13, s7
	s_lshl_b32 s65, s11, 1
	s_bfe_u32 s66, s10, 0x10001
	s_or_b32 s5, s65, s66
	s_mov_b64 s[12:13], s[58:59]
	s_mul_hi_i32 s6, s5, 0x108000
	s_mul_i32 s5, s5, 0x108000
	s_add_u32 s36, s12, s5
	s_mov_b64 s[14:15], s[58:59]
	s_mov_b64 s[10:11], s[58:59]
	s_addc_u32 s37, s13, s6
	v_mbcnt_lo_u32_b32 v0, -1, 0
	v_mbcnt_hi_u32_b32 v0, -1, v0
	s_add_u32 s40, s14, s5
	v_add_u32_e32 v84, s89, v0
	s_addc_u32 s41, s15, s6
	v_readfirstlane_b32 s67, v84
	s_ashr_i32 s5, s67, 6
	s_lshl_b32 s6, s5, 5
	s_ashr_i32 s7, s6, 31
	s_lshl_b64 s[42:43], s[6:7], 9
	s_add_u32 s42, s35, s42
	s_addc_u32 s43, s44, s43
	s_lshl_b32 s35, s5, 4
	v_bfe_u32 v190, v84, 2, 4
	v_and_b32_e32 v196, 63, v84
	v_and_or_b32 v2, s35, 48, v190
	v_lshlrev_b32_e32 v208, 4, v196
	v_lshlrev_b32_e32 v2, 7, v2
	v_mov_b32_e32 v3, v209
	s_ashr_i32 s35, s67, 3
	v_lshl_add_u64 v[0:1], s[36:37], 0, v[208:209]
	s_lshl_b32 s36, s5, 9
	v_lshl_add_u64 v[2:3], s[40:41], 0, v[2:3]
	s_and_b32 s40, s35, 0xffffffe0
	v_lshlrev_b32_e32 v199, 3, v84
	s_ashr_i32 s37, s36, 31
	s_ashr_i32 s41, s40, 31
	v_and_b32_e32 v56, 24, v199
	s_and_b32 s7, s67, 0x3fffffc0
	v_lshl_add_u64 v[80:81], s[36:37], 1, v[0:1]
	s_mov_b64 s[44:45], 0x14900000
	v_lshl_add_u64 v[2:3], s[40:41], 1, v[2:3]
	v_lshlrev_b32_e32 v4, 1, v56
	v_mov_b32_e32 v5, v209
	s_lshl_b32 s35, s5, 10
	v_lshl_add_u64 v[0:1], v[80:81], 0, s[44:45]
	v_lshl_add_u64 v[82:83], v[2:3], 0, v[4:5]
	s_mov_b64 s[44:45], 0x15200000
	s_cmp_lg_u32 0, -1
	v_lshl_add_u64 v[2:3], v[82:83], 0, s[44:45]
	s_cselect_b32 s44, 0, 0
	s_add_i32 s35, s35, s44
	s_mov_b32 s44, m0
	s_mov_b32 m0, s35
	s_nop 0
	global_load_lds_dwordx4 v[0:1], off
	s_mov_b32 m0, s44
	s_add_i32 s49, s35, 0x6000
	s_mov_b32 s44, m0
	s_mov_b32 m0, s49
	s_nop 0
	global_load_lds_dwordx4 v[2:3], off
	s_mov_b32 m0, s44
	s_mov_b64 s[44:45], 0x14902000
	v_and_b32_e32 v197, 31, v84
	v_lshl_add_u64 v[0:1], v[80:81], 0, s[44:45]
	v_bfe_u32 v198, v84, 5, 1
	s_add_i32 s44, s35, 0x2000
	s_mov_b32 s45, m0
	s_mov_b32 m0, s44
	s_nop 0
	global_load_lds_dwordx4 v[0:1], off
	s_mov_b32 m0, s45
	v_lshlrev_b32_e32 v0, 9, v197
	v_lshl_or_b32 v0, v198, 4, v0
	v_mov_b32_e32 v1, v209
	v_lshl_add_u64 v[0:1], s[42:43], 0, v[0:1]
	s_mov_b32 s42, 0x13800000
	v_add_co_u32_e32 v2, vcc, s42, v0
	s_mov_b64 s[42:43], 0x13800000
	s_nop 0
	v_addc_co_u32_e32 v3, vcc, 0, v1, vcc
	global_load_dwordx4 v[140:143], v[2:3], off
	v_lshl_add_u64 v[0:1], v[0:1], 0, s[42:43]
	global_load_dwordx4 v[132:135], v[0:1], off offset:32
	global_load_dwordx4 v[120:123], v[0:1], off offset:64
	global_load_dwordx4 v[112:115], v[0:1], off offset:96
	v_lshlrev_b32_e32 v2, 10, v198
	v_lshlrev_b32_e32 v3, 4, v197
	v_mov_b32_e32 v14, v209
	v_mov_b32_e32 v15, v209
	v_add3_u32 v202, 0, v2, v3
	v_mov_b32_e32 v0, v209
	v_mov_b32_e32 v1, v209
	v_mov_b32_e32 v2, v209
	v_mov_b32_e32 v3, v209
	v_mov_b32_e32 v4, v209
	v_mov_b32_e32 v6, v209
	v_mov_b32_e32 v7, v209
	v_mov_b32_e32 v8, v209
	v_mov_b32_e32 v9, v209
	v_mov_b32_e32 v10, v209
	v_mov_b32_e32 v11, v209
	v_mov_b32_e32 v12, v209
	v_mov_b32_e32 v13, v209
	v_mov_b64_e32 v[30:31], v[14:15]
	v_mov_b64_e32 v[28:29], v[12:13]
	v_mov_b64_e32 v[26:27], v[10:11]
	v_mov_b64_e32 v[24:25], v[8:9]
	v_mov_b64_e32 v[22:23], v[6:7]
	v_mov_b64_e32 v[20:21], v[4:5]
	v_mov_b64_e32 v[18:19], v[2:3]
	v_mov_b64_e32 v[16:17], v[0:1]
	s_mov_b64 s[42:43], 0x14904000
	v_lshl_add_u64 v[32:33], v[80:81], 0, s[42:43]
	s_add_i32 s42, s35, 0x4000
	s_mov_b32 s43, m0
	s_mov_b32 m0, s42
	s_nop 0
	global_load_lds_dwordx4 v[32:33], off
	s_mov_b32 m0, s43
	s_waitcnt vmcnt(3) lgkmcnt(0)
	s_barrier
; __device__ __forceinline__ float max3f(float a,float b,float c){float r;asm("v_max3_f32 %0, %1, %2, %3":"=v"(r):"v"(a),"v"(b),"v"(c));return r;}
; __device__ __forceinline__ void qkt(f32x16&p0,f32x16&p1,const char*Kslot,const bf16x8*qr,const f32x16&negm,int r32,int hi){
;   const char*kb=Kslot+hi*1024+r32*16;
;   #pragma unroll
;   for(int d0=0;d0<4;++d0){
;     const bf16x8 b0=*reinterpret_cast<const bf16x8*>(kb+d0*2048);
;     const bf16x8 b1=*reinterpret_cast<const bf16x8*>(kb+d0*2048+512);
;     if(d0==0){p0=__builtin_amdgcn_mfma_f32_32x32x16_bf16(b0,qr[0],negm,0,0,0);p1=__builtin_amdgcn_mfma_f32_32x32x16_bf16(b1,qr[0],negm,0,0,0);}
;     else{p0=__builtin_amdgcn_mfma_f32_32x32x16_bf16(b0,qr[d0],p0,0,0,0);p1=__builtin_amdgcn_mfma_f32_32x32x16_bf16(b1,qr[d0],p1,0,0,0);}}
; }
; __device__ __forceinline__ void kload8(bf16x8*kf,lds_cptr kp){
;   kf[0]=*(const __attribute__((address_space(3))) bf16x8*)(kp);      kf[1]=*(const __attribute__((address_space(3))) bf16x8*)(kp+512);
;   kf[2]=*(const __attribute__((address_space(3))) bf16x8*)(kp+2048); kf[3]=*(const __attribute__((address_space(3))) bf16x8*)(kp+2560);
;   kf[4]=*(const __attribute__((address_space(3))) bf16x8*)(kp+4096); kf[5]=*(const __attribute__((address_space(3))) bf16x8*)(kp+4608);
;   kf[6]=*(const __attribute__((address_space(3))) bf16x8*)(kp+6144); kf[7]=*(const __attribute__((address_space(3))) bf16x8*)(kp+6656);
; }
; __device__ __forceinline__ void kload2(bf16x8*kf,lds_cptr kp,int j){ kf[2*j]=*(const __attribute__((address_space(3))) bf16x8*)(kp+j*2048); kf[2*j+1]=*(const __attribute__((address_space(3))) bf16x8*)(kp+j*2048+512); }
; __device__ __forceinline__ s16x4 vtr(lds_cptr p){ return __builtin_bit_cast(s16x4,__builtin_amdgcn_ds_read_tr16_b64_v4i16((__attribute__((address_space(3))) v4i16_t*)p)); }
; __device__ __forceinline__ float rowmax(const f32x16&p0,const f32x16&p1){
;   float a=max3f(p0[0],p0[1],p1[0]),b=max3f(p0[2],p0[3],p1[1]);a=max3f(a,p1[2],p1[3]);
;   #pragma unroll
;   for(int r=4;r<16;r+=4){a=max3f(a,p0[r],p0[r+1]);b=max3f(b,p0[r+2],p0[r+3]);a=max3f(a,p1[r],p1[r+1]);b=max3f(b,p1[r+2],p1[r+3]);}
;   const float m=max2f(a,b);
;   auto rr=__builtin_amdgcn_permlane32_swap(__float_as_uint(m),__float_as_uint(m),false,false);
;   return max2f(__uint_as_float(rr[0]),__uint_as_float(rr[1]));
; }
	ds_read_b128 v[48:51], v202
	ds_read_b128 v[52:55], v202 offset:512
	s_waitcnt vmcnt(0) lgkmcnt(0)
	v_mfma_f32_32x32x16_bf16 v[32:47], v[48:51], v[140:143], v[16:31]
	v_lshlrev_b32_e32 v57, 1, v84
	s_lshl_b32 s7, s7, 2
	v_lshlrev_b32_e32 v85, 8, v198
	s_add_i32 s7, s7, 0
	s_mov_b32 s44, 1
	s_mov_b32 s68, 0
	s_movk_i32 s60, 0x2000
	v_mfma_f32_32x32x16_bf16 v[16:31], v[52:55], v[140:143], v[16:31]
	ds_read_b128 v[48:51], v202 offset:2048
	ds_read_b128 v[52:55], v202 offset:2560
	s_movk_i32 s47, 0x4000
	s_andn2_b64 vcc, exec, s[38:39]
	v_cmp_gt_u32_e64 s[38:39], 32, v196
	v_lshlrev_b32_e32 v204, 4, v198
	v_lshl_add_u32 v200, v197, 2, s7
	s_waitcnt lgkmcnt(1)
	v_mfma_f32_32x32x16_bf16 v[32:47], v[48:51], v[132:135], v[32:47]
	s_waitcnt lgkmcnt(0)
	v_mfma_f32_32x32x16_bf16 v[16:31], v[52:55], v[132:135], v[16:31]
	ds_read_b128 v[48:51], v202 offset:4096
	ds_read_b128 v[52:55], v202 offset:4608
	s_waitcnt lgkmcnt(1)
	v_mfma_f32_32x32x16_bf16 v[32:47], v[48:51], v[120:123], v[32:47]
	ds_read_b128 v[48:51], v202 offset:6144
	s_waitcnt lgkmcnt(1)
	v_mfma_f32_32x32x16_bf16 v[16:31], v[52:55], v[120:123], v[16:31]
	ds_read_b128 v[52:55], v202 offset:6656
	s_waitcnt lgkmcnt(1)
	v_mfma_f32_32x32x16_bf16 v[32:47], v[48:51], v[112:115], v[32:47]
	v_lshlrev_b32_e32 v48, 4, v84
	v_and_b32_e32 v49, 32, v57
	v_and_b32_e32 v87, 0xc0, v48
	v_add3_u32 v86, 0, v49, v56
	v_add3_u32 v203, v86, v85, v87
	s_waitcnt lgkmcnt(0)
	v_mfma_f32_32x32x16_bf16 v[16:31], v[52:55], v[112:115], v[16:31]
	s_nop 15
	s_nop 7
	s_nop 0
	v_max3_f32 v48, v32, v33, v16
	v_max3_f32 v49, v34, v35, v17
	s_nop 0
	v_max3_f32 v48, v48, v18, v19
	v_max3_f32 v49, v49, v38, v39
	s_nop 0
	v_max3_f32 v48, v48, v36, v37
	v_max3_f32 v49, v49, v22, v23
	s_nop 0
	v_max3_f32 v48, v48, v20, v21
	v_max3_f32 v49, v49, v42, v43
	s_nop 0
	v_max3_f32 v48, v48, v40, v41
	v_max3_f32 v49, v49, v26, v27
	s_nop 0
	v_max3_f32 v48, v48, v24, v25
	v_max3_f32 v49, v49, v46, v47
	s_nop 0
	v_max3_f32 v48, v48, v44, v45
	v_max3_f32 v49, v49, v30, v31
	s_nop 0
	v_max3_f32 v48, v48, v28, v29
	s_nop 0
	v_max_f32_e32 v48, v48, v49
	s_nop 0
	v_mov_b32_e32 v49, v48
	s_nop 1
	v_permlane32_swap_b32_e32 v48, v49
	v_max_f32_e32 v48, v48, v49
	s_nop 0
	v_add_f32_e32 v201, v209, v48
	v_sub_f32_e32 v49, v32, v48
	v_sub_f32_e32 v50, v33, v48
	v_sub_f32_e32 v51, v34, v48
	v_sub_f32_e32 v52, v35, v48
	v_sub_f32_e32 v53, v36, v48
	s_nop 0
	v_xor_b32_e32 v32, 0x80000000, v201
	v_sub_f32_e32 v54, v37, v48
	v_sub_f32_e32 v55, v38, v48
	v_sub_f32_e32 v56, v39, v48
	v_sub_f32_e32 v57, v40, v48
	v_sub_f32_e32 v58, v41, v48
	v_sub_f32_e32 v59, v42, v48
	v_sub_f32_e32 v60, v43, v48
	v_sub_f32_e32 v61, v44, v48
	v_sub_f32_e32 v62, v45, v48
	v_sub_f32_e32 v63, v46, v48
	v_sub_f32_e32 v79, v47, v48
	v_mov_b32_e32 v33, v32
	v_mov_b32_e32 v34, v32
	v_mov_b32_e32 v35, v32
	v_mov_b32_e32 v36, v32
	v_mov_b32_e32 v37, v32
	v_mov_b32_e32 v38, v32
	v_mov_b32_e32 v39, v32
	v_mov_b32_e32 v40, v32
	v_mov_b32_e32 v41, v32
	v_mov_b32_e32 v42, v32
	v_mov_b32_e32 v43, v32
	v_mov_b32_e32 v44, v32
	v_mov_b32_e32 v45, v32
	v_mov_b32_e32 v46, v32
	v_mov_b32_e32 v47, v32
	v_sub_f32_e32 v16, v16, v48
	v_sub_f32_e32 v17, v17, v48
	s_waitcnt vmcnt(0) lgkmcnt(0)
	s_barrier
	v_sub_f32_e32 v18, v18, v48
	v_sub_f32_e32 v19, v19, v48
	v_sub_f32_e32 v20, v20, v48
	v_sub_f32_e32 v21, v21, v48
	v_sub_f32_e32 v22, v22, v48
	v_sub_f32_e32 v23, v23, v48
	v_sub_f32_e32 v24, v24, v48
	v_sub_f32_e32 v25, v25, v48
	v_sub_f32_e32 v26, v26, v48
	v_sub_f32_e32 v27, v27, v48
	v_sub_f32_e32 v28, v28, v48
	v_sub_f32_e32 v29, v29, v48
	v_sub_f32_e32 v30, v30, v48
	v_sub_f32_e32 v31, v31, v48
	v_exp_f32_e32 v64, v49
	v_exp_f32_e32 v48, v16
	v_exp_f32_e32 v49, v17
	v_lshl_add_u64 v[16:17], v[80:81], 0, s[74:75]
	s_mov_b32 s42, m0
	s_mov_b32 m0, s35
	s_nop 0
	global_load_lds_dwordx4 v[16:17], off
	s_mov_b32 m0, s42
	v_lshl_add_u64 v[16:17], v[82:83], 0, s[84:85]
	s_add_i32 s42, s35, 0x8000
	s_mov_b32 s43, m0
	s_mov_b32 m0, s42
	s_nop 0
	global_load_lds_dwordx4 v[16:17], off
	s_mov_b32 m0, s43
	ds_read_b128 v[172:175], v202 offset:8192
	ds_read_b128 v[168:171], v202 offset:8704
	ds_read_b128 v[164:167], v202 offset:10240
	ds_read_b128 v[160:163], v202 offset:10752
	ds_read_b128 v[156:159], v202 offset:12288
	ds_read_b128 v[152:155], v202 offset:12800
	ds_read_b128 v[148:151], v202 offset:14336
	ds_read_b128 v[144:147], v202 offset:14848
	v_exp_f32_e32 v65, v50
	v_exp_f32_e32 v66, v51
	v_exp_f32_e32 v67, v52
	v_exp_f32_e32 v68, v53
	v_exp_f32_e32 v69, v54
	v_exp_f32_e32 v70, v55
	v_exp_f32_e32 v71, v56
	v_exp_f32_e32 v72, v57
	v_exp_f32_e32 v73, v58
	v_exp_f32_e32 v74, v59
	v_exp_f32_e32 v75, v60
	v_exp_f32_e32 v76, v61
	v_exp_f32_e32 v77, v62
	v_exp_f32_e32 v78, v63
	v_exp_f32_e32 v79, v79
	v_exp_f32_e32 v50, v18
	v_exp_f32_e32 v51, v19
	v_exp_f32_e32 v52, v20
	v_exp_f32_e32 v53, v21
	v_exp_f32_e32 v54, v22
	v_exp_f32_e32 v55, v23
	v_exp_f32_e32 v56, v24
	v_exp_f32_e32 v57, v25
	v_exp_f32_e32 v58, v26
	v_exp_f32_e32 v59, v27
	v_exp_f32_e32 v60, v28
	v_exp_f32_e32 v61, v29
	v_exp_f32_e32 v62, v30
	v_exp_f32_e32 v63, v31
	s_waitcnt vmcnt(2) lgkmcnt(0)
	s_barrier
	v_and_b32_e32 v16, 3, v84
	v_lshlrev_b32_e32 v180, 4, v16
	s_cbranch_vccnz .LBB0_658
	s_lshl_b32 s44, s67, 5
	v_mov_b32_e32 v181, v209
	s_and_b32 s44, s44, 0x1800
	s_add_i32 s42, s66, s65
	v_lshl_add_u64 v[0:1], s[40:41], 1, v[180:181]
	v_lshl_or_b32 v2, v190, 7, s44
	v_mov_b32_e32 v3, v209
	s_lshl_b64 s[44:45], s[36:37], 1
	v_lshl_add_u64 v[0:1], v[0:1], 0, v[2:3]
	s_add_u32 s44, s12, s44
	v_mov_b32_e32 v16, v209
	v_mov_b32_e32 v17, v209
	v_lshl_add_u64 v[182:183], s[14:15], 0, v[0:1]
	s_addc_u32 s45, s13, s45
	v_mov_b32_e32 v18, v209
	v_mov_b32_e32 v19, v209
	v_mov_b32_e32 v20, v209
	v_mov_b32_e32 v21, v209
	v_mov_b32_e32 v22, v209
	v_mov_b32_e32 v23, v209
	v_mov_b32_e32 v24, v209
	v_mov_b32_e32 v25, v209
	v_mov_b32_e32 v26, v209
	v_mov_b32_e32 v27, v209
	v_mov_b32_e32 v28, v209
	v_mov_b32_e32 v29, v209
	v_mov_b32_e32 v30, v209
	v_mov_b32_e32 v31, v209
	v_mov_b64_e32 v[0:1], v[16:17]
	s_mul_hi_i32 s43, s42, 0x108000
	s_mul_i32 s42, s42, 0x108000
	v_lshl_add_u64 v[184:185], s[44:45], 0, v[208:209]
	s_mov_b32 s44, 0
	s_movk_i32 s68, 0x4000
	s_movk_i32 s70, 0x2000
	v_mov_b32_e32 v192, 0
	s_mov_b32 s69, 6
	v_mov_b64_e32 v[2:3], v[18:19]
	v_mov_b64_e32 v[4:5], v[20:21]
	v_mov_b64_e32 v[6:7], v[22:23]
	v_mov_b64_e32 v[8:9], v[24:25]
	v_mov_b64_e32 v[10:11], v[26:27]
	v_mov_b64_e32 v[12:13], v[28:29]
	v_mov_b64_e32 v[14:15], v[30:31]

; __device__ __forceinline__ int crow(int r,int hi){return (r&3)+8*(r>>2)+4*hi;}
; template<int THRL,bool DV128,int PQ,int PK,int PV,int PO> __device__ __forceinline__ void attn_unit(const bf16*Qb,const bf16*__restrict__ Kb,const bf16*__restrict__ Vb,bf16*Ob,const int NT,char*shm,const int wave0){
;     ...
;   float rli[16];
;   #pragma unroll
;   for(int r=0;r<16;++r)rli[r]=__builtin_amdgcn_rcpf(wsf[32+crow(r,hi)]);
;   bf16*Ow=Ob+(long)(wid*QBLK)*PO;
;   { bf16*stg=(bf16*)(shm+L_OST)+wid*2048;
;     #pragma unroll
;     for(int hf=0;hf<VS;++hf){
;       #pragma unroll
;       for(int r=0;r<16;++r){const int orow=crow(r,hi);
;         #pragma unroll
;         for(int d0=0;d0<2;++d0)stg[orow*64+d0*32+r32]=__float2bfloat16(o[2*hf+d0][r]*rli[r]);}
.LBB0_714:
	s_or_b64 exec, exec, s[12:13]
	s_waitcnt lgkmcnt(0)
	s_lshl_b32 s7, s46, 10
	ds_read_b128 v[64:67], v80 offset:128
	ds_read_b128 v[68:71], v80 offset:160
	s_add_u32 s7, s10, s7
	s_addc_u32 s10, s11, 0
	s_lshl_b32 s11, s35, 8
	s_add_u32 s7, s7, s11
	s_addc_u32 s10, s10, 0
	s_mul_hi_i32 s11, s4, 0xa00
	s_mulk_i32 s4, 0xa00
	s_add_u32 s4, s7, s4
	s_waitcnt lgkmcnt(1)
	v_rcp_f32_e32 v72, v64
	v_rcp_f32_e32 v73, v65
	v_rcp_f32_e32 v74, v66
	v_rcp_f32_e32 v75, v67
	ds_read_b128 v[64:67], v80 offset:192
	s_addc_u32 s7, s10, s11
	s_mul_hi_i32 s10, s6, 0xa00
	s_mulk_i32 s6, 0xa00
	s_add_u32 s6, s4, s6
	s_addc_u32 s7, s7, s10
	s_lshl_b32 s4, s5, 12
	s_add_i32 s4, s4, 0
	s_waitcnt lgkmcnt(1)
	v_rcp_f32_e32 v76, v68
	v_rcp_f32_e32 v77, v69
	v_rcp_f32_e32 v78, v70
	v_rcp_f32_e32 v79, v71
	ds_read_b128 v[68:71], v80 offset:224
	s_waitcnt lgkmcnt(1)
	v_rcp_f32_e32 v80, v64
	v_rcp_f32_e32 v81, v65
	s_add_i32 s4, s4, 0x12800
	v_lshlrev_b32_e32 v64, 9, v245
	v_lshlrev_b32_e32 v65, 1, v244
	v_mul_f32_e32 v32, v32, v72
	v_add3_u32 v82, s4, v64, v65
	v_cvt_pk_bf16_f32 v32, v32, s0
	ds_write_b16 v82, v32
	v_mul_f32_e32 v32, v48, v72
	v_cvt_pk_bf16_f32 v32, v32, s0
	ds_write_b16 v82, v32 offset:64
	v_mul_f32_e32 v32, v33, v73
	v_cvt_pk_bf16_f32 v32, v32, s0
	ds_write_b16 v82, v32 offset:128
	v_mul_f32_e32 v32, v49, v73
	v_cvt_pk_bf16_f32 v32, v32, s0
	ds_write_b16 v82, v32 offset:192
	v_mul_f32_e32 v32, v34, v74
	v_cvt_pk_bf16_f32 v32, v32, s0
	ds_write_b16 v82, v32 offset:256
	v_mul_f32_e32 v32, v50, v74
	v_cvt_pk_bf16_f32 v32, v32, s0
	ds_write_b16 v82, v32 offset:320
	v_mul_f32_e32 v32, v35, v75
	v_cvt_pk_bf16_f32 v32, v32, s0
	ds_write_b16 v82, v32 offset:384
	v_mul_f32_e32 v32, v51, v75
	v_cvt_pk_bf16_f32 v32, v32, s0
	ds_write_b16 v82, v32 offset:448
	v_mul_f32_e32 v32, v36, v76
	v_cvt_pk_bf16_f32 v32, v32, s0
	ds_write_b16 v82, v32 offset:1024
	v_mul_f32_e32 v32, v52, v76
	v_cvt_pk_bf16_f32 v32, v32, s0
	ds_write_b16 v82, v32 offset:1088
	v_mul_f32_e32 v32, v37, v77
	v_cvt_pk_bf16_f32 v32, v32, s0
	ds_write_b16 v82, v32 offset:1152
	v_mul_f32_e32 v32, v53, v77
	v_cvt_pk_bf16_f32 v32, v32, s0
	ds_write_b16 v82, v32 offset:1216
	v_mul_f32_e32 v32, v38, v78
	v_cvt_pk_bf16_f32 v32, v32, s0
	ds_write_b16 v82, v32 offset:1280
	v_mul_f32_e32 v32, v54, v78
	v_cvt_pk_bf16_f32 v32, v32, s0
	ds_write_b16 v82, v32 offset:1344
	v_mul_f32_e32 v32, v39, v79
	v_cvt_pk_bf16_f32 v32, v32, s0
	ds_write_b16 v82, v32 offset:1408
	v_mul_f32_e32 v32, v55, v79
	v_cvt_pk_bf16_f32 v32, v32, s0
	ds_write_b16 v82, v32 offset:1472
	v_mul_f32_e32 v32, v40, v80
	v_cvt_pk_bf16_f32 v32, v32, s0
	ds_write_b16 v82, v32 offset:2048
	v_mul_f32_e32 v32, v56, v80
	v_cvt_pk_bf16_f32 v32, v32, s0
	v_rcp_f32_e32 v66, v66
	ds_write_b16 v82, v32 offset:2112
	v_mul_f32_e32 v32, v41, v81
	v_cvt_pk_bf16_f32 v32, v32, s0
	ds_write_b16 v82, v32 offset:2176
	v_mul_f32_e32 v32, v57, v81
	v_cvt_pk_bf16_f32 v32, v32, s0
	v_rcp_f32_e32 v67, v67
	ds_write_b16 v82, v32 offset:2240
	v_mul_f32_e32 v32, v42, v66
	v_cvt_pk_bf16_f32 v32, v32, s0
	ds_write_b16 v82, v32 offset:2304
	v_mul_f32_e32 v32, v58, v66
	v_cvt_pk_bf16_f32 v32, v32, s0
	s_waitcnt lgkmcnt(14)
	v_rcp_f32_e32 v68, v68
	ds_write_b16 v82, v32 offset:2368
	v_mul_f32_e32 v32, v43, v67
	v_cvt_pk_bf16_f32 v32, v32, s0
	ds_write_b16 v82, v32 offset:2432
	v_mul_f32_e32 v32, v59, v67
	v_cvt_pk_bf16_f32 v32, v32, s0
	v_rcp_f32_e32 v69, v69
	ds_write_b16 v82, v32 offset:2496
	v_mul_f32_e32 v32, v44, v68
	v_cvt_pk_bf16_f32 v32, v32, s0
	ds_write_b16 v82, v32 offset:3072
	v_mul_f32_e32 v32, v60, v68
	v_cvt_pk_bf16_f32 v32, v32, s0
	v_rcp_f32_e32 v70, v70
	ds_write_b16 v82, v32 offset:3136
	v_mul_f32_e32 v32, v45, v69
	v_cvt_pk_bf16_f32 v32, v32, s0
	ds_write_b16 v82, v32 offset:3200
	v_mul_f32_e32 v32, v61, v69
	v_cvt_pk_bf16_f32 v32, v32, s0
	v_rcp_f32_e32 v71, v71
	ds_write_b16 v82, v32 offset:3264
	v_mul_f32_e32 v32, v46, v70
	v_cvt_pk_bf16_f32 v32, v32, s0
	ds_write_b16 v82, v32 offset:3328
	v_mul_f32_e32 v32, v62, v70
	v_cvt_pk_bf16_f32 v32, v32, s0
	ds_write_b16 v82, v32 offset:3392
	v_mul_f32_e32 v32, v47, v71
	v_cvt_pk_bf16_f32 v32, v32, s0
	ds_write_b16 v82, v32 offset:3456
	v_mul_f32_e32 v32, v63, v71
	v_lshrrev_b32_e32 v83, 3, v243
	v_lshlrev_b32_e32 v64, 1, v246
	v_cvt_pk_bf16_f32 v32, v32, s0
	v_and_b32_e32 v208, 0x70, v64
	v_lshlrev_b32_e32 v84, 7, v83
	ds_write_b16 v82, v32 offset:3520
	v_add3_u32 v84, s4, v208, v84
	s_waitcnt lgkmcnt(0)
	ds_read_b128 v[32:35], v84
	v_mul_u32_u24_e32 v36, 0x500, v83
	v_lshl_add_u64 v[64:65], s[6:7], 0, v[208:209]
	v_lshlrev_b32_e32 v208, 1, v36
	v_lshl_add_u64 v[36:37], v[64:65], 0, v[208:209]
	s_mov_b32 s4, 0x8200000
	v_add_co_u32_e32 v38, vcc, s4, v36
	s_mov_b32 s4, 0x8205000
	s_nop 0
	v_addc_co_u32_e32 v39, vcc, 0, v37, vcc
	s_waitcnt lgkmcnt(0)
; __device__ __forceinline__ int crow(int r,int hi){return (r&3)+8*(r>>2)+4*hi;}
; template<int THRL,bool DV128,int PQ,int PK,int PV,int PO> __device__ __forceinline__ void attn_unit(const bf16*Qb,const bf16*__restrict__ Kb,const bf16*__restrict__ Vb,bf16*Ob,const int NT,char*shm,const int wave0){
;     ...
;   { bf16*stg=(bf16*)(shm+L_OST)+wid*2048;
;     #pragma unroll
;     for(int hf=0;hf<VS;++hf){
;       #pragma unroll
;       for(int r=0;r<16;++r){const int orow=crow(r,hi);
;         #pragma unroll
;         for(int d0=0;d0<2;++d0)stg[orow*64+d0*32+r32]=__float2bfloat16(o[2*hf+d0][r]*rli[r]);}
;       asm volatile("s_waitcnt lgkmcnt(0)":::"memory");
;       #pragma unroll
;       for(int i=0;i<4;++i){const int row=i*8+(lane>>3),ch=lane&7; const u32x4 v=*(const u32x4*)(stg+row*64+ch*8); ATTN_STORE16(Ow+(long)row*PO+hf*64+ch*8,v);}
;       asm volatile("s_waitcnt lgkmcnt(0)":::"memory"); } }
;   asm volatile("s_waitcnt lgkmcnt(0)\n\ts_barrier":::"memory");
	global_store_dwordx4 v[38:39], v[32:35], off offset:512
	ds_read_b128 v[32:35], v84 offset:1024
	v_add_co_u32_e32 v38, vcc, s4, v36
	s_mov_b32 s4, 0x820a000
	s_nop 0
	v_addc_co_u32_e32 v39, vcc, 0, v37, vcc
	s_waitcnt lgkmcnt(0)
	global_store_dwordx4 v[38:39], v[32:35], off offset:512
	ds_read_b128 v[32:35], v84 offset:2048
	v_add_co_u32_e32 v38, vcc, s4, v36
	s_mov_b32 s4, 0x820f000
	s_nop 0
	v_addc_co_u32_e32 v39, vcc, 0, v37, vcc
	s_waitcnt lgkmcnt(0)
	global_store_dwordx4 v[38:39], v[32:35], off offset:512
	ds_read_b128 v[32:35], v84 offset:3072
	v_add_co_u32_e32 v38, vcc, s4, v36
	v_mul_f32_e32 v0, v0, v72
	s_nop 0
	v_addc_co_u32_e32 v39, vcc, 0, v37, vcc
	s_waitcnt lgkmcnt(0)
	global_store_dwordx4 v[38:39], v[32:35], off offset:512
	v_cvt_pk_bf16_f32 v0, v0, s0
	s_waitcnt lgkmcnt(0)
	ds_write_b16 v82, v0 offset:64
	v_mul_f32_e32 v0, v17, v73
	v_cvt_pk_bf16_f32 v0, v0, s0
	ds_write_b16 v82, v0 offset:128
	v_mul_f32_e32 v0, v1, v73
	v_cvt_pk_bf16_f32 v0, v0, s0
	ds_write_b16 v82, v0 offset:192
	v_mul_f32_e32 v0, v18, v74
	v_cvt_pk_bf16_f32 v0, v0, s0
	ds_write_b16 v82, v0 offset:256
	v_mul_f32_e32 v0, v2, v74
	v_cvt_pk_bf16_f32 v0, v0, s0
	ds_write_b16 v82, v0 offset:320
	v_mul_f32_e32 v0, v19, v75
	v_cvt_pk_bf16_f32 v0, v0, s0
	ds_write_b16 v82, v0 offset:384
	v_mul_f32_e32 v0, v3, v75
	v_cvt_pk_bf16_f32 v0, v0, s0
	ds_write_b16 v82, v0 offset:448
	v_mul_f32_e32 v0, v20, v76
	v_cvt_pk_bf16_f32 v0, v0, s0
	ds_write_b16 v82, v0 offset:1024
	v_mul_f32_e32 v0, v4, v76
	v_cvt_pk_bf16_f32 v0, v0, s0
	ds_write_b16 v82, v0 offset:1088
	v_mul_f32_e32 v0, v21, v77
	v_cvt_pk_bf16_f32 v0, v0, s0
	ds_write_b16 v82, v0 offset:1152
	v_mul_f32_e32 v0, v5, v77
	v_cvt_pk_bf16_f32 v0, v0, s0
	ds_write_b16 v82, v0 offset:1216
	v_mul_f32_e32 v0, v22, v78
	v_cvt_pk_bf16_f32 v0, v0, s0
	ds_write_b16 v82, v0 offset:1280
	v_mul_f32_e32 v0, v6, v78
	v_cvt_pk_bf16_f32 v0, v0, s0
	ds_write_b16 v82, v0 offset:1344
	v_mul_f32_e32 v0, v23, v79
	v_cvt_pk_bf16_f32 v0, v0, s0
	ds_write_b16 v82, v0 offset:1408
	v_mul_f32_e32 v0, v7, v79
	v_cvt_pk_bf16_f32 v0, v0, s0
	ds_write_b16 v82, v0 offset:1472
	v_mul_f32_e32 v0, v24, v80
	v_cvt_pk_bf16_f32 v0, v0, s0
	ds_write_b16 v82, v0 offset:2048
	v_mul_f32_e32 v0, v8, v80
	v_cvt_pk_bf16_f32 v0, v0, s0
	ds_write_b16 v82, v0 offset:2112
	v_mul_f32_e32 v0, v25, v81
	v_cvt_pk_bf16_f32 v0, v0, s0
	ds_write_b16 v82, v0 offset:2176
	v_mul_f32_e32 v0, v9, v81
	v_cvt_pk_bf16_f32 v0, v0, s0
	ds_write_b16 v82, v0 offset:2240
	v_mul_f32_e32 v0, v26, v66
	v_cvt_pk_bf16_f32 v0, v0, s0
	ds_write_b16 v82, v0 offset:2304
	v_mul_f32_e32 v0, v10, v66
	v_cvt_pk_bf16_f32 v0, v0, s0
	ds_write_b16 v82, v0 offset:2368
	v_mul_f32_e32 v0, v27, v67
	v_cvt_pk_bf16_f32 v0, v0, s0
	ds_write_b16 v82, v0 offset:2432
	v_mul_f32_e32 v0, v11, v67
	v_cvt_pk_bf16_f32 v0, v0, s0
	ds_write_b16 v82, v0 offset:2496
	v_mul_f32_e32 v0, v28, v68
	v_cvt_pk_bf16_f32 v0, v0, s0
	ds_write_b16 v82, v0 offset:3072
	v_mul_f32_e32 v0, v12, v68
	v_cvt_pk_bf16_f32 v0, v0, s0
	ds_write_b16 v82, v0 offset:3136
	v_mul_f32_e32 v0, v29, v69
	v_cvt_pk_bf16_f32 v0, v0, s0
	ds_write_b16 v82, v0 offset:3200
	v_mul_f32_e32 v0, v13, v69
	v_cvt_pk_bf16_f32 v0, v0, s0
	ds_write_b16 v82, v0 offset:3264
	v_mul_f32_e32 v0, v30, v70
	v_cvt_pk_bf16_f32 v0, v0, s0
	ds_write_b16 v82, v0 offset:3328
	v_mul_f32_e32 v0, v14, v70
	v_cvt_pk_bf16_f32 v0, v0, s0
	ds_write_b16 v82, v0 offset:3392
	v_mul_f32_e32 v0, v31, v71
	v_cvt_pk_bf16_f32 v0, v0, s0
	v_mul_f32_e32 v16, v16, v72
	ds_write_b16 v82, v0 offset:3456
	v_mul_f32_e32 v0, v15, v71
	v_cvt_pk_bf16_f32 v16, v16, s0
	v_cvt_pk_bf16_f32 v0, v0, s0
	ds_write_b16 v82, v16
	ds_write_b16 v82, v0 offset:3520
	s_waitcnt lgkmcnt(0)
	ds_read_b128 v[0:3], v84
	s_mov_b64 s[4:5], 0x8200200
	v_lshl_add_u64 v[4:5], v[36:37], 0, s[4:5]
	s_mov_b64 s[4:5], 0x8205200
	s_add_i32 s34, s34, s54
	s_waitcnt lgkmcnt(0)
	global_store_dwordx4 v[4:5], v[0:3], off offset:128
	ds_read_b128 v[0:3], v84 offset:1024
	v_lshl_add_u64 v[4:5], v[36:37], 0, s[4:5]
	s_mov_b64 s[4:5], 0x820a200
	s_cmp_ge_i32 s34, s23
	s_waitcnt lgkmcnt(0)
	global_store_dwordx4 v[4:5], v[0:3], off offset:128
	ds_read_b128 v[0:3], v84 offset:2048
	v_lshl_add_u64 v[4:5], v[36:37], 0, s[4:5]
	s_mov_b64 s[4:5], 0x820f200
	s_waitcnt lgkmcnt(0)
	global_store_dwordx4 v[4:5], v[0:3], off offset:128
	ds_read_b128 v[0:3], v84 offset:3072
	v_lshl_add_u64 v[4:5], v[36:37], 0, s[4:5]
	s_waitcnt lgkmcnt(0)
	global_store_dwordx4 v[4:5], v[0:3], off offset:128
	s_waitcnt lgkmcnt(0)
	s_waitcnt lgkmcnt(0)
	s_barrier
	s_cbranch_scc1 .LBB0_633

; __device__ __forceinline__ int lane_id_v() { int l; asm volatile("v_mbcnt_lo_u32_b32 %0, -1, 0\n\tv_mbcnt_hi_u32_b32 %0, -1, %0" : "=v"(l)); return l; }
; #define WAIT_BAR(N) asm volatile("s_waitcnt vmcnt(" #N ") lgkmcnt(0)\n\ts_barrier":::"memory")
;   #define DMA_K(t,slot) glds16(ksrc+(long)(t)*KVBLK*PK,(unsigned)__builtin_amdgcn_readfirstlane(kdst+(slot)))
;   #define DMA_V(t,slot) do{ glds16(vsrc+(long)(t)*KVBLK*PV,(unsigned)__builtin_amdgcn_readfirstlane(vdst+VS*(slot))); if constexpr(DV128){ glds16(vsrc+64+(long)(t)*KVBLK*PV,(unsigned)__builtin_amdgcn_readfirstlane(vdst+VS*(slot)+8192)); } }while(0)
;   #define CMASK(P0,P1,t) do{}while(0)
;   #define CMASK(P0,P1,t) do{}while(0)
;   #define CMASK(P0,P1,t) do{}while(0)
; template<int THRL,bool DV128,int PQ,int PK,int PV,int PO> __device__ __forceinline__ void attn_unit(const bf16*Qb,const bf16*__restrict__ Kb,const bf16*__restrict__ Vb,bf16*Ob,const int NT,char*shm,const int wave0){
;   int tid_o=wave0*64+lane_id_v(); asm volatile("":"+v"(tid_o)); const int tid=tid_o,lane=tid&63,r32=lane&31,hi=lane>>5; const int wid=__builtin_amdgcn_readfirstlane(tid>>6);
;   const bf16*Qw=Qb+(long)(wid*QBLK)*PQ;
;   const bf16*Kh=Kb,*Vh=Vb;
;   const unsigned lds0=(unsigned)(uintptr_t)shm;
;   constexpr int VS=DV128?2:1, L_WS=LDS_V+NSLOT*SLOTB*VS, L_OST=L_WS+NW*64*4;
;   float*wsf=(float*)(shm+L_WS)+wid*64;
;   const bf16*ksrc=Kh+(long)lane*PK+wid*8;
;   const bf16*vsrc=Vh+(long)(16*(wid&3)+(lane>>2))*PV+(wid>>2)*32+(lane&3)*8;
;   const unsigned kdst=lds0+LDS_K+wid*1024, vdst=lds0+LDS_V+wid*1024;
;     ...
;   const char*Kbase=shm+LDS_K; bf16x8 kf[8];
;   const lds_cptr shm3=(lds_cptr)shm; const lds_cptr kp0=shm3+LDS_K+hi*1024+r32*16; const lds_cptr vp0=shm3+LDS_V+((lane>>4)&1)*32+(lane&3)*8+(4*hi+((lane&15)>>2))*64;
;   DMA_K(0,0);DMA_V(0,0);DMA_K(1,SLOTB);
;   bf16x8 qr[4];
;   #pragma unroll
;   for(int d0=0;d0<4;++d0)qr[d0]=*reinterpret_cast<const bf16x8*>(&Qw[(long)r32*PQ+d0*16+hi*8]);
;   float mhat=0.f,l_reg=0.f;f32x16 o[4];o[0]=f32x16{};o[1]=f32x16{};o[2]=f32x16{};o[3]=f32x16{};f32x16 negm=f32x16{};asm volatile("":"+v"(negm));
;     ...
;   bool resc=false;
;     ...
;   f32x16 pA0,pA1,pB0,pB1;
;   int sl_prev=0,sl_cur=0,sl_next=SLOTB;
;     ...
;   DMA_K(2,2*SLOTB);
;   WAIT_BAR(3);
;   qkt(pA0,pA1,Kbase,qr,negm,r32,hi);asm volatile("s_nop 15\n\ts_nop 7":"+v"(pA0),"+v"(pA1));CMASK(pA0,pA1,0);
;   START(pA0,pA1);
.LBB0_719:
	s_bfe_u32 s35, s11, 0x20001
	s_lshl_b32 s5, s11, 7
	s_and_b32 s46, s11, 1
	s_mov_b64 s[6:7], s[58:59]
	s_lshl_b32 s66, s35, 1
	s_and_b32 s5, s5, 0x380
	s_add_u32 s12, s6, s5
	s_addc_u32 s13, s7, 0
	s_ashr_i32 s5, s4, 31
	s_lshl_b64 s[6:7], s[4:5], 10
	s_add_u32 s44, s12, s6
	s_addc_u32 s45, s13, s7
	s_and_b32 s67, s11, -8
	s_or_b32 s5, s66, s67
	s_or_b32 s5, s5, s46
	s_mov_b64 s[12:13], s[58:59]
	s_mul_hi_i32 s6, s5, 0x108000
	s_mul_i32 s5, s5, 0x108000
	s_add_u32 s36, s12, s5
	s_addc_u32 s37, s13, s6
	s_lshl_b32 s68, s10, 2
	s_mov_b64 s[14:15], s[58:59]
	s_or_b32 s5, s68, s35
	s_mov_b64 s[10:11], s[58:59]
	s_mul_hi_i32 s6, s5, 0x210000
	s_mul_i32 s5, s5, 0x210000
	v_mbcnt_lo_u32_b32 v0, -1, 0
	v_mbcnt_hi_u32_b32 v0, -1, v0
	s_add_u32 s40, s14, s5
	v_add_u32_e32 v60, s89, v0
	s_addc_u32 s41, s15, s6
	v_readfirstlane_b32 s69, v60
	s_ashr_i32 s5, s69, 6
	s_lshl_b32 s6, s5, 5
	s_ashr_i32 s7, s6, 31
	v_and_b32_e32 v243, 63, v60
	s_lshl_b64 s[42:43], s[6:7], 10
	s_add_u32 s42, s44, s42
	v_lshlrev_b32_e32 v208, 4, v243
	s_addc_u32 s43, s45, s43
	v_lshl_add_u64 v[0:1], s[36:37], 0, v[208:209]
	s_lshl_b32 s36, s5, 9
	s_ashr_i32 s37, s36, 31
	v_lshl_add_u64 v[48:49], s[36:37], 1, v[0:1]
	s_mov_b64 s[44:45], 0x17c00000
	v_lshl_add_u64 v[0:1], v[48:49], 0, s[44:45]
	s_lshl_b32 s44, s5, 4
	v_bfe_u32 v216, v60, 2, 4
	v_and_or_b32 v2, s44, 48, v216
	v_lshlrev_b32_e32 v2, 8, v2
	v_mov_b32_e32 v3, v209
	v_lshl_add_u64 v[2:3], s[40:41], 0, v[2:3]
	s_ashr_i32 s40, s69, 3
	s_andn2_b32 s40, s40, 31
	v_lshlrev_b32_e32 v246, 3, v60
	s_ashr_i32 s41, s40, 31
	v_and_b32_e32 v61, 24, v246
	s_and_b32 s7, s69, 0x3fffffc0
	v_lshl_add_u64 v[2:3], s[40:41], 1, v[2:3]
	v_lshlrev_b32_e32 v4, 1, v61
	v_mov_b32_e32 v5, v209
	s_lshl_b32 s49, s5, 10
	v_lshl_add_u64 v[50:51], v[2:3], 0, v[4:5]
	s_mov_b64 s[44:45], 0x19d00000
	s_cmp_lg_u32 0, -1
	v_lshl_add_u64 v[2:3], v[50:51], 0, s[44:45]
	s_cselect_b32 s44, 0, 0
	s_add_i32 s49, s49, s44
	s_mov_b32 s44, m0
	s_mov_b32 m0, s49
	s_nop 0
	global_load_lds_dwordx4 v[0:1], off
	s_mov_b32 m0, s44
	s_add_i32 s60, s49, 0x6000
	s_mov_b32 s44, m0
	s_mov_b32 m0, s60
	s_nop 0
	global_load_lds_dwordx4 v[2:3], off
	s_mov_b32 m0, s44
	s_mov_b64 s[44:45], 0x19d00080
	v_lshl_add_u64 v[0:1], v[50:51], 0, s[44:45]
	s_add_i32 s44, s49, 0x8000
	s_mov_b32 s45, m0
	s_mov_b32 m0, s44
	s_nop 0
	global_load_lds_dwordx4 v[0:1], off
	s_mov_b32 m0, s45
	s_mov_b64 s[44:45], 0x17c02000
	v_and_b32_e32 v244, 31, v60
	v_lshl_add_u64 v[0:1], v[48:49], 0, s[44:45]
	v_bfe_u32 v245, v60, 5, 1
	s_add_i32 s44, s49, 0x2000
	s_mov_b32 s45, m0
	s_mov_b32 m0, s44
	s_nop 0
	global_load_lds_dwordx4 v[0:1], off
	s_mov_b32 m0, s45
	v_lshlrev_b32_e32 v0, 10, v244
	v_lshl_or_b32 v0, v245, 4, v0
	v_mov_b32_e32 v1, v209
	v_lshl_add_u64 v[0:1], s[42:43], 0, v[0:1]
	s_mov_b32 s42, 0x15b00000
	v_add_co_u32_e32 v2, vcc, s42, v0
	s_mov_b64 s[42:43], 0x15b00000
	s_nop 0
	v_addc_co_u32_e32 v3, vcc, 0, v1, vcc
	global_load_dwordx4 v[172:175], v[2:3], off
	v_lshl_add_u64 v[0:1], v[0:1], 0, s[42:43]
	global_load_dwordx4 v[168:171], v[0:1], off offset:32
	global_load_dwordx4 v[164:167], v[0:1], off offset:64
	global_load_dwordx4 v[156:159], v[0:1], off offset:96
	v_lshlrev_b32_e32 v2, 10, v245
	v_lshlrev_b32_e32 v3, 4, v244
	v_mov_b32_e32 v14, v209
	v_mov_b32_e32 v15, v209
	v_add3_u32 v250, 0, v2, v3
	v_mov_b32_e32 v0, v209
	v_mov_b32_e32 v1, v209
	v_mov_b32_e32 v2, v209
	v_mov_b32_e32 v3, v209
	v_mov_b32_e32 v4, v209
	v_mov_b32_e32 v6, v209
	v_mov_b32_e32 v7, v209
	v_mov_b32_e32 v8, v209
	v_mov_b32_e32 v9, v209
	v_mov_b32_e32 v10, v209
	v_mov_b32_e32 v11, v209
	v_mov_b32_e32 v12, v209
	v_mov_b32_e32 v13, v209
	v_mov_b64_e32 v[30:31], v[14:15]
	v_mov_b64_e32 v[28:29], v[12:13]
	v_mov_b64_e32 v[26:27], v[10:11]
	v_mov_b64_e32 v[24:25], v[8:9]
	v_mov_b64_e32 v[22:23], v[6:7]
	v_mov_b64_e32 v[20:21], v[4:5]
	v_mov_b64_e32 v[18:19], v[2:3]
	v_mov_b64_e32 v[16:17], v[0:1]
	s_mov_b64 s[42:43], 0x17c04000
	v_lshl_add_u64 v[32:33], v[48:49], 0, s[42:43]
	s_add_i32 s42, s49, 0x4000
	s_mov_b32 s43, m0
	s_mov_b32 m0, s42
	s_nop 0
	global_load_lds_dwordx4 v[32:33], off
	s_mov_b32 m0, s43
	s_waitcnt vmcnt(3) lgkmcnt(0)
	s_barrier
	ds_read_b128 v[52:55], v250
	ds_read_b128 v[56:59], v250 offset:512
	s_waitcnt vmcnt(0) lgkmcnt(0)
	v_mfma_f32_32x32x16_bf16 v[32:47], v[52:55], v[172:175], v[16:31]
	s_mov_b64 s[70:71], 0x17c06000
	v_lshlrev_b32_e32 v62, 1, v60
	s_lshl_b32 s7, s7, 2
	s_add_i32 s7, s7, 0
	s_add_i32 s7, s7, 0x12000
	s_mov_b32 s42, 1
	s_mov_b32 s61, 0
	v_mfma_f32_32x32x16_bf16 v[16:31], v[56:59], v[172:175], v[16:31]
	ds_read_b128 v[52:55], v250 offset:2048
	ds_read_b128 v[56:59], v250 offset:2560
	s_movk_i32 s65, 0x2000
	s_movk_i32 s44, 0x4000
	s_andn2_b64 vcc, exec, s[38:39]
	v_cmp_gt_u32_e64 s[38:39], 32, v243
	v_lshlrev_b32_e32 v251, 4, v245
	v_lshl_add_u32 v247, v244, 2, s7
	s_waitcnt lgkmcnt(1)
	v_mfma_f32_32x32x16_bf16 v[32:47], v[52:55], v[168:171], v[32:47]
	s_waitcnt lgkmcnt(0)
	v_mfma_f32_32x32x16_bf16 v[16:31], v[56:59], v[168:171], v[16:31]
	ds_read_b128 v[52:55], v250 offset:4096
	ds_read_b128 v[56:59], v250 offset:4608
	s_waitcnt lgkmcnt(1)
	v_mfma_f32_32x32x16_bf16 v[32:47], v[52:55], v[164:167], v[32:47]
	s_waitcnt lgkmcnt(0)
	v_mfma_f32_32x32x16_bf16 v[16:31], v[56:59], v[164:167], v[16:31]
	ds_read_b128 v[52:55], v250 offset:6144
	ds_read_b128 v[56:59], v250 offset:6656
	s_waitcnt lgkmcnt(1)
	v_mfma_f32_32x32x16_bf16 v[32:47], v[52:55], v[156:159], v[32:47]
	v_and_b32_e32 v52, 32, v62
	v_lshlrev_b32_e32 v54, 4, v60
	v_add3_u32 v52, 0, v52, v61
	v_lshlrev_b32_e32 v53, 8, v245
	v_and_b32_e32 v54, 0xc0, v54
	v_add3_u32 v248, v52, v53, v54
	s_waitcnt lgkmcnt(0)
	v_mfma_f32_32x32x16_bf16 v[16:31], v[56:59], v[156:159], v[16:31]
	s_nop 15
	s_nop 7
	s_nop 0
	v_max3_f32 v55, v32, v33, v16
	v_max3_f32 v56, v34, v35, v17
	s_nop 0
	v_max3_f32 v55, v55, v18, v19
	v_max3_f32 v56, v56, v38, v39
	s_nop 0
	v_max3_f32 v55, v55, v36, v37
	v_max3_f32 v56, v56, v22, v23
	s_nop 0
	v_max3_f32 v55, v55, v20, v21
	v_max3_f32 v56, v56, v42, v43
	s_nop 0
	v_max3_f32 v55, v55, v40, v41
	v_max3_f32 v56, v56, v26, v27
	s_nop 0
	v_max3_f32 v55, v55, v24, v25
	v_max3_f32 v56, v56, v46, v47
	s_nop 0
	v_max3_f32 v55, v55, v44, v45
	v_max3_f32 v56, v56, v30, v31
	s_nop 0
	v_max3_f32 v55, v55, v28, v29
	s_nop 0
	v_max_f32_e32 v55, v55, v56
	s_nop 0
	v_mov_b32_e32 v56, v55
	s_nop 1
	v_permlane32_swap_b32_e32 v55, v56
	v_max_f32_e32 v55, v55, v56
	s_nop 0
	v_add_f32_e32 v249, v209, v55
	v_sub_f32_e32 v16, v16, v55
	v_sub_f32_e32 v17, v17, v55
	v_sub_f32_e32 v32, v32, v55
	v_sub_f32_e32 v33, v33, v55
	v_sub_f32_e32 v34, v34, v55
	s_nop 0
	v_xor_b32_e32 v64, 0x80000000, v249
	v_mov_b32_e32 v65, v64
	v_mov_b32_e32 v66, v64
	v_mov_b32_e32 v67, v64
	v_mov_b32_e32 v68, v64
	v_mov_b32_e32 v69, v64
	v_mov_b32_e32 v70, v64
	v_mov_b32_e32 v71, v64
	v_mov_b32_e32 v72, v64
	v_mov_b32_e32 v73, v64
	v_mov_b32_e32 v74, v64
	v_mov_b32_e32 v75, v64
	v_mov_b32_e32 v76, v64
	v_mov_b32_e32 v77, v64
	v_mov_b32_e32 v78, v64
	v_mov_b32_e32 v79, v64
	s_waitcnt vmcnt(0) lgkmcnt(0)
	s_barrier
; #define WAIT_BAR(N) asm volatile("s_waitcnt vmcnt(" #N ") lgkmcnt(0)\n\ts_barrier":::"memory")
;   #define DMA_K(t,slot) glds16(ksrc+(long)(t)*KVBLK*PK,(unsigned)__builtin_amdgcn_readfirstlane(kdst+(slot)))
;   #define DMA_V(t,slot) do{ glds16(vsrc+(long)(t)*KVBLK*PV,(unsigned)__builtin_amdgcn_readfirstlane(vdst+VS*(slot))); if constexpr(DV128){ glds16(vsrc+64+(long)(t)*KVBLK*PV,(unsigned)__builtin_amdgcn_readfirstlane(vdst+VS*(slot)+8192)); } }while(0)
;   #define CMASK(P0,P1,t) do{}while(0)
;   #define START(P0,P1) do{ const float rm=rowmax(P0,P1); resc=false; \
;     { const float dl=rm; mhat=fadd_s(mhat,dl); \
;       _Pragma("unroll") for(int r=0;r<16;++r){P0[r]=fsub_s(P0[r],dl);P1[r]=fsub_s(P1[r],dl);} \
;       _Pragma("unroll") for(int r=0;r<16;++r)negm[r]=-mhat; asm volatile("":"+v"(negm)); } \
;     _Pragma("unroll") for(int r=0;r<16;++r)P0[r]=__builtin_amdgcn_exp2f(P0[r]); }while(0)
;   #define ROT() do{sl_prev=sl_cur;sl_cur=sl_next;sl_next=(sl_next==(NSLOT-1)*SLOTB)?0:sl_next+SLOTB;}while(0)
;   #define WB2() do{ if constexpr(DV128){WAIT_BAR(3);}else{WAIT_BAR(2);} }while(0)
;   #define CMASK(P0,P1,t) do{}while(0)
;   #define CMASK(P0,P1,t) do{}while(0)
; template<int THRL,bool DV128,int PQ,int PK,int PV,int PO> __device__ __forceinline__ void attn_unit(const bf16*Qb,const bf16*__restrict__ Kb,const bf16*__restrict__ Vb,bf16*Ob,const int NT,char*shm,const int wave0){
;     ...
;   f32x16 pA0,pA1,pB0,pB1;
;   int sl_prev=0,sl_cur=0,sl_next=SLOTB;
;     ...
;   DMA_K(2,2*SLOTB);
;   WAIT_BAR(3);
;   qkt(pA0,pA1,Kbase,qr,negm,r32,hi);asm volatile("s_nop 15\n\ts_nop 7":"+v"(pA0),"+v"(pA1));CMASK(pA0,pA1,0);
;   START(pA0,pA1);
;   _Pragma("unroll") for(int r=0;r<16;++r)pA1[r]=__builtin_amdgcn_exp2f(pA1[r]);
;   WAIT_BAR(0);
;   DMA_K(3,0);DMA_V(1,SLOTB);
;   ROT();
;   kload8(kf,kp0+sl_cur);
;     ...
;   WB2();
	v_exp_f32_e32 v80, v16
	v_exp_f32_e32 v81, v17
	v_lshl_add_u64 v[16:17], v[48:49], 0, s[70:71]
	s_mov_b32 s43, m0
	s_mov_b32 m0, s49
	s_nop 0
	global_load_lds_dwordx4 v[16:17], off
	s_mov_b32 m0, s43
	s_mov_b64 s[70:71], 0x19d04000
	v_lshl_add_u64 v[16:17], v[50:51], 0, s[70:71]
	s_add_i32 s43, s49, 0xa000
	s_mov_b32 s45, m0
	s_mov_b32 m0, s43
	s_nop 0
	global_load_lds_dwordx4 v[16:17], off
	s_mov_b32 m0, s45
	s_mov_b64 s[70:71], 0x19d04080
	v_lshl_add_u64 v[16:17], v[50:51], 0, s[70:71]
	s_add_i32 s43, s49, 0xc000
	s_mov_b32 s45, m0
	s_mov_b32 m0, s43
	s_nop 0
	global_load_lds_dwordx4 v[16:17], off
	s_mov_b32 m0, s45
	ds_read_b128 v[204:207], v250 offset:8192
	ds_read_b128 v[200:203], v250 offset:8704
	ds_read_b128 v[196:199], v250 offset:10240
	ds_read_b128 v[192:195], v250 offset:10752
	ds_read_b128 v[188:191], v250 offset:12288
	ds_read_b128 v[184:187], v250 offset:12800
	ds_read_b128 v[180:183], v250 offset:14336
	ds_read_b128 v[176:179], v250 offset:14848
	v_sub_f32_e32 v18, v18, v55
	v_sub_f32_e32 v35, v35, v55
	v_sub_f32_e32 v19, v19, v55
	v_sub_f32_e32 v36, v36, v55
	v_sub_f32_e32 v20, v20, v55
	v_sub_f32_e32 v37, v37, v55
	v_sub_f32_e32 v21, v21, v55
	v_sub_f32_e32 v38, v38, v55
	v_sub_f32_e32 v22, v22, v55
	v_sub_f32_e32 v39, v39, v55
	v_sub_f32_e32 v23, v23, v55
	v_sub_f32_e32 v40, v40, v55
	v_sub_f32_e32 v24, v24, v55
	v_sub_f32_e32 v41, v41, v55
	v_sub_f32_e32 v25, v25, v55
	v_sub_f32_e32 v42, v42, v55
	v_sub_f32_e32 v26, v26, v55
	v_sub_f32_e32 v43, v43, v55
	v_sub_f32_e32 v27, v27, v55
	v_sub_f32_e32 v44, v44, v55
	v_sub_f32_e32 v28, v28, v55
	v_sub_f32_e32 v45, v45, v55
	v_sub_f32_e32 v29, v29, v55
	v_sub_f32_e32 v46, v46, v55
	v_sub_f32_e32 v30, v30, v55
	v_sub_f32_e32 v47, v47, v55
	v_sub_f32_e32 v31, v31, v55
	v_exp_f32_e32 v96, v32
	v_exp_f32_e32 v97, v33
	v_exp_f32_e32 v98, v34
	v_exp_f32_e32 v99, v35
	v_exp_f32_e32 v100, v36
	v_exp_f32_e32 v101, v37
	v_exp_f32_e32 v102, v38
	v_exp_f32_e32 v103, v39
	v_exp_f32_e32 v104, v40
	v_exp_f32_e32 v105, v41
	v_exp_f32_e32 v106, v42
	v_exp_f32_e32 v107, v43
	v_exp_f32_e32 v108, v44
	v_exp_f32_e32 v109, v45
	v_exp_f32_e32 v110, v46
	v_exp_f32_e32 v111, v47
	v_exp_f32_e32 v82, v18
	v_exp_f32_e32 v83, v19
	v_exp_f32_e32 v84, v20
	v_exp_f32_e32 v85, v21
	v_exp_f32_e32 v86, v22
	v_exp_f32_e32 v87, v23
	v_exp_f32_e32 v88, v24
	v_exp_f32_e32 v89, v25
	v_exp_f32_e32 v90, v26
	v_exp_f32_e32 v91, v27
	v_exp_f32_e32 v92, v28
	v_exp_f32_e32 v93, v29
	v_exp_f32_e32 v94, v30
	v_exp_f32_e32 v95, v31
	s_waitcnt vmcnt(3) lgkmcnt(0)
	s_barrier
	v_and_b32_e32 v16, 3, v60
	v_lshlrev_b32_e32 v210, 4, v16
	s_cbranch_vccnz .LBB0_735
	s_add_i32 s42, s68, s35
	s_mul_hi_i32 s44, s42, 0x210000
	s_mul_i32 s45, s42, 0x210000
	s_lshl_b64 s[42:43], s[40:41], 1
	s_add_u32 s42, s42, s45
	v_mov_b32_e32 v211, v209
	s_addc_u32 s43, s43, s44
	v_lshl_add_u64 v[0:1], s[42:43], 0, v[210:211]
	s_lshl_b32 s42, s69, 6
	s_and_b32 s42, s42, 0x3000
	v_lshl_or_b32 v2, v216, 8, s42
	v_mov_b32_e32 v3, v209
	v_lshl_add_u64 v[0:1], v[0:1], 0, v[2:3]
	v_lshl_add_u64 v[0:1], s[14:15], 0, v[0:1]
	s_mov_b64 s[42:43], 0x19d0c080
	v_lshl_add_u64 v[212:213], v[0:1], 0, s[42:43]
	s_add_i32 s42, s67, s66
	s_add_i32 s42, s42, s46
	s_mul_hi_i32 s44, s42, 0x108000
	s_mul_i32 s45, s42, 0x108000
	s_lshl_b64 s[42:43], s[36:37], 1
	s_add_u32 s42, s12, s42
	s_addc_u32 s43, s13, s43
	s_add_u32 s42, s42, s45
	s_addc_u32 s43, s43, s44
	v_lshl_add_u64 v[0:1], s[42:43], 0, v[208:209]
	s_mov_b64 s[42:43], 0x17c0a000
	v_mov_b32_e32 v32, v209
	v_mov_b32_e32 v33, v209
	v_mov_b32_e32 v46, v209
	v_mov_b32_e32 v47, v209
	v_lshl_add_u64 v[214:215], v[0:1], 0, s[42:43]
	v_mov_b32_e32 v34, v209
	v_mov_b32_e32 v35, v209
	v_mov_b32_e32 v36, v209
	v_mov_b32_e32 v37, v209
	v_mov_b32_e32 v38, v209
	v_mov_b32_e32 v39, v209
	v_mov_b32_e32 v40, v209
	v_mov_b32_e32 v41, v209
	v_mov_b32_e32 v42, v209
	v_mov_b32_e32 v43, v209
	v_mov_b32_e32 v44, v209
	v_mov_b32_e32 v45, v209
	v_mov_b64_e32 v[62:63], v[46:47]
	v_mov_b64_e32 v[16:17], v[32:33]
	v_mov_b64_e32 v[0:1], v[32:33]
	s_mov_b32 s70, 6
	s_mov_b32 s72, 0
	s_movk_i32 s61, 0x4000
	s_movk_i32 s71, 0x2000
	v_mov_b32_e32 v252, 0
	v_mov_b64_e32 v[60:61], v[44:45]
	v_mov_b64_e32 v[58:59], v[42:43]
	v_mov_b64_e32 v[56:57], v[40:41]
	v_mov_b64_e32 v[54:55], v[38:39]
	v_mov_b64_e32 v[52:53], v[36:37]
	v_mov_b64_e32 v[50:51], v[34:35]
	v_mov_b64_e32 v[48:49], v[32:33]
	v_mov_b64_e32 v[18:19], v[34:35]
	v_mov_b64_e32 v[20:21], v[36:37]
	v_mov_b64_e32 v[22:23], v[38:39]
	v_mov_b64_e32 v[24:25], v[40:41]
	v_mov_b64_e32 v[26:27], v[42:43]
	v_mov_b64_e32 v[28:29], v[44:45]
	v_mov_b64_e32 v[30:31], v[46:47]
	v_mov_b64_e32 v[2:3], v[34:35]
	v_mov_b64_e32 v[4:5], v[36:37]
	v_mov_b64_e32 v[6:7], v[38:39]
	v_mov_b64_e32 v[8:9], v[40:41]
	v_mov_b64_e32 v[10:11], v[42:43]
	v_mov_b64_e32 v[12:13], v[44:45]
	v_mov_b64_e32 v[14:15], v[46:47]

; #define LAS __attribute__((address_space(3)))
; __device__ __forceinline__ int opq(int i) { asm volatile("" : "+s"(i)); return i; }
; #define LAM ((float*)(wsb(a.ws) + WS_LAM))
; #define YH ((float*)(wsb(a.ws) + WS_YH))
; #define YHC ((float*)(wsb(a.ws) + WS_YHC))
; __global__ void __launch_bounds__(NTHR, 2) fwd_mega(Args a) {
;     ...
;         for (int rep_ = 0; rep_ < REP_MERGE; ++rep_) {
;             PHASE_IDS
;             LAS float* S = (LAS float*)lds;
;             const float* go = a.in[opq(27)] + l * 1024;
;             const float lam = LAM[l], lam_init = 0.8f - 0.6f * expf(-0.3f * (float)l);
;             const int ntile = need_ctx ? 528 : 512;
;             for (int tl = bx; tl < ntile; tl += G) {
;                 const int r0 = tl * 64; const float* yb; int cstride;
;                 if (r0 < ML) { yb = YH + (size_t)(r0 >> 13) * 256 * 8192 + (r0 & 8191); cstride = 8192; } else { const int rr = r0 - ML; yb = YHC + (size_t)(rr >> 8) * 256 * 256 + (rr & 255); cstride = 256; }
;                 for (int i = 0; i < 32; ++i) { const int c = i * 8 + wave; S[lane * 257 + c] = yb[(size_t)c * cstride + lane]; }
.LBB0_843:
	s_waitcnt lgkmcnt(0)
	s_barrier
	v_readlane_b32 s4, v253, 0
	v_mbcnt_lo_u32_b32 v0, -1, 0
	v_mbcnt_hi_u32_b32 v0, -1, v0
	s_cmp_lt_i32 s4, s48
	v_add_u32_e32 v1, s89, v0
	s_mov_b32 s10, 27
	v_readfirstlane_b32 s6, v1
	s_mov_b64 s[4:5], s[58:59]
	s_cbranch_scc0 .LBB0_855
	v_readlane_b32 s12, v254, 53
	s_ashr_i32 s11, s10, 31
	s_ashr_i32 s6, s6, 6
	v_cvt_f32_u32_e32 v0, s12
	s_lshl_b64 s[10:11], s[10:11], 3
	v_readlane_b32 s13, v254, 54
	s_add_u32 s10, s90, s10
	v_mul_f32_e32 v0, 0xbe99999a, v0
	v_mul_f32_e32 v2, 0x3fb8aa3b, v0
	v_fma_f32 v3, v0, s28, -v2
	v_rndne_f32_e32 v4, v2
	v_fmac_f32_e32 v3, 0x32a5705f, v0
	v_sub_f32_e32 v2, v2, v4
	v_add_f32_e32 v2, v2, v3
	v_exp_f32_e32 v2, v2
	v_cvt_i32_f32_e32 v3, v4
	v_cmp_ngt_f32_e32 vcc, s24, v0
	s_addc_u32 s11, s91, s11
	s_lshl_b64 s[12:13], s[12:13], 2
	v_ldexp_f32 v2, v2, v3
	v_cndmask_b32_e32 v2, 0, v2, vcc
	v_cmp_nlt_f32_e32 vcc, s25, v0
	s_add_u32 s4, s4, s12
	s_addc_u32 s5, s5, s13
	v_cndmask_b32_e32 v0, v232, v2, vcc
	v_mov_b32_e32 v2, 0xbf4ccccd
	v_fmamk_f32 v0, v0, 0x3f19999a, v2
	v_add_f32_e32 v12, 1.0, v0
	v_mov_b32_e32 v0, s4
	s_mov_b32 s4, 0x180000
	v_add_co_u32_e32 v2, vcc, s4, v0
	v_mov_b32_e32 v0, s5
	s_nop 0
	v_addc_co_u32_e32 v3, vcc, 0, v0, vcc
	global_load_dword v0, v[2:3], off
	s_load_dwordx2 s[10:11], s[10:11], 0x0
	v_readlane_b32 s4, v255, 17
	v_readlane_b32 s5, v255, 18
	s_lshl_b64 s[4:5], s[4:5], 2
	v_and_b32_e32 v9, 63, v1
	s_waitcnt lgkmcnt(0)
	s_add_u32 s4, s10, s4
	s_addc_u32 s5, s11, s5
	v_lshlrev_b32_e32 v208, 4, v9
	v_lshl_add_u64 v[4:5], s[4:5], 0, v[208:209]
	v_lshlrev_b32_e32 v208, 5, v9
	s_ashr_i32 s7, s6, 31
	v_lshl_add_u64 v[6:7], s[4:5], 0, v[208:209]
	s_lshl_b64 s[4:5], s[6:7], 2
	s_lshl_b32 s7, s6, 2
	s_add_i32 s7, s7, 0
	s_lshl_b32 s10, s6, 3
	v_mov_b32_e32 v13, s7
	s_movk_i32 s7, 0x404
	s_mulk_i32 s6, 0x2020
	v_mul_u32_u24_e32 v10, 0x404, v9
	v_lshlrev_b32_e32 v2, 2, v9
	v_mul_i32_i24_e32 v11, 0xfffffc0c, v9
	v_lshlrev_b32_e32 v8, 3, v9
	v_mad_u32_u24 v13, v9, s7, v13
	v_readlane_b32 s7, v254, 28
	s_add_i32 s6, s6, 0
	v_mov_b32_e32 v3, v209
	s_add_u32 s5, s4, 0x60
	s_add_u32 s23, s4, 64
	s_add_u32 s34, s4, 32
	s_add_i32 s35, s7, s10
	v_add3_u32 v14, v10, v11, s6
	v_lshlrev_b32_e32 v208, 1, v2
	v_lshlrev_b32_e32 v8, 1, v8
	v_readlane_b32 s40, v253, 0
	s_waitcnt vmcnt(0)
	v_mov_b32_e32 v1, v0

; __device__ __forceinline__ unsigned pk2(float lo, float hi) { const f32x2_cv v = {lo, hi}; const bf16x2_cv b = __builtin_convertvector(v, bf16x2_cv); return __builtin_bit_cast(unsigned, b); }
; __device__ __forceinline__ float bflo(unsigned w) { return __uint_as_float(w << 16); }
; __device__ __forceinline__ float bfhi(unsigned w) { return __uint_as_float(w & 0xffff0000u); }
; __global__ void __launch_bounds__(NTHR, 2) fwd_mega(Args a) {
;     ...
;                 for (int k = 0; k < 8; ++k) {
;                     const int row = wave * 8 + k, r = r0 + row; const bf16_t* yr = YRAW + (size_t)r * 1280; bf16_t* hr = H + (size_t)r * 1024;
;                     { const v2u w = *(const v2u*)(yr + 4 * lane); const float y0 = bflo(w.x), y1 = bfhi(w.x), y2 = bflo(w.y), y3 = bfhi(w.y);
;                       const float ss = wave_sum(y0 * y0 + y1 * y1 + y2 * y2 + y3 * y3); const float rinv = 1.0f / sqrtf(ss * (1.0f / 256.0f) + EPSF);
;                       const f32x4 g4 = *(const f32x4*)(go + 4 * lane); v2u o; o.x = pk2(y0 * rinv * g4.x, y1 * rinv * g4.y); o.y = pk2(y2 * rinv * g4.z, y3 * rinv * g4.w); *(v2u*)(hr + 4 * lane) = o; }
;                     { const float y0 = S[row * 257 + 4 * lane], y1 = S[row * 257 + 4 * lane + 1], y2 = S[row * 257 + 4 * lane + 2], y3 = S[row * 257 + 4 * lane + 3];
;                       const float ss = wave_sum(y0 * y0 + y1 * y1 + y2 * y2 + y3 * y3); const float rinv = 1.0f / sqrtf(ss * (1.0f / 256.0f) + EPSF);
;                       const f32x4 g4 = *(const f32x4*)(go + 256 + 4 * lane); v2u o; o.x = pk2(y0 * rinv * g4.x, y1 * rinv * g4.y); o.y = pk2(y2 * rinv * g4.z, y3 * rinv * g4.w); *(v2u*)(hr + 256 + 4 * lane) = o; }
.LBB0_853:
	s_mov_b64 s[10:11], s[58:59]
	s_ashr_i32 s7, s6, 31
	s_mul_i32 s13, s6, 0xa00
	s_mul_hi_i32 s12, s6, 0xa00
	s_add_u32 s10, s10, s13
	s_addc_u32 s11, s11, s12
	s_add_u32 s12, s10, 0x8200000
	s_addc_u32 s13, s11, 0
	s_mov_b64 s[10:11], s[58:59]
	v_lshl_add_u64 v[10:11], s[12:13], 0, v[208:209]
	global_load_dwordx2 v[10:11], v[10:11], off
	s_nop 0
	global_load_dwordx4 v[16:19], v[4:5], off
	s_lshl_b64 s[36:37], s[6:7], 11
	s_add_u32 s7, s10, s36
	s_addc_u32 s11, s11, s37
	s_add_u32 s10, s7, 0x4000000
	s_addc_u32 s11, s11, 0
	s_add_i32 s6, s6, 1
	s_waitcnt vmcnt(0) lgkmcnt(0)
	v_lshlrev_b32_e32 v24, 16, v10
	v_and_b32_e32 v25, 0xffff0000, v10
	v_lshlrev_b32_e32 v20, 16, v11
	v_and_b32_e32 v21, 0xffff0000, v11
	v_pk_mul_f32 v[10:11], v[24:25], v[24:25]
	v_pk_mul_f32 v[22:23], v[20:21], v[20:21]
	v_add_f32_e32 v9, v10, v11
	v_add_f32_e32 v9, v22, v9
	v_add_f32_e32 v9, v23, v9
	s_nop 1
	v_add_f32_dpp v9, v9, v9 quad_perm:[1,0,3,2] row_mask:0xf bank_mask:0xf bound_ctrl:1
	s_nop 1
	v_add_f32_dpp v9, v9, v9 quad_perm:[2,3,0,1] row_mask:0xf bank_mask:0xf bound_ctrl:1
	s_nop 1
	v_add_f32_dpp v9, v9, v9 row_half_mirror row_mask:0xf bank_mask:0xf bound_ctrl:1
	s_nop 1
	v_add_f32_dpp v9, v9, v9 row_mirror row_mask:0xf bank_mask:0xf bound_ctrl:1
	v_mov_b32_e32 v10, v9
	s_nop 1
	v_permlane16_swap_b32_e32 v9, v10
	v_add_f32_e32 v9, v9, v10
	v_mov_b32_e32 v10, v9
	s_nop 1
	v_permlane32_swap_b32_e32 v9, v10
	v_add_f32_e32 v9, v9, v10
	v_fmamk_f32 v9, v9, 0x3b800000, v220
	v_cmp_gt_f32_e32 vcc, s30, v9
	v_mul_f32_e32 v10, 0x4f800000, v9
	s_nop 0
	v_cndmask_b32_e32 v9, v9, v10, vcc
	v_sqrt_f32_e32 v10, v9
	s_nop 0
	v_add_u32_e32 v11, -1, v10
	v_fma_f32 v15, -v11, v10, v9
	v_cmp_ge_f32_e64 s[38:39], 0, v15
	v_add_u32_e32 v15, 1, v10
	s_nop 0
	v_cndmask_b32_e64 v11, v10, v11, s[38:39]
	v_fma_f32 v10, -v15, v10, v9
	v_cmp_lt_f32_e64 s[38:39], 0, v10
	s_nop 1
	v_cndmask_b32_e64 v10, v11, v15, s[38:39]
	v_mul_f32_e32 v11, 0x37800000, v10
	v_cndmask_b32_e32 v10, v10, v11, vcc
	v_cmp_class_f32_e32 vcc, v9, v221
	s_nop 1
	v_cndmask_b32_e32 v9, v10, v9, vcc
	v_div_scale_f32 v10, s[36:37], v9, v9, 1.0
	v_rcp_f32_e32 v11, v10
	s_nop 0
	v_fma_f32 v15, -v10, v11, 1.0
	v_fmac_f32_e32 v11, v15, v11
	v_div_scale_f32 v15, vcc, 1.0, v9, 1.0
	v_mul_f32_e32 v22, v15, v11
	v_fma_f32 v23, -v10, v22, v15
	v_fmac_f32_e32 v22, v23, v11
	v_fma_f32 v10, -v10, v22, v15
	v_div_fmas_f32 v10, v10, v11, v22
	v_div_fixup_f32 v10, v10, v9, 1.0
	v_pk_mul_f32 v[22:23], v[10:11], v[24:25] op_sel_hi:[0,1]
	v_pk_mul_f32 v[10:11], v[10:11], v[20:21] op_sel_hi:[0,1]
	v_pk_mul_f32 v[16:17], v[16:17], v[22:23]
	v_pk_mul_f32 v[10:11], v[18:19], v[10:11]
	v_cvt_pk_bf16_f32 v16, v16, v17
	v_cvt_pk_bf16_f32 v17, v10, v11
	v_lshl_add_u64 v[10:11], s[10:11], 0, v[208:209]
	global_store_dwordx2 v[10:11], v[16:17], off
	global_load_dwordx4 v[16:19], v[4:5], off offset:1024
	v_add_u32_e32 v9, s14, v14
	ds_read2_b32 v[20:21], v9 offset0:2 offset1:3
	ds_read2_b32 v[24:25], v9 offset1:1
	s_addk_i32 s14, 0x404
	s_cmpk_eq_i32 s14, 0x2020
	s_waitcnt lgkmcnt(0)
	v_pk_mul_f32 v[22:23], v[20:21], v[20:21]
	v_pk_mul_f32 v[26:27], v[24:25], v[24:25]
	s_nop 0
	v_add_f32_e32 v9, v26, v27
	v_add_f32_e32 v9, v9, v22
	v_add_f32_e32 v9, v9, v23
	s_nop 1
	v_add_f32_dpp v9, v9, v9 quad_perm:[1,0,3,2] row_mask:0xf bank_mask:0xf bound_ctrl:1
	s_nop 1
	v_add_f32_dpp v9, v9, v9 quad_perm:[2,3,0,1] row_mask:0xf bank_mask:0xf bound_ctrl:1
	s_nop 1
	v_add_f32_dpp v9, v9, v9 row_half_mirror row_mask:0xf bank_mask:0xf bound_ctrl:1
	s_nop 1
	v_add_f32_dpp v9, v9, v9 row_mirror row_mask:0xf bank_mask:0xf bound_ctrl:1
	v_mov_b32_e32 v15, v9
	s_nop 1
	v_permlane16_swap_b32_e32 v9, v15
	v_add_f32_e32 v9, v9, v15
	v_mov_b32_e32 v15, v9
	s_nop 1
	v_permlane32_swap_b32_e32 v9, v15
	v_add_f32_e32 v9, v9, v15
	v_fmamk_f32 v9, v9, 0x3b800000, v220
	v_cmp_gt_f32_e32 vcc, s30, v9
	v_mul_f32_e32 v15, 0x4f800000, v9
	s_nop 0
	v_cndmask_b32_e32 v9, v9, v15, vcc
	v_sqrt_f32_e32 v15, v9
	s_nop 0
	v_add_u32_e32 v22, -1, v15
	v_fma_f32 v23, -v22, v15, v9
	v_cmp_ge_f32_e64 s[38:39], 0, v23
	v_add_u32_e32 v23, 1, v15
	s_nop 0
	v_cndmask_b32_e64 v22, v15, v22, s[38:39]
	v_fma_f32 v15, -v23, v15, v9
	v_cmp_lt_f32_e64 s[38:39], 0, v15
	s_nop 1
	v_cndmask_b32_e64 v15, v22, v23, s[38:39]
	v_mul_f32_e32 v22, 0x37800000, v15
	v_cndmask_b32_e32 v15, v15, v22, vcc
	v_cmp_class_f32_e32 vcc, v9, v221
	s_nop 1
	v_cndmask_b32_e32 v9, v15, v9, vcc
	v_div_scale_f32 v15, s[36:37], v9, v9, 1.0
	v_rcp_f32_e32 v22, v15
	s_nop 0
	v_fma_f32 v23, -v15, v22, 1.0
	v_fmac_f32_e32 v22, v23, v22
	v_div_scale_f32 v23, vcc, 1.0, v9, 1.0
	v_mul_f32_e32 v26, v23, v22
	v_fma_f32 v27, -v15, v26, v23
	v_fmac_f32_e32 v26, v27, v22
	v_fma_f32 v15, -v15, v26, v23
	v_div_fmas_f32 v15, v15, v22, v26
	v_div_fixup_f32 v22, v15, v9, 1.0
	v_pk_mul_f32 v[24:25], v[24:25], v[22:23] op_sel_hi:[1,0]
	v_pk_mul_f32 v[20:21], v[20:21], v[22:23] op_sel_hi:[1,0]
	v_mov_b32_e32 v9, v209
	s_waitcnt vmcnt(0)
; __device__ __forceinline__ unsigned pk2(float lo, float hi) { const f32x2_cv v = {lo, hi}; const bf16x2_cv b = __builtin_convertvector(v, bf16x2_cv); return __builtin_bit_cast(unsigned, b); }
; __device__ __forceinline__ float bflo(unsigned w) { return __uint_as_float(w << 16); }
; __device__ __forceinline__ float bfhi(unsigned w) { return __uint_as_float(w & 0xffff0000u); }
; __global__ void __launch_bounds__(NTHR, 2) fwd_mega(Args a) {
;     ...
;                       const f32x4 g4 = *(const f32x4*)(go + 256 + 4 * lane); v2u o; o.x = pk2(y0 * rinv * g4.x, y1 * rinv * g4.y); o.y = pk2(y2 * rinv * g4.z, y3 * rinv * g4.w); *(v2u*)(hr + 256 + 4 * lane) = o; }
;                     { const v4u w0 = *(const v4u*)(yr + 256 + 8 * lane), w1 = *(const v4u*)(yr + 768 + 8 * lane);
;                       float d[8];
;                       d[0] = bflo(w0.x) - lam * bflo(w1.x); d[1] = bfhi(w0.x) - lam * bfhi(w1.x); d[2] = bflo(w0.y) - lam * bflo(w1.y); d[3] = bfhi(w0.y) - lam * bfhi(w1.y);
;                       d[4] = bflo(w0.z) - lam * bflo(w1.z); d[5] = bfhi(w0.z) - lam * bfhi(w1.z); d[6] = bflo(w0.w) - lam * bflo(w1.w); d[7] = bfhi(w0.w) - lam * bfhi(w1.w);
;                       float ss = 0.f;
; #pragma unroll
;                       for (int q = 0; q < 8; ++q) ss += d[q] * d[q];
;                       ss = row16_sum(ss);
;                       const float rinv = (1.0f - lam_init) / sqrtf(ss * (1.0f / 128.0f) + EPSF);
;                       const f32x4 ga = *(const f32x4*)(go + 512 + 8 * lane), gb = *(const f32x4*)(go + 512 + 8 * lane + 4);
;                       v4u o; o.x = pk2(d[0] * rinv * ga.x, d[1] * rinv * ga.y); o.y = pk2(d[2] * rinv * ga.z, d[3] * rinv * ga.w); o.z = pk2(d[4] * rinv * gb.x, d[5] * rinv * gb.y); o.w = pk2(d[6] * rinv * gb.z, d[7] * rinv * gb.w);
;                       *(v4u*)(hr + 512 + 8 * lane) = o; }
	v_pk_mul_f32 v[16:17], v[16:17], v[24:25]
	v_pk_mul_f32 v[18:19], v[18:19], v[20:21]
	v_cvt_pk_bf16_f32 v16, v16, v17
	v_cvt_pk_bf16_f32 v17, v18, v19
	global_store_dwordx2 v[10:11], v[16:17], off offset:512
	v_lshl_add_u64 v[10:11], s[12:13], 0, v[8:9]
	global_load_dwordx4 v[16:19], v[10:11], off offset:512
	global_load_dwordx4 v[20:23], v[10:11], off offset:1536
	global_load_dwordx4 v[24:27], v[6:7], off offset:2064
	global_load_dwordx4 v[28:31], v[6:7], off offset:2048
	s_waitcnt vmcnt(0) lgkmcnt(0)
	v_lshlrev_b32_e32 v10, 16, v19
	v_and_b32_e32 v11, 0xffff0000, v19
	v_lshlrev_b32_e32 v34, 16, v18
	v_and_b32_e32 v35, 0xffff0000, v18
	v_lshlrev_b32_e32 v18, 16, v22
	v_and_b32_e32 v19, 0xffff0000, v22
	v_pk_fma_f32 v[18:19], v[0:1], v[18:19], v[34:35] neg_lo:[1,0,0] neg_hi:[1,0,0]
	v_lshlrev_b32_e32 v34, 16, v17
	v_and_b32_e32 v35, 0xffff0000, v17
	v_lshlrev_b32_e32 v38, 16, v16
	v_and_b32_e32 v39, 0xffff0000, v16
	v_lshlrev_b32_e32 v16, 16, v20
	v_and_b32_e32 v17, 0xffff0000, v20
	v_lshlrev_b32_e32 v36, 16, v21
	v_and_b32_e32 v37, 0xffff0000, v21
	v_pk_fma_f32 v[16:17], v[0:1], v[16:17], v[38:39] neg_lo:[1,0,0] neg_hi:[1,0,0]
	v_pk_fma_f32 v[34:35], v[0:1], v[36:37], v[34:35] neg_lo:[1,0,0] neg_hi:[1,0,0]
	v_pk_mul_f32 v[20:21], v[16:17], v[16:17]
	v_pk_mul_f32 v[36:37], v[34:35], v[34:35]
	v_add_f32_e32 v15, v20, v21
	v_add_f32_e32 v15, v15, v36
	v_lshlrev_b32_e32 v32, 16, v23
	v_and_b32_e32 v33, 0xffff0000, v23
	v_pk_mul_f32 v[22:23], v[18:19], v[18:19]
	v_add_f32_e32 v15, v15, v37
	v_pk_fma_f32 v[10:11], v[0:1], v[32:33], v[10:11] neg_lo:[1,0,0] neg_hi:[1,0,0]
	v_add_f32_e32 v15, v15, v22
	v_pk_mul_f32 v[32:33], v[10:11], v[10:11]
	v_add_f32_e32 v15, v15, v23
	v_add_f32_e32 v15, v15, v32
	v_add_f32_e32 v15, v15, v33
	s_nop 1
	v_add_f32_dpp v15, v15, v15 quad_perm:[1,0,3,2] row_mask:0xf bank_mask:0xf bound_ctrl:1
	s_nop 1
	v_add_f32_dpp v15, v15, v15 quad_perm:[2,3,0,1] row_mask:0xf bank_mask:0xf bound_ctrl:1
	s_nop 1
	v_add_f32_dpp v15, v15, v15 row_half_mirror row_mask:0xf bank_mask:0xf bound_ctrl:1
	s_nop 1
	v_add_f32_dpp v15, v15, v15 row_mirror row_mask:0xf bank_mask:0xf bound_ctrl:1
	v_fmamk_f32 v15, v15, 0x3c000000, v220
	v_cmp_gt_f32_e32 vcc, s30, v15
	v_mul_f32_e32 v20, 0x4f800000, v15
	s_nop 0
	v_cndmask_b32_e32 v15, v15, v20, vcc
	v_sqrt_f32_e32 v20, v15
	s_nop 0
	v_add_u32_e32 v21, -1, v20
	v_fma_f32 v22, -v21, v20, v15
	v_cmp_ge_f32_e64 s[38:39], 0, v22
	v_add_u32_e32 v22, 1, v20
	s_nop 0
	v_cndmask_b32_e64 v21, v20, v21, s[38:39]
	v_fma_f32 v20, -v22, v20, v15
	v_cmp_lt_f32_e64 s[38:39], 0, v20
	s_nop 1
	v_cndmask_b32_e64 v20, v21, v22, s[38:39]
	v_mul_f32_e32 v21, 0x37800000, v20
	v_cndmask_b32_e32 v20, v20, v21, vcc
	v_cmp_class_f32_e32 vcc, v15, v221
	s_nop 1
	v_cndmask_b32_e32 v15, v20, v15, vcc
	v_div_scale_f32 v20, s[12:13], v15, v15, v12
	v_rcp_f32_e32 v21, v20
	s_nop 0
	v_fma_f32 v22, -v20, v21, 1.0
	v_fmac_f32_e32 v21, v22, v21
	v_div_scale_f32 v22, vcc, v12, v15, v12
	v_mul_f32_e32 v23, v22, v21
	v_fma_f32 v32, -v20, v23, v22
	v_fmac_f32_e32 v23, v32, v21
	v_fma_f32 v20, -v20, v23, v22
	v_div_fmas_f32 v20, v20, v21, v23
	v_div_fixup_f32 v20, v20, v15, v12
	v_pk_mul_f32 v[16:17], v[16:17], v[20:21] op_sel_hi:[1,0]
	v_pk_mul_f32 v[22:23], v[34:35], v[20:21] op_sel_hi:[1,0]
	v_pk_mul_f32 v[18:19], v[18:19], v[20:21] op_sel_hi:[1,0]
	v_pk_mul_f32 v[10:11], v[10:11], v[20:21] op_sel_hi:[1,0]
	v_pk_mul_f32 v[16:17], v[28:29], v[16:17]
	v_pk_mul_f32 v[22:23], v[30:31], v[22:23]
	v_pk_mul_f32 v[18:19], v[24:25], v[18:19]
	v_pk_mul_f32 v[10:11], v[26:27], v[10:11]
	v_cvt_pk_bf16_f32 v16, v16, v17
	v_cvt_pk_bf16_f32 v17, v22, v23
	v_cvt_pk_bf16_f32 v18, v18, v19
	v_cvt_pk_bf16_f32 v19, v10, v11
	v_lshl_add_u64 v[10:11], s[10:11], 0, v[8:9]
	global_store_dwordx4 v[10:11], v[16:19], off offset:1024
	s_cbranch_scc0 .LBB0_853
	v_readlane_b32 s6, v254, 29
	s_add_i32 s40, s40, s54
	s_add_i32 s35, s35, s6
	s_cmp_ge_i32 s40, s48
	s_waitcnt lgkmcnt(0)
	s_barrier
	s_cbranch_scc0 .LBB0_845

; __device__ __forceinline__ void norm_mod(const float* xl, const float* xc, const float* g, const float* mod, int shoff, int scoff, bf16_t* H, int nrows, int gw, int NGW, int lane) {
;     for (int r = gw; r < nrows; r += 4 * NGW) {
;         int rr[4]; const float* xp[4]; const float* mp[4];
; #pragma unroll
;         for (int k = 0; k < 4; ++k) { const int rk = r + k * NGW; rr[k] = rk < nrows ? rk : r; xp[k] = rr[k] < ML ? xl + (size_t)rr[k] * 1024 : xc + (size_t)(rr[k] - ML) * 1024; mp[k] = mod + (rr[k] < ML ? (rr[k] >> 13) : 4) * 6144; }
;         f32x4 v[4][4]; float ss[4];
; #pragma unroll
;         for (int k = 0; k < 4; ++k)
; #pragma unroll
;             for (int j = 0; j < 4; ++j) v[k][j] = ((const f32x4*)xp[k])[lane + 64 * j];
; #pragma unroll
;         for (int k = 0; k < 4; ++k) { ss[k] = 0.f;
; #pragma unroll
;             for (int j = 0; j < 4; ++j) ss[k] += (v[k][j].x * v[k][j].x + v[k][j].y * v[k][j].y) + (v[k][j].z * v[k][j].z + v[k][j].w * v[k][j].w); }
.LBB0_982:
	s_add_i32 s4, s2, 0xffff8000
	s_ashr_i32 s6, s2, 13
	s_cmp_lt_i32 s2, 0x8000
	v_readlane_b32 s66, v254, 35
	s_cselect_b32 s5, s3, 0
	s_cselect_b32 s4, s2, s4
	v_readlane_b32 s67, v254, 36
	s_mulk_i32 s6, 0x1800
	s_cselect_b32 s7, s67, s23
	s_cselect_b32 s10, s66, s13
	s_cselect_b32 s6, s6, 0x6000
	s_lshl_b64 s[4:5], s[4:5], 12
	s_add_u32 s10, s10, s4
	s_addc_u32 s11, s7, s5
	s_ashr_i32 s7, s6, 31
	s_lshl_b64 s[4:5], s[6:7], 2
	s_add_u32 s12, s81, s4
	v_readlane_b32 s38, v254, 55
	s_addc_u32 s52, s38, s5
	s_add_u32 s4, s92, s2
	s_addc_u32 s5, 0, s3
	s_add_u32 s53, s92, s2
	s_cmp_lt_i32 s53, s86
	s_cselect_b64 s[44:45], -1, 0
	s_and_b64 s[6:7], s[44:45], exec
	s_cselect_b32 s34, s53, s2
	s_cmp_lt_i32 s34, 0x8000
	s_cselect_b64 s[6:7], -1, 0
	s_ashr_i32 s35, s34, 31
	s_add_i32 s36, s34, 0xffff8000
	s_and_b64 s[14:15], s[6:7], exec
	s_cselect_b32 s15, s35, 0
	s_cselect_b32 s14, s34, s36
	s_cselect_b32 s35, s67, s23
	s_cselect_b32 s36, s66, s13
	s_lshl_b64 s[14:15], s[14:15], 12
	s_add_u32 s36, s36, s14
	s_addc_u32 s37, s35, s15
	s_ashr_i32 s14, s34, 13
	s_mulk_i32 s14, 0x1800
	s_and_b64 s[6:7], s[6:7], exec
	s_cselect_b32 s6, s14, 0x6000
	s_ashr_i32 s7, s6, 31
	s_lshl_b64 s[6:7], s[6:7], 2
	s_add_u32 s6, s81, s6
	s_addc_u32 s7, s38, s7
	s_add_u32 s42, s92, s53
	s_cmp_lt_i32 s42, s86
	s_cselect_b64 s[40:41], -1, 0
	s_and_b64 s[14:15], s[40:41], exec
	s_cselect_b32 s15, s42, s2
	s_cmp_lt_i32 s15, 0x8000
	s_cselect_b64 s[48:49], -1, 0
	s_ashr_i32 s14, s15, 31
	s_add_i32 s38, s15, 0xffff8000
	s_and_b64 s[34:35], s[48:49], exec
	s_cselect_b32 s35, s14, 0
	s_cselect_b32 s34, s15, s38
	s_cselect_b32 s14, s67, s23
	s_cselect_b32 s38, s66, s13
	s_lshl_b64 s[34:35], s[34:35], 12
	s_add_u32 s38, s38, s34
	s_addc_u32 s39, s14, s35
	s_add_u32 s34, s92, s42
	s_cmp_lt_i32 s34, s86
	s_cselect_b64 s[42:43], -1, 0
	s_and_b64 s[46:47], s[42:43], exec
	s_cselect_b32 s14, s34, s2
	v_mov_b32_e32 v87, v209
	s_cmp_lt_i32 s14, 0x8000
	v_lshl_add_u64 v[4:5], s[10:11], 0, v[86:87]
	s_cselect_b64 s[60:61], -1, 0
	s_ashr_i32 s35, s14, 31
	s_add_i32 s46, s14, 0xffff8000
	global_load_dwordx4 v[64:67], v[4:5], off
	global_load_dwordx4 v[44:47], v[4:5], off offset:1024
	s_and_b64 s[10:11], s[60:61], exec
	s_cselect_b32 s11, s35, 0
	s_cselect_b32 s10, s14, s46
	s_cselect_b32 s35, s67, s23
	s_cselect_b32 s46, s66, s13
	s_lshl_b64 s[10:11], s[10:11], 12
	s_add_u32 s10, s46, s10
	s_addc_u32 s11, s35, s11
	v_lshl_add_u64 v[0:1], s[10:11], 0, v[86:87]
	global_load_dwordx4 v[48:51], v[0:1], off
	global_load_dwordx4 v[32:35], v[0:1], off offset:1024
	global_load_dwordx4 v[16:19], v[0:1], off offset:2048
	s_nop 0
	global_load_dwordx4 v[0:3], v[0:1], off offset:3072
	s_nop 0
	global_load_dwordx4 v[28:31], v[4:5], off offset:2048
	global_load_dwordx4 v[12:15], v[4:5], off offset:3072
	v_lshl_add_u64 v[4:5], s[36:37], 0, v[86:87]
	global_load_dwordx4 v[60:63], v[4:5], off
	global_load_dwordx4 v[40:43], v[4:5], off offset:1024
	global_load_dwordx4 v[24:27], v[4:5], off offset:2048
	global_load_dwordx4 v[8:11], v[4:5], off offset:3072
	v_lshl_add_u64 v[4:5], s[38:39], 0, v[86:87]
	global_load_dwordx4 v[56:59], v[4:5], off
	global_load_dwordx4 v[36:39], v[4:5], off offset:1024
	global_load_dwordx4 v[20:23], v[4:5], off offset:2048
	s_nop 0
	global_load_dwordx4 v[4:7], v[4:5], off offset:3072
	s_add_u32 s10, s12, 0x4000
	s_addc_u32 s11, s52, 0
	s_add_u32 s36, s12, 0x3000
	s_addc_u32 s37, s52, 0
	s_cmp_ge_i32 s53, s86
	s_waitcnt vmcnt(0) lgkmcnt(0)
	v_mul_f32_e32 v52, v65, v65
	v_mul_f32_e32 v53, v67, v67
	v_mul_f32_e32 v54, v45, v45
	v_mul_f32_e32 v55, v47, v47
	v_fmac_f32_e32 v52, v64, v64
	v_fmac_f32_e32 v53, v66, v66
	v_fmac_f32_e32 v54, v44, v44
	v_fmac_f32_e32 v55, v46, v46
	v_add_f32_e32 v52, v52, v53
	v_add_f32_e32 v53, v54, v55
	v_add_f32_e32 v52, v52, v53
	v_mul_f32_e32 v53, v49, v49
	v_mul_f32_e32 v54, v51, v51
	v_mul_f32_e32 v55, v33, v33
	v_mul_f32_e32 v73, v35, v35
	v_mul_f32_e32 v75, v17, v17
	v_mul_f32_e32 v77, v19, v19
	v_fmac_f32_e32 v53, v48, v48
	v_fmac_f32_e32 v54, v50, v50
	v_fmac_f32_e32 v55, v32, v32
	v_fmac_f32_e32 v73, v34, v34
	v_mul_f32_e32 v87, v1, v1
	v_mul_f32_e32 v88, v3, v3
	v_fmac_f32_e32 v75, v16, v16
	v_fmac_f32_e32 v77, v18, v18
	v_add_f32_e32 v53, v53, v54
	v_add_f32_e32 v54, v55, v73
	v_fmac_f32_e32 v87, v0, v0
	v_fmac_f32_e32 v88, v2, v2
	v_add_f32_e32 v55, v75, v77
	v_add_f32_e32 v53, v53, v54
	v_add_f32_e32 v73, v87, v88
	v_add_f32_e32 v53, v53, v55
	v_add_f32_e32 v73, v53, v73
	v_mul_f32_e32 v53, v29, v29
	v_mul_f32_e32 v54, v31, v31
	v_fmac_f32_e32 v53, v28, v28
	v_fmac_f32_e32 v54, v30, v30
	v_add_f32_e32 v53, v53, v54
	v_add_f32_e32 v52, v52, v53
	v_mul_f32_e32 v53, v13, v13
	v_mul_f32_e32 v54, v15, v15
	v_fmac_f32_e32 v53, v12, v12
	v_fmac_f32_e32 v54, v14, v14
	v_add_f32_e32 v53, v53, v54
	v_add_f32_e32 v52, v52, v53
	v_mul_f32_e32 v53, v61, v61
	v_mul_f32_e32 v54, v63, v63
	v_fmac_f32_e32 v53, v60, v60
	v_fmac_f32_e32 v54, v62, v62
	v_add_f32_e32 v53, v53, v54
	v_mul_f32_e32 v54, v41, v41
	v_mul_f32_e32 v55, v43, v43
	v_fmac_f32_e32 v54, v40, v40
	v_fmac_f32_e32 v55, v42, v42
	v_add_f32_e32 v54, v54, v55
	v_add_f32_e32 v53, v53, v54
	v_mul_f32_e32 v54, v25, v25
	v_mul_f32_e32 v55, v27, v27
	v_fmac_f32_e32 v54, v24, v24
	v_fmac_f32_e32 v55, v26, v26
	v_add_f32_e32 v54, v54, v55
	v_add_f32_e32 v53, v53, v54
	v_mul_f32_e32 v54, v9, v9
	v_mul_f32_e32 v55, v11, v11
	v_fmac_f32_e32 v54, v8, v8
	v_fmac_f32_e32 v55, v10, v10
	v_add_f32_e32 v54, v54, v55
	v_add_f32_e32 v75, v53, v54
	v_mul_f32_e32 v53, v57, v57
	v_mul_f32_e32 v54, v59, v59
	v_fmac_f32_e32 v53, v56, v56
	v_fmac_f32_e32 v54, v58, v58
	v_add_f32_e32 v53, v53, v54
; __device__ __forceinline__ unsigned pk2(float lo, float hi) { const f32x2_cv v = {lo, hi}; const bf16x2_cv b = __builtin_convertvector(v, bf16x2_cv); return __builtin_bit_cast(unsigned, b); }
; __device__ __forceinline__ void norm_mod(const float* xl, const float* xc, const float* g, const float* mod, int shoff, int scoff, bf16_t* H, int nrows, int gw, int NGW, int lane) {
;     ...
;         for (int o = 1; o < 64; o <<= 1) {
; #pragma unroll
;             for (int k = 0; k < 4; ++k) { if (o == 1) ss[k] = wave_sum(ss[k]); } }
; #pragma unroll
;         for (int j = 0; j < 4; ++j) { const int col = 4 * lane + 256 * j;
;             const f32x4 g4 = *(const f32x4*)(g + col);
; #pragma unroll
;             for (int k = 0; k < 4; ++k) { if (k == 0 || r + k * NGW < nrows) {
;                 const float rinv = 1.0f / sqrtf(ss[k] * (1.0f / 1024.0f) + EPSF);
;                 const f32x4 sc4 = *(const f32x4*)(mp[k] + scoff + col), sh4 = *(const f32x4*)(mp[k] + shoff + col); const f32x4 o = (v[k][j] * rinv * g4) * (sc4 + 1.0f) + sh4;
;                 v2u w; w.x = pk2(o.x, o.y); w.y = pk2(o.z, o.w); *(v2u*)(H + (size_t)rr[k] * 1024 + col) = w; } }
	v_mul_f32_e32 v54, v37, v37
	v_mul_f32_e32 v55, v39, v39
	v_fmac_f32_e32 v54, v36, v36
	v_fmac_f32_e32 v55, v38, v38
	v_add_f32_e32 v54, v54, v55
	v_add_f32_e32 v53, v53, v54
	v_mul_f32_e32 v54, v21, v21
	v_mul_f32_e32 v55, v23, v23
	v_fmac_f32_e32 v54, v20, v20
	v_fmac_f32_e32 v55, v22, v22
	v_add_f32_e32 v54, v54, v55
	v_add_f32_e32 v53, v53, v54
	v_mul_f32_e32 v54, v5, v5
	v_mul_f32_e32 v55, v7, v7
	v_add_f32_dpp v52, v52, v52 quad_perm:[1,0,3,2] row_mask:0xf bank_mask:0xf bound_ctrl:1
	v_fmac_f32_e32 v54, v4, v4
	v_fmac_f32_e32 v55, v6, v6
	v_add_f32_dpp v52, v52, v52 quad_perm:[2,3,0,1] row_mask:0xf bank_mask:0xf bound_ctrl:1
	v_add_f32_e32 v54, v54, v55
	v_lshl_add_u64 v[88:89], s[10:11], 0, v[208:209]
	v_add_f32_dpp v52, v52, v52 row_half_mirror row_mask:0xf bank_mask:0xf bound_ctrl:1
	v_add_f32_e32 v77, v53, v54
	global_load_dwordx4 v[90:93], v[88:89], off
	v_add_f32_dpp v87, v52, v52 row_mirror row_mask:0xf bank_mask:0xf bound_ctrl:1
	global_load_dwordx4 v[52:55], v[68:69], off
	v_lshl_add_u64 v[88:89], s[36:37], 0, v[208:209]
	global_load_dwordx4 v[94:97], v[88:89], off
	v_mov_b32_e32 v88, v87
	s_nop 1
	v_permlane16_swap_b32_e32 v87, v88
	v_add_f32_dpp v75, v75, v75 quad_perm:[1,0,3,2] row_mask:0xf bank_mask:0xf bound_ctrl:1
	v_add_f32_e32 v87, v87, v88
	v_mov_b32_e32 v88, v87
	v_add_f32_dpp v75, v75, v75 quad_perm:[2,3,0,1] row_mask:0xf bank_mask:0xf bound_ctrl:1
	s_nop 0
	v_permlane32_swap_b32_e32 v87, v88
	v_add_f32_dpp v75, v75, v75 row_half_mirror row_mask:0xf bank_mask:0xf bound_ctrl:1
	v_add_f32_e32 v88, v87, v88
	v_fmamk_f32 v88, v88, 0x3a800000, v220
	v_add_f32_dpp v75, v75, v75 row_mirror row_mask:0xf bank_mask:0xf bound_ctrl:1
	v_mov_b32_e32 v87, v75
	s_nop 1
	v_permlane16_swap_b32_e32 v75, v87
	v_add_f32_e32 v75, v75, v87
	v_mov_b32_e32 v87, v75
	s_nop 1
	v_permlane32_swap_b32_e32 v75, v87
	v_add_f32_e32 v89, v75, v87
	s_nop 0
	v_add_f32_dpp v75, v77, v77 quad_perm:[1,0,3,2] row_mask:0xf bank_mask:0xf bound_ctrl:1
	v_add_f32_dpp v73, v73, v73 quad_perm:[1,0,3,2] row_mask:0xf bank_mask:0xf bound_ctrl:1
	v_mul_f32_e32 v98, 0x4f800000, v88
	v_add_f32_dpp v75, v75, v75 quad_perm:[2,3,0,1] row_mask:0xf bank_mask:0xf bound_ctrl:1
	v_cmp_gt_f32_e32 vcc, s30, v88
	v_add_f32_dpp v73, v73, v73 quad_perm:[2,3,0,1] row_mask:0xf bank_mask:0xf bound_ctrl:1
	v_add_f32_dpp v75, v75, v75 row_half_mirror row_mask:0xf bank_mask:0xf bound_ctrl:1
	v_cndmask_b32_e32 v88, v88, v98, vcc
	v_add_f32_dpp v73, v73, v73 row_half_mirror row_mask:0xf bank_mask:0xf bound_ctrl:1
	v_add_f32_dpp v75, v75, v75 row_mirror row_mask:0xf bank_mask:0xf bound_ctrl:1
	v_mov_b32_e32 v77, v75
	v_sqrt_f32_e32 v98, v88
	s_nop 0
	v_permlane16_swap_b32_e32 v75, v77
	v_add_f32_dpp v73, v73, v73 row_mirror row_mask:0xf bank_mask:0xf bound_ctrl:1
	v_add_f32_e32 v77, v75, v77
	v_mov_b32_e32 v75, v73
	s_nop 1
	v_permlane16_swap_b32_e32 v73, v75
	v_add_f32_e32 v73, v73, v75
	v_add_u32_e32 v75, -1, v98
	v_fma_f32 v99, -v75, v98, v88
	v_cmp_ge_f32_e64 s[38:39], 0, v99
	v_add_u32_e32 v99, 1, v98
	v_mov_b32_e32 v87, v77
	v_cndmask_b32_e64 v75, v98, v75, s[38:39]
	v_fma_f32 v98, -v99, v98, v88
	v_cmp_lt_f32_e64 s[38:39], 0, v98
	v_permlane32_swap_b32_e32 v77, v87
	s_nop 0
	v_cndmask_b32_e64 v75, v75, v99, s[38:39]
	v_mul_f32_e32 v98, 0x37800000, v75
	v_cndmask_b32_e32 v75, v75, v98, vcc
	v_cmp_class_f32_e32 vcc, v88, v221
	s_waitcnt vmcnt(0) lgkmcnt(0)
	v_pk_add_f32 v[92:93], v[92:93], 1.0 op_sel_hi:[1,0]
	v_cndmask_b32_e32 v88, v75, v88, vcc
	v_div_scale_f32 v98, s[38:39], v88, v88, 1.0
	v_rcp_f32_e32 v99, v98
	v_pk_add_f32 v[90:91], v[90:91], 1.0 op_sel_hi:[1,0]
	v_mov_b32_e32 v75, v73
	s_nop 1
	v_permlane32_swap_b32_e32 v73, v75
	v_fma_f32 v100, -v98, v99, 1.0
	v_fmac_f32_e32 v99, v100, v99
	v_div_scale_f32 v100, vcc, 1.0, v88, 1.0
	v_mul_f32_e32 v101, v100, v99
	v_fma_f32 v102, -v98, v101, v100
	v_fmac_f32_e32 v101, v102, v99
	v_fma_f32 v98, -v98, v101, v100
	v_div_fmas_f32 v98, v98, v99, v101
	v_div_fixup_f32 v88, v98, v88, 1.0
	v_pk_mul_f32 v[66:67], v[66:67], v[88:89] op_sel_hi:[1,0]
	v_pk_mul_f32 v[64:65], v[64:65], v[88:89] op_sel_hi:[1,0]
	v_pk_mul_f32 v[66:67], v[66:67], v[54:55]
	v_pk_mul_f32 v[64:65], v[64:65], v[52:53]
	v_pk_fma_f32 v[66:67], v[66:67], v[92:93], v[96:97]
	v_pk_fma_f32 v[64:65], v[64:65], v[90:91], v[94:95]
	s_nop 0
	v_cvt_pk_bf16_f32 v64, v64, v65
	v_cvt_pk_bf16_f32 v65, v66, v67
	global_store_dwordx2 v[84:85], v[64:65], off
	v_fmamk_f32 v64, v89, 0x3a800000, v220
	v_cmp_gt_f32_e32 vcc, s30, v64
	v_mul_f32_e32 v65, 0x4f800000, v64
	s_cbranch_scc1 .LBB0_984
	v_cndmask_b32_e32 v66, v64, v65, vcc
	v_sqrt_f32_e32 v67, v66
	v_lshl_add_u64 v[94:95], s[6:7], 0, v[208:209]
	v_add_u32_e32 v89, -1, v67
	v_fma_f32 v90, -v89, v67, v66
	v_cmp_ge_f32_e64 s[38:39], 0, v90
	v_add_u32_e32 v90, 1, v67
	s_nop 0
	v_cndmask_b32_e64 v89, v67, v89, s[38:39]
	v_fma_f32 v67, -v90, v67, v66
	v_cmp_lt_f32_e64 s[38:39], 0, v67
	s_nop 1
	v_cndmask_b32_e64 v67, v89, v90, s[38:39]
	v_mul_f32_e32 v89, 0x37800000, v67
	v_cndmask_b32_e32 v67, v67, v89, vcc
	v_cmp_class_f32_e32 vcc, v66, v221
	s_nop 1
	v_cndmask_b32_e32 v66, v67, v66, vcc
	v_div_scale_f32 v67, s[38:39], v66, v66, 1.0
	v_rcp_f32_e32 v89, v67
	s_bfe_i64 s[38:39], s[4:5], 0x200000
	s_lshl_b64 s[38:39], s[38:39], 11
	v_fma_f32 v90, -v67, v89, 1.0
	v_fmac_f32_e32 v89, v90, v89
	v_div_scale_f32 v90, vcc, 1.0, v66, 1.0
	v_mul_f32_e32 v91, v90, v89
	v_fma_f32 v92, -v67, v91, v90
	v_fmac_f32_e32 v91, v92, v89
	v_fma_f32 v67, -v67, v91, v90
	v_div_fmas_f32 v67, v67, v89, v91
	v_add_co_u32_e32 v90, vcc, s80, v94
	v_div_fixup_f32 v66, v67, v66, 1.0
	s_nop 0
	v_addc_co_u32_e32 v91, vcc, 0, v95, vcc
	v_add_co_u32_e32 v94, vcc, s72, v94
	global_load_dwordx4 v[90:93], v[90:91], off
	s_nop 0
	v_addc_co_u32_e32 v95, vcc, 0, v95, vcc
	global_load_dwordx4 v[94:97], v[94:95], off
	v_pk_mul_f32 v[62:63], v[62:63], v[66:67] op_sel_hi:[1,0]
	v_pk_mul_f32 v[60:61], v[60:61], v[66:67] op_sel_hi:[1,0]
	v_pk_mul_f32 v[62:63], v[62:63], v[54:55]
	v_pk_mul_f32 v[60:61], v[60:61], v[52:53]
	s_waitcnt vmcnt(0) lgkmcnt(0)
	v_pk_add_f32 v[66:67], v[92:93], 1.0 op_sel_hi:[1,0]
	v_pk_add_f32 v[90:91], v[90:91], 1.0 op_sel_hi:[1,0]
	v_pk_fma_f32 v[62:63], v[62:63], v[66:67], v[96:97]
	v_pk_fma_f32 v[60:61], v[60:61], v[90:91], v[94:95]
	s_nop 0
	v_cvt_pk_bf16_f32 v60, v60, v61
	v_cvt_pk_bf16_f32 v61, v62, v63
	v_lshl_add_u64 v[62:63], v[70:71], 0, s[38:39]
	global_store_dwordx2 v[62:63], v[60:61], off
; __device__ __forceinline__ unsigned pk2(float lo, float hi) { const f32x2_cv v = {lo, hi}; const bf16x2_cv b = __builtin_convertvector(v, bf16x2_cv); return __builtin_bit_cast(unsigned, b); }
; __device__ __forceinline__ void norm_mod(const float* xl, const float* xc, const float* g, const float* mod, int shoff, int scoff, bf16_t* H, int nrows, int gw, int NGW, int lane) {
;     ...
;         for (int j = 0; j < 4; ++j) { const int col = 4 * lane + 256 * j;
;             const f32x4 g4 = *(const f32x4*)(g + col);
; #pragma unroll
;             for (int k = 0; k < 4; ++k) { if (k == 0 || r + k * NGW < nrows) {
;                 const float rinv = 1.0f / sqrtf(ss[k] * (1.0f / 1024.0f) + EPSF);
;                 const f32x4 sc4 = *(const f32x4*)(mp[k] + scoff + col), sh4 = *(const f32x4*)(mp[k] + shoff + col); const f32x4 o = (v[k][j] * rinv * g4) * (sc4 + 1.0f) + sh4;
;                 v2u w; w.x = pk2(o.x, o.y); w.y = pk2(o.z, o.w); *(v2u*)(H + (size_t)rr[k] * 1024 + col) = w; } }
.LBB0_984:
	v_readlane_b32 s12, v254, 13
	s_add_u32 s46, s12, s2
	s_addc_u32 s47, 0, s3
	s_ashr_i32 s12, s15, 13
	s_mulk_i32 s12, 0x1800
	s_and_b64 s[38:39], s[48:49], exec
	s_cselect_b32 s38, s12, 0x6000
	s_ashr_i32 s39, s38, 31
	s_lshl_b64 s[38:39], s[38:39], 2
	v_add_f32_e32 v60, v77, v87
	s_add_u32 s48, s81, s38
	v_readlane_b32 s35, v254, 55
	v_cndmask_b32_e64 v61, 0, 1, s[40:41]
	v_fmamk_f32 v60, v60, 0x3a800000, v220
	s_addc_u32 s49, s35, s39
	v_cmp_ne_u32_e64 s[38:39], 1, v61
	s_andn2_b64 vcc, exec, s[40:41]
	v_cmp_gt_f32_e64 s[40:41], s30, v60
	v_mul_f32_e32 v61, 0x4f800000, v60
	s_cbranch_vccnz .LBB0_986
	v_cndmask_b32_e64 v62, v60, v61, s[40:41]
	v_sqrt_f32_e32 v63, v62
	s_nop 0
	v_add_u32_e32 v66, -1, v63
	v_fma_f32 v67, -v66, v63, v62
	v_cmp_ge_f32_e32 vcc, 0, v67
	v_add_u32_e32 v67, 1, v63
	s_nop 0
	v_cndmask_b32_e32 v66, v63, v66, vcc
	v_fma_f32 v63, -v67, v63, v62
	v_cmp_lt_f32_e32 vcc, 0, v63
	s_nop 1
	v_cndmask_b32_e32 v63, v66, v67, vcc
	v_mul_f32_e32 v66, 0x37800000, v63
	v_cndmask_b32_e64 v63, v63, v66, s[40:41]
	v_cmp_class_f32_e32 vcc, v62, v221
	s_nop 1
	v_cndmask_b32_e32 v62, v63, v62, vcc
	v_div_scale_f32 v63, s[40:41], v62, v62, 1.0
	v_rcp_f32_e32 v66, v63
	s_bfe_i64 s[40:41], s[46:47], 0x200000
	s_lshl_b64 s[40:41], s[40:41], 11
	v_fma_f32 v67, -v63, v66, 1.0
	v_fmac_f32_e32 v66, v67, v66
	v_div_scale_f32 v67, vcc, 1.0, v62, 1.0
	v_mul_f32_e32 v77, v67, v66
	v_fma_f32 v87, -v63, v77, v67
	v_fmac_f32_e32 v77, v87, v66
	v_fma_f32 v63, -v63, v77, v67
	v_div_fmas_f32 v63, v63, v66, v77
	v_lshl_add_u64 v[66:67], s[48:49], 0, v[208:209]
	v_add_co_u32_e32 v90, vcc, s80, v66
	v_div_fixup_f32 v62, v63, v62, 1.0
	s_nop 0
	v_addc_co_u32_e32 v91, vcc, 0, v67, vcc
	v_add_co_u32_e32 v66, vcc, s72, v66
	global_load_dwordx4 v[90:93], v[90:91], off
	s_nop 0
	v_addc_co_u32_e32 v67, vcc, 0, v67, vcc
	global_load_dwordx4 v[94:97], v[66:67], off
	v_pk_mul_f32 v[58:59], v[58:59], v[62:63] op_sel_hi:[1,0]
	v_pk_mul_f32 v[56:57], v[56:57], v[62:63] op_sel_hi:[1,0]
	v_pk_mul_f32 v[58:59], v[54:55], v[58:59]
	v_pk_mul_f32 v[56:57], v[52:53], v[56:57]
	s_waitcnt vmcnt(0) lgkmcnt(0)
	v_pk_add_f32 v[62:63], v[92:93], 1.0 op_sel_hi:[1,0]
	v_pk_add_f32 v[66:67], v[90:91], 1.0 op_sel_hi:[1,0]
	v_pk_fma_f32 v[58:59], v[58:59], v[62:63], v[96:97]
	v_pk_fma_f32 v[56:57], v[56:57], v[66:67], v[94:95]
	s_nop 0
	v_cvt_pk_bf16_f32 v56, v56, v57
	v_cvt_pk_bf16_f32 v57, v58, v59
	v_lshl_add_u64 v[58:59], v[70:71], 0, s[40:41]
	global_store_dwordx2 v[58:59], v[56:57], off
.LBB0_986:
	s_mul_i32 s12, s54, 24
	s_add_u32 s52, s12, s2
	s_addc_u32 s53, 0, s3
	s_ashr_i32 s12, s14, 13
	s_mulk_i32 s12, 0x1800
	s_and_b64 s[14:15], s[60:61], exec
	s_cselect_b32 s14, s12, 0x6000
	s_ashr_i32 s15, s14, 31
	s_lshl_b64 s[14:15], s[14:15], 2
	v_add_f32_e32 v56, v73, v75
	s_add_u32 s60, s81, s14
	v_cndmask_b32_e64 v57, 0, 1, s[42:43]
	v_fmamk_f32 v56, v56, 0x3a800000, v220
	s_addc_u32 s61, s35, s15
	v_cmp_ne_u32_e64 s[40:41], 1, v57
	s_andn2_b64 vcc, exec, s[42:43]
	v_cmp_gt_f32_e64 s[42:43], s30, v56
	v_mul_f32_e32 v57, 0x4f800000, v56
	s_cbranch_vccnz .LBB0_988
	v_cndmask_b32_e64 v58, v56, v57, s[42:43]
	v_sqrt_f32_e32 v59, v58
	s_nop 0
	v_add_u32_e32 v62, -1, v59
	v_fma_f32 v63, -v62, v59, v58
	v_cmp_ge_f32_e32 vcc, 0, v63
	v_add_u32_e32 v63, 1, v59
	s_nop 0
	v_cndmask_b32_e32 v62, v59, v62, vcc
	v_fma_f32 v59, -v63, v59, v58
	v_cmp_lt_f32_e32 vcc, 0, v59
	s_nop 1
	v_cndmask_b32_e32 v59, v62, v63, vcc
	v_mul_f32_e32 v62, 0x37800000, v59
	v_cndmask_b32_e64 v59, v59, v62, s[42:43]
	v_cmp_class_f32_e32 vcc, v58, v221
	s_nop 1
	v_cndmask_b32_e32 v58, v59, v58, vcc
	v_div_scale_f32 v59, s[14:15], v58, v58, 1.0
	v_rcp_f32_e32 v62, v59
	s_bfe_i64 s[14:15], s[52:53], 0x200000
	s_lshl_b64 s[14:15], s[14:15], 11
	v_fma_f32 v63, -v59, v62, 1.0
	v_fmac_f32_e32 v62, v63, v62
	v_div_scale_f32 v63, vcc, 1.0, v58, 1.0
	v_mul_f32_e32 v66, v63, v62
	v_fma_f32 v67, -v59, v66, v63
	v_fmac_f32_e32 v66, v67, v62
	v_fma_f32 v59, -v59, v66, v63
	v_div_fmas_f32 v59, v59, v62, v66
	v_lshl_add_u64 v[62:63], s[60:61], 0, v[208:209]
	v_add_co_u32_e32 v66, vcc, s80, v62
	v_div_fixup_f32 v58, v59, v58, 1.0
	s_nop 0
	v_addc_co_u32_e32 v67, vcc, 0, v63, vcc
	v_add_co_u32_e32 v62, vcc, s72, v62
	global_load_dwordx4 v[90:93], v[66:67], off
	s_nop 0
	v_addc_co_u32_e32 v63, vcc, 0, v63, vcc
	global_load_dwordx4 v[94:97], v[62:63], off
	v_pk_mul_f32 v[50:51], v[50:51], v[58:59] op_sel_hi:[1,0]
	v_pk_mul_f32 v[48:49], v[48:49], v[58:59] op_sel_hi:[1,0]
	v_pk_mul_f32 v[50:51], v[54:55], v[50:51]
	v_pk_mul_f32 v[48:49], v[52:53], v[48:49]
	s_waitcnt vmcnt(0) lgkmcnt(0)
	v_pk_add_f32 v[52:53], v[92:93], 1.0 op_sel_hi:[1,0]
	v_pk_add_f32 v[54:55], v[90:91], 1.0 op_sel_hi:[1,0]
	v_pk_fma_f32 v[50:51], v[50:51], v[52:53], v[96:97]
	v_pk_fma_f32 v[48:49], v[48:49], v[54:55], v[94:95]
	s_nop 0
	v_cvt_pk_bf16_f32 v48, v48, v49
	v_cvt_pk_bf16_f32 v49, v50, v51
	v_lshl_add_u64 v[50:51], v[70:71], 0, s[14:15]
	global_store_dwordx2 v[50:51], v[48:49], off
; __device__ __forceinline__ unsigned pk2(float lo, float hi) { const f32x2_cv v = {lo, hi}; const bf16x2_cv b = __builtin_convertvector(v, bf16x2_cv); return __builtin_bit_cast(unsigned, b); }
; __device__ __forceinline__ void norm_mod(const float* xl, const float* xc, const float* g, const float* mod, int shoff, int scoff, bf16_t* H, int nrows, int gw, int NGW, int lane) {
;     ...
;         for (int j = 0; j < 4; ++j) { const int col = 4 * lane + 256 * j;
;             const f32x4 g4 = *(const f32x4*)(g + col);
; #pragma unroll
;             for (int k = 0; k < 4; ++k) { if (k == 0 || r + k * NGW < nrows) {
;                 const float rinv = 1.0f / sqrtf(ss[k] * (1.0f / 1024.0f) + EPSF);
;                 const f32x4 sc4 = *(const f32x4*)(mp[k] + scoff + col), sh4 = *(const f32x4*)(mp[k] + shoff + col); const f32x4 o = (v[k][j] * rinv * g4) * (sc4 + 1.0f) + sh4;
;                 v2u w; w.x = pk2(o.x, o.y); w.y = pk2(o.z, o.w); *(v2u*)(H + (size_t)rr[k] * 1024 + col) = w; } }
.LBB0_988:
	v_lshlrev_b32_e32 v52, 2, v72
	v_mov_b32_e32 v53, v209
	v_lshl_add_u64 v[54:55], s[10:11], 0, v[52:53]
	global_load_dwordx4 v[48:51], v[68:69], off offset:1024
	global_load_dwordx4 v[90:93], v[54:55], off
	v_lshl_add_u64 v[54:55], s[36:37], 0, v[52:53]
	global_load_dwordx4 v[94:97], v[54:55], off
	v_mov_b32_e32 v89, v88
	v_mov_b32_e32 v54, v88
	v_mov_b32_e32 v55, v88
	v_pk_mul_f32 v[46:47], v[46:47], v[54:55]
	v_pk_mul_f32 v[44:45], v[44:45], v[88:89]
	s_andn2_b64 vcc, exec, s[44:45]
	s_waitcnt vmcnt(0)
	v_pk_mul_f32 v[46:47], v[46:47], v[50:51]
	v_pk_mul_f32 v[44:45], v[44:45], v[48:49]
	s_waitcnt lgkmcnt(0)
	v_pk_add_f32 v[54:55], v[92:93], 1.0 op_sel_hi:[1,0]
	v_pk_add_f32 v[58:59], v[90:91], 1.0 op_sel_hi:[1,0]
	v_pk_fma_f32 v[46:47], v[46:47], v[54:55], v[96:97]
	v_pk_fma_f32 v[44:45], v[44:45], v[58:59], v[94:95]
	s_nop 0
	v_cvt_pk_bf16_f32 v44, v44, v45
	v_cvt_pk_bf16_f32 v45, v46, v47
	global_store_dwordx2 v[84:85], v[44:45], off offset:512
	v_cndmask_b32_e64 v44, 0, 1, s[44:45]
	v_cmp_ne_u32_e64 s[42:43], 1, v44
	s_cbranch_vccnz .LBB0_999
	v_cmp_gt_f32_e32 vcc, s30, v64
	v_lshl_add_u64 v[58:59], s[6:7], 0, v[52:53]
	s_nop 0
	v_cndmask_b32_e32 v44, v64, v65, vcc
	v_sqrt_f32_e32 v45, v44
	s_nop 0
	v_add_u32_e32 v46, -1, v45
	v_fma_f32 v47, -v46, v45, v44
	v_cmp_ge_f32_e64 s[44:45], 0, v47
	v_add_u32_e32 v47, 1, v45
	s_nop 0
	v_cndmask_b32_e64 v46, v45, v46, s[44:45]
	v_fma_f32 v45, -v47, v45, v44
	v_cmp_lt_f32_e64 s[44:45], 0, v45
	s_nop 1
	v_cndmask_b32_e64 v45, v46, v47, s[44:45]
	v_mul_f32_e32 v46, 0x37800000, v45
	v_cndmask_b32_e32 v45, v45, v46, vcc
	v_cmp_class_f32_e32 vcc, v44, v221
	s_nop 1
	v_cndmask_b32_e32 v44, v45, v44, vcc
	v_div_scale_f32 v45, s[14:15], v44, v44, 1.0
	v_rcp_f32_e32 v46, v45
	s_bfe_i64 s[14:15], s[4:5], 0x200000
	s_lshl_b64 s[14:15], s[14:15], 11
	v_fma_f32 v47, -v45, v46, 1.0
	v_fmac_f32_e32 v46, v47, v46
	v_div_scale_f32 v47, vcc, 1.0, v44, 1.0
	v_mul_f32_e32 v54, v47, v46
	v_fma_f32 v55, -v45, v54, v47
	v_fmac_f32_e32 v54, v55, v46
	v_fma_f32 v45, -v45, v54, v47
	v_div_fmas_f32 v45, v45, v46, v54
	v_div_fixup_f32 v54, v45, v44, 1.0
	v_add_co_u32_e32 v44, vcc, s80, v58
	v_pk_mul_f32 v[42:43], v[42:43], v[54:55] op_sel_hi:[1,0]
	s_nop 0
	v_addc_co_u32_e32 v45, vcc, 0, v59, vcc
	v_add_co_u32_e32 v58, vcc, s72, v58
	global_load_dwordx4 v[44:47], v[44:45], off
	s_nop 0
	v_addc_co_u32_e32 v59, vcc, 0, v59, vcc
	global_load_dwordx4 v[90:93], v[58:59], off
	v_pk_mul_f32 v[40:41], v[40:41], v[54:55] op_sel_hi:[1,0]
	v_pk_mul_f32 v[42:43], v[42:43], v[50:51]
	v_pk_mul_f32 v[40:41], v[40:41], v[48:49]
	s_waitcnt vmcnt(0) lgkmcnt(0)
	v_pk_add_f32 v[46:47], v[46:47], 1.0 op_sel_hi:[1,0]
	v_pk_add_f32 v[44:45], v[44:45], 1.0 op_sel_hi:[1,0]
	v_pk_fma_f32 v[42:43], v[42:43], v[46:47], v[92:93]
	v_pk_fma_f32 v[40:41], v[40:41], v[44:45], v[90:91]
	s_nop 0
	v_cvt_pk_bf16_f32 v40, v40, v41
	v_cvt_pk_bf16_f32 v41, v42, v43
	v_lshl_add_u64 v[42:43], v[78:79], 0, s[14:15]
	global_store_dwordx2 v[42:43], v[40:41], off
	s_and_b64 vcc, exec, s[38:39]
	s_cbranch_vccz .LBB0_1000

; __device__ __forceinline__ unsigned pk2(float lo, float hi) { const f32x2_cv v = {lo, hi}; const bf16x2_cv b = __builtin_convertvector(v, bf16x2_cv); return __builtin_bit_cast(unsigned, b); }
; __device__ __forceinline__ void norm_mod(const float* xl, const float* xc, const float* g, const float* mod, int shoff, int scoff, bf16_t* H, int nrows, int gw, int NGW, int lane) {
;     ...
;         for (int j = 0; j < 4; ++j) { const int col = 4 * lane + 256 * j;
;             const f32x4 g4 = *(const f32x4*)(g + col);
; #pragma unroll
;             for (int k = 0; k < 4; ++k) { if (k == 0 || r + k * NGW < nrows) {
;                 const float rinv = 1.0f / sqrtf(ss[k] * (1.0f / 1024.0f) + EPSF);
;                 const f32x4 sc4 = *(const f32x4*)(mp[k] + scoff + col), sh4 = *(const f32x4*)(mp[k] + shoff + col); const f32x4 o = (v[k][j] * rinv * g4) * (sc4 + 1.0f) + sh4;
;                 v2u w; w.x = pk2(o.x, o.y); w.y = pk2(o.z, o.w); *(v2u*)(H + (size_t)rr[k] * 1024 + col) = w; } }
.LBB0_991:
	v_cmp_gt_f32_e32 vcc, s30, v56
	v_mov_b32_e32 v53, v209
	s_nop 0
	v_cndmask_b32_e32 v36, v56, v57, vcc
	v_sqrt_f32_e32 v37, v36
	s_nop 0
	v_add_u32_e32 v38, -1, v37
	v_fma_f32 v39, -v38, v37, v36
	v_cmp_ge_f32_e64 s[44:45], 0, v39
	v_add_u32_e32 v39, 1, v37
	s_nop 0
	v_cndmask_b32_e64 v38, v37, v38, s[44:45]
	v_fma_f32 v37, -v39, v37, v36
	v_cmp_lt_f32_e64 s[44:45], 0, v37
	s_nop 1
	v_cndmask_b32_e64 v37, v38, v39, s[44:45]
	v_mul_f32_e32 v38, 0x37800000, v37
	v_cndmask_b32_e32 v37, v37, v38, vcc
	v_cmp_class_f32_e32 vcc, v36, v221
	s_nop 1
	v_cndmask_b32_e32 v36, v37, v36, vcc
	v_div_scale_f32 v37, s[14:15], v36, v36, 1.0
	v_rcp_f32_e32 v38, v37
	s_bfe_i64 s[14:15], s[52:53], 0x200000
	s_lshl_b64 s[14:15], s[14:15], 11
	v_fma_f32 v39, -v37, v38, 1.0
	v_fmac_f32_e32 v38, v39, v38
	v_div_scale_f32 v39, vcc, 1.0, v36, 1.0
	v_mul_f32_e32 v40, v39, v38
	v_fma_f32 v41, -v37, v40, v39
	v_fmac_f32_e32 v40, v41, v38
	v_fma_f32 v37, -v37, v40, v39
	v_div_fmas_f32 v37, v37, v38, v40
	v_lshl_add_u64 v[40:41], s[60:61], 0, v[52:53]
	v_div_fixup_f32 v44, v37, v36, 1.0
	v_add_co_u32_e32 v36, vcc, s80, v40
	v_pk_mul_f32 v[34:35], v[34:35], v[44:45] op_sel_hi:[1,0]
	s_nop 0
	v_addc_co_u32_e32 v37, vcc, 0, v41, vcc
	v_add_co_u32_e32 v40, vcc, s72, v40
	global_load_dwordx4 v[36:39], v[36:37], off
	s_nop 0
	v_addc_co_u32_e32 v41, vcc, 0, v41, vcc
	global_load_dwordx4 v[40:43], v[40:41], off
	v_pk_mul_f32 v[32:33], v[32:33], v[44:45] op_sel_hi:[1,0]
	v_pk_mul_f32 v[34:35], v[34:35], v[50:51]
	v_pk_mul_f32 v[32:33], v[32:33], v[48:49]
	s_waitcnt vmcnt(0) lgkmcnt(0)
	v_pk_add_f32 v[38:39], v[38:39], 1.0 op_sel_hi:[1,0]
	v_pk_add_f32 v[36:37], v[36:37], 1.0 op_sel_hi:[1,0]
	v_pk_fma_f32 v[34:35], v[34:35], v[38:39], v[42:43]
	v_pk_fma_f32 v[32:33], v[32:33], v[36:37], v[40:41]
	s_nop 0
	v_cvt_pk_bf16_f32 v32, v32, v33
	v_cvt_pk_bf16_f32 v33, v34, v35
	v_lshl_add_u64 v[34:35], v[78:79], 0, s[14:15]
	global_store_dwordx2 v[34:35], v[32:33], off
.LBB0_992:
	v_lshlrev_b32_e32 v36, 2, v74
	v_mov_b32_e32 v37, v209
	v_lshl_add_u64 v[38:39], s[10:11], 0, v[36:37]
	global_load_dwordx4 v[32:35], v[68:69], off offset:2048
	v_lshl_add_u64 v[42:43], s[36:37], 0, v[36:37]
	global_load_dwordx4 v[38:41], v[38:39], off
	v_mov_b32_e32 v46, v88
	global_load_dwordx4 v[42:45], v[42:43], off
	v_mov_b32_e32 v47, v88
	v_pk_mul_f32 v[30:31], v[30:31], v[46:47]
	v_pk_mul_f32 v[28:29], v[28:29], v[88:89]
	s_and_b64 vcc, exec, s[42:43]
	s_waitcnt vmcnt(0)
	v_pk_mul_f32 v[30:31], v[30:31], v[34:35]
	v_pk_mul_f32 v[28:29], v[28:29], v[32:33]
	s_waitcnt lgkmcnt(0)
	v_pk_add_f32 v[40:41], v[40:41], 1.0 op_sel_hi:[1,0]
	v_pk_add_f32 v[38:39], v[38:39], 1.0 op_sel_hi:[1,0]
	v_pk_fma_f32 v[30:31], v[30:31], v[40:41], v[44:45]
	v_pk_fma_f32 v[28:29], v[28:29], v[38:39], v[42:43]
	s_nop 0
	v_cvt_pk_bf16_f32 v28, v28, v29
	v_cvt_pk_bf16_f32 v29, v30, v31
	global_store_dwordx2 v[84:85], v[28:29], off offset:1024
	s_cbranch_vccnz .LBB0_1001
	v_cmp_gt_f32_e32 vcc, s30, v64
	s_nop 1
	v_cndmask_b32_e32 v28, v64, v65, vcc
	v_sqrt_f32_e32 v29, v28
	s_nop 0
	v_add_u32_e32 v30, -1, v29
	v_fma_f32 v31, -v30, v29, v28
	v_cmp_ge_f32_e64 s[44:45], 0, v31
	v_add_u32_e32 v31, 1, v29
	s_nop 0
	v_cndmask_b32_e64 v30, v29, v30, s[44:45]
	v_fma_f32 v29, -v31, v29, v28
	v_cmp_lt_f32_e64 s[44:45], 0, v29
	s_nop 1
	v_cndmask_b32_e64 v29, v30, v31, s[44:45]
	v_mul_f32_e32 v30, 0x37800000, v29
	v_cndmask_b32_e32 v29, v29, v30, vcc
	v_cmp_class_f32_e32 vcc, v28, v221
	s_nop 1
	v_cndmask_b32_e32 v28, v29, v28, vcc
	v_div_scale_f32 v29, s[14:15], v28, v28, 1.0
	v_rcp_f32_e32 v30, v29
	s_bfe_i64 s[14:15], s[4:5], 0x200000
	s_lshl_b64 s[14:15], s[14:15], 11
	v_fma_f32 v31, -v29, v30, 1.0
	v_fmac_f32_e32 v30, v31, v30
	v_div_scale_f32 v31, vcc, 1.0, v28, 1.0
	v_mul_f32_e32 v38, v31, v30
	v_fma_f32 v39, -v29, v38, v31
	v_fmac_f32_e32 v38, v39, v30
	v_fma_f32 v29, -v29, v38, v31
	v_div_fmas_f32 v29, v29, v30, v38
	v_lshl_add_u64 v[38:39], s[6:7], 0, v[36:37]
	v_div_fixup_f32 v42, v29, v28, 1.0
	v_add_co_u32_e32 v28, vcc, s80, v38
	v_pk_mul_f32 v[26:27], v[26:27], v[42:43] op_sel_hi:[1,0]
	s_nop 0
	v_addc_co_u32_e32 v29, vcc, 0, v39, vcc
	v_add_co_u32_e32 v38, vcc, s72, v38
	global_load_dwordx4 v[28:31], v[28:29], off
	s_nop 0
	v_addc_co_u32_e32 v39, vcc, 0, v39, vcc
	global_load_dwordx4 v[38:41], v[38:39], off
	v_pk_mul_f32 v[24:25], v[24:25], v[42:43] op_sel_hi:[1,0]
	v_pk_mul_f32 v[26:27], v[26:27], v[34:35]
	v_pk_mul_f32 v[24:25], v[24:25], v[32:33]
	s_waitcnt vmcnt(0) lgkmcnt(0)
	v_pk_add_f32 v[30:31], v[30:31], 1.0 op_sel_hi:[1,0]
	v_pk_add_f32 v[28:29], v[28:29], 1.0 op_sel_hi:[1,0]
	v_pk_fma_f32 v[26:27], v[26:27], v[30:31], v[40:41]
	v_pk_fma_f32 v[24:25], v[24:25], v[28:29], v[38:39]
	s_nop 0
	v_cvt_pk_bf16_f32 v24, v24, v25
	v_cvt_pk_bf16_f32 v25, v26, v27
	v_lshl_add_u64 v[26:27], v[80:81], 0, s[14:15]
	global_store_dwordx2 v[26:27], v[24:25], off
	s_and_b64 vcc, exec, s[38:39]
	s_cbranch_vccz .LBB0_1002

; __device__ __forceinline__ unsigned pk2(float lo, float hi) { const f32x2_cv v = {lo, hi}; const bf16x2_cv b = __builtin_convertvector(v, bf16x2_cv); return __builtin_bit_cast(unsigned, b); }
; __device__ __forceinline__ void norm_mod(const float* xl, const float* xc, const float* g, const float* mod, int shoff, int scoff, bf16_t* H, int nrows, int gw, int NGW, int lane) {
;     ...
;         for (int j = 0; j < 4; ++j) { const int col = 4 * lane + 256 * j;
;             const f32x4 g4 = *(const f32x4*)(g + col);
; #pragma unroll
;             for (int k = 0; k < 4; ++k) { if (k == 0 || r + k * NGW < nrows) {
;                 const float rinv = 1.0f / sqrtf(ss[k] * (1.0f / 1024.0f) + EPSF);
;                 const f32x4 sc4 = *(const f32x4*)(mp[k] + scoff + col), sh4 = *(const f32x4*)(mp[k] + shoff + col); const f32x4 o = (v[k][j] * rinv * g4) * (sc4 + 1.0f) + sh4;
;                 v2u w; w.x = pk2(o.x, o.y); w.y = pk2(o.z, o.w); *(v2u*)(H + (size_t)rr[k] * 1024 + col) = w; } }
.LBB0_995:
	v_cmp_gt_f32_e32 vcc, s30, v56
	v_mov_b32_e32 v37, v209
	s_nop 0
	v_cndmask_b32_e32 v20, v56, v57, vcc
	v_sqrt_f32_e32 v21, v20
	s_nop 0
	v_add_u32_e32 v22, -1, v21
	v_fma_f32 v23, -v22, v21, v20
	v_cmp_ge_f32_e64 s[44:45], 0, v23
	v_add_u32_e32 v23, 1, v21
	s_nop 0
	v_cndmask_b32_e64 v22, v21, v22, s[44:45]
	v_fma_f32 v21, -v23, v21, v20
	v_cmp_lt_f32_e64 s[44:45], 0, v21
	s_nop 1
	v_cndmask_b32_e64 v21, v22, v23, s[44:45]
	v_mul_f32_e32 v22, 0x37800000, v21
	v_cndmask_b32_e32 v21, v21, v22, vcc
	v_cmp_class_f32_e32 vcc, v20, v221
	s_nop 1
	v_cndmask_b32_e32 v20, v21, v20, vcc
	v_div_scale_f32 v21, s[14:15], v20, v20, 1.0
	v_rcp_f32_e32 v22, v21
	s_bfe_i64 s[14:15], s[52:53], 0x200000
	s_lshl_b64 s[14:15], s[14:15], 11
	v_fma_f32 v23, -v21, v22, 1.0
	v_fmac_f32_e32 v22, v23, v22
	v_div_scale_f32 v23, vcc, 1.0, v20, 1.0
	v_mul_f32_e32 v24, v23, v22
	v_fma_f32 v25, -v21, v24, v23
	v_fmac_f32_e32 v24, v25, v22
	v_fma_f32 v21, -v21, v24, v23
	v_div_fmas_f32 v21, v21, v22, v24
	v_lshl_add_u64 v[24:25], s[60:61], 0, v[36:37]
	v_div_fixup_f32 v28, v21, v20, 1.0
	v_add_co_u32_e32 v20, vcc, s80, v24
	v_pk_mul_f32 v[18:19], v[18:19], v[28:29] op_sel_hi:[1,0]
	s_nop 0
	v_addc_co_u32_e32 v21, vcc, 0, v25, vcc
	v_add_co_u32_e32 v24, vcc, s72, v24
	global_load_dwordx4 v[20:23], v[20:21], off
	s_nop 0
	v_addc_co_u32_e32 v25, vcc, 0, v25, vcc
	global_load_dwordx4 v[24:27], v[24:25], off
	v_pk_mul_f32 v[16:17], v[16:17], v[28:29] op_sel_hi:[1,0]
	v_pk_mul_f32 v[18:19], v[18:19], v[34:35]
	v_pk_mul_f32 v[16:17], v[16:17], v[32:33]
	s_waitcnt vmcnt(0) lgkmcnt(0)
	v_pk_add_f32 v[22:23], v[22:23], 1.0 op_sel_hi:[1,0]
	v_pk_add_f32 v[20:21], v[20:21], 1.0 op_sel_hi:[1,0]
	v_pk_fma_f32 v[18:19], v[18:19], v[22:23], v[26:27]
	v_pk_fma_f32 v[16:17], v[16:17], v[20:21], v[24:25]
	s_nop 0
	v_cvt_pk_bf16_f32 v16, v16, v17
	v_cvt_pk_bf16_f32 v17, v18, v19
	v_lshl_add_u64 v[18:19], v[80:81], 0, s[14:15]
	global_store_dwordx2 v[18:19], v[16:17], off
.LBB0_996:
	v_lshlrev_b32_e32 v20, 2, v76
	v_mov_b32_e32 v21, v209
	v_lshl_add_u64 v[22:23], s[10:11], 0, v[20:21]
	global_load_dwordx4 v[16:19], v[68:69], off offset:3072
	v_lshl_add_u64 v[26:27], s[36:37], 0, v[20:21]
	global_load_dwordx4 v[22:25], v[22:23], off
	v_mov_b32_e32 v30, v88
	global_load_dwordx4 v[26:29], v[26:27], off
	v_mov_b32_e32 v31, v88
	v_pk_mul_f32 v[12:13], v[12:13], v[88:89]
	v_pk_mul_f32 v[14:15], v[14:15], v[30:31]
	s_and_b64 vcc, exec, s[42:43]
	s_waitcnt vmcnt(0)
	v_pk_mul_f32 v[14:15], v[14:15], v[18:19]
	v_pk_mul_f32 v[12:13], v[12:13], v[16:17]
	s_waitcnt lgkmcnt(0)
	v_pk_add_f32 v[24:25], v[24:25], 1.0 op_sel_hi:[1,0]
	v_pk_add_f32 v[22:23], v[22:23], 1.0 op_sel_hi:[1,0]
	v_pk_fma_f32 v[14:15], v[14:15], v[24:25], v[28:29]
	v_pk_fma_f32 v[12:13], v[12:13], v[22:23], v[26:27]
	s_nop 0
	v_cvt_pk_bf16_f32 v12, v12, v13
	v_cvt_pk_bf16_f32 v13, v14, v15
	global_store_dwordx2 v[84:85], v[12:13], off offset:1536
	s_cbranch_vccnz .LBB0_1003
	v_lshl_add_u64 v[22:23], s[6:7], 0, v[20:21]
	v_add_co_u32_e32 v12, vcc, s80, v22
	s_bfe_i64 s[4:5], s[4:5], 0x200000
	s_nop 0
	v_addc_co_u32_e32 v13, vcc, 0, v23, vcc
	v_add_co_u32_e32 v22, vcc, s72, v22
	global_load_dwordx4 v[12:15], v[12:13], off
	s_nop 0
	v_addc_co_u32_e32 v23, vcc, 0, v23, vcc
	global_load_dwordx4 v[22:25], v[22:23], off
	v_cmp_gt_f32_e32 vcc, s30, v64
	s_lshl_b64 s[4:5], s[4:5], 11
	s_waitcnt vmcnt(0) lgkmcnt(0)
	v_pk_add_f32 v[14:15], v[14:15], 1.0 op_sel_hi:[1,0]
	v_cndmask_b32_e32 v21, v64, v65, vcc
	v_sqrt_f32_e32 v26, v21
	v_pk_add_f32 v[12:13], v[12:13], 1.0 op_sel_hi:[1,0]
	v_add_u32_e32 v27, -1, v26
	v_add_u32_e32 v28, 1, v26
	v_fma_f32 v29, -v27, v26, v21
	v_fma_f32 v30, -v28, v26, v21
	v_cmp_ge_f32_e64 s[42:43], 0, v29
	s_nop 1
	v_cndmask_b32_e64 v26, v26, v27, s[42:43]
	v_cmp_lt_f32_e64 s[42:43], 0, v30
	s_nop 1
	v_cndmask_b32_e64 v26, v26, v28, s[42:43]
	v_mul_f32_e32 v27, 0x37800000, v26
	v_cndmask_b32_e32 v26, v26, v27, vcc
	v_cmp_class_f32_e32 vcc, v21, v221
	s_nop 1
	v_cndmask_b32_e32 v21, v26, v21, vcc
	v_div_scale_f32 v26, s[6:7], v21, v21, 1.0
	v_rcp_f32_e32 v27, v26
	v_div_scale_f32 v28, vcc, 1.0, v21, 1.0
	v_fma_f32 v29, -v26, v27, 1.0
	v_fmac_f32_e32 v27, v29, v27
	v_mul_f32_e32 v29, v28, v27
	v_fma_f32 v30, -v26, v29, v28
	v_fmac_f32_e32 v29, v30, v27
	v_fma_f32 v26, -v26, v29, v28
	v_div_fmas_f32 v26, v26, v27, v29
	v_div_fixup_f32 v26, v26, v21, 1.0
	v_pk_mul_f32 v[10:11], v[10:11], v[26:27] op_sel_hi:[1,0]
	v_pk_mul_f32 v[8:9], v[8:9], v[26:27] op_sel_hi:[1,0]
	v_pk_mul_f32 v[10:11], v[10:11], v[18:19]
	v_pk_mul_f32 v[8:9], v[8:9], v[16:17]
	v_pk_fma_f32 v[10:11], v[10:11], v[14:15], v[24:25]
	v_pk_fma_f32 v[8:9], v[8:9], v[12:13], v[22:23]
	s_nop 0
	v_cvt_pk_bf16_f32 v8, v8, v9
	v_cvt_pk_bf16_f32 v9, v10, v11
	v_lshl_add_u64 v[10:11], v[82:83], 0, s[4:5]
	global_store_dwordx2 v[10:11], v[8:9], off
	s_and_b64 vcc, exec, s[38:39]
	s_cbranch_vccz .LBB0_1004

; __device__ __forceinline__ unsigned pk2(float lo, float hi) { const f32x2_cv v = {lo, hi}; const bf16x2_cv b = __builtin_convertvector(v, bf16x2_cv); return __builtin_bit_cast(unsigned, b); }
; __device__ __forceinline__ void norm_mod(const float* xl, const float* xc, const float* g, const float* mod, int shoff, int scoff, bf16_t* H, int nrows, int gw, int NGW, int lane) {
;     ...
;         for (int j = 0; j < 4; ++j) { const int col = 4 * lane + 256 * j;
;             const f32x4 g4 = *(const f32x4*)(g + col);
; #pragma unroll
;             for (int k = 0; k < 4; ++k) { if (k == 0 || r + k * NGW < nrows) {
;                 const float rinv = 1.0f / sqrtf(ss[k] * (1.0f / 1024.0f) + EPSF);
;                 const f32x4 sc4 = *(const f32x4*)(mp[k] + scoff + col), sh4 = *(const f32x4*)(mp[k] + shoff + col); const f32x4 o = (v[k][j] * rinv * g4) * (sc4 + 1.0f) + sh4;
;                 v2u w; w.x = pk2(o.x, o.y); w.y = pk2(o.z, o.w); *(v2u*)(H + (size_t)rr[k] * 1024 + col) = w; } }
.LBB0_1000:
	v_cmp_gt_f32_e32 vcc, s30, v60
	v_mov_b32_e32 v53, v209
	s_nop 0
	v_cndmask_b32_e32 v40, v60, v61, vcc
	v_sqrt_f32_e32 v41, v40
	s_nop 0
	v_add_u32_e32 v42, -1, v41
	v_fma_f32 v43, -v42, v41, v40
	v_cmp_ge_f32_e64 s[44:45], 0, v43
	v_add_u32_e32 v43, 1, v41
	s_nop 0
	v_cndmask_b32_e64 v42, v41, v42, s[44:45]
	v_fma_f32 v41, -v43, v41, v40
	v_cmp_lt_f32_e64 s[44:45], 0, v41
	s_nop 1
	v_cndmask_b32_e64 v41, v42, v43, s[44:45]
	v_mul_f32_e32 v42, 0x37800000, v41
	v_cndmask_b32_e32 v41, v41, v42, vcc
	v_cmp_class_f32_e32 vcc, v40, v221
	s_nop 1
	v_cndmask_b32_e32 v40, v41, v40, vcc
	v_div_scale_f32 v41, s[14:15], v40, v40, 1.0
	v_rcp_f32_e32 v42, v41
	s_bfe_i64 s[14:15], s[46:47], 0x200000
	s_lshl_b64 s[14:15], s[14:15], 11
	v_fma_f32 v43, -v41, v42, 1.0
	v_fmac_f32_e32 v42, v43, v42
	v_div_scale_f32 v43, vcc, 1.0, v40, 1.0
	v_mul_f32_e32 v44, v43, v42
	v_fma_f32 v45, -v41, v44, v43
	v_fmac_f32_e32 v44, v45, v42
	v_fma_f32 v41, -v41, v44, v43
	v_div_fmas_f32 v41, v41, v42, v44
	v_lshl_add_u64 v[44:45], s[48:49], 0, v[52:53]
	v_div_fixup_f32 v54, v41, v40, 1.0
	v_add_co_u32_e32 v40, vcc, s80, v44
	v_pk_mul_f32 v[38:39], v[38:39], v[54:55] op_sel_hi:[1,0]
	s_nop 0
	v_addc_co_u32_e32 v41, vcc, 0, v45, vcc
	v_add_co_u32_e32 v44, vcc, s72, v44
	global_load_dwordx4 v[40:43], v[40:41], off
	s_nop 0
	v_addc_co_u32_e32 v45, vcc, 0, v45, vcc
	global_load_dwordx4 v[44:47], v[44:45], off
	v_pk_mul_f32 v[36:37], v[36:37], v[54:55] op_sel_hi:[1,0]
	v_pk_mul_f32 v[38:39], v[38:39], v[50:51]
	v_pk_mul_f32 v[36:37], v[36:37], v[48:49]
	s_waitcnt vmcnt(0) lgkmcnt(0)
	v_pk_add_f32 v[42:43], v[42:43], 1.0 op_sel_hi:[1,0]
	v_pk_add_f32 v[40:41], v[40:41], 1.0 op_sel_hi:[1,0]
	v_pk_fma_f32 v[38:39], v[38:39], v[42:43], v[46:47]
	v_pk_fma_f32 v[36:37], v[36:37], v[40:41], v[44:45]
	s_nop 0
	v_cvt_pk_bf16_f32 v36, v36, v37
	v_cvt_pk_bf16_f32 v37, v38, v39
	v_lshl_add_u64 v[38:39], v[78:79], 0, s[14:15]
	global_store_dwordx2 v[38:39], v[36:37], off
	s_and_b64 vcc, exec, s[40:41]
	s_cbranch_vccz .LBB0_991
	s_branch .LBB0_992

; __device__ __forceinline__ unsigned pk2(float lo, float hi) { const f32x2_cv v = {lo, hi}; const bf16x2_cv b = __builtin_convertvector(v, bf16x2_cv); return __builtin_bit_cast(unsigned, b); }
; __device__ __forceinline__ void norm_mod(const float* xl, const float* xc, const float* g, const float* mod, int shoff, int scoff, bf16_t* H, int nrows, int gw, int NGW, int lane) {
;     ...
;         for (int j = 0; j < 4; ++j) { const int col = 4 * lane + 256 * j;
;             const f32x4 g4 = *(const f32x4*)(g + col);
; #pragma unroll
;             for (int k = 0; k < 4; ++k) { if (k == 0 || r + k * NGW < nrows) {
;                 const float rinv = 1.0f / sqrtf(ss[k] * (1.0f / 1024.0f) + EPSF);
;                 const f32x4 sc4 = *(const f32x4*)(mp[k] + scoff + col), sh4 = *(const f32x4*)(mp[k] + shoff + col); const f32x4 o = (v[k][j] * rinv * g4) * (sc4 + 1.0f) + sh4;
;                 v2u w; w.x = pk2(o.x, o.y); w.y = pk2(o.z, o.w); *(v2u*)(H + (size_t)rr[k] * 1024 + col) = w; } }
.LBB0_1002:
	v_cmp_gt_f32_e32 vcc, s30, v60
	v_mov_b32_e32 v37, v209
	s_nop 0
	v_cndmask_b32_e32 v24, v60, v61, vcc
	v_sqrt_f32_e32 v25, v24
	s_nop 0
	v_add_u32_e32 v26, -1, v25
	v_fma_f32 v27, -v26, v25, v24
	v_cmp_ge_f32_e64 s[44:45], 0, v27
	v_add_u32_e32 v27, 1, v25
	s_nop 0
	v_cndmask_b32_e64 v26, v25, v26, s[44:45]
	v_fma_f32 v25, -v27, v25, v24
	v_cmp_lt_f32_e64 s[44:45], 0, v25
	s_nop 1
	v_cndmask_b32_e64 v25, v26, v27, s[44:45]
	v_mul_f32_e32 v26, 0x37800000, v25
	v_cndmask_b32_e32 v25, v25, v26, vcc
	v_cmp_class_f32_e32 vcc, v24, v221
	s_nop 1
	v_cndmask_b32_e32 v24, v25, v24, vcc
	v_div_scale_f32 v25, s[14:15], v24, v24, 1.0
	v_rcp_f32_e32 v26, v25
	s_bfe_i64 s[14:15], s[46:47], 0x200000
	s_lshl_b64 s[14:15], s[14:15], 11
	v_fma_f32 v27, -v25, v26, 1.0
	v_fmac_f32_e32 v26, v27, v26
	v_div_scale_f32 v27, vcc, 1.0, v24, 1.0
	v_mul_f32_e32 v28, v27, v26
	v_fma_f32 v29, -v25, v28, v27
	v_fmac_f32_e32 v28, v29, v26
	v_fma_f32 v25, -v25, v28, v27
	v_div_fmas_f32 v25, v25, v26, v28
	v_lshl_add_u64 v[28:29], s[48:49], 0, v[36:37]
	v_div_fixup_f32 v38, v25, v24, 1.0
	v_add_co_u32_e32 v24, vcc, s80, v28
	v_pk_mul_f32 v[22:23], v[22:23], v[38:39] op_sel_hi:[1,0]
	s_nop 0
	v_addc_co_u32_e32 v25, vcc, 0, v29, vcc
	v_add_co_u32_e32 v28, vcc, s72, v28
	global_load_dwordx4 v[24:27], v[24:25], off
	s_nop 0
	v_addc_co_u32_e32 v29, vcc, 0, v29, vcc
	global_load_dwordx4 v[28:31], v[28:29], off
	v_pk_mul_f32 v[20:21], v[20:21], v[38:39] op_sel_hi:[1,0]
	v_pk_mul_f32 v[22:23], v[22:23], v[34:35]
	v_pk_mul_f32 v[20:21], v[20:21], v[32:33]
	s_waitcnt vmcnt(0) lgkmcnt(0)
	v_pk_add_f32 v[26:27], v[26:27], 1.0 op_sel_hi:[1,0]
	v_pk_add_f32 v[24:25], v[24:25], 1.0 op_sel_hi:[1,0]
	v_pk_fma_f32 v[22:23], v[22:23], v[26:27], v[30:31]
	v_pk_fma_f32 v[20:21], v[20:21], v[24:25], v[28:29]
	s_nop 0
	v_cvt_pk_bf16_f32 v20, v20, v21
	v_cvt_pk_bf16_f32 v21, v22, v23
	v_lshl_add_u64 v[22:23], v[80:81], 0, s[14:15]
	global_store_dwordx2 v[22:23], v[20:21], off
	s_and_b64 vcc, exec, s[40:41]
	s_cbranch_vccz .LBB0_995
	s_branch .LBB0_996

; __device__ __forceinline__ unsigned pk2(float lo, float hi) { const f32x2_cv v = {lo, hi}; const bf16x2_cv b = __builtin_convertvector(v, bf16x2_cv); return __builtin_bit_cast(unsigned, b); }
; __device__ __forceinline__ void norm_mod(const float* xl, const float* xc, const float* g, const float* mod, int shoff, int scoff, bf16_t* H, int nrows, int gw, int NGW, int lane) {
;     ...
;         for (int j = 0; j < 4; ++j) { const int col = 4 * lane + 256 * j;
;             const f32x4 g4 = *(const f32x4*)(g + col);
; #pragma unroll
;             for (int k = 0; k < 4; ++k) { if (k == 0 || r + k * NGW < nrows) {
;                 const float rinv = 1.0f / sqrtf(ss[k] * (1.0f / 1024.0f) + EPSF);
;                 const f32x4 sc4 = *(const f32x4*)(mp[k] + scoff + col), sh4 = *(const f32x4*)(mp[k] + shoff + col); const f32x4 o = (v[k][j] * rinv * g4) * (sc4 + 1.0f) + sh4;
;                 v2u w; w.x = pk2(o.x, o.y); w.y = pk2(o.z, o.w); *(v2u*)(H + (size_t)rr[k] * 1024 + col) = w; } }
.LBB0_1004:
	v_mov_b32_e32 v21, v209
	v_lshl_add_u64 v[12:13], s[48:49], 0, v[20:21]
	v_add_co_u32_e32 v8, vcc, s80, v12
	s_bfe_i64 s[4:5], s[46:47], 0x200000
	s_nop 0
	v_addc_co_u32_e32 v9, vcc, 0, v13, vcc
	v_add_co_u32_e32 v12, vcc, s72, v12
	global_load_dwordx4 v[8:11], v[8:9], off
	s_nop 0
	v_addc_co_u32_e32 v13, vcc, 0, v13, vcc
	global_load_dwordx4 v[12:15], v[12:13], off
	v_cmp_gt_f32_e32 vcc, s30, v60
	s_lshl_b64 s[4:5], s[4:5], 11
	s_waitcnt vmcnt(0) lgkmcnt(0)
	v_pk_add_f32 v[10:11], v[10:11], 1.0 op_sel_hi:[1,0]
	v_cndmask_b32_e32 v21, v60, v61, vcc
	v_sqrt_f32_e32 v22, v21
	v_pk_add_f32 v[8:9], v[8:9], 1.0 op_sel_hi:[1,0]
	v_add_u32_e32 v23, -1, v22
	v_add_u32_e32 v24, 1, v22
	v_fma_f32 v25, -v23, v22, v21
	v_fma_f32 v26, -v24, v22, v21
	v_cmp_ge_f32_e64 s[38:39], 0, v25
	s_nop 1
	v_cndmask_b32_e64 v22, v22, v23, s[38:39]
	v_cmp_lt_f32_e64 s[38:39], 0, v26
	s_nop 1
	v_cndmask_b32_e64 v22, v22, v24, s[38:39]
	v_mul_f32_e32 v23, 0x37800000, v22
	v_cndmask_b32_e32 v22, v22, v23, vcc
	v_cmp_class_f32_e32 vcc, v21, v221
	s_nop 1
	v_cndmask_b32_e32 v21, v22, v21, vcc
	v_div_scale_f32 v22, s[6:7], v21, v21, 1.0
	v_rcp_f32_e32 v23, v22
	v_div_scale_f32 v24, vcc, 1.0, v21, 1.0
	v_fma_f32 v25, -v22, v23, 1.0
	v_fmac_f32_e32 v23, v25, v23
	v_mul_f32_e32 v25, v24, v23
	v_fma_f32 v26, -v22, v25, v24
	v_fmac_f32_e32 v25, v26, v23
	v_fma_f32 v22, -v22, v25, v24
	v_div_fmas_f32 v22, v22, v23, v25
	v_div_fixup_f32 v22, v22, v21, 1.0
	v_pk_mul_f32 v[6:7], v[6:7], v[22:23] op_sel_hi:[1,0]
	v_pk_mul_f32 v[4:5], v[4:5], v[22:23] op_sel_hi:[1,0]
	v_pk_mul_f32 v[6:7], v[6:7], v[18:19]
	v_pk_mul_f32 v[4:5], v[4:5], v[16:17]
	v_pk_fma_f32 v[6:7], v[6:7], v[10:11], v[14:15]
	v_pk_fma_f32 v[4:5], v[4:5], v[8:9], v[12:13]
	s_nop 0
	v_cvt_pk_bf16_f32 v4, v4, v5
	v_cvt_pk_bf16_f32 v5, v6, v7
	v_lshl_add_u64 v[6:7], v[82:83], 0, s[4:5]
	global_store_dwordx2 v[6:7], v[4:5], off
	s_and_b64 vcc, exec, s[40:41]
	s_cbranch_vccnz .LBB0_981
.LBB0_1005:
	v_mov_b32_e32 v21, v209
	v_lshl_add_u64 v[8:9], s[60:61], 0, v[20:21]
	v_add_co_u32_e32 v4, vcc, s80, v8
	s_bfe_i64 s[4:5], s[52:53], 0x200000
	s_nop 0
	v_addc_co_u32_e32 v5, vcc, 0, v9, vcc
	v_add_co_u32_e32 v8, vcc, s72, v8
	global_load_dwordx4 v[4:7], v[4:5], off
	s_nop 0
	v_addc_co_u32_e32 v9, vcc, 0, v9, vcc
	global_load_dwordx4 v[8:11], v[8:9], off
	v_cmp_gt_f32_e32 vcc, s30, v56
	s_lshl_b64 s[4:5], s[4:5], 11
	s_waitcnt vmcnt(0) lgkmcnt(0)
	v_pk_add_f32 v[6:7], v[6:7], 1.0 op_sel_hi:[1,0]
	v_cndmask_b32_e32 v12, v56, v57, vcc
	v_sqrt_f32_e32 v13, v12
	v_pk_add_f32 v[4:5], v[4:5], 1.0 op_sel_hi:[1,0]
	v_add_u32_e32 v14, -1, v13
	v_add_u32_e32 v15, 1, v13
	v_fma_f32 v20, -v14, v13, v12
	v_fma_f32 v21, -v15, v13, v12
	v_cmp_ge_f32_e64 s[38:39], 0, v20
	s_nop 1
	v_cndmask_b32_e64 v13, v13, v14, s[38:39]
	v_cmp_lt_f32_e64 s[38:39], 0, v21
	s_nop 1
	v_cndmask_b32_e64 v13, v13, v15, s[38:39]
	v_mul_f32_e32 v14, 0x37800000, v13
	v_cndmask_b32_e32 v13, v13, v14, vcc
	v_cmp_class_f32_e32 vcc, v12, v221
	s_nop 1
	v_cndmask_b32_e32 v12, v13, v12, vcc
	v_div_scale_f32 v13, s[6:7], v12, v12, 1.0
	v_rcp_f32_e32 v14, v13
	v_div_scale_f32 v15, vcc, 1.0, v12, 1.0
	v_fma_f32 v20, -v13, v14, 1.0
	v_fmac_f32_e32 v14, v20, v14
	v_mul_f32_e32 v20, v15, v14
	v_fma_f32 v21, -v13, v20, v15
	v_fmac_f32_e32 v20, v21, v14
	v_fma_f32 v13, -v13, v20, v15
	v_div_fmas_f32 v13, v13, v14, v20
	v_div_fixup_f32 v12, v13, v12, 1.0
	v_pk_mul_f32 v[2:3], v[2:3], v[12:13] op_sel_hi:[1,0]
	v_pk_mul_f32 v[0:1], v[0:1], v[12:13] op_sel_hi:[1,0]
	v_pk_mul_f32 v[2:3], v[2:3], v[18:19]
	v_pk_mul_f32 v[0:1], v[0:1], v[16:17]
	v_pk_fma_f32 v[2:3], v[2:3], v[6:7], v[10:11]
	v_pk_fma_f32 v[0:1], v[0:1], v[4:5], v[8:9]
	s_nop 0
	v_cvt_pk_bf16_f32 v0, v0, v1
	v_cvt_pk_bf16_f32 v1, v2, v3
	v_lshl_add_u64 v[2:3], v[82:83], 0, s[4:5]
	global_store_dwordx2 v[2:3], v[0:1], off
	s_branch .LBB0_981

; __device__ __forceinline__ float dpp_ror1(float v) { return __builtin_bit_cast(float, __builtin_amdgcn_update_dpp(0, __builtin_bit_cast(int, v), 0x121, 0xF, 0xF, false)); }
;     __device__ __forceinline__ void operator()(const pg8::f32x4 (&acc)[2][2][4][2], const pg8::Unit& u, int wr, int wc, int fr, int fq) const {
;         const int ch0 = u.pn * 128 + wc * 32 + 8 * fq;
;         float w0[8], w1[8], w2[8], bb[8];
; #pragma unroll
;         for (int hq = 0; hq < 2; ++hq) { const pg8::f32x4 q0 = *(const pg8::f32x4*)(cw + ch0 + 4 * hq), q1 = *(const pg8::f32x4*)(cw + DFF + ch0 + 4 * hq), q2 = *(const pg8::f32x4*)(cw + 2 * DFF + ch0 + 4 * hq), q3 = *(const pg8::f32x4*)(cb + ch0 + 4 * hq);
; #pragma unroll
;             for (int e = 0; e < 4; ++e) { w0[4 * hq + e] = q0[e]; w1[4 * hq + e] = q1[e]; w2[4 * hq + e] = q2[e]; bb[4 * hq + e] = q3[e]; } }
; #pragma unroll
;         for (int ai = 0; ai < 2; ++ai) {
;             const int kb = u.pm * 4 + ai * 2 + wr;
;             float ruP[8], rdC[8];
; #pragma unroll
;             for (int c = 0; c < 8; ++c) { ruP[c] = 0.f; rdC[c] = dpp_rol1(acc[ai][0][0][c >> 2][c & 3]); }
; #pragma unroll
;             for (int m = 0; m < 4; ++m) {
;                 const int rl = 16 * m + fr, gr = 62 * kb - 1 + rl;
;                 bool first, last; if (gr < ML) { const int t = gr & 8191; first = t == 0; last = t == 8191; } else { const int t = (gr - ML) & 255; first = t == 0; last = t == 255; }
;                 float res[8];
; #pragma unroll
;                 for (int c = 0; c < 8; ++c) {
;                     const int n = c >> 2, e = c & 3;
;                     const float x0 = acc[ai][0][m][n][e];
;                     const float ruC = dpp_ror1(x0), rdN = m < 3 ? dpp_rol1(acc[ai][0][m < 3 ? m + 1 : 3][n][e]) : 0.f;
;                     float xu = fr == 0 ? ruP[c] : ruC, xd = fr == 15 ? rdN : rdC[c];
;                     xu = first ? 0.f : xu; xd = last ? 0.f : xd;
;                     ruP[c] = ruC; rdC[c] = rdN;
;                     const float x = w0[c] * xu + w1[c] * x0 + w2[c] * xd + bb[c];
;                     const float u2 = -2.302208198f * (x + 0.044715f * x * x * x);
;                     res[c] = x * __builtin_amdgcn_rcpf(1.0f + __builtin_amdgcn_exp2f(u2)) * acc[ai][1][m][n][e];
.LBB0_1084:
	v_lshl_or_b32 v170, s52, 7, v177
	v_ashrrev_i32_e32 v171, 31, v170
	v_lshlrev_b64 v[56:57], 2, v[170:171]
	v_lshl_add_u64 v[60:61], s[10:11], 0, v[56:57]
	v_lshl_add_u64 v[62:63], s[68:69], 0, v[56:57]
	v_lshl_add_u64 v[64:65], s[70:71], 0, v[56:57]
	v_lshl_add_u64 v[84:85], s[36:37], 0, v[56:57]
	global_load_dwordx4 v[56:59], v[60:61], off offset:16
	global_load_dwordx4 v[76:79], v[60:61], off
	global_load_dwordx4 v[68:71], v[62:63], off offset:16
	global_load_dwordx4 v[92:95], v[62:63], off
	s_nop 0
	global_load_dwordx4 v[60:63], v[64:65], off offset:16
	global_load_dwordx4 v[80:83], v[64:65], off
	s_nop 0
	global_load_dwordx4 v[64:67], v[84:85], off offset:16
	s_nop 0
	global_load_dwordx4 v[84:87], v[84:85], off
	s_lshl_b32 s12, s65, 2
	s_add_i32 s65, s12, s88
	s_mul_i32 s65, s65, 62
	s_add_i32 s73, s65, -1
	v_add_u32_e32 v194, s73, v172
	v_mov_b32_e32 v198, v209
	v_mov_b32_e32 v199, v209
	v_mov_b32_e32 v200, v209
	v_mov_b32_e32 v201, v209
	v_mov_b32_e32 v202, v209
	v_mov_b32_e32 v203, v209
	v_mov_b32_e32 v196, v209
	v_mov_b32_e32 v197, v209
	v_mov_b32_e32 v184, v209
	v_mov_b32_e32 v183, v209
	v_mov_b32_e32 v181, v209
	v_mov_b32_e32 v179, v209
	v_mov_b32_e32 v188, v209
	v_mov_b32_e32 v187, v209
	v_mov_b32_e32 v186, v209
	v_mov_b32_e32 v185, v209
	v_mov_b32_e32 v192, v209
	v_mov_b32_e32 v191, v209
	v_mov_b32_e32 v190, v209
	v_mov_b32_e32 v189, v209
	v_mov_b32_e32 v195, v209
	v_mov_b32_e32 v193, v209
	v_mov_b32_e32 v182, v209
	v_mov_b32_e32 v180, v209
	v_cmp_gt_i32_e32 vcc, s86, v194
	v_mov_b32_dpp v198, v152 row_ror:15 row_mask:0xf bank_mask:0xf
	v_mov_b32_dpp v199, v153 row_ror:15 row_mask:0xf bank_mask:0xf
	v_mov_b32_dpp v200, v154 row_ror:15 row_mask:0xf bank_mask:0xf
	v_mov_b32_dpp v201, v155 row_ror:15 row_mask:0xf bank_mask:0xf
	v_mov_b32_dpp v202, v156 row_ror:15 row_mask:0xf bank_mask:0xf
	v_mov_b32_dpp v203, v157 row_ror:15 row_mask:0xf bank_mask:0xf
	v_mov_b32_dpp v196, v158 row_ror:15 row_mask:0xf bank_mask:0xf
	v_mov_b32_dpp v197, v159 row_ror:15 row_mask:0xf bank_mask:0xf
	v_mov_b32_dpp v184, v152 row_ror:1 row_mask:0xf bank_mask:0xf
	v_mov_b32_dpp v183, v140 row_ror:15 row_mask:0xf bank_mask:0xf
	v_mov_b32_dpp v181, v153 row_ror:1 row_mask:0xf bank_mask:0xf
	v_mov_b32_dpp v179, v141 row_ror:15 row_mask:0xf bank_mask:0xf
	v_mov_b32_dpp v188, v154 row_ror:1 row_mask:0xf bank_mask:0xf
	v_mov_b32_dpp v187, v142 row_ror:15 row_mask:0xf bank_mask:0xf
	v_mov_b32_dpp v186, v155 row_ror:1 row_mask:0xf bank_mask:0xf
	v_mov_b32_dpp v185, v143 row_ror:15 row_mask:0xf bank_mask:0xf
	v_mov_b32_dpp v192, v156 row_ror:1 row_mask:0xf bank_mask:0xf
	v_mov_b32_dpp v191, v136 row_ror:15 row_mask:0xf bank_mask:0xf
	v_mov_b32_dpp v190, v157 row_ror:1 row_mask:0xf bank_mask:0xf
	v_mov_b32_dpp v189, v137 row_ror:15 row_mask:0xf bank_mask:0xf
	v_mov_b32_dpp v195, v158 row_ror:1 row_mask:0xf bank_mask:0xf
	v_mov_b32_dpp v193, v138 row_ror:15 row_mask:0xf bank_mask:0xf
	v_mov_b32_dpp v182, v159 row_ror:1 row_mask:0xf bank_mask:0xf
	v_mov_b32_dpp v180, v139 row_ror:15 row_mask:0xf bank_mask:0xf
	s_and_b64 s[48:49], s[42:43], vcc
	s_and_saveexec_b64 s[52:53], s[48:49]
	s_movk_i32 s12, 0xff
	s_movk_i32 s78, 0x1fff
	s_cbranch_execz .LBB0_1086
	v_and_b32_e32 v204, 0x1fff, v194
	v_and_b32_e32 v205, 0xff, v194
	v_cmp_gt_i32_e32 vcc, s97, v194
	v_cmp_eq_u32_e64 s[48:49], s78, v204
	s_waitcnt vmcnt(0)
	v_pk_mul_f32 v[156:157], v[156:157], v[68:69]
	v_cndmask_b32_e32 v206, v205, v204, vcc
	v_cndmask_b32_e64 v204, 0, 1, s[48:49]
	v_cmp_eq_u32_e64 s[48:49], s12, v205
	v_cndmask_b32_e64 v202, v202, v191, s[40:41]
	v_cndmask_b32_e64 v203, v203, v189, s[40:41]
	v_cndmask_b32_e64 v205, 0, 1, s[48:49]
	v_cndmask_b32_e32 v204, v205, v204, vcc
	v_and_b32_e32 v207, 1, v204
	v_cmp_eq_u32_e32 vcc, 0, v206
	v_cmp_eq_u32_e64 s[48:49], 1, v207
	v_pk_mul_f32 v[152:153], v[152:153], v[92:93]
	v_cndmask_b32_e64 v205, v190, 0, vcc
	v_cndmask_b32_e64 v204, v192, 0, vcc
	v_pk_fma_f32 v[156:157], v[56:57], v[204:205], v[156:157]
	v_cndmask_b32_e64 v203, v203, 0, s[48:49]
	v_cndmask_b32_e64 v202, v202, 0, s[48:49]
	v_pk_fma_f32 v[156:157], v[60:61], v[202:203], v[156:157]
	v_cndmask_b32_e64 v198, v198, v183, s[40:41]
	v_pk_add_f32 v[156:157], v[64:65], v[156:157]
	v_cndmask_b32_e64 v199, v199, v179, s[40:41]
	v_mul_f32_e32 v202, 0x3d372713, v156
	v_mul_f32_e32 v203, 0x3d372713, v157
	v_mul_f32_e32 v202, v156, v202
	v_mul_f32_e32 v203, v157, v203
	v_fma_f32 v202, v156, v202, v156
	v_fma_f32 v203, v157, v203, v157
	v_mul_f32_e32 v202, 0xc0135761, v202
	v_mul_f32_e32 v203, 0xc0135761, v203
	v_exp_f32_e32 v202, v202
	v_exp_f32_e32 v203, v203
	v_cndmask_b32_e64 v199, v199, 0, s[48:49]
	v_cndmask_b32_e64 v198, v198, 0, s[48:49]
	v_add_f32_e32 v202, 1.0, v202
	v_add_f32_e32 v203, 1.0, v203
	v_rcp_f32_e32 v202, v202
	v_rcp_f32_e32 v203, v203
	v_pk_mul_f32 v[158:159], v[158:159], v[70:71]
	v_cndmask_b32_e64 v196, v196, v193, s[40:41]
	v_cndmask_b32_e64 v197, v197, v180, s[40:41]
	v_pk_mul_f32 v[156:157], v[156:157], v[202:203]
	v_cndmask_b32_e64 v197, v197, 0, s[48:49]
	v_pk_mul_f32 v[156:157], v[144:145], v[156:157]
	v_pk_mul_f32 v[144:145], v[154:155], v[94:95]
	v_cndmask_b32_e64 v155, v186, 0, vcc
	v_cndmask_b32_e64 v154, v188, 0, vcc
	v_pk_fma_f32 v[144:145], v[78:79], v[154:155], v[144:145]
	v_cndmask_b32_e64 v154, v200, v187, s[40:41]
	v_cndmask_b32_e64 v155, v201, v185, s[40:41]
	v_cndmask_b32_e64 v155, v155, 0, s[48:49]
	v_cndmask_b32_e64 v154, v154, 0, s[48:49]
	v_pk_fma_f32 v[144:145], v[82:83], v[154:155], v[144:145]
	v_cndmask_b32_e64 v201, v181, 0, vcc
	v_pk_add_f32 v[144:145], v[86:87], v[144:145]
	v_cndmask_b32_e64 v200, v184, 0, vcc
	v_mul_f32_e32 v154, 0x3d372713, v144
; __device__ __forceinline__ unsigned pk2(float lo, float hi) { const f32x2_cv v = {lo, hi}; const bf16x2_cv b = __builtin_convertvector(v, bf16x2_cv); return __builtin_bit_cast(unsigned, b); }
; __device__ __forceinline__ float dpp_ror1(float v) { return __builtin_bit_cast(float, __builtin_amdgcn_update_dpp(0, __builtin_bit_cast(int, v), 0x121, 0xF, 0xF, false)); }
; __device__ __forceinline__ float dpp_rol1(float v) { return __builtin_bit_cast(float, __builtin_amdgcn_update_dpp(0, __builtin_bit_cast(int, v), 0x12F, 0xF, 0xF, false)); }
;     __device__ __forceinline__ void operator()(const pg8::f32x4 (&acc)[2][2][4][2], const pg8::Unit& u, int wr, int wc, int fr, int fq) const {
;     ...
;                 for (int c = 0; c < 8; ++c) {
;                     const int n = c >> 2, e = c & 3;
;                     const float x0 = acc[ai][0][m][n][e];
;                     const float ruC = dpp_ror1(x0), rdN = m < 3 ? dpp_rol1(acc[ai][0][m < 3 ? m + 1 : 3][n][e]) : 0.f;
;                     float xu = fr == 0 ? ruP[c] : ruC, xd = fr == 15 ? rdN : rdC[c];
;                     xu = first ? 0.f : xu; xd = last ? 0.f : xd;
;                     ruP[c] = ruC; rdC[c] = rdN;
;                     const float x = w0[c] * xu + w1[c] * x0 + w2[c] * xd + bb[c];
;                     const float u2 = -2.302208198f * (x + 0.044715f * x * x * x);
;                     res[c] = x * __builtin_amdgcn_rcpf(1.0f + __builtin_amdgcn_exp2f(u2)) * acc[ai][1][m][n][e];
;                 }
;                 if (rl >= 1 && rl <= 62 && gr < nrows) { v4u o; o.x = pk2(res[0], res[1]); o.y = pk2(res[2], res[3]); o.z = pk2(res[4], res[5]); o.w = pk2(res[6], res[7]);
;                     *(v4u*)(G + (size_t)gr * DFF + ch0) = o; }
	v_mul_f32_e32 v155, 0x3d372713, v145
	v_mul_f32_e32 v154, v144, v154
	v_mul_f32_e32 v155, v145, v155
	v_fma_f32 v154, v144, v154, v144
	v_fma_f32 v155, v145, v155, v145
	v_pk_fma_f32 v[152:153], v[76:77], v[200:201], v[152:153]
	v_mul_f32_e32 v154, 0xc0135761, v154
	v_mul_f32_e32 v155, 0xc0135761, v155
	v_pk_fma_f32 v[152:153], v[80:81], v[198:199], v[152:153]
	v_exp_f32_e32 v154, v154
	v_exp_f32_e32 v155, v155
	v_pk_add_f32 v[152:153], v[84:85], v[152:153]
	v_cndmask_b32_e64 v196, v196, 0, s[48:49]
	v_mul_f32_e32 v198, 0x3d372713, v152
	v_mul_f32_e32 v199, 0x3d372713, v153
	v_mul_f32_e32 v198, v152, v198
	v_mul_f32_e32 v199, v153, v199
	v_fma_f32 v198, v152, v198, v152
	v_fma_f32 v199, v153, v199, v153
	v_add_f32_e32 v154, 1.0, v154
	v_add_f32_e32 v155, 1.0, v155
	v_mul_f32_e32 v198, 0xc0135761, v198
	v_mul_f32_e32 v199, 0xc0135761, v199
	v_rcp_f32_e32 v154, v154
	v_rcp_f32_e32 v155, v155
	v_exp_f32_e32 v198, v198
	v_exp_f32_e32 v199, v199
	v_pk_mul_f32 v[144:145], v[144:145], v[154:155]
	v_add_f32_e32 v154, 1.0, v198
	v_add_f32_e32 v155, 1.0, v199
	v_cndmask_b32_e64 v199, v182, 0, vcc
	v_cndmask_b32_e64 v198, v195, 0, vcc
	v_pk_fma_f32 v[158:159], v[58:59], v[198:199], v[158:159]
	v_rcp_f32_e32 v154, v154
	v_pk_fma_f32 v[158:159], v[62:63], v[196:197], v[158:159]
	v_rcp_f32_e32 v155, v155
	v_pk_add_f32 v[158:159], v[66:67], v[158:159]
	v_pk_mul_f32 v[150:151], v[150:151], v[144:145]
	v_mul_f32_e32 v196, 0x3d372713, v158
	v_mul_f32_e32 v197, 0x3d372713, v159
	v_mul_f32_e32 v196, v158, v196
	v_mul_f32_e32 v197, v159, v197
	v_fma_f32 v196, v158, v196, v158
	v_fma_f32 v197, v159, v197, v159
	v_mul_f32_e32 v196, 0xc0135761, v196
	v_mul_f32_e32 v197, 0xc0135761, v197
	v_exp_f32_e32 v196, v196
	v_exp_f32_e32 v197, v197
	v_pk_mul_f32 v[144:145], v[152:153], v[154:155]
	v_add_f32_e32 v196, 1.0, v196
	v_add_f32_e32 v197, 1.0, v197
	v_rcp_f32_e32 v196, v196
	v_rcp_f32_e32 v197, v197
	v_pk_mul_f32 v[144:145], v[148:149], v[144:145]
	v_pk_mul_f32 v[148:149], v[158:159], v[196:197]
	s_nop 0
	v_pk_mul_f32 v[148:149], v[146:147], v[148:149]
	v_cvt_pk_bf16_f32 v144, v144, v145
	v_cvt_pk_bf16_f32 v147, v148, v149
	v_mov_b64_e32 v[148:149], s[6:7]
	v_mad_i64_i32 v[148:149], s[48:49], v194, s1, v[148:149]
	v_cvt_pk_bf16_f32 v145, v150, v151
	v_cvt_pk_bf16_f32 v146, v156, v157
	v_lshl_add_u64 v[148:149], v[170:171], 1, v[148:149]
	global_store_dwordx4 v[148:149], v[144:147], off
.LBB0_1086:
	s_or_b64 exec, exec, s[52:53]
	v_add_u32_e32 v194, s73, v174
	v_mov_b32_e32 v149, v209
	v_mov_b32_e32 v148, v209
	v_mov_b32_e32 v146, v209
	v_mov_b32_e32 v144, v209
	v_mov_b32_e32 v153, v209
	v_mov_b32_e32 v152, v209
	v_mov_b32_e32 v151, v209
	v_mov_b32_e32 v150, v209
	v_mov_b32_e32 v157, v209
	v_mov_b32_e32 v156, v209
	v_mov_b32_e32 v155, v209
	v_mov_b32_e32 v154, v209
	v_mov_b32_e32 v159, v209
	v_mov_b32_e32 v158, v209
	v_mov_b32_e32 v147, v209
	v_mov_b32_e32 v145, v209
	v_mov_b32_dpp v149, v140 row_ror:1 row_mask:0xf bank_mask:0xf
	v_mov_b32_dpp v148, v124 row_ror:15 row_mask:0xf bank_mask:0xf
	v_mov_b32_dpp v146, v141 row_ror:1 row_mask:0xf bank_mask:0xf
	v_mov_b32_dpp v144, v125 row_ror:15 row_mask:0xf bank_mask:0xf
	v_mov_b32_dpp v153, v142 row_ror:1 row_mask:0xf bank_mask:0xf
	v_mov_b32_dpp v152, v126 row_ror:15 row_mask:0xf bank_mask:0xf
	v_mov_b32_dpp v151, v143 row_ror:1 row_mask:0xf bank_mask:0xf
	v_mov_b32_dpp v150, v127 row_ror:15 row_mask:0xf bank_mask:0xf
	v_mov_b32_dpp v157, v136 row_ror:1 row_mask:0xf bank_mask:0xf
	v_mov_b32_dpp v156, v120 row_ror:15 row_mask:0xf bank_mask:0xf
	v_mov_b32_dpp v155, v137 row_ror:1 row_mask:0xf bank_mask:0xf
	v_mov_b32_dpp v154, v121 row_ror:15 row_mask:0xf bank_mask:0xf
	v_mov_b32_dpp v159, v138 row_ror:1 row_mask:0xf bank_mask:0xf
	v_mov_b32_dpp v158, v122 row_ror:15 row_mask:0xf bank_mask:0xf
	v_mov_b32_dpp v147, v139 row_ror:1 row_mask:0xf bank_mask:0xf
	v_mov_b32_dpp v145, v123 row_ror:15 row_mask:0xf bank_mask:0xf
	v_cmp_gt_i32_e32 vcc, s86, v194
	s_and_saveexec_b64 s[80:81], vcc
	s_cbranch_execz .LBB0_1088
	v_and_b32_e32 v200, 0x1fff, v194
	v_and_b32_e32 v201, 0xff, v194
	v_cmp_gt_i32_e64 s[48:49], s97, v194
	v_cndmask_b32_e64 v195, v159, v195, s[38:39]
	v_mov_b32_e32 v198, v138
	v_cndmask_b32_e64 v196, v201, v200, s[48:49]
	v_cmp_eq_u32_e32 vcc, 0, v196
	s_waitcnt vmcnt(0)
; __device__ __forceinline__ unsigned pk2(float lo, float hi) { const f32x2_cv v = {lo, hi}; const bf16x2_cv b = __builtin_convertvector(v, bf16x2_cv); return __builtin_bit_cast(unsigned, b); }
; __device__ __forceinline__ float dpp_ror1(float v) { return __builtin_bit_cast(float, __builtin_amdgcn_update_dpp(0, __builtin_bit_cast(int, v), 0x121, 0xF, 0xF, false)); }
; __device__ __forceinline__ float dpp_rol1(float v) { return __builtin_bit_cast(float, __builtin_amdgcn_update_dpp(0, __builtin_bit_cast(int, v), 0x12F, 0xF, 0xF, false)); }
;     __device__ __forceinline__ void operator()(const pg8::f32x4 (&acc)[2][2][4][2], const pg8::Unit& u, int wr, int wc, int fr, int fq) const {
;     ...
;                     const float ruC = dpp_ror1(x0), rdN = m < 3 ? dpp_rol1(acc[ai][0][m < 3 ? m + 1 : 3][n][e]) : 0.f;
;                     float xu = fr == 0 ? ruP[c] : ruC, xd = fr == 15 ? rdN : rdC[c];
;                     xu = first ? 0.f : xu; xd = last ? 0.f : xd;
;                     ruP[c] = ruC; rdC[c] = rdN;
;                     const float x = w0[c] * xu + w1[c] * x0 + w2[c] * xd + bb[c];
;                     const float u2 = -2.302208198f * (x + 0.044715f * x * x * x);
;                     res[c] = x * __builtin_amdgcn_rcpf(1.0f + __builtin_amdgcn_exp2f(u2)) * acc[ai][1][m][n][e];
;                 }
;                 if (rl >= 1 && rl <= 62 && gr < nrows) { v4u o; o.x = pk2(res[0], res[1]); o.y = pk2(res[2], res[3]); o.z = pk2(res[4], res[5]); o.w = pk2(res[6], res[7]);
;                     *(v4u*)(G + (size_t)gr * DFF + ch0) = o; }
	v_mov_b32_e32 v199, v58
	v_mov_b32_e32 v196, v70
	v_cndmask_b32_e64 v197, v195, 0, vcc
	v_cmp_eq_u32_e64 s[52:53], s78, v200
	v_pk_mul_f32 v[196:197], v[198:199], v[196:197]
	v_cndmask_b32_e64 v193, v193, v158, s[40:41]
	v_cndmask_b32_e64 v195, 0, 1, s[52:53]
	v_cmp_eq_u32_e64 s[52:53], s12, v201
	v_add_f32_e32 v138, v196, v197
	v_cndmask_b32_e64 v192, v157, v192, s[38:39]
	v_cndmask_b32_e64 v196, 0, 1, s[52:53]
	v_cndmask_b32_e64 v195, v196, v195, s[48:49]
	v_and_b32_e32 v195, 1, v195
	v_cmp_eq_u32_e64 s[48:49], 1, v195
	v_mov_b32_e32 v196, v136
	v_mov_b32_e32 v197, v56
	v_cndmask_b32_e64 v193, v193, 0, s[48:49]
	v_fmac_f32_e32 v138, v62, v193
	v_add_f32_e32 v138, v66, v138
	v_mul_f32_e32 v193, 0x3d372713, v138
	v_mul_f32_e32 v193, v138, v193
	v_fma_f32 v193, v138, v193, v138
	v_mul_f32_e32 v193, 0xc0135761, v193
	v_exp_f32_e32 v195, v193
	v_cndmask_b32_e64 v193, v192, 0, vcc
	v_mov_b32_e32 v192, v68
	v_pk_mul_f32 v[192:193], v[196:197], v[192:193]
	v_cndmask_b32_e64 v191, v191, v156, s[40:41]
	v_add_f32_e32 v136, v192, v193
	v_cndmask_b32_e64 v191, v191, 0, s[48:49]
	v_fmac_f32_e32 v136, v60, v191
	v_add_f32_e32 v136, v64, v136
	v_mul_f32_e32 v191, 0x3d372713, v136
	v_mul_f32_e32 v191, v136, v191
	v_fma_f32 v191, v136, v191, v136
	v_mul_f32_e32 v191, 0xc0135761, v191
	v_exp_f32_e32 v191, v191
	v_add_f32_e32 v192, 1.0, v195
	v_rcp_f32_e32 v192, v192
	v_add_f32_e32 v191, 1.0, v191
	v_rcp_f32_e32 v191, v191
	v_mul_f32_e32 v138, v138, v192
	v_mul_f32_e32 v138, v130, v138
	v_mul_f32_e32 v130, v136, v191
	v_cndmask_b32_e64 v136, v155, v190, s[38:39]
	v_cndmask_b32_e64 v191, v136, 0, vcc
	v_mov_b32_e32 v136, v137
	v_mov_b32_e32 v137, v57
	v_mov_b32_e32 v190, v69
	v_pk_mul_f32 v[136:137], v[136:137], v[190:191]
	v_mul_f32_e32 v130, v128, v130
	v_add_f32_e32 v136, v136, v137
	v_cndmask_b32_e64 v137, v189, v154, s[40:41]
	v_cndmask_b32_e64 v137, v137, 0, s[48:49]
	v_fmac_f32_e32 v136, v61, v137
	v_add_f32_e32 v190, v65, v136
	v_mul_f32_e32 v136, 0x3d372713, v190
	v_mul_f32_e32 v136, v190, v136
	v_fma_f32 v136, v190, v136, v190
	v_mul_f32_e32 v136, 0xc0135761, v136
	v_exp_f32_e32 v191, v136
	v_cndmask_b32_e64 v136, v153, v188, s[38:39]
	v_cndmask_b32_e64 v137, v136, 0, vcc
	v_mov_b32_e32 v188, v142
	v_mov_b32_e32 v189, v78
	v_mov_b32_e32 v136, v94
	v_pk_mul_f32 v[136:137], v[188:189], v[136:137]
	v_mov_b32_e32 v142, v143
	v_add_f32_e32 v136, v136, v137
	v_cndmask_b32_e64 v137, v187, v152, s[40:41]
	v_cndmask_b32_e64 v137, v137, 0, s[48:49]
	v_fmac_f32_e32 v136, v82, v137
	v_add_f32_e32 v187, v86, v136
	v_mul_f32_e32 v136, 0x3d372713, v187
	v_mul_f32_e32 v136, v187, v136
	v_fma_f32 v136, v187, v136, v187
	v_mul_f32_e32 v136, 0xc0135761, v136
	v_exp_f32_e32 v136, v136
	v_mov_b32_e32 v143, v79
	v_add_f32_e32 v128, 1.0, v191
	v_rcp_f32_e32 v128, v128
	v_add_f32_e32 v136, 1.0, v136
	v_rcp_f32_e32 v188, v136
	v_cndmask_b32_e64 v136, v151, v186, s[38:39]
	v_cndmask_b32_e64 v137, v136, 0, vcc
	v_mov_b32_e32 v136, v95
	v_pk_mul_f32 v[136:137], v[142:143], v[136:137]
	v_mul_f32_e32 v128, v190, v128
	v_add_f32_e32 v136, v136, v137
	v_cndmask_b32_e64 v137, v185, v150, s[40:41]
	v_cndmask_b32_e64 v137, v137, 0, s[48:49]
	v_fmac_f32_e32 v136, v83, v137
	v_add_f32_e32 v142, v87, v136
	v_mul_f32_e32 v136, 0x3d372713, v142
	v_mul_f32_e32 v136, v142, v136
	v_fma_f32 v136, v142, v136, v142
	v_mul_f32_e32 v136, 0xc0135761, v136
	v_exp_f32_e32 v136, v136
	v_mul_f32_e32 v143, v129, v128
	v_mov_b32_e32 v137, v76
	v_mul_f32_e32 v185, v187, v188
	v_add_f32_e32 v128, 1.0, v136
	v_rcp_f32_e32 v186, v128
	v_cndmask_b32_e64 v128, v149, v184, s[38:39]
	v_cndmask_b32_e64 v129, v128, 0, vcc
	v_mov_b32_e32 v136, v140
	v_mov_b32_e32 v128, v92
	v_pk_mul_f32 v[128:129], v[136:137], v[128:129]
	v_mul_f32_e32 v137, v134, v185
	v_add_f32_e32 v128, v128, v129
	v_cndmask_b32_e64 v129, v183, v148, s[40:41]
	v_cndmask_b32_e64 v129, v129, 0, s[48:49]
	v_fmac_f32_e32 v128, v80, v129
	v_add_f32_e32 v136, v84, v128
	v_mul_f32_e32 v128, 0x3d372713, v136
	v_mul_f32_e32 v128, v136, v128
	v_fma_f32 v128, v136, v128, v136
	v_mul_f32_e32 v128, 0xc0135761, v128
	v_exp_f32_e32 v128, v128
	v_mul_f32_e32 v129, v142, v186
	v_mul_f32_e32 v140, v135, v129
	v_mov_b32_e32 v134, v141
	v_add_f32_e32 v128, 1.0, v128
	v_rcp_f32_e32 v142, v128
	v_cndmask_b32_e64 v128, v146, v181, s[38:39]
	v_cndmask_b32_e64 v129, v128, 0, vcc
	v_mov_b32_e32 v135, v77
	v_mov_b32_e32 v128, v93
	v_pk_mul_f32 v[128:129], v[134:135], v[128:129]
	v_mov_b32_e32 v134, v139
	v_add_f32_e32 v128, v128, v129
	v_cndmask_b32_e64 v129, v179, v144, s[40:41]
	v_cndmask_b32_e64 v129, v129, 0, s[48:49]
	v_fmac_f32_e32 v128, v81, v129
	v_add_f32_e32 v141, v85, v128
	v_mul_f32_e32 v128, 0x3d372713, v141
	v_mul_f32_e32 v128, v141, v128
	v_fma_f32 v128, v141, v128, v141
	v_mul_f32_e32 v128, 0xc0135761, v128
	v_exp_f32_e32 v179, v128
	v_cndmask_b32_e64 v128, v147, v182, s[38:39]
	v_cndmask_b32_e64 v129, v128, 0, vcc
	v_mov_b32_e32 v135, v59
	v_mov_b32_e32 v128, v71
	v_pk_mul_f32 v[128:129], v[134:135], v[128:129]
	v_add_f32_e32 v135, 1.0, v179
	v_add_f32_e32 v128, v128, v129
	v_cndmask_b32_e64 v129, v180, v145, s[40:41]
	v_cndmask_b32_e64 v129, v129, 0, s[48:49]
	v_fmac_f32_e32 v128, v63, v129
	v_add_f32_e32 v128, v67, v128
	v_mul_f32_e32 v129, 0x3d372713, v128
	v_mul_f32_e32 v129, v128, v129
	v_fma_f32 v129, v128, v129, v128
	v_mul_f32_e32 v129, 0xc0135761, v129
	v_exp_f32_e32 v129, v129
	v_rcp_f32_e32 v135, v135
	v_mul_f32_e32 v134, v136, v142
	v_mul_f32_e32 v132, v132, v134
	v_add_f32_e32 v129, 1.0, v129
	v_rcp_f32_e32 v129, v129
	v_mul_f32_e32 v134, v141, v135
	v_mul_f32_e32 v133, v133, v134
	v_cvt_pk_bf16_f32 v130, v130, v143
	v_mul_f32_e32 v128, v128, v129
	v_mul_f32_e32 v131, v131, v128
	v_cvt_pk_bf16_f32 v128, v132, v133
	v_mov_b64_e32 v[132:133], s[6:7]
	v_mad_i64_i32 v[132:133], s[48:49], v194, s1, v[132:133]
	v_cvt_pk_bf16_f32 v129, v137, v140
	v_cvt_pk_bf16_f32 v131, v138, v131
	v_lshl_add_u64 v[132:133], v[170:171], 1, v[132:133]
	global_store_dwordx4 v[132:133], v[128:131], off
; __device__ __forceinline__ float dpp_ror1(float v) { return __builtin_bit_cast(float, __builtin_amdgcn_update_dpp(0, __builtin_bit_cast(int, v), 0x121, 0xF, 0xF, false)); }
; __device__ __forceinline__ float dpp_rol1(float v) { return __builtin_bit_cast(float, __builtin_amdgcn_update_dpp(0, __builtin_bit_cast(int, v), 0x12F, 0xF, 0xF, false)); }
;     __device__ __forceinline__ void operator()(const pg8::f32x4 (&acc)[2][2][4][2], const pg8::Unit& u, int wr, int wc, int fr, int fq) const {
;     ...
;                 bool first, last; if (gr < ML) { const int t = gr & 8191; first = t == 0; last = t == 8191; } else { const int t = (gr - ML) & 255; first = t == 0; last = t == 255; }
;                 float res[8];
; #pragma unroll
;                 for (int c = 0; c < 8; ++c) {
;                     const int n = c >> 2, e = c & 3;
;                     const float x0 = acc[ai][0][m][n][e];
;                     const float ruC = dpp_ror1(x0), rdN = m < 3 ? dpp_rol1(acc[ai][0][m < 3 ? m + 1 : 3][n][e]) : 0.f;
;                     float xu = fr == 0 ? ruP[c] : ruC, xd = fr == 15 ? rdN : rdC[c];
;                     xu = first ? 0.f : xu; xd = last ? 0.f : xd;
;                     ruP[c] = ruC; rdC[c] = rdN;
;                     const float x = w0[c] * xu + w1[c] * x0 + w2[c] * xd + bb[c];
;                     const float u2 = -2.302208198f * (x + 0.044715f * x * x * x);
;                     res[c] = x * __builtin_amdgcn_rcpf(1.0f + __builtin_amdgcn_exp2f(u2)) * acc[ai][1][m][n][e];
.LBB0_1088:
	s_or_b64 exec, exec, s[80:81]
	v_add_u32_e32 v179, s73, v175
	v_mov_b32_e32 v142, v209
	v_mov_b32_e32 v140, v209
	v_mov_b32_e32 v143, v209
	v_mov_b32_e32 v141, v209
	v_mov_b32_e32 v138, v209
	v_mov_b32_e32 v136, v209
	v_mov_b32_e32 v139, v209
	v_mov_b32_e32 v137, v209
	v_mov_b32_e32 v134, v209
	v_mov_b32_e32 v132, v209
	v_mov_b32_e32 v135, v209
	v_mov_b32_e32 v133, v209
	v_mov_b32_e32 v130, v209
	v_mov_b32_e32 v128, v209
	v_mov_b32_e32 v131, v209
	v_mov_b32_e32 v129, v209
	v_mov_b32_dpp v142, v124 row_ror:1 row_mask:0xf bank_mask:0xf
	v_mov_b32_dpp v140, v108 row_ror:15 row_mask:0xf bank_mask:0xf
	v_mov_b32_dpp v143, v125 row_ror:1 row_mask:0xf bank_mask:0xf
	v_mov_b32_dpp v141, v109 row_ror:15 row_mask:0xf bank_mask:0xf
	v_mov_b32_dpp v138, v126 row_ror:1 row_mask:0xf bank_mask:0xf
	v_mov_b32_dpp v136, v110 row_ror:15 row_mask:0xf bank_mask:0xf
	v_mov_b32_dpp v139, v127 row_ror:1 row_mask:0xf bank_mask:0xf
	v_mov_b32_dpp v137, v111 row_ror:15 row_mask:0xf bank_mask:0xf
	v_mov_b32_dpp v134, v120 row_ror:1 row_mask:0xf bank_mask:0xf
	v_mov_b32_dpp v132, v104 row_ror:15 row_mask:0xf bank_mask:0xf
	v_mov_b32_dpp v135, v121 row_ror:1 row_mask:0xf bank_mask:0xf
	v_mov_b32_dpp v133, v105 row_ror:15 row_mask:0xf bank_mask:0xf
	v_mov_b32_dpp v130, v122 row_ror:1 row_mask:0xf bank_mask:0xf
	v_mov_b32_dpp v128, v106 row_ror:15 row_mask:0xf bank_mask:0xf
	v_mov_b32_dpp v131, v123 row_ror:1 row_mask:0xf bank_mask:0xf
	v_mov_b32_dpp v129, v107 row_ror:15 row_mask:0xf bank_mask:0xf
	v_cmp_gt_i32_e32 vcc, s86, v179
	s_and_saveexec_b64 s[80:81], vcc
	v_readlane_b32 s79, v254, 48
	v_readlane_b32 s83, v254, 49
	s_cbranch_execz .LBB0_1090
	v_and_b32_e32 v184, 0x1fff, v179
	v_and_b32_e32 v185, 0xff, v179
	v_cmp_gt_i32_e64 s[48:49], s97, v179
	v_cndmask_b32_e64 v159, v130, v159, s[38:39]
	v_mov_b32_e32 v182, v122
	v_cndmask_b32_e64 v180, v185, v184, s[48:49]
	v_cmp_eq_u32_e32 vcc, 0, v180
	s_waitcnt vmcnt(0)
	v_mov_b32_e32 v183, v58
	v_mov_b32_e32 v180, v70
	v_cndmask_b32_e64 v181, v159, 0, vcc
	v_cmp_eq_u32_e64 s[52:53], s78, v184
	v_pk_mul_f32 v[180:181], v[182:183], v[180:181]
	v_cndmask_b32_e64 v158, v158, v128, s[40:41]
	v_cndmask_b32_e64 v159, 0, 1, s[52:53]
	v_cmp_eq_u32_e64 s[52:53], s12, v185
	v_add_f32_e32 v122, v180, v181
	v_cndmask_b32_e64 v157, v134, v157, s[38:39]
	v_cndmask_b32_e64 v180, 0, 1, s[52:53]
	v_cndmask_b32_e64 v159, v180, v159, s[48:49]
	v_and_b32_e32 v159, 1, v159
	v_cmp_eq_u32_e64 s[48:49], 1, v159
	v_cndmask_b32_e64 v159, v157, 0, vcc
	v_mov_b32_e32 v180, v120
	v_cndmask_b32_e64 v158, v158, 0, s[48:49]
	v_fmac_f32_e32 v122, v62, v158
	v_add_f32_e32 v122, v66, v122
	v_mul_f32_e32 v158, 0x3d372713, v122
	v_mul_f32_e32 v158, v122, v158
	v_fma_f32 v158, v122, v158, v122
	v_mul_f32_e32 v158, 0xc0135761, v158
	v_exp_f32_e32 v182, v158
	v_mov_b32_e32 v181, v56
	v_mov_b32_e32 v158, v68
	v_pk_mul_f32 v[158:159], v[180:181], v[158:159]
	v_cndmask_b32_e64 v156, v156, v132, s[40:41]
	v_add_f32_e32 v120, v158, v159
	v_cndmask_b32_e64 v156, v156, 0, s[48:49]
	v_fmac_f32_e32 v120, v60, v156
	v_add_f32_e32 v120, v64, v120
	v_mul_f32_e32 v156, 0x3d372713, v120
	v_mul_f32_e32 v156, v120, v156
	v_fma_f32 v156, v120, v156, v120
	v_mul_f32_e32 v156, 0xc0135761, v156
	v_exp_f32_e32 v156, v156
	v_add_f32_e32 v157, 1.0, v182
	v_rcp_f32_e32 v157, v157
	v_add_f32_e32 v156, 1.0, v156
	v_rcp_f32_e32 v156, v156
	v_mul_f32_e32 v122, v122, v157
	v_mul_f32_e32 v122, v114, v122
	v_mul_f32_e32 v114, v120, v156
	v_cndmask_b32_e64 v120, v135, v155, s[38:39]
	v_cndmask_b32_e64 v157, v120, 0, vcc
	v_mov_b32_e32 v120, v121
	v_mov_b32_e32 v121, v57
	v_mov_b32_e32 v156, v69
	v_pk_mul_f32 v[120:121], v[120:121], v[156:157]
	v_mov_b32_e32 v155, v78
	v_add_f32_e32 v120, v120, v121
	v_cndmask_b32_e64 v121, v154, v133, s[40:41]
	v_cndmask_b32_e64 v121, v121, 0, s[48:49]
	v_fmac_f32_e32 v120, v61, v121
	v_add_f32_e32 v156, v65, v120
	v_mul_f32_e32 v120, 0x3d372713, v156
	v_mul_f32_e32 v120, v156, v120
	v_fma_f32 v120, v156, v120, v156
	v_mul_f32_e32 v120, 0xc0135761, v120
	v_exp_f32_e32 v157, v120
	v_cndmask_b32_e64 v120, v138, v153, s[38:39]
	v_cndmask_b32_e64 v121, v120, 0, vcc
	v_mov_b32_e32 v154, v126
	v_mov_b32_e32 v120, v94
	v_pk_mul_f32 v[120:121], v[154:155], v[120:121]
	v_mov_b32_e32 v126, v127
	v_add_f32_e32 v120, v120, v121
	v_cndmask_b32_e64 v121, v152, v136, s[40:41]
	v_cndmask_b32_e64 v121, v121, 0, s[48:49]
	v_fmac_f32_e32 v120, v82, v121
	v_add_f32_e32 v152, v86, v120
	v_mul_f32_e32 v120, 0x3d372713, v152
	v_mul_f32_e32 v120, v152, v120
	v_fma_f32 v120, v152, v120, v152
	v_mul_f32_e32 v120, 0xc0135761, v120
	v_exp_f32_e32 v120, v120
	v_mov_b32_e32 v127, v79
	v_mul_f32_e32 v114, v112, v114
	v_add_f32_e32 v112, 1.0, v157
	v_add_f32_e32 v120, 1.0, v120
	v_rcp_f32_e32 v153, v120
	v_cndmask_b32_e64 v120, v139, v151, s[38:39]
	v_cndmask_b32_e64 v121, v120, 0, vcc
	v_mov_b32_e32 v120, v95
	v_pk_mul_f32 v[120:121], v[126:127], v[120:121]
	v_rcp_f32_e32 v112, v112
	v_add_f32_e32 v120, v120, v121
	v_cndmask_b32_e64 v121, v150, v137, s[40:41]
	v_cndmask_b32_e64 v121, v121, 0, s[48:49]
	v_fmac_f32_e32 v120, v83, v121
	v_add_f32_e32 v126, v87, v120
	v_mul_f32_e32 v120, 0x3d372713, v126
	v_mul_f32_e32 v120, v126, v120
	v_fma_f32 v120, v126, v120, v126
	v_mul_f32_e32 v120, 0xc0135761, v120
	v_exp_f32_e32 v120, v120
	v_mul_f32_e32 v112, v156, v112
	v_mul_f32_e32 v127, v113, v112
	v_mov_b32_e32 v121, v76
	v_add_f32_e32 v112, 1.0, v120
	v_rcp_f32_e32 v151, v112
	v_cndmask_b32_e64 v112, v142, v149, s[38:39]
	v_cndmask_b32_e64 v113, v112, 0, vcc
	v_mov_b32_e32 v120, v124
	v_mov_b32_e32 v112, v92
	v_pk_mul_f32 v[112:113], v[120:121], v[112:113]
	v_mul_f32_e32 v150, v152, v153
; __device__ __forceinline__ unsigned pk2(float lo, float hi) { const f32x2_cv v = {lo, hi}; const bf16x2_cv b = __builtin_convertvector(v, bf16x2_cv); return __builtin_bit_cast(unsigned, b); }
; __device__ __forceinline__ float dpp_ror1(float v) { return __builtin_bit_cast(float, __builtin_amdgcn_update_dpp(0, __builtin_bit_cast(int, v), 0x121, 0xF, 0xF, false)); }
; __device__ __forceinline__ float dpp_rol1(float v) { return __builtin_bit_cast(float, __builtin_amdgcn_update_dpp(0, __builtin_bit_cast(int, v), 0x12F, 0xF, 0xF, false)); }
;     __device__ __forceinline__ void operator()(const pg8::f32x4 (&acc)[2][2][4][2], const pg8::Unit& u, int wr, int wc, int fr, int fq) const {
;     ...
;                     const float ruC = dpp_ror1(x0), rdN = m < 3 ? dpp_rol1(acc[ai][0][m < 3 ? m + 1 : 3][n][e]) : 0.f;
;                     float xu = fr == 0 ? ruP[c] : ruC, xd = fr == 15 ? rdN : rdC[c];
;                     xu = first ? 0.f : xu; xd = last ? 0.f : xd;
;                     ruP[c] = ruC; rdC[c] = rdN;
;                     const float x = w0[c] * xu + w1[c] * x0 + w2[c] * xd + bb[c];
;                     const float u2 = -2.302208198f * (x + 0.044715f * x * x * x);
;                     res[c] = x * __builtin_amdgcn_rcpf(1.0f + __builtin_amdgcn_exp2f(u2)) * acc[ai][1][m][n][e];
;                 }
;                 if (rl >= 1 && rl <= 62 && gr < nrows) { v4u o; o.x = pk2(res[0], res[1]); o.y = pk2(res[2], res[3]); o.z = pk2(res[4], res[5]); o.w = pk2(res[6], res[7]);
;                     *(v4u*)(G + (size_t)gr * DFF + ch0) = o; }
	v_add_f32_e32 v112, v112, v113
	v_cndmask_b32_e64 v113, v148, v140, s[40:41]
	v_cndmask_b32_e64 v113, v113, 0, s[48:49]
	v_fmac_f32_e32 v112, v80, v113
	v_add_f32_e32 v120, v84, v112
	v_mul_f32_e32 v112, 0x3d372713, v120
	v_mul_f32_e32 v112, v120, v112
	v_fma_f32 v112, v120, v112, v120
	v_mul_f32_e32 v112, 0xc0135761, v112
	v_exp_f32_e32 v112, v112
	v_mul_f32_e32 v113, v126, v151
	v_mul_f32_e32 v121, v118, v150
	v_mul_f32_e32 v124, v119, v113
	v_add_f32_e32 v112, 1.0, v112
	v_rcp_f32_e32 v126, v112
	v_cndmask_b32_e64 v112, v143, v146, s[38:39]
	v_cndmask_b32_e64 v113, v112, 0, vcc
	v_mov_b32_e32 v118, v125
	v_mov_b32_e32 v119, v77
	v_mov_b32_e32 v112, v93
	v_pk_mul_f32 v[112:113], v[118:119], v[112:113]
	v_mov_b32_e32 v118, v123
	v_add_f32_e32 v112, v112, v113
	v_cndmask_b32_e64 v113, v144, v141, s[40:41]
	v_cndmask_b32_e64 v113, v113, 0, s[48:49]
	v_fmac_f32_e32 v112, v81, v113
	v_add_f32_e32 v125, v85, v112
	v_mul_f32_e32 v112, 0x3d372713, v125
	v_mul_f32_e32 v112, v125, v112
	v_fma_f32 v112, v125, v112, v125
	v_mul_f32_e32 v112, 0xc0135761, v112
	v_exp_f32_e32 v144, v112
	v_cndmask_b32_e64 v112, v131, v147, s[38:39]
	v_cndmask_b32_e64 v113, v112, 0, vcc
	v_mov_b32_e32 v119, v59
	v_mov_b32_e32 v112, v71
	v_pk_mul_f32 v[112:113], v[118:119], v[112:113]
	v_add_f32_e32 v119, 1.0, v144
	v_add_f32_e32 v112, v112, v113
	v_cndmask_b32_e64 v113, v145, v129, s[40:41]
	v_cndmask_b32_e64 v113, v113, 0, s[48:49]
	v_fmac_f32_e32 v112, v63, v113
	v_add_f32_e32 v112, v67, v112
	v_mul_f32_e32 v113, 0x3d372713, v112
	v_mul_f32_e32 v113, v112, v113
	v_fma_f32 v113, v112, v113, v112
	v_mul_f32_e32 v113, 0xc0135761, v113
	v_exp_f32_e32 v113, v113
	v_rcp_f32_e32 v119, v119
	v_mul_f32_e32 v118, v120, v126
	v_mul_f32_e32 v116, v116, v118
	v_add_f32_e32 v113, 1.0, v113
	v_rcp_f32_e32 v113, v113
	v_mul_f32_e32 v118, v125, v119
	v_mul_f32_e32 v117, v117, v118
	v_cvt_pk_bf16_f32 v114, v114, v127
	v_mul_f32_e32 v112, v112, v113
	v_mul_f32_e32 v115, v115, v112
	v_cvt_pk_bf16_f32 v112, v116, v117
	v_mov_b64_e32 v[116:117], s[6:7]
	v_mad_i64_i32 v[116:117], s[48:49], v179, s1, v[116:117]
	v_cvt_pk_bf16_f32 v113, v121, v124
	v_cvt_pk_bf16_f32 v115, v122, v115
	v_lshl_add_u64 v[116:117], v[170:171], 1, v[116:117]
	global_store_dwordx4 v[116:117], v[112:115], off
.LBB0_1090:
	s_or_b64 exec, exec, s[80:81]
	s_nop 0
	v_add_u32_e32 v112, s73, v176
	v_mov_b32_e32 v119, v209
	v_mov_b32_e32 v120, v209
	v_mov_b32_e32 v117, v209
	v_mov_b32_e32 v118, v209
	v_mov_b32_e32 v115, v209
	v_mov_b32_e32 v116, v209
	v_mov_b32_e32 v113, v209
	v_mov_b32_e32 v114, v209
	v_cmp_gt_i32_e32 vcc, s86, v112
	v_mov_b32_dpp v119, v108 row_ror:1 row_mask:0xf bank_mask:0xf
	v_mov_b32_dpp v120, v109 row_ror:1 row_mask:0xf bank_mask:0xf
	v_mov_b32_dpp v117, v110 row_ror:1 row_mask:0xf bank_mask:0xf
	v_mov_b32_dpp v118, v111 row_ror:1 row_mask:0xf bank_mask:0xf
	v_mov_b32_dpp v115, v104 row_ror:1 row_mask:0xf bank_mask:0xf
	v_mov_b32_dpp v116, v105 row_ror:1 row_mask:0xf bank_mask:0xf
	v_mov_b32_dpp v113, v106 row_ror:1 row_mask:0xf bank_mask:0xf
	v_mov_b32_dpp v114, v107 row_ror:1 row_mask:0xf bank_mask:0xf
	s_and_b64 s[48:49], s[44:45], vcc
	s_and_saveexec_b64 s[52:53], s[48:49]
	s_cbranch_execz .LBB0_1092
	v_and_b32_e32 v121, 0x1fff, v112
	v_and_b32_e32 v122, 0xff, v112
	v_cmp_gt_i32_e32 vcc, s97, v112
	v_cmp_eq_u32_e64 s[48:49], s78, v121
	v_cndmask_b32_e64 v119, v119, v142, s[38:39]
	v_cndmask_b32_e32 v123, v122, v121, vcc
	v_cndmask_b32_e64 v121, 0, 1, s[48:49]
	v_cmp_eq_u32_e64 s[48:49], s12, v122
	v_cndmask_b32_e64 v120, v120, v143, s[38:39]
	s_waitcnt vmcnt(0)
	v_pk_mul_f32 v[108:109], v[108:109], v[92:93]
	v_cndmask_b32_e64 v122, 0, 1, s[48:49]
	v_cndmask_b32_e32 v121, v122, v121, vcc
	v_and_b32_e32 v122, 1, v121
	v_cmp_eq_u32_e64 s[48:49], 0, v123
	v_cmp_eq_u32_e32 vcc, 1, v122
	v_cndmask_b32_e64 v117, v117, v138, s[38:39]
	v_cndmask_b32_e64 v121, v120, 0, s[48:49]
	v_cndmask_b32_e64 v120, v119, 0, s[48:49]
	v_pk_fma_f32 v[108:109], v[76:77], v[120:121], v[108:109]
	v_cndmask_b32_e64 v121, v141, 0, vcc
	v_cndmask_b32_e64 v120, v140, 0, vcc
	v_pk_fma_f32 v[108:109], v[80:81], v[120:121], v[108:109]
	v_cndmask_b32_e64 v118, v118, v139, s[38:39]
	v_pk_add_f32 v[108:109], v[84:85], v[108:109]
	v_pk_mul_f32 v[110:111], v[110:111], v[94:95]
	v_mul_f32_e32 v119, 0x3d372713, v108
	v_mul_f32_e32 v119, v108, v119
	v_fma_f32 v119, v108, v119, v108
	v_mul_f32_e32 v119, 0xc0135761, v119
	v_exp_f32_e32 v119, v119
	v_mul_f32_e32 v120, 0x3d372713, v109
	v_mul_f32_e32 v120, v109, v120
	v_fma_f32 v120, v109, v120, v109
	v_mul_f32_e32 v120, 0xc0135761, v120
	v_add_f32_e32 v119, 1.0, v119
	v_exp_f32_e32 v121, v120
	v_rcp_f32_e32 v120, v119
	v_cndmask_b32_e64 v119, v118, 0, s[48:49]
	v_cndmask_b32_e64 v118, v117, 0, s[48:49]
	v_pk_fma_f32 v[110:111], v[78:79], v[118:119], v[110:111]
	v_cndmask_b32_e64 v119, v137, 0, vcc
	v_cndmask_b32_e64 v118, v136, 0, vcc
	v_pk_fma_f32 v[110:111], v[82:83], v[118:119], v[110:111]
	v_add_f32_e32 v121, 1.0, v121
	v_pk_add_f32 v[110:111], v[86:87], v[110:111]
	v_rcp_f32_e32 v121, v121
	v_mul_f32_e32 v117, 0x3d372713, v110
	v_mul_f32_e32 v117, v110, v117
	v_mul_f32_e32 v118, 0x3d372713, v111
	v_fma_f32 v117, v110, v117, v110
	v_mul_f32_e32 v118, v111, v118
	v_mul_f32_e32 v117, 0xc0135761, v117
	v_fma_f32 v118, v111, v118, v111
	v_exp_f32_e32 v117, v117
	v_mul_f32_e32 v118, 0xc0135761, v118
	v_exp_f32_e32 v119, v118
	v_pk_mul_f32 v[108:109], v[108:109], v[120:121]
	v_add_f32_e32 v117, 1.0, v117
	v_rcp_f32_e32 v118, v117
	v_add_f32_e32 v117, 1.0, v119
	v_rcp_f32_e32 v119, v117
	v_pk_mul_f32 v[100:101], v[100:101], v[108:109]
	v_cndmask_b32_e64 v113, v113, v130, s[38:39]
; __device__ __forceinline__ unsigned pk2(float lo, float hi) { const f32x2_cv v = {lo, hi}; const bf16x2_cv b = __builtin_convertvector(v, bf16x2_cv); return __builtin_bit_cast(unsigned, b); }
; __device__ __forceinline__ float dpp_ror1(float v) { return __builtin_bit_cast(float, __builtin_amdgcn_update_dpp(0, __builtin_bit_cast(int, v), 0x121, 0xF, 0xF, false)); }
; __device__ __forceinline__ float dpp_rol1(float v) { return __builtin_bit_cast(float, __builtin_amdgcn_update_dpp(0, __builtin_bit_cast(int, v), 0x12F, 0xF, 0xF, false)); }
;     __device__ __forceinline__ void operator()(const pg8::f32x4 (&acc)[2][2][4][2], const pg8::Unit& u, int wr, int wc, int fr, int fq) const {
;     ...
;                     const float ruC = dpp_ror1(x0), rdN = m < 3 ? dpp_rol1(acc[ai][0][m < 3 ? m + 1 : 3][n][e]) : 0.f;
;                     float xu = fr == 0 ? ruP[c] : ruC, xd = fr == 15 ? rdN : rdC[c];
;                     xu = first ? 0.f : xu; xd = last ? 0.f : xd;
;                     ruP[c] = ruC; rdC[c] = rdN;
;                     const float x = w0[c] * xu + w1[c] * x0 + w2[c] * xd + bb[c];
;                     const float u2 = -2.302208198f * (x + 0.044715f * x * x * x);
;                     res[c] = x * __builtin_amdgcn_rcpf(1.0f + __builtin_amdgcn_exp2f(u2)) * acc[ai][1][m][n][e];
;                 }
;                 if (rl >= 1 && rl <= 62 && gr < nrows) { v4u o; o.x = pk2(res[0], res[1]); o.y = pk2(res[2], res[3]); o.z = pk2(res[4], res[5]); o.w = pk2(res[6], res[7]);
;                     *(v4u*)(G + (size_t)gr * DFF + ch0) = o; }
	v_cndmask_b32_e64 v114, v114, v131, s[38:39]
	v_pk_mul_f32 v[108:109], v[110:111], v[118:119]
	v_cndmask_b32_e64 v110, v115, v134, s[38:39]
	v_cndmask_b32_e64 v111, v116, v135, s[38:39]
	v_pk_mul_f32 v[104:105], v[104:105], v[68:69]
	v_cndmask_b32_e64 v111, v111, 0, s[48:49]
	v_cndmask_b32_e64 v110, v110, 0, s[48:49]
	v_pk_mul_f32 v[106:107], v[106:107], v[70:71]
	v_cndmask_b32_e64 v115, v114, 0, s[48:49]
	v_cndmask_b32_e64 v114, v113, 0, s[48:49]
	v_pk_fma_f32 v[104:105], v[56:57], v[110:111], v[104:105]
	v_cndmask_b32_e64 v111, v133, 0, vcc
	v_cndmask_b32_e64 v110, v132, 0, vcc
	v_pk_fma_f32 v[106:107], v[58:59], v[114:115], v[106:107]
	v_cndmask_b32_e64 v115, v129, 0, vcc
	v_cndmask_b32_e64 v114, v128, 0, vcc
	v_pk_fma_f32 v[104:105], v[60:61], v[110:111], v[104:105]
	v_pk_fma_f32 v[106:107], v[62:63], v[114:115], v[106:107]
	v_pk_add_f32 v[104:105], v[64:65], v[104:105]
	v_pk_add_f32 v[106:107], v[66:67], v[106:107]
	v_mul_f32_e32 v110, 0x3d372713, v104
	v_mul_f32_e32 v111, 0x3d372713, v105
	v_mul_f32_e32 v113, 0x3d372713, v106
	v_mul_f32_e32 v110, v104, v110
	v_mul_f32_e32 v111, v105, v111
	v_mul_f32_e32 v113, v106, v113
	v_mul_f32_e32 v114, 0x3d372713, v107
	v_fma_f32 v110, v104, v110, v104
	v_fma_f32 v111, v105, v111, v105
	v_fma_f32 v113, v106, v113, v106
	v_mul_f32_e32 v114, v107, v114
	v_mul_f32_e32 v110, 0xc0135761, v110
	v_mul_f32_e32 v111, 0xc0135761, v111
	v_mul_f32_e32 v113, 0xc0135761, v113
	v_fma_f32 v114, v107, v114, v107
	v_exp_f32_e32 v110, v110
	v_exp_f32_e32 v111, v111
	v_exp_f32_e32 v113, v113
	v_mul_f32_e32 v114, 0xc0135761, v114
	v_exp_f32_e32 v115, v114
	v_add_f32_e32 v110, 1.0, v110
	v_add_f32_e32 v111, 1.0, v111
	v_add_f32_e32 v113, 1.0, v113
	v_rcp_f32_e32 v110, v110
	v_rcp_f32_e32 v111, v111
	v_rcp_f32_e32 v114, v113
	v_add_f32_e32 v113, 1.0, v115
	v_rcp_f32_e32 v115, v113
	v_pk_mul_f32 v[104:105], v[104:105], v[110:111]
	v_pk_mul_f32 v[102:103], v[102:103], v[108:109]
	v_pk_mul_f32 v[104:105], v[96:97], v[104:105]
	v_pk_mul_f32 v[96:97], v[106:107], v[114:115]
	s_nop 0
	v_pk_mul_f32 v[106:107], v[98:99], v[96:97]
	v_cvt_pk_bf16_f32 v96, v100, v101
	v_mov_b64_e32 v[100:101], s[6:7]
	v_mad_i64_i32 v[100:101], s[48:49], v112, s1, v[100:101]
	v_cvt_pk_bf16_f32 v97, v102, v103
	v_cvt_pk_bf16_f32 v98, v104, v105
	v_cvt_pk_bf16_f32 v99, v106, v107
	v_lshl_add_u64 v[100:101], v[170:171], 1, v[100:101]
	global_store_dwordx4 v[100:101], v[96:99], off
.LBB0_1092:
	s_or_b64 exec, exec, s[52:53]
	s_addk_i32 s65, 0x7b
	v_add_u32_e32 v111, s65, v172
	v_mov_b32_e32 v115, v209
	v_mov_b32_e32 v116, v209
	v_mov_b32_e32 v117, v209
	v_mov_b32_e32 v118, v209
	v_mov_b32_e32 v119, v209
	v_mov_b32_e32 v120, v209
	v_mov_b32_e32 v113, v209
	v_mov_b32_e32 v114, v209
	v_mov_b32_e32 v101, v209
	v_mov_b32_e32 v100, v209
	v_mov_b32_e32 v98, v209
	v_mov_b32_e32 v96, v209
	v_mov_b32_e32 v105, v209
	v_mov_b32_e32 v104, v209
	v_mov_b32_e32 v103, v209
	v_mov_b32_e32 v102, v209
	v_mov_b32_e32 v109, v209
	v_mov_b32_e32 v108, v209
	v_mov_b32_e32 v107, v209
	v_mov_b32_e32 v106, v209
	v_mov_b32_e32 v112, v209
	v_mov_b32_e32 v110, v209
	v_mov_b32_e32 v99, v209
	v_mov_b32_e32 v97, v209
	v_cmp_gt_i32_e32 vcc, s86, v111
	v_mov_b32_dpp v115, v72 row_ror:15 row_mask:0xf bank_mask:0xf
	v_mov_b32_dpp v116, v73 row_ror:15 row_mask:0xf bank_mask:0xf
	v_mov_b32_dpp v117, v74 row_ror:15 row_mask:0xf bank_mask:0xf
	v_mov_b32_dpp v118, v75 row_ror:15 row_mask:0xf bank_mask:0xf
	v_mov_b32_dpp v119, v88 row_ror:15 row_mask:0xf bank_mask:0xf
	v_mov_b32_dpp v120, v89 row_ror:15 row_mask:0xf bank_mask:0xf
	v_mov_b32_dpp v113, v90 row_ror:15 row_mask:0xf bank_mask:0xf
	v_mov_b32_dpp v114, v91 row_ror:15 row_mask:0xf bank_mask:0xf
	v_mov_b32_dpp v101, v72 row_ror:1 row_mask:0xf bank_mask:0xf
	v_mov_b32_dpp v100, v44 row_ror:15 row_mask:0xf bank_mask:0xf
	v_mov_b32_dpp v98, v73 row_ror:1 row_mask:0xf bank_mask:0xf
	v_mov_b32_dpp v96, v45 row_ror:15 row_mask:0xf bank_mask:0xf
	v_mov_b32_dpp v105, v74 row_ror:1 row_mask:0xf bank_mask:0xf
	v_mov_b32_dpp v104, v46 row_ror:15 row_mask:0xf bank_mask:0xf
	v_mov_b32_dpp v103, v75 row_ror:1 row_mask:0xf bank_mask:0xf
	v_mov_b32_dpp v102, v47 row_ror:15 row_mask:0xf bank_mask:0xf
	v_mov_b32_dpp v109, v88 row_ror:1 row_mask:0xf bank_mask:0xf
	v_mov_b32_dpp v108, v40 row_ror:15 row_mask:0xf bank_mask:0xf
	v_mov_b32_dpp v107, v89 row_ror:1 row_mask:0xf bank_mask:0xf
	v_mov_b32_dpp v106, v41 row_ror:15 row_mask:0xf bank_mask:0xf
	v_mov_b32_dpp v112, v90 row_ror:1 row_mask:0xf bank_mask:0xf
	v_mov_b32_dpp v110, v42 row_ror:15 row_mask:0xf bank_mask:0xf
	v_mov_b32_dpp v99, v91 row_ror:1 row_mask:0xf bank_mask:0xf
	v_mov_b32_dpp v97, v43 row_ror:15 row_mask:0xf bank_mask:0xf
	s_and_b64 s[48:49], s[42:43], vcc
	s_and_saveexec_b64 s[52:53], s[48:49]
	s_cbranch_execz .LBB0_1094
; __device__ __forceinline__ unsigned pk2(float lo, float hi) { const f32x2_cv v = {lo, hi}; const bf16x2_cv b = __builtin_convertvector(v, bf16x2_cv); return __builtin_bit_cast(unsigned, b); }
; __device__ __forceinline__ float dpp_ror1(float v) { return __builtin_bit_cast(float, __builtin_amdgcn_update_dpp(0, __builtin_bit_cast(int, v), 0x121, 0xF, 0xF, false)); }
; __device__ __forceinline__ float dpp_rol1(float v) { return __builtin_bit_cast(float, __builtin_amdgcn_update_dpp(0, __builtin_bit_cast(int, v), 0x12F, 0xF, 0xF, false)); }
;     __device__ __forceinline__ void operator()(const pg8::f32x4 (&acc)[2][2][4][2], const pg8::Unit& u, int wr, int wc, int fr, int fq) const {
;     ...
;                 bool first, last; if (gr < ML) { const int t = gr & 8191; first = t == 0; last = t == 8191; } else { const int t = (gr - ML) & 255; first = t == 0; last = t == 255; }
;                 float res[8];
; #pragma unroll
;                 for (int c = 0; c < 8; ++c) {
;                     const int n = c >> 2, e = c & 3;
;                     const float x0 = acc[ai][0][m][n][e];
;                     const float ruC = dpp_ror1(x0), rdN = m < 3 ? dpp_rol1(acc[ai][0][m < 3 ? m + 1 : 3][n][e]) : 0.f;
;                     float xu = fr == 0 ? ruP[c] : ruC, xd = fr == 15 ? rdN : rdC[c];
;                     xu = first ? 0.f : xu; xd = last ? 0.f : xd;
;                     ruP[c] = ruC; rdC[c] = rdN;
;                     const float x = w0[c] * xu + w1[c] * x0 + w2[c] * xd + bb[c];
;                     const float u2 = -2.302208198f * (x + 0.044715f * x * x * x);
;                     res[c] = x * __builtin_amdgcn_rcpf(1.0f + __builtin_amdgcn_exp2f(u2)) * acc[ai][1][m][n][e];
;                 }
;                 if (rl >= 1 && rl <= 62 && gr < nrows) { v4u o; o.x = pk2(res[0], res[1]); o.y = pk2(res[2], res[3]); o.z = pk2(res[4], res[5]); o.w = pk2(res[6], res[7]);
;                     *(v4u*)(G + (size_t)gr * DFF + ch0) = o; }
	v_and_b32_e32 v121, 0x1fff, v111
	v_and_b32_e32 v122, 0xff, v111
	v_cmp_gt_i32_e32 vcc, s97, v111
	v_cmp_eq_u32_e64 s[48:49], s78, v121
	s_waitcnt vmcnt(0)
	v_pk_mul_f32 v[88:89], v[88:89], v[68:69]
	v_cndmask_b32_e32 v123, v122, v121, vcc
	v_cndmask_b32_e64 v121, 0, 1, s[48:49]
	v_cmp_eq_u32_e64 s[48:49], s12, v122
	v_cndmask_b32_e64 v119, v119, v108, s[40:41]
	v_cndmask_b32_e64 v120, v120, v106, s[40:41]
	v_cndmask_b32_e64 v122, 0, 1, s[48:49]
	v_cndmask_b32_e32 v121, v122, v121, vcc
	v_and_b32_e32 v121, 1, v121
	v_cmp_eq_u32_e32 vcc, 0, v123
	v_cmp_eq_u32_e64 s[48:49], 1, v121
	v_pk_mul_f32 v[72:73], v[72:73], v[92:93]
	v_cndmask_b32_e64 v123, v107, 0, vcc
	v_cndmask_b32_e64 v122, v109, 0, vcc
	v_pk_fma_f32 v[88:89], v[56:57], v[122:123], v[88:89]
	v_cndmask_b32_e64 v121, v120, 0, s[48:49]
	v_cndmask_b32_e64 v120, v119, 0, s[48:49]
	v_pk_fma_f32 v[88:89], v[60:61], v[120:121], v[88:89]
	v_cndmask_b32_e64 v115, v115, v100, s[40:41]
	v_pk_add_f32 v[88:89], v[64:65], v[88:89]
	v_cndmask_b32_e64 v116, v116, v96, s[40:41]
	v_mul_f32_e32 v119, 0x3d372713, v88
	v_mul_f32_e32 v119, v88, v119
	v_mul_f32_e32 v120, 0x3d372713, v89
	v_fma_f32 v119, v88, v119, v88
	v_mul_f32_e32 v120, v89, v120
	v_mul_f32_e32 v119, 0xc0135761, v119
	v_fma_f32 v120, v89, v120, v89
	v_exp_f32_e32 v119, v119
	v_mul_f32_e32 v120, 0xc0135761, v120
	v_exp_f32_e32 v121, v120
	v_pk_mul_f32 v[90:91], v[90:91], v[70:71]
	v_add_f32_e32 v119, 1.0, v119
	v_rcp_f32_e32 v120, v119
	v_add_f32_e32 v119, 1.0, v121
	v_rcp_f32_e32 v121, v119
	v_cndmask_b32_e64 v119, v98, 0, vcc
	v_cndmask_b32_e64 v113, v113, v110, s[40:41]
	v_cndmask_b32_e64 v114, v114, v97, s[40:41]
	v_pk_mul_f32 v[88:89], v[88:89], v[120:121]
	s_nop 0
	v_pk_mul_f32 v[88:89], v[48:49], v[88:89]
	v_pk_mul_f32 v[48:49], v[74:75], v[94:95]
	v_cndmask_b32_e64 v75, v103, 0, vcc
	v_cndmask_b32_e64 v74, v105, 0, vcc
	v_pk_fma_f32 v[48:49], v[78:79], v[74:75], v[48:49]
	v_cndmask_b32_e64 v74, v117, v104, s[40:41]
	v_cndmask_b32_e64 v75, v118, v102, s[40:41]
	v_cndmask_b32_e64 v75, v75, 0, s[48:49]
	v_cndmask_b32_e64 v74, v74, 0, s[48:49]
	v_pk_fma_f32 v[48:49], v[82:83], v[74:75], v[48:49]
	v_cndmask_b32_e64 v118, v101, 0, vcc
	v_pk_add_f32 v[48:49], v[86:87], v[48:49]
	v_pk_fma_f32 v[72:73], v[76:77], v[118:119], v[72:73]
	v_mul_f32_e32 v74, 0x3d372713, v48
	v_mul_f32_e32 v75, 0x3d372713, v49
	v_mul_f32_e32 v74, v48, v74
	v_mul_f32_e32 v75, v49, v75
	v_fma_f32 v74, v48, v74, v48
	v_fma_f32 v75, v49, v75, v49
	v_cndmask_b32_e64 v117, v116, 0, s[48:49]
	v_cndmask_b32_e64 v116, v115, 0, s[48:49]
	v_mul_f32_e32 v74, 0xc0135761, v74
	v_mul_f32_e32 v75, 0xc0135761, v75
	v_pk_fma_f32 v[72:73], v[80:81], v[116:117], v[72:73]
	v_exp_f32_e32 v74, v74
	v_exp_f32_e32 v75, v75
	v_pk_add_f32 v[72:73], v[84:85], v[72:73]
	v_cndmask_b32_e64 v117, v99, 0, vcc
	v_mul_f32_e32 v116, 0x3d372713, v73
	v_mul_f32_e32 v115, 0x3d372713, v72
	v_mul_f32_e32 v116, v73, v116
	v_mul_f32_e32 v115, v72, v115
	v_fma_f32 v116, v73, v116, v73
	v_add_f32_e32 v74, 1.0, v74
	v_add_f32_e32 v75, 1.0, v75
	v_fma_f32 v115, v72, v115, v72
	v_mul_f32_e32 v116, 0xc0135761, v116
	v_rcp_f32_e32 v74, v74
	v_rcp_f32_e32 v75, v75
	v_mul_f32_e32 v115, 0xc0135761, v115
	v_exp_f32_e32 v116, v116
	v_exp_f32_e32 v115, v115
	v_pk_mul_f32 v[48:49], v[48:49], v[74:75]
	v_add_f32_e32 v75, 1.0, v116
	v_cndmask_b32_e64 v116, v112, 0, vcc
	v_add_f32_e32 v74, 1.0, v115
	v_pk_fma_f32 v[90:91], v[58:59], v[116:117], v[90:91]
	v_cndmask_b32_e64 v115, v114, 0, s[48:49]
	v_cndmask_b32_e64 v114, v113, 0, s[48:49]
	v_pk_fma_f32 v[90:91], v[62:63], v[114:115], v[90:91]
	v_rcp_f32_e32 v74, v74
	v_pk_add_f32 v[90:91], v[66:67], v[90:91]
	v_rcp_f32_e32 v75, v75
	v_mul_f32_e32 v113, 0x3d372713, v90
	v_mul_f32_e32 v113, v90, v113
	v_mul_f32_e32 v114, 0x3d372713, v91
	v_fma_f32 v113, v90, v113, v90
	v_mul_f32_e32 v114, v91, v114
	v_mul_f32_e32 v113, 0xc0135761, v113
	v_fma_f32 v114, v91, v114, v91
	v_exp_f32_e32 v113, v113
	v_mul_f32_e32 v114, 0xc0135761, v114
	v_exp_f32_e32 v115, v114
	v_pk_mul_f32 v[54:55], v[54:55], v[48:49]
	v_add_f32_e32 v113, 1.0, v113
	v_rcp_f32_e32 v114, v113
	v_add_f32_e32 v113, 1.0, v115
	v_rcp_f32_e32 v115, v113
	v_pk_mul_f32 v[48:49], v[72:73], v[74:75]
	s_nop 0
	v_pk_mul_f32 v[48:49], v[52:53], v[48:49]
	v_pk_mul_f32 v[52:53], v[90:91], v[114:115]
	v_cvt_pk_bf16_f32 v48, v48, v49
	v_pk_mul_f32 v[52:53], v[50:51], v[52:53]
	v_cvt_pk_bf16_f32 v49, v54, v55
	v_cvt_pk_bf16_f32 v51, v52, v53
	v_mov_b64_e32 v[52:53], s[6:7]
	v_mad_i64_i32 v[52:53], s[48:49], v111, s1, v[52:53]
	v_cvt_pk_bf16_f32 v50, v88, v89
	v_lshl_add_u64 v[52:53], v[170:171], 1, v[52:53]
	global_store_dwordx4 v[52:53], v[48:51], off
; __device__ __forceinline__ float dpp_ror1(float v) { return __builtin_bit_cast(float, __builtin_amdgcn_update_dpp(0, __builtin_bit_cast(int, v), 0x121, 0xF, 0xF, false)); }
; __device__ __forceinline__ float dpp_rol1(float v) { return __builtin_bit_cast(float, __builtin_amdgcn_update_dpp(0, __builtin_bit_cast(int, v), 0x12F, 0xF, 0xF, false)); }
;     __device__ __forceinline__ void operator()(const pg8::f32x4 (&acc)[2][2][4][2], const pg8::Unit& u, int wr, int wc, int fr, int fq) const {
;     ...
;                 bool first, last; if (gr < ML) { const int t = gr & 8191; first = t == 0; last = t == 8191; } else { const int t = (gr - ML) & 255; first = t == 0; last = t == 255; }
;                 float res[8];
; #pragma unroll
;                 for (int c = 0; c < 8; ++c) {
;                     const int n = c >> 2, e = c & 3;
;                     const float x0 = acc[ai][0][m][n][e];
;                     const float ruC = dpp_ror1(x0), rdN = m < 3 ? dpp_rol1(acc[ai][0][m < 3 ? m + 1 : 3][n][e]) : 0.f;
;                     float xu = fr == 0 ? ruP[c] : ruC, xd = fr == 15 ? rdN : rdC[c];
;                     xu = first ? 0.f : xu; xd = last ? 0.f : xd;
;                     ruP[c] = ruC; rdC[c] = rdN;
;                     const float x = w0[c] * xu + w1[c] * x0 + w2[c] * xd + bb[c];
;                     const float u2 = -2.302208198f * (x + 0.044715f * x * x * x);
;                     res[c] = x * __builtin_amdgcn_rcpf(1.0f + __builtin_amdgcn_exp2f(u2)) * acc[ai][1][m][n][e];
.LBB0_1094:
	s_or_b64 exec, exec, s[52:53]
	v_add_u32_e32 v111, s65, v174
	v_mov_b32_e32 v53, v209
	v_mov_b32_e32 v52, v209
	v_mov_b32_e32 v50, v209
	v_mov_b32_e32 v48, v209
	v_mov_b32_e32 v73, v209
	v_mov_b32_e32 v72, v209
	v_mov_b32_e32 v55, v209
	v_mov_b32_e32 v54, v209
	v_mov_b32_e32 v89, v209
	v_mov_b32_e32 v88, v209
	v_mov_b32_e32 v75, v209
	v_mov_b32_e32 v74, v209
	v_mov_b32_e32 v91, v209
	v_mov_b32_e32 v90, v209
	v_mov_b32_e32 v51, v209
	v_mov_b32_e32 v49, v209
	v_mov_b32_dpp v53, v44 row_ror:1 row_mask:0xf bank_mask:0xf
	v_mov_b32_dpp v52, v28 row_ror:15 row_mask:0xf bank_mask:0xf
	v_mov_b32_dpp v50, v45 row_ror:1 row_mask:0xf bank_mask:0xf
	v_mov_b32_dpp v48, v29 row_ror:15 row_mask:0xf bank_mask:0xf
	v_mov_b32_dpp v73, v46 row_ror:1 row_mask:0xf bank_mask:0xf
	v_mov_b32_dpp v72, v30 row_ror:15 row_mask:0xf bank_mask:0xf
	v_mov_b32_dpp v55, v47 row_ror:1 row_mask:0xf bank_mask:0xf
	v_mov_b32_dpp v54, v31 row_ror:15 row_mask:0xf bank_mask:0xf
	v_mov_b32_dpp v89, v40 row_ror:1 row_mask:0xf bank_mask:0xf
	v_mov_b32_dpp v88, v24 row_ror:15 row_mask:0xf bank_mask:0xf
	v_mov_b32_dpp v75, v41 row_ror:1 row_mask:0xf bank_mask:0xf
	v_mov_b32_dpp v74, v25 row_ror:15 row_mask:0xf bank_mask:0xf
	v_mov_b32_dpp v91, v42 row_ror:1 row_mask:0xf bank_mask:0xf
	v_mov_b32_dpp v90, v26 row_ror:15 row_mask:0xf bank_mask:0xf
	v_mov_b32_dpp v51, v43 row_ror:1 row_mask:0xf bank_mask:0xf
	v_mov_b32_dpp v49, v27 row_ror:15 row_mask:0xf bank_mask:0xf
	v_cmp_gt_i32_e32 vcc, s86, v111
	s_and_saveexec_b64 s[80:81], vcc
	s_cbranch_execz .LBB0_1096
	v_and_b32_e32 v116, 0x1fff, v111
	v_and_b32_e32 v117, 0xff, v111
	v_cmp_gt_i32_e64 s[48:49], s97, v111
	v_cndmask_b32_e64 v112, v91, v112, s[38:39]
	v_mov_b32_e32 v114, v42
	v_cndmask_b32_e64 v113, v117, v116, s[48:49]
	v_cmp_eq_u32_e32 vcc, 0, v113
	s_waitcnt vmcnt(0)
	v_mov_b32_e32 v115, v58
	v_cmp_eq_u32_e64 s[52:53], s78, v116
	v_cndmask_b32_e64 v113, v112, 0, vcc
	v_mov_b32_e32 v112, v70
	v_pk_mul_f32 v[112:113], v[114:115], v[112:113]
	v_cndmask_b32_e64 v109, v89, v109, s[38:39]
	v_add_f32_e32 v42, v112, v113
	v_cndmask_b32_e64 v112, 0, 1, s[52:53]
	v_cmp_eq_u32_e64 s[52:53], s12, v117
	v_cndmask_b32_e64 v110, v110, v90, s[40:41]
	v_mov_b32_e32 v114, v40
	v_cndmask_b32_e64 v113, 0, 1, s[52:53]
	v_cndmask_b32_e64 v112, v113, v112, s[48:49]
	v_and_b32_e32 v112, 1, v112
	v_cmp_eq_u32_e64 s[48:49], 1, v112
	v_cndmask_b32_e64 v113, v109, 0, vcc
	v_mov_b32_e32 v115, v56
	v_mov_b32_e32 v112, v68
	v_cndmask_b32_e64 v110, v110, 0, s[48:49]
	v_pk_mul_f32 v[112:113], v[114:115], v[112:113]
	v_cndmask_b32_e64 v108, v108, v88, s[40:41]
	v_fmac_f32_e32 v42, v62, v110
	v_add_f32_e32 v40, v112, v113
	v_cndmask_b32_e64 v108, v108, 0, s[48:49]
	v_add_f32_e32 v42, v66, v42
	v_fmac_f32_e32 v40, v60, v108
	v_mul_f32_e32 v110, 0x3d372713, v42
	v_add_f32_e32 v40, v64, v40
	v_mul_f32_e32 v110, v42, v110
	v_mul_f32_e32 v108, 0x3d372713, v40
	v_fma_f32 v110, v42, v110, v42
	v_mul_f32_e32 v108, v40, v108
	v_mul_f32_e32 v110, 0xc0135761, v110
	v_fma_f32 v108, v40, v108, v40
	v_exp_f32_e32 v110, v110
	v_mul_f32_e32 v108, 0xc0135761, v108
	v_exp_f32_e32 v108, v108
	v_add_f32_e32 v109, 1.0, v110
	v_rcp_f32_e32 v109, v109
	v_add_f32_e32 v108, 1.0, v108
	v_rcp_f32_e32 v108, v108
	v_mul_f32_e32 v42, v42, v109
	v_mul_f32_e32 v42, v34, v42
	v_mul_f32_e32 v34, v40, v108
	v_cndmask_b32_e64 v40, v75, v107, s[38:39]
	v_cndmask_b32_e64 v109, v40, 0, vcc
	v_mov_b32_e32 v40, v41
	v_mov_b32_e32 v41, v57
	v_mov_b32_e32 v108, v69
	v_pk_mul_f32 v[40:41], v[40:41], v[108:109]
	v_mov_b32_e32 v107, v78
	v_add_f32_e32 v40, v40, v41
	v_cndmask_b32_e64 v41, v106, v74, s[40:41]
	v_cndmask_b32_e64 v41, v41, 0, s[48:49]
	v_fmac_f32_e32 v40, v61, v41
	v_add_f32_e32 v108, v65, v40
	v_mul_f32_e32 v40, 0x3d372713, v108
	v_mul_f32_e32 v40, v108, v40
	v_fma_f32 v40, v108, v40, v108
	v_mul_f32_e32 v40, 0xc0135761, v40
	v_exp_f32_e32 v109, v40
	v_cndmask_b32_e64 v40, v73, v105, s[38:39]
	v_cndmask_b32_e64 v41, v40, 0, vcc
	v_mov_b32_e32 v106, v46
	v_mov_b32_e32 v40, v94
	v_pk_mul_f32 v[40:41], v[106:107], v[40:41]
	v_mov_b32_e32 v46, v47
	v_add_f32_e32 v40, v40, v41
	v_cndmask_b32_e64 v41, v104, v72, s[40:41]
	v_cndmask_b32_e64 v41, v41, 0, s[48:49]
	v_fmac_f32_e32 v40, v82, v41
	v_add_f32_e32 v104, v86, v40
	v_mul_f32_e32 v40, 0x3d372713, v104
	v_mul_f32_e32 v40, v104, v40
	v_fma_f32 v40, v104, v40, v104
	v_mul_f32_e32 v40, 0xc0135761, v40
	v_exp_f32_e32 v40, v40
	v_mov_b32_e32 v47, v79
	v_mul_f32_e32 v34, v32, v34
	v_add_f32_e32 v32, 1.0, v109
	v_add_f32_e32 v40, 1.0, v40
	v_rcp_f32_e32 v105, v40
	v_cndmask_b32_e64 v40, v55, v103, s[38:39]
	v_cndmask_b32_e64 v41, v40, 0, vcc
	v_mov_b32_e32 v40, v95
	v_pk_mul_f32 v[40:41], v[46:47], v[40:41]
	v_rcp_f32_e32 v32, v32
	v_add_f32_e32 v40, v40, v41
	v_cndmask_b32_e64 v41, v102, v54, s[40:41]
	v_cndmask_b32_e64 v41, v41, 0, s[48:49]
	v_fmac_f32_e32 v40, v83, v41
	v_add_f32_e32 v46, v87, v40
	v_mul_f32_e32 v40, 0x3d372713, v46
	v_mul_f32_e32 v40, v46, v40
	v_fma_f32 v40, v46, v40, v46
	v_mul_f32_e32 v40, 0xc0135761, v40
	v_exp_f32_e32 v40, v40
	v_mul_f32_e32 v32, v108, v32
	v_mul_f32_e32 v47, v33, v32
	v_mov_b32_e32 v41, v76
	v_add_f32_e32 v32, 1.0, v40
	v_rcp_f32_e32 v103, v32
	v_cndmask_b32_e64 v32, v53, v101, s[38:39]
	v_cndmask_b32_e64 v33, v32, 0, vcc
	v_mov_b32_e32 v40, v44
	v_mov_b32_e32 v32, v92
	v_pk_mul_f32 v[32:33], v[40:41], v[32:33]
	v_mul_f32_e32 v102, v104, v105
	v_add_f32_e32 v32, v32, v33
	v_cndmask_b32_e64 v33, v100, v52, s[40:41]
	v_cndmask_b32_e64 v33, v33, 0, s[48:49]
	v_fmac_f32_e32 v32, v80, v33
	v_add_f32_e32 v40, v84, v32
	v_mul_f32_e32 v32, 0x3d372713, v40
	v_mul_f32_e32 v32, v40, v32
; __device__ __forceinline__ unsigned pk2(float lo, float hi) { const f32x2_cv v = {lo, hi}; const bf16x2_cv b = __builtin_convertvector(v, bf16x2_cv); return __builtin_bit_cast(unsigned, b); }
; __device__ __forceinline__ float dpp_ror1(float v) { return __builtin_bit_cast(float, __builtin_amdgcn_update_dpp(0, __builtin_bit_cast(int, v), 0x121, 0xF, 0xF, false)); }
; __device__ __forceinline__ float dpp_rol1(float v) { return __builtin_bit_cast(float, __builtin_amdgcn_update_dpp(0, __builtin_bit_cast(int, v), 0x12F, 0xF, 0xF, false)); }
;     __device__ __forceinline__ void operator()(const pg8::f32x4 (&acc)[2][2][4][2], const pg8::Unit& u, int wr, int wc, int fr, int fq) const {
;     ...
;                     const float ruC = dpp_ror1(x0), rdN = m < 3 ? dpp_rol1(acc[ai][0][m < 3 ? m + 1 : 3][n][e]) : 0.f;
;                     float xu = fr == 0 ? ruP[c] : ruC, xd = fr == 15 ? rdN : rdC[c];
;                     xu = first ? 0.f : xu; xd = last ? 0.f : xd;
;                     ruP[c] = ruC; rdC[c] = rdN;
;                     const float x = w0[c] * xu + w1[c] * x0 + w2[c] * xd + bb[c];
;                     const float u2 = -2.302208198f * (x + 0.044715f * x * x * x);
;                     res[c] = x * __builtin_amdgcn_rcpf(1.0f + __builtin_amdgcn_exp2f(u2)) * acc[ai][1][m][n][e];
;                 }
;                 if (rl >= 1 && rl <= 62 && gr < nrows) { v4u o; o.x = pk2(res[0], res[1]); o.y = pk2(res[2], res[3]); o.z = pk2(res[4], res[5]); o.w = pk2(res[6], res[7]);
;                     *(v4u*)(G + (size_t)gr * DFF + ch0) = o; }
	v_fma_f32 v32, v40, v32, v40
	v_mul_f32_e32 v32, 0xc0135761, v32
	v_exp_f32_e32 v32, v32
	v_mul_f32_e32 v33, v46, v103
	v_mul_f32_e32 v41, v38, v102
	v_mul_f32_e32 v44, v39, v33
	v_add_f32_e32 v32, 1.0, v32
	v_rcp_f32_e32 v46, v32
	v_cndmask_b32_e64 v32, v50, v98, s[38:39]
	v_cndmask_b32_e64 v33, v32, 0, vcc
	v_mov_b32_e32 v38, v45
	v_mov_b32_e32 v39, v77
	v_mov_b32_e32 v32, v93
	v_pk_mul_f32 v[32:33], v[38:39], v[32:33]
	v_mov_b32_e32 v38, v43
	v_add_f32_e32 v32, v32, v33
	v_cndmask_b32_e64 v33, v96, v48, s[40:41]
	v_cndmask_b32_e64 v33, v33, 0, s[48:49]
	v_fmac_f32_e32 v32, v81, v33
	v_add_f32_e32 v45, v85, v32
	v_mul_f32_e32 v32, 0x3d372713, v45
	v_mul_f32_e32 v32, v45, v32
	v_fma_f32 v32, v45, v32, v45
	v_mul_f32_e32 v32, 0xc0135761, v32
	v_exp_f32_e32 v96, v32
	v_cndmask_b32_e64 v32, v51, v99, s[38:39]
	v_cndmask_b32_e64 v33, v32, 0, vcc
	v_mov_b32_e32 v39, v59
	v_mov_b32_e32 v32, v71
	v_pk_mul_f32 v[32:33], v[38:39], v[32:33]
	v_add_f32_e32 v39, 1.0, v96
	v_add_f32_e32 v32, v32, v33
	v_cndmask_b32_e64 v33, v97, v49, s[40:41]
	v_cndmask_b32_e64 v33, v33, 0, s[48:49]
	v_fmac_f32_e32 v32, v63, v33
	v_add_f32_e32 v32, v67, v32
	v_mul_f32_e32 v33, 0x3d372713, v32
	v_mul_f32_e32 v33, v32, v33
	v_fma_f32 v33, v32, v33, v32
	v_mul_f32_e32 v33, 0xc0135761, v33
	v_exp_f32_e32 v33, v33
	v_rcp_f32_e32 v39, v39
	v_mul_f32_e32 v38, v40, v46
	v_mul_f32_e32 v36, v36, v38
	v_add_f32_e32 v33, 1.0, v33
	v_rcp_f32_e32 v33, v33
	v_mul_f32_e32 v38, v45, v39
	v_mul_f32_e32 v37, v37, v38
	v_cvt_pk_bf16_f32 v34, v34, v47
	v_mul_f32_e32 v32, v32, v33
	v_mul_f32_e32 v35, v35, v32
	v_cvt_pk_bf16_f32 v32, v36, v37
	v_mov_b64_e32 v[36:37], s[6:7]
	v_mad_i64_i32 v[36:37], s[48:49], v111, s1, v[36:37]
	v_cvt_pk_bf16_f32 v33, v41, v44
	v_cvt_pk_bf16_f32 v35, v42, v35
	v_lshl_add_u64 v[36:37], v[170:171], 1, v[36:37]
	global_store_dwordx4 v[36:37], v[32:35], off
.LBB0_1096:
	s_or_b64 exec, exec, s[80:81]
	v_add_u32_e32 v96, s65, v175
	v_mov_b32_e32 v46, v209
	v_mov_b32_e32 v44, v209
	v_mov_b32_e32 v47, v209
	v_mov_b32_e32 v45, v209
	v_mov_b32_e32 v42, v209
	v_mov_b32_e32 v40, v209
	v_mov_b32_e32 v43, v209
	v_mov_b32_e32 v41, v209
	v_mov_b32_e32 v38, v209
	v_mov_b32_e32 v36, v209
	v_mov_b32_e32 v39, v209
	v_mov_b32_e32 v37, v209
	v_mov_b32_e32 v34, v209
	v_mov_b32_e32 v32, v209
	v_mov_b32_e32 v35, v209
	v_mov_b32_e32 v33, v209
	v_mov_b32_dpp v46, v28 row_ror:1 row_mask:0xf bank_mask:0xf
	v_mov_b32_dpp v44, v12 row_ror:15 row_mask:0xf bank_mask:0xf
	v_mov_b32_dpp v47, v29 row_ror:1 row_mask:0xf bank_mask:0xf
	v_mov_b32_dpp v45, v13 row_ror:15 row_mask:0xf bank_mask:0xf
	v_mov_b32_dpp v42, v30 row_ror:1 row_mask:0xf bank_mask:0xf
	v_mov_b32_dpp v40, v14 row_ror:15 row_mask:0xf bank_mask:0xf
	v_mov_b32_dpp v43, v31 row_ror:1 row_mask:0xf bank_mask:0xf
	v_mov_b32_dpp v41, v15 row_ror:15 row_mask:0xf bank_mask:0xf
	v_mov_b32_dpp v38, v24 row_ror:1 row_mask:0xf bank_mask:0xf
	v_mov_b32_dpp v36, v8 row_ror:15 row_mask:0xf bank_mask:0xf
	v_mov_b32_dpp v39, v25 row_ror:1 row_mask:0xf bank_mask:0xf
	v_mov_b32_dpp v37, v9 row_ror:15 row_mask:0xf bank_mask:0xf
	v_mov_b32_dpp v34, v26 row_ror:1 row_mask:0xf bank_mask:0xf
	v_mov_b32_dpp v32, v10 row_ror:15 row_mask:0xf bank_mask:0xf
	v_mov_b32_dpp v35, v27 row_ror:1 row_mask:0xf bank_mask:0xf
	v_mov_b32_dpp v33, v11 row_ror:15 row_mask:0xf bank_mask:0xf
	v_cmp_gt_i32_e32 vcc, s86, v96
	s_and_saveexec_b64 s[80:81], vcc
	s_cbranch_execz .LBB0_1098
	v_and_b32_e32 v97, 0x1fff, v96
	v_and_b32_e32 v102, 0xff, v96
	v_cmp_gt_i32_e64 s[48:49], s97, v96
	v_cndmask_b32_e64 v91, v34, v91, s[38:39]
	v_cmp_eq_u32_e64 s[52:53], s78, v97
	v_cndmask_b32_e64 v98, v102, v97, s[48:49]
	v_cmp_eq_u32_e32 vcc, 0, v98
	v_mov_b32_e32 v100, v26
	s_waitcnt vmcnt(0)
	v_mov_b32_e32 v101, v58
	v_cndmask_b32_e64 v99, v91, 0, vcc
	v_cndmask_b32_e64 v91, 0, 1, s[52:53]
	v_cmp_eq_u32_e64 s[52:53], s12, v102
	v_mov_b32_e32 v98, v70
	v_pk_mul_f32 v[98:99], v[100:101], v[98:99]
	v_cndmask_b32_e64 v97, 0, 1, s[52:53]
	v_cndmask_b32_e64 v91, v97, v91, s[48:49]
	v_and_b32_e32 v91, 1, v91
	v_cndmask_b32_e64 v90, v90, v32, s[40:41]
	v_cmp_eq_u32_e64 s[48:49], 1, v91
	v_add_f32_e32 v26, v98, v99
	v_cndmask_b32_e64 v89, v38, v89, s[38:39]
	v_cndmask_b32_e64 v90, v90, 0, s[48:49]
	v_fmac_f32_e32 v26, v62, v90
	v_add_f32_e32 v26, v66, v26
	v_mul_f32_e32 v90, 0x3d372713, v26
	v_mul_f32_e32 v90, v26, v90
	v_fma_f32 v90, v26, v90, v26
	v_mul_f32_e32 v90, 0xc0135761, v90
	v_exp_f32_e32 v97, v90
	v_cndmask_b32_e64 v91, v89, 0, vcc
	v_mov_b32_e32 v98, v24
	v_mov_b32_e32 v99, v56
	v_mov_b32_e32 v90, v68
	v_pk_mul_f32 v[90:91], v[98:99], v[90:91]
	v_cndmask_b32_e64 v88, v88, v36, s[40:41]
	v_add_f32_e32 v24, v90, v91
	v_cndmask_b32_e64 v88, v88, 0, s[48:49]
	v_fmac_f32_e32 v24, v60, v88
	v_add_f32_e32 v24, v64, v24
	v_mul_f32_e32 v88, 0x3d372713, v24
	v_mul_f32_e32 v88, v24, v88
	v_fma_f32 v88, v24, v88, v24
	v_mul_f32_e32 v88, 0xc0135761, v88
	v_exp_f32_e32 v88, v88
	v_add_f32_e32 v89, 1.0, v97
	v_rcp_f32_e32 v89, v89
	v_add_f32_e32 v88, 1.0, v88
	v_rcp_f32_e32 v88, v88
	v_mul_f32_e32 v26, v26, v89
	v_mul_f32_e32 v26, v18, v26
	v_mul_f32_e32 v18, v24, v88
	v_cndmask_b32_e64 v24, v39, v75, s[38:39]
	v_cndmask_b32_e64 v89, v24, 0, vcc
	v_mov_b32_e32 v24, v25
	v_mov_b32_e32 v25, v57
	v_mov_b32_e32 v88, v69
	v_pk_mul_f32 v[24:25], v[24:25], v[88:89]
	v_mov_b32_e32 v75, v78
	v_add_f32_e32 v24, v24, v25
	v_cndmask_b32_e64 v25, v74, v37, s[40:41]
	v_cndmask_b32_e64 v25, v25, 0, s[48:49]
	v_fmac_f32_e32 v24, v61, v25
	v_add_f32_e32 v88, v65, v24
	v_mul_f32_e32 v24, 0x3d372713, v88
	v_mul_f32_e32 v24, v88, v24
	v_fma_f32 v24, v88, v24, v88
	v_mul_f32_e32 v24, 0xc0135761, v24
; __device__ __forceinline__ unsigned pk2(float lo, float hi) { const f32x2_cv v = {lo, hi}; const bf16x2_cv b = __builtin_convertvector(v, bf16x2_cv); return __builtin_bit_cast(unsigned, b); }
;     __device__ __forceinline__ void operator()(const pg8::f32x4 (&acc)[2][2][4][2], const pg8::Unit& u, int wr, int wc, int fr, int fq) const {
;     ...
;                     float xu = fr == 0 ? ruP[c] : ruC, xd = fr == 15 ? rdN : rdC[c];
;                     xu = first ? 0.f : xu; xd = last ? 0.f : xd;
;                     ruP[c] = ruC; rdC[c] = rdN;
;                     const float x = w0[c] * xu + w1[c] * x0 + w2[c] * xd + bb[c];
;                     const float u2 = -2.302208198f * (x + 0.044715f * x * x * x);
;                     res[c] = x * __builtin_amdgcn_rcpf(1.0f + __builtin_amdgcn_exp2f(u2)) * acc[ai][1][m][n][e];
;                 }
;                 if (rl >= 1 && rl <= 62 && gr < nrows) { v4u o; o.x = pk2(res[0], res[1]); o.y = pk2(res[2], res[3]); o.z = pk2(res[4], res[5]); o.w = pk2(res[6], res[7]);
;                     *(v4u*)(G + (size_t)gr * DFF + ch0) = o; }
	v_exp_f32_e32 v89, v24
	v_cndmask_b32_e64 v24, v42, v73, s[38:39]
	v_cndmask_b32_e64 v25, v24, 0, vcc
	v_mov_b32_e32 v74, v30
	v_mov_b32_e32 v24, v94
	v_pk_mul_f32 v[24:25], v[74:75], v[24:25]
	v_mov_b32_e32 v30, v31
	v_add_f32_e32 v24, v24, v25
	v_cndmask_b32_e64 v25, v72, v40, s[40:41]
	v_cndmask_b32_e64 v25, v25, 0, s[48:49]
	v_fmac_f32_e32 v24, v82, v25
	v_add_f32_e32 v72, v86, v24
	v_mul_f32_e32 v24, 0x3d372713, v72
	v_mul_f32_e32 v24, v72, v24
	v_fma_f32 v24, v72, v24, v72
	v_mul_f32_e32 v24, 0xc0135761, v24
	v_exp_f32_e32 v24, v24
	v_mov_b32_e32 v31, v79
	v_mul_f32_e32 v18, v16, v18
	v_add_f32_e32 v16, 1.0, v89
	v_add_f32_e32 v24, 1.0, v24
	v_rcp_f32_e32 v73, v24
	v_cndmask_b32_e64 v24, v43, v55, s[38:39]
	v_cndmask_b32_e64 v25, v24, 0, vcc
	v_mov_b32_e32 v24, v95
	v_pk_mul_f32 v[24:25], v[30:31], v[24:25]
	v_rcp_f32_e32 v16, v16
	v_add_f32_e32 v24, v24, v25
	v_cndmask_b32_e64 v25, v54, v41, s[40:41]
	v_cndmask_b32_e64 v25, v25, 0, s[48:49]
	v_fmac_f32_e32 v24, v83, v25
	v_add_f32_e32 v30, v87, v24
	v_mul_f32_e32 v24, 0x3d372713, v30
	v_mul_f32_e32 v24, v30, v24
	v_fma_f32 v24, v30, v24, v30
	v_mul_f32_e32 v24, 0xc0135761, v24
	v_exp_f32_e32 v24, v24
	v_mul_f32_e32 v16, v88, v16
	v_mul_f32_e32 v31, v17, v16
	v_mov_b32_e32 v25, v76
	v_add_f32_e32 v16, 1.0, v24
	v_rcp_f32_e32 v55, v16
	v_cndmask_b32_e64 v16, v46, v53, s[38:39]
	v_cndmask_b32_e64 v17, v16, 0, vcc
	v_mov_b32_e32 v24, v28
	v_mov_b32_e32 v16, v92
	v_pk_mul_f32 v[16:17], v[24:25], v[16:17]
	v_mul_f32_e32 v54, v72, v73
	v_add_f32_e32 v16, v16, v17
	v_cndmask_b32_e64 v17, v52, v44, s[40:41]
	v_cndmask_b32_e64 v17, v17, 0, s[48:49]
	v_fmac_f32_e32 v16, v80, v17
	v_add_f32_e32 v24, v84, v16
	v_mul_f32_e32 v16, 0x3d372713, v24
	v_mul_f32_e32 v16, v24, v16
	v_fma_f32 v16, v24, v16, v24
	v_mul_f32_e32 v16, 0xc0135761, v16
	v_exp_f32_e32 v16, v16
	v_mul_f32_e32 v17, v30, v55
	v_mul_f32_e32 v25, v22, v54
	v_mul_f32_e32 v28, v23, v17
	v_add_f32_e32 v16, 1.0, v16
	v_rcp_f32_e32 v30, v16
	v_cndmask_b32_e64 v16, v47, v50, s[38:39]
	v_cndmask_b32_e64 v17, v16, 0, vcc
	v_mov_b32_e32 v22, v29
	v_mov_b32_e32 v23, v77
	v_mov_b32_e32 v16, v93
	v_pk_mul_f32 v[16:17], v[22:23], v[16:17]
	v_mov_b32_e32 v22, v27
	v_add_f32_e32 v16, v16, v17
	v_cndmask_b32_e64 v17, v48, v45, s[40:41]
	v_cndmask_b32_e64 v17, v17, 0, s[48:49]
	v_fmac_f32_e32 v16, v81, v17
	v_add_f32_e32 v29, v85, v16
	v_mul_f32_e32 v16, 0x3d372713, v29
	v_mul_f32_e32 v16, v29, v16
	v_fma_f32 v16, v29, v16, v29
	v_mul_f32_e32 v16, 0xc0135761, v16
	v_exp_f32_e32 v48, v16
	v_cndmask_b32_e64 v16, v35, v51, s[38:39]
	v_cndmask_b32_e64 v17, v16, 0, vcc
	v_mov_b32_e32 v23, v59
	v_mov_b32_e32 v16, v71
	v_pk_mul_f32 v[16:17], v[22:23], v[16:17]
	v_add_f32_e32 v23, 1.0, v48
	v_add_f32_e32 v16, v16, v17
	v_cndmask_b32_e64 v17, v49, v33, s[40:41]
	v_cndmask_b32_e64 v17, v17, 0, s[48:49]
	v_fmac_f32_e32 v16, v63, v17
	v_add_f32_e32 v16, v67, v16
	v_mul_f32_e32 v17, 0x3d372713, v16
	v_mul_f32_e32 v17, v16, v17
	v_fma_f32 v17, v16, v17, v16
	v_mul_f32_e32 v17, 0xc0135761, v17
	v_exp_f32_e32 v17, v17
	v_rcp_f32_e32 v23, v23
	v_mul_f32_e32 v22, v24, v30
	v_mul_f32_e32 v20, v20, v22
	v_add_f32_e32 v17, 1.0, v17
	v_rcp_f32_e32 v17, v17
	v_mul_f32_e32 v22, v29, v23
	v_mul_f32_e32 v21, v21, v22
	v_cvt_pk_bf16_f32 v18, v18, v31
	v_mul_f32_e32 v16, v16, v17
	v_mul_f32_e32 v19, v19, v16
	v_cvt_pk_bf16_f32 v16, v20, v21
	v_mov_b64_e32 v[20:21], s[6:7]
	v_mad_i64_i32 v[20:21], s[48:49], v96, s1, v[20:21]
	v_cvt_pk_bf16_f32 v17, v25, v28
	v_cvt_pk_bf16_f32 v19, v26, v19
	v_lshl_add_u64 v[20:21], v[170:171], 1, v[20:21]
	global_store_dwordx4 v[20:21], v[16:19], off
; __device__ __forceinline__ unsigned pk2(float lo, float hi) { const f32x2_cv v = {lo, hi}; const bf16x2_cv b = __builtin_convertvector(v, bf16x2_cv); return __builtin_bit_cast(unsigned, b); }
; __device__ __forceinline__ float dpp_ror1(float v) { return __builtin_bit_cast(float, __builtin_amdgcn_update_dpp(0, __builtin_bit_cast(int, v), 0x121, 0xF, 0xF, false)); }
; __device__ __forceinline__ float dpp_rol1(float v) { return __builtin_bit_cast(float, __builtin_amdgcn_update_dpp(0, __builtin_bit_cast(int, v), 0x12F, 0xF, 0xF, false)); }
;     __device__ __forceinline__ void operator()(const pg8::f32x4 (&acc)[2][2][4][2], const pg8::Unit& u, int wr, int wc, int fr, int fq) const {
;     ...
;                     const float ruC = dpp_ror1(x0), rdN = m < 3 ? dpp_rol1(acc[ai][0][m < 3 ? m + 1 : 3][n][e]) : 0.f;
;                     float xu = fr == 0 ? ruP[c] : ruC, xd = fr == 15 ? rdN : rdC[c];
;                     xu = first ? 0.f : xu; xd = last ? 0.f : xd;
;                     ruP[c] = ruC; rdC[c] = rdN;
;                     const float x = w0[c] * xu + w1[c] * x0 + w2[c] * xd + bb[c];
;                     const float u2 = -2.302208198f * (x + 0.044715f * x * x * x);
;                     res[c] = x * __builtin_amdgcn_rcpf(1.0f + __builtin_amdgcn_exp2f(u2)) * acc[ai][1][m][n][e];
;                 }
;                 if (rl >= 1 && rl <= 62 && gr < nrows) { v4u o; o.x = pk2(res[0], res[1]); o.y = pk2(res[2], res[3]); o.z = pk2(res[4], res[5]); o.w = pk2(res[6], res[7]);
;                     *(v4u*)(G + (size_t)gr * DFF + ch0) = o; }
.LBB0_1098:
	s_or_b64 exec, exec, s[80:81]
	s_nop 0
	v_add_u32_e32 v16, s65, v176
	v_mov_b32_e32 v23, v209
	v_mov_b32_e32 v24, v209
	v_mov_b32_e32 v21, v209
	v_mov_b32_e32 v22, v209
	v_mov_b32_e32 v19, v209
	v_mov_b32_e32 v20, v209
	v_mov_b32_e32 v17, v209
	v_mov_b32_e32 v18, v209
	v_cmp_gt_i32_e32 vcc, s86, v16
	v_mov_b32_dpp v23, v12 row_ror:1 row_mask:0xf bank_mask:0xf
	v_mov_b32_dpp v24, v13 row_ror:1 row_mask:0xf bank_mask:0xf
	v_mov_b32_dpp v21, v14 row_ror:1 row_mask:0xf bank_mask:0xf
	v_mov_b32_dpp v22, v15 row_ror:1 row_mask:0xf bank_mask:0xf
	v_mov_b32_dpp v19, v8 row_ror:1 row_mask:0xf bank_mask:0xf
	v_mov_b32_dpp v20, v9 row_ror:1 row_mask:0xf bank_mask:0xf
	v_mov_b32_dpp v17, v10 row_ror:1 row_mask:0xf bank_mask:0xf
	v_mov_b32_dpp v18, v11 row_ror:1 row_mask:0xf bank_mask:0xf
	s_and_b64 s[48:49], s[44:45], vcc
	s_and_saveexec_b64 s[52:53], s[48:49]
	s_cbranch_execz .LBB0_1100
	v_and_b32_e32 v25, 0x1fff, v16
	v_and_b32_e32 v26, 0xff, v16
	v_cmp_gt_i32_e32 vcc, s97, v16
	v_cmp_eq_u32_e64 s[48:49], s78, v25
	v_cndmask_b32_e64 v23, v23, v46, s[38:39]
	v_cndmask_b32_e32 v27, v26, v25, vcc
	v_cndmask_b32_e64 v25, 0, 1, s[48:49]
	v_cmp_eq_u32_e64 s[48:49], s12, v26
	v_cndmask_b32_e64 v24, v24, v47, s[38:39]
	s_waitcnt vmcnt(0)
	v_pk_mul_f32 v[12:13], v[12:13], v[92:93]
	v_cndmask_b32_e64 v26, 0, 1, s[48:49]
	v_cndmask_b32_e32 v25, v26, v25, vcc
	v_and_b32_e32 v26, 1, v25
	v_cmp_eq_u32_e64 s[48:49], 0, v27
	v_cmp_eq_u32_e32 vcc, 1, v26
	v_cndmask_b32_e64 v21, v21, v42, s[38:39]
	v_cndmask_b32_e64 v25, v24, 0, s[48:49]
	v_cndmask_b32_e64 v24, v23, 0, s[48:49]
	v_pk_fma_f32 v[12:13], v[76:77], v[24:25], v[12:13]
	v_cndmask_b32_e64 v25, v45, 0, vcc
	v_cndmask_b32_e64 v24, v44, 0, vcc
	v_pk_fma_f32 v[12:13], v[80:81], v[24:25], v[12:13]
	v_cndmask_b32_e64 v22, v22, v43, s[38:39]
	v_pk_add_f32 v[12:13], v[84:85], v[12:13]
	v_pk_mul_f32 v[14:15], v[14:15], v[94:95]
	v_mul_f32_e32 v23, 0x3d372713, v12
	v_mul_f32_e32 v23, v12, v23
	v_fma_f32 v23, v12, v23, v12
	v_mul_f32_e32 v23, 0xc0135761, v23
	v_exp_f32_e32 v23, v23
	v_mul_f32_e32 v24, 0x3d372713, v13
	v_mul_f32_e32 v24, v13, v24
	v_fma_f32 v24, v13, v24, v13
	v_mul_f32_e32 v24, 0xc0135761, v24
	v_add_f32_e32 v23, 1.0, v23
	v_exp_f32_e32 v25, v24
	v_rcp_f32_e32 v24, v23
	v_cndmask_b32_e64 v23, v22, 0, s[48:49]
	v_cndmask_b32_e64 v22, v21, 0, s[48:49]
	v_pk_fma_f32 v[14:15], v[78:79], v[22:23], v[14:15]
	v_cndmask_b32_e64 v23, v41, 0, vcc
	v_cndmask_b32_e64 v22, v40, 0, vcc
	v_pk_fma_f32 v[14:15], v[82:83], v[22:23], v[14:15]
	v_add_f32_e32 v25, 1.0, v25
	v_pk_add_f32 v[14:15], v[86:87], v[14:15]
	v_rcp_f32_e32 v25, v25
	v_mul_f32_e32 v21, 0x3d372713, v14
	v_mul_f32_e32 v21, v14, v21
	v_mul_f32_e32 v22, 0x3d372713, v15
	v_fma_f32 v21, v14, v21, v14
	v_mul_f32_e32 v22, v15, v22
	v_mul_f32_e32 v21, 0xc0135761, v21
	v_fma_f32 v22, v15, v22, v15
	v_exp_f32_e32 v21, v21
	v_mul_f32_e32 v22, 0xc0135761, v22
	v_exp_f32_e32 v23, v22
	v_pk_mul_f32 v[12:13], v[12:13], v[24:25]
	v_add_f32_e32 v21, 1.0, v21
	v_rcp_f32_e32 v22, v21
	v_add_f32_e32 v21, 1.0, v23
	v_rcp_f32_e32 v23, v21
	v_pk_mul_f32 v[4:5], v[4:5], v[12:13]
	v_cndmask_b32_e64 v17, v17, v34, s[38:39]
	v_cndmask_b32_e64 v18, v18, v35, s[38:39]
	v_pk_mul_f32 v[12:13], v[14:15], v[22:23]
	v_cndmask_b32_e64 v14, v19, v38, s[38:39]
	v_cndmask_b32_e64 v15, v20, v39, s[38:39]
	v_pk_mul_f32 v[8:9], v[8:9], v[68:69]
	v_cndmask_b32_e64 v15, v15, 0, s[48:49]
	v_cndmask_b32_e64 v14, v14, 0, s[48:49]
	v_pk_mul_f32 v[10:11], v[10:11], v[70:71]
	v_cndmask_b32_e64 v19, v18, 0, s[48:49]
	v_cndmask_b32_e64 v18, v17, 0, s[48:49]
	v_pk_fma_f32 v[8:9], v[56:57], v[14:15], v[8:9]
	v_cndmask_b32_e64 v15, v37, 0, vcc
	v_cndmask_b32_e64 v14, v36, 0, vcc
	v_pk_fma_f32 v[10:11], v[58:59], v[18:19], v[10:11]
	v_cndmask_b32_e64 v19, v33, 0, vcc
	v_cndmask_b32_e64 v18, v32, 0, vcc
	v_pk_fma_f32 v[8:9], v[60:61], v[14:15], v[8:9]
	v_pk_fma_f32 v[10:11], v[62:63], v[18:19], v[10:11]
	v_pk_add_f32 v[8:9], v[64:65], v[8:9]
	v_pk_add_f32 v[10:11], v[66:67], v[10:11]
	v_mul_f32_e32 v14, 0x3d372713, v8
	v_mul_f32_e32 v15, 0x3d372713, v9
	v_mul_f32_e32 v17, 0x3d372713, v10
	v_mul_f32_e32 v14, v8, v14
	v_mul_f32_e32 v15, v9, v15
	v_mul_f32_e32 v17, v10, v17
	v_mul_f32_e32 v18, 0x3d372713, v11
	v_fma_f32 v14, v8, v14, v8
	v_fma_f32 v15, v9, v15, v9
	v_fma_f32 v17, v10, v17, v10
	v_mul_f32_e32 v18, v11, v18
	v_mul_f32_e32 v14, 0xc0135761, v14
	v_mul_f32_e32 v15, 0xc0135761, v15
	v_mul_f32_e32 v17, 0xc0135761, v17
	v_fma_f32 v18, v11, v18, v11
	v_exp_f32_e32 v14, v14
	v_exp_f32_e32 v15, v15
	v_exp_f32_e32 v17, v17
	v_mul_f32_e32 v18, 0xc0135761, v18
	v_exp_f32_e32 v19, v18
	v_add_f32_e32 v14, 1.0, v14
	v_add_f32_e32 v15, 1.0, v15
	v_add_f32_e32 v17, 1.0, v17
	v_rcp_f32_e32 v14, v14
	v_rcp_f32_e32 v15, v15
	v_rcp_f32_e32 v18, v17
	v_add_f32_e32 v17, 1.0, v19
	v_rcp_f32_e32 v19, v17
	v_pk_mul_f32 v[8:9], v[8:9], v[14:15]
	v_pk_mul_f32 v[6:7], v[6:7], v[12:13]
	v_pk_mul_f32 v[8:9], v[0:1], v[8:9]
	v_pk_mul_f32 v[0:1], v[10:11], v[18:19]
	s_nop 0
	v_pk_mul_f32 v[10:11], v[2:3], v[0:1]
	v_cvt_pk_bf16_f32 v0, v4, v5
	v_mov_b64_e32 v[4:5], s[6:7]
	v_mad_i64_i32 v[4:5], s[48:49], v16, s1, v[4:5]
	v_cvt_pk_bf16_f32 v1, v6, v7
	v_cvt_pk_bf16_f32 v2, v8, v9
	v_cvt_pk_bf16_f32 v3, v10, v11
	v_lshl_add_u64 v[4:5], v[170:171], 1, v[4:5]
	global_store_dwordx4 v[4:5], v[0:3], off

;     ...
; #pragma unroll 8
;     for (int i = 0; i < 32; ++i) { const int kk = 2 * i + (lane >> 5); scr[kk * 33 + (lane & 31)] = W[(size_t)(k0 + kk) * N + n0 + (lane & 31)]; }
.LBB0_1186:
	s_lshl_b32 s37, s34, 1
	s_lshl_b32 s36, s23, 1
	v_or_b32_e32 v11, s37, v2
	v_or_b32_e32 v3, s36, v1
	v_add_u32_e32 v14, s13, v11
	v_add_u32_e32 v12, s15, v3
	v_mad_u64_u32 v[14:15], s[38:39], v14, s1, v[10:11]
	v_mad_u64_u32 v[12:13], s[38:39], v12, s1, v[10:11]
	v_mov_b32_e32 v15, v209
	v_lshl_add_u64 v[14:15], v[14:15], 2, s[6:7]
	v_mov_b32_e32 v13, v209
	v_lshl_add_u64 v[12:13], v[12:13], 2, s[6:7]
	global_load_dword v19, v[14:15], off
	global_load_dword v20, v[12:13], off
	v_mad_u64_u32 v[12:13], s[38:39], v11, s33, v[6:7]
	v_mad_u64_u32 v[14:15], s[38:39], v3, s33, v[6:7]
	s_add_i32 s39, s37, 4
	s_add_i32 s38, s36, 4
	v_or_b32_e32 v11, s39, v2
	v_or_b32_e32 v3, s38, v1
	s_add_i32 s34, s34, 16
	s_add_i32 s23, s23, 16
	s_add_i32 s35, s35, -16
	s_waitcnt vmcnt(0)
	ds_write_b32 v12, v19
	ds_write_b32 v14, v20
	v_add_u32_e32 v14, s13, v11
	v_add_u32_e32 v12, s15, v3
	v_mad_u64_u32 v[14:15], s[38:39], v14, s1, v[10:11]
	v_mad_u64_u32 v[12:13], s[38:39], v12, s1, v[10:11]
	v_mov_b32_e32 v15, v209
	v_lshl_add_u64 v[14:15], v[14:15], 2, s[6:7]
	v_mov_b32_e32 v13, v209
	v_lshl_add_u64 v[12:13], v[12:13], 2, s[6:7]
	global_load_dword v19, v[14:15], off
	global_load_dword v20, v[12:13], off
	v_mad_u64_u32 v[12:13], s[38:39], v11, s33, v[6:7]
	v_mad_u64_u32 v[14:15], s[38:39], v3, s33, v[6:7]
	s_add_i32 s39, s37, 8
	s_add_i32 s38, s36, 8
	v_or_b32_e32 v11, s39, v2
	v_or_b32_e32 v3, s38, v1
	s_waitcnt vmcnt(1)
	ds_write_b32 v12, v19
	s_waitcnt vmcnt(0)
	ds_write_b32 v14, v20
	v_add_u32_e32 v14, s13, v11
	v_add_u32_e32 v12, s15, v3
	v_mad_u64_u32 v[14:15], s[38:39], v14, s1, v[10:11]
	v_mad_u64_u32 v[12:13], s[38:39], v12, s1, v[10:11]
	v_mov_b32_e32 v15, v209
	v_lshl_add_u64 v[14:15], v[14:15], 2, s[6:7]
	v_mov_b32_e32 v13, v209
	v_lshl_add_u64 v[12:13], v[12:13], 2, s[6:7]
	global_load_dword v19, v[14:15], off
	global_load_dword v20, v[12:13], off
	v_mad_u64_u32 v[12:13], s[38:39], v11, s33, v[6:7]
	v_mad_u64_u32 v[14:15], s[38:39], v3, s33, v[6:7]
	s_add_i32 s39, s37, 12
	s_add_i32 s38, s36, 12
	v_or_b32_e32 v11, s39, v2
	v_or_b32_e32 v3, s38, v1
	s_waitcnt vmcnt(1)
	ds_write_b32 v12, v19
	s_waitcnt vmcnt(0)
	ds_write_b32 v14, v20
	v_add_u32_e32 v14, s13, v11
	v_add_u32_e32 v12, s15, v3
	v_mad_u64_u32 v[14:15], s[38:39], v14, s1, v[10:11]
	v_mad_u64_u32 v[12:13], s[38:39], v12, s1, v[10:11]
	v_mov_b32_e32 v15, v209
	v_lshl_add_u64 v[14:15], v[14:15], 2, s[6:7]
	v_mov_b32_e32 v13, v209
	v_lshl_add_u64 v[12:13], v[12:13], 2, s[6:7]
	global_load_dword v19, v[14:15], off
	global_load_dword v20, v[12:13], off
	v_mad_u64_u32 v[12:13], s[38:39], v11, s33, v[6:7]
	v_mad_u64_u32 v[14:15], s[38:39], v3, s33, v[6:7]
	s_add_i32 s39, s37, 16
	s_add_i32 s38, s36, 16
	v_or_b32_e32 v11, s39, v2
	v_or_b32_e32 v3, s38, v1
	s_waitcnt vmcnt(1)
	ds_write_b32 v12, v19
	s_waitcnt vmcnt(0)
	ds_write_b32 v14, v20
	v_add_u32_e32 v14, s13, v11
	v_add_u32_e32 v12, s15, v3
	v_mad_u64_u32 v[14:15], s[38:39], v14, s1, v[10:11]
	v_mad_u64_u32 v[12:13], s[38:39], v12, s1, v[10:11]
	v_mov_b32_e32 v15, v209
	v_lshl_add_u64 v[14:15], v[14:15], 2, s[6:7]
	v_mov_b32_e32 v13, v209
	v_lshl_add_u64 v[12:13], v[12:13], 2, s[6:7]
	global_load_dword v19, v[14:15], off
	global_load_dword v20, v[12:13], off
	v_mad_u64_u32 v[12:13], s[38:39], v11, s33, v[6:7]
	v_mad_u64_u32 v[14:15], s[38:39], v3, s33, v[6:7]
	s_add_i32 s39, s37, 20
	s_add_i32 s38, s36, 20
	v_or_b32_e32 v11, s39, v2
	v_or_b32_e32 v3, s38, v1
	s_waitcnt vmcnt(1)
	ds_write_b32 v12, v19
	s_waitcnt vmcnt(0)
	ds_write_b32 v14, v20
	v_add_u32_e32 v14, s13, v11
	v_add_u32_e32 v12, s15, v3
	v_mad_u64_u32 v[14:15], s[38:39], v14, s1, v[10:11]
	v_mad_u64_u32 v[12:13], s[38:39], v12, s1, v[10:11]
	v_mov_b32_e32 v15, v209
	v_lshl_add_u64 v[14:15], v[14:15], 2, s[6:7]
	v_mov_b32_e32 v13, v209
	v_lshl_add_u64 v[12:13], v[12:13], 2, s[6:7]
	global_load_dword v19, v[14:15], off
	global_load_dword v20, v[12:13], off
	v_mad_u64_u32 v[12:13], s[38:39], v11, s33, v[6:7]
	v_mad_u64_u32 v[14:15], s[38:39], v3, s33, v[6:7]
	s_add_i32 s39, s37, 24
	s_add_i32 s38, s36, 24
	v_or_b32_e32 v11, s39, v2
	v_or_b32_e32 v3, s38, v1
	s_add_i32 s37, s37, 28
	s_add_i32 s36, s36, 28
	s_cmp_lg_u32 s35, 0
	s_waitcnt vmcnt(1)
	ds_write_b32 v12, v19
	s_waitcnt vmcnt(0)
	ds_write_b32 v14, v20
	v_add_u32_e32 v14, s13, v11
	v_add_u32_e32 v12, s15, v3
	v_mad_u64_u32 v[14:15], s[38:39], v14, s1, v[10:11]
	v_mad_u64_u32 v[12:13], s[38:39], v12, s1, v[10:11]
	v_mov_b32_e32 v15, v209
	v_lshl_add_u64 v[14:15], v[14:15], 2, s[6:7]
	v_mov_b32_e32 v13, v209
	v_lshl_add_u64 v[12:13], v[12:13], 2, s[6:7]
	global_load_dword v19, v[14:15], off
	global_load_dword v20, v[12:13], off
	v_mad_u64_u32 v[12:13], s[38:39], v11, s33, v[6:7]
	v_mad_u64_u32 v[14:15], s[38:39], v3, s33, v[6:7]
	v_or_b32_e32 v11, s37, v2
	v_or_b32_e32 v3, s36, v1
	s_waitcnt vmcnt(1)
	ds_write_b32 v12, v19
	s_waitcnt vmcnt(0)
	ds_write_b32 v14, v20
	v_add_u32_e32 v14, s13, v11
	v_add_u32_e32 v12, s15, v3
	v_mad_u64_u32 v[14:15], s[36:37], v14, s1, v[10:11]
	v_mad_u64_u32 v[12:13], s[36:37], v12, s1, v[10:11]
	v_mov_b32_e32 v15, v209
	v_lshl_add_u64 v[14:15], v[14:15], 2, s[6:7]
	v_mov_b32_e32 v13, v209
	v_lshl_add_u64 v[12:13], v[12:13], 2, s[6:7]
	global_load_dword v19, v[14:15], off
	global_load_dword v20, v[12:13], off
	v_mad_u64_u32 v[12:13], s[36:37], v11, s33, v[6:7]
	v_mad_u64_u32 v[14:15], s[36:37], v3, s33, v[6:7]
	s_waitcnt vmcnt(1)
	ds_write_b32 v12, v19
	s_waitcnt vmcnt(0)
	ds_write_b32 v14, v20
	s_cbranch_scc1 .LBB0_1186
; #define LAS __attribute__((address_space(3)))
; __device__ __forceinline__ unsigned pk2(float lo, float hi) { const f32x2_cv v = {lo, hi}; const bf16x2_cv b = __builtin_convertvector(v, bf16x2_cv); return __builtin_bit_cast(unsigned, b); }
;     ...
;     const int c = lane & 7;
; #pragma unroll
;     for (int j = 0; j < 4; ++j) { const int n = (lane >> 3) + 8 * j; const LAS float* s = scr + (8 * c) * 33 + n;
;         v4u o; o.x = pk2(s[0 * 33], s[1 * 33]); o.y = pk2(s[2 * 33], s[3 * 33]); o.z = pk2(s[4 * 33], s[5 * 33]); o.w = pk2(s[6 * 33], s[7 * 33]);
;         int row = n0 + n; if (PERM_UP == 2) { const int nl = row & 255; row = (row & ~255) + 128 * ((nl >> 5) & 1) + 32 * (nl >> 6) + (nl & 31); }
;         if (PERM_UP == 1) { const bool isv = row >= DFF; const int ch = isv ? row - DFF : row; row = (ch >> 7) * 256 + (isv ? 128 : 0) + (ch & 127); }
;         *(v4u*)(WT + (size_t)row * K + k0 + 8 * c) = o; }
;     asm volatile("s_waitcnt lgkmcnt(0)" ::: "memory");
	s_and_b32 s6, 0xffff, s13
	s_lshl_b32 s6, s6, 1
	s_add_u32 s6, s10, s6
	s_addc_u32 s7, s11, 0
	v_lshlrev_b32_e32 v208, 1, v8
	s_waitcnt lgkmcnt(0)
	v_lshl_add_u64 v[10:11], s[6:7], 0, v[208:209]
	s_mov_b64 s[6:7], 0x980000
	v_lshl_add_u64 v[14:15], v[10:11], 0, s[6:7]
	ds_read_b32 v3, v9
	ds_read_b32 v10, v9 offset:132
	s_and_b32 s6, 0xffff, s12
	s_cmpk_gt_u32 s6, 0x57
	s_cselect_b64 vcc, -1, 0
	s_and_b64 s[6:7], vcc, exec
	s_waitcnt lgkmcnt(0)
	v_cvt_pk_bf16_f32 v10, v3, v10
	ds_read_b32 v3, v9 offset:264
	ds_read_b32 v11, v9 offset:396
	s_cselect_b32 s6, 0x80, 0
	s_waitcnt lgkmcnt(0)
	v_cvt_pk_bf16_f32 v11, v3, v11
	ds_read_b32 v3, v9 offset:528
	ds_read_b32 v12, v9 offset:660
	s_waitcnt lgkmcnt(0)
	v_cvt_pk_bf16_f32 v12, v3, v12
	ds_read_b32 v3, v9 offset:792
	ds_read_b32 v13, v9 offset:924
	s_waitcnt lgkmcnt(0)
	v_cvt_pk_bf16_f32 v13, v3, v13
	v_or_b32_e32 v3, s3, v7
	v_add_u32_e32 v19, 0xfffff500, v3
	v_cndmask_b32_e32 v3, v3, v19, vcc
	v_lshlrev_b32_e32 v19, 1, v3
	v_and_b32_e32 v19, 0xffffff00, v19
	v_and_b32_e32 v3, 0x67, v3
	v_or3_b32 v20, v3, v19, s6
	v_ashrrev_i32_e32 v21, 31, v20
	v_lshlrev_b64 v[20:21], 11, v[20:21]
	v_lshl_add_u64 v[20:21], v[14:15], 0, v[20:21]
	global_store_dwordx4 v[20:21], v[10:13], off
	ds_read_b32 v3, v9 offset:32
	ds_read_b32 v10, v9 offset:164
	s_waitcnt lgkmcnt(0)
	v_cvt_pk_bf16_f32 v10, v3, v10
	ds_read_b32 v3, v9 offset:296
	ds_read_b32 v11, v9 offset:428
	s_waitcnt lgkmcnt(0)
	v_cvt_pk_bf16_f32 v11, v3, v11
	ds_read_b32 v3, v9 offset:560
	ds_read_b32 v12, v9 offset:692
	s_waitcnt lgkmcnt(0)
	v_cvt_pk_bf16_f32 v12, v3, v12
	ds_read_b32 v3, v9 offset:824
	ds_read_b32 v13, v9 offset:956
	s_waitcnt lgkmcnt(0)
	v_cvt_pk_bf16_f32 v13, v3, v13
	v_or_b32_e32 v3, s3, v16
	v_add_u32_e32 v19, 0xfffff500, v3
	v_cndmask_b32_e32 v3, v3, v19, vcc
	v_lshlrev_b32_e32 v19, 1, v3
	v_and_b32_e32 v19, 0xffffff00, v19
	v_and_b32_e32 v3, 0x6f, v3
	v_or3_b32 v20, v3, v19, s6
	v_ashrrev_i32_e32 v21, 31, v20
	v_lshlrev_b64 v[20:21], 11, v[20:21]
	v_lshl_add_u64 v[20:21], v[14:15], 0, v[20:21]
	global_store_dwordx4 v[20:21], v[10:13], off
	ds_read_b32 v3, v9 offset:64
	ds_read_b32 v10, v9 offset:196
	s_waitcnt lgkmcnt(0)
	v_cvt_pk_bf16_f32 v10, v3, v10
	ds_read_b32 v3, v9 offset:328
	ds_read_b32 v11, v9 offset:460
	s_waitcnt lgkmcnt(0)
	v_cvt_pk_bf16_f32 v11, v3, v11
	ds_read_b32 v3, v9 offset:592
	ds_read_b32 v12, v9 offset:724
	s_waitcnt lgkmcnt(0)
	v_cvt_pk_bf16_f32 v12, v3, v12
	ds_read_b32 v3, v9 offset:856
	ds_read_b32 v13, v9 offset:988
	s_waitcnt lgkmcnt(0)
	v_cvt_pk_bf16_f32 v13, v3, v13
	v_or_b32_e32 v3, s3, v17
	v_add_u32_e32 v19, 0xfffff500, v3
	v_cndmask_b32_e32 v3, v3, v19, vcc
	v_lshlrev_b32_e32 v19, 1, v3
	v_and_b32_e32 v19, 0xffffff00, v19
	v_and_b32_e32 v3, 0x77, v3
	v_or3_b32 v20, v3, v19, s6
	v_ashrrev_i32_e32 v21, 31, v20
	v_lshlrev_b64 v[20:21], 11, v[20:21]
	v_lshl_add_u64 v[20:21], v[14:15], 0, v[20:21]
	global_store_dwordx4 v[20:21], v[10:13], off
	ds_read_b32 v3, v9 offset:96
	ds_read_b32 v10, v9 offset:228
	s_waitcnt lgkmcnt(0)
	v_cvt_pk_bf16_f32 v10, v3, v10
	ds_read_b32 v3, v9 offset:360
	ds_read_b32 v11, v9 offset:492
	s_waitcnt lgkmcnt(0)
	v_cvt_pk_bf16_f32 v11, v3, v11
	ds_read_b32 v3, v9 offset:624
	ds_read_b32 v12, v9 offset:756
	s_waitcnt lgkmcnt(0)
	v_cvt_pk_bf16_f32 v12, v3, v12
	ds_read_b32 v3, v9 offset:888
	ds_read_b32 v13, v9 offset:1020
	s_waitcnt lgkmcnt(0)
	v_cvt_pk_bf16_f32 v13, v3, v13
	v_or_b32_e32 v3, s3, v18
	v_add_u32_e32 v19, 0xfffff500, v3
	v_cndmask_b32_e32 v3, v3, v19, vcc
	v_lshlrev_b32_e32 v19, 1, v3
	v_and_b32_e32 v19, 0xffffff00, v19
	v_and_b32_e32 v3, 0x7f, v3
	v_or3_b32 v20, v3, v19, s6
	v_ashrrev_i32_e32 v21, 31, v20
	v_lshlrev_b64 v[20:21], 11, v[20:21]
	v_lshl_add_u64 v[14:15], v[14:15], 0, v[20:21]
	global_store_dwordx4 v[14:15], v[10:13], off
	s_waitcnt lgkmcnt(0)
	s_mov_b64 s[6:7], 0

;     ...
; #pragma unroll 8
;     for (int i = 0; i < 32; ++i) { const int kk = 2 * i + (lane >> 5); scr[kk * 33 + (lane & 31)] = W[(size_t)(k0 + kk) * N + n0 + (lane & 31)]; }
.LBB0_1190:
	s_lshl_b32 s36, s23, 1
	s_lshl_b32 s35, s12, 1
	v_or_b32_e32 v19, s36, v2
	v_or_b32_e32 v11, s35, v1
	v_add_lshl_u32 v13, v19, s13, 10
	v_add_lshl_u32 v12, v11, s15, 10
	v_or_b32_e32 v208, v10, v13
	v_or_b32_e32 v12, v3, v12
	v_lshl_add_u64 v[14:15], v[208:209], 2, s[6:7]
	v_mov_b32_e32 v13, v209
	v_lshl_add_u64 v[12:13], v[12:13], 2, s[6:7]
	global_load_dword v20, v[14:15], off
	global_load_dword v21, v[12:13], off
	v_mad_u64_u32 v[12:13], s[38:39], v19, s33, v[6:7]
	v_mad_u64_u32 v[14:15], s[38:39], v11, s33, v[6:7]
	s_add_i32 s38, s36, 4
	s_add_i32 s37, s35, 4
	v_or_b32_e32 v19, s38, v2
	v_or_b32_e32 v11, s37, v1
	v_add_lshl_u32 v13, v19, s13, 10
	v_or_b32_e32 v208, v10, v13
	v_mov_b32_e32 v13, v209
	s_add_i32 s37, s35, 8
	s_add_i32 s23, s23, 16
	s_add_i32 s12, s12, 16
	s_add_i32 s34, s34, -16
	s_waitcnt vmcnt(0)
	ds_write_b32 v12, v20
	ds_write_b32 v14, v21
	v_add_lshl_u32 v12, v11, s15, 10
	v_or_b32_e32 v12, v3, v12
	v_lshl_add_u64 v[14:15], v[208:209], 2, s[6:7]
	v_lshl_add_u64 v[12:13], v[12:13], 2, s[6:7]
	global_load_dword v20, v[14:15], off
	global_load_dword v21, v[12:13], off
	v_mad_u64_u32 v[12:13], s[38:39], v19, s33, v[6:7]
	v_mad_u64_u32 v[14:15], s[38:39], v11, s33, v[6:7]
	s_add_i32 s38, s36, 8
	s_nop 0
	v_or_b32_e32 v19, s38, v2
	v_or_b32_e32 v11, s37, v1
	v_add_lshl_u32 v13, v19, s13, 10
	v_or_b32_e32 v208, v10, v13
	v_mov_b32_e32 v13, v209
	s_add_i32 s37, s35, 12
	s_waitcnt vmcnt(1)
	ds_write_b32 v12, v20
	s_waitcnt vmcnt(0)
	ds_write_b32 v14, v21
	v_add_lshl_u32 v12, v11, s15, 10
	v_or_b32_e32 v12, v3, v12
	v_lshl_add_u64 v[14:15], v[208:209], 2, s[6:7]
	v_lshl_add_u64 v[12:13], v[12:13], 2, s[6:7]
	global_load_dword v20, v[14:15], off
	global_load_dword v21, v[12:13], off
	v_mad_u64_u32 v[12:13], s[38:39], v19, s33, v[6:7]
	v_mad_u64_u32 v[14:15], s[38:39], v11, s33, v[6:7]
	s_add_i32 s38, s36, 12
	s_nop 0
	v_or_b32_e32 v19, s38, v2
	v_or_b32_e32 v11, s37, v1
	v_add_lshl_u32 v13, v19, s13, 10
	v_or_b32_e32 v208, v10, v13
	v_mov_b32_e32 v13, v209
	s_add_i32 s37, s35, 16
	s_waitcnt vmcnt(1)
	ds_write_b32 v12, v20
	s_waitcnt vmcnt(0)
	ds_write_b32 v14, v21
	v_add_lshl_u32 v12, v11, s15, 10
	v_or_b32_e32 v12, v3, v12
	v_lshl_add_u64 v[14:15], v[208:209], 2, s[6:7]
	v_lshl_add_u64 v[12:13], v[12:13], 2, s[6:7]
	global_load_dword v20, v[14:15], off
	global_load_dword v21, v[12:13], off
	v_mad_u64_u32 v[12:13], s[38:39], v19, s33, v[6:7]
	v_mad_u64_u32 v[14:15], s[38:39], v11, s33, v[6:7]
	s_add_i32 s38, s36, 16
	s_nop 0
	v_or_b32_e32 v19, s38, v2
	v_or_b32_e32 v11, s37, v1
	v_add_lshl_u32 v13, v19, s13, 10
	v_or_b32_e32 v208, v10, v13
	v_mov_b32_e32 v13, v209
	s_add_i32 s37, s35, 20
	s_waitcnt vmcnt(1)
	ds_write_b32 v12, v20
	s_waitcnt vmcnt(0)
	ds_write_b32 v14, v21
	v_add_lshl_u32 v12, v11, s15, 10
	v_or_b32_e32 v12, v3, v12
	v_lshl_add_u64 v[14:15], v[208:209], 2, s[6:7]
	v_lshl_add_u64 v[12:13], v[12:13], 2, s[6:7]
	global_load_dword v20, v[14:15], off
	global_load_dword v21, v[12:13], off
	v_mad_u64_u32 v[12:13], s[38:39], v19, s33, v[6:7]
	v_mad_u64_u32 v[14:15], s[38:39], v11, s33, v[6:7]
	s_add_i32 s38, s36, 20
	s_nop 0
	v_or_b32_e32 v19, s38, v2
	v_or_b32_e32 v11, s37, v1
	v_add_lshl_u32 v13, v19, s13, 10
	v_or_b32_e32 v208, v10, v13
	v_mov_b32_e32 v13, v209
	s_add_i32 s37, s35, 24
	s_add_i32 s35, s35, 28
	s_waitcnt vmcnt(1)
	ds_write_b32 v12, v20
	s_waitcnt vmcnt(0)
	ds_write_b32 v14, v21
	v_add_lshl_u32 v12, v11, s15, 10
	v_or_b32_e32 v12, v3, v12
	v_lshl_add_u64 v[14:15], v[208:209], 2, s[6:7]
	v_lshl_add_u64 v[12:13], v[12:13], 2, s[6:7]
	global_load_dword v20, v[14:15], off
	global_load_dword v21, v[12:13], off
	v_mad_u64_u32 v[12:13], s[38:39], v19, s33, v[6:7]
	v_mad_u64_u32 v[14:15], s[38:39], v11, s33, v[6:7]
	s_add_i32 s38, s36, 24
	s_nop 0
	v_or_b32_e32 v19, s38, v2
	v_or_b32_e32 v11, s37, v1
	v_add_lshl_u32 v13, v19, s13, 10
	v_or_b32_e32 v208, v10, v13
	v_mov_b32_e32 v13, v209
	s_add_i32 s36, s36, 28
	s_cmp_lg_u32 s34, 0
	s_waitcnt vmcnt(1)
	ds_write_b32 v12, v20
	s_waitcnt vmcnt(0)
	ds_write_b32 v14, v21
	v_add_lshl_u32 v12, v11, s15, 10
	v_or_b32_e32 v12, v3, v12
	v_lshl_add_u64 v[14:15], v[208:209], 2, s[6:7]
	v_lshl_add_u64 v[12:13], v[12:13], 2, s[6:7]
	global_load_dword v20, v[14:15], off
	global_load_dword v21, v[12:13], off
	v_mad_u64_u32 v[12:13], s[38:39], v19, s33, v[6:7]
	v_or_b32_e32 v19, s36, v2
	v_mad_u64_u32 v[14:15], s[38:39], v11, s33, v[6:7]
	v_or_b32_e32 v11, s35, v1
	v_add_lshl_u32 v13, v19, s13, 10
	v_or_b32_e32 v208, v10, v13
	v_mov_b32_e32 v15, v209
	s_waitcnt vmcnt(1)
	ds_write_b32 v12, v20
	s_waitcnt vmcnt(0)
	ds_write_b32 v14, v21
	v_add_lshl_u32 v12, v11, s15, 10
	v_or_b32_e32 v14, v3, v12
	v_lshl_add_u64 v[12:13], v[208:209], 2, s[6:7]
	v_lshl_add_u64 v[14:15], v[14:15], 2, s[6:7]
	global_load_dword v20, v[12:13], off
	global_load_dword v21, v[14:15], off
	v_mad_u64_u32 v[12:13], s[36:37], v19, s33, v[6:7]
	v_mad_u64_u32 v[14:15], s[36:37], v11, s33, v[6:7]
	s_waitcnt vmcnt(1)
	ds_write_b32 v12, v20
	s_waitcnt vmcnt(0)
	ds_write_b32 v14, v21
	s_cbranch_scc1 .LBB0_1190
; #define LAS __attribute__((address_space(3)))
; __device__ __forceinline__ unsigned pk2(float lo, float hi) { const f32x2_cv v = {lo, hi}; const bf16x2_cv b = __builtin_convertvector(v, bf16x2_cv); return __builtin_bit_cast(unsigned, b); }
;     ...
;     const int c = lane & 7;
; #pragma unroll
;     for (int j = 0; j < 4; ++j) { const int n = (lane >> 3) + 8 * j; const LAS float* s = scr + (8 * c) * 33 + n;
;         v4u o; o.x = pk2(s[0 * 33], s[1 * 33]); o.y = pk2(s[2 * 33], s[3 * 33]); o.z = pk2(s[4 * 33], s[5 * 33]); o.w = pk2(s[6 * 33], s[7 * 33]);
;         int row = n0 + n; if (PERM_UP == 2) { const int nl = row & 255; row = (row & ~255) + 128 * ((nl >> 5) & 1) + 32 * (nl >> 6) + (nl & 31); }
;         if (PERM_UP == 1) { const bool isv = row >= DFF; const int ch = isv ? row - DFF : row; row = (ch >> 7) * 256 + (isv ? 128 : 0) + (ch & 127); }
;         *(v4u*)(WT + (size_t)row * K + k0 + 8 * c) = o; }
;     asm volatile("s_waitcnt lgkmcnt(0)" ::: "memory");
	s_lshl_b32 s6, s13, 1
	s_add_u32 s6, s10, s6
	s_addc_u32 s7, s11, 0
	v_lshlrev_b32_e32 v208, 1, v8
	s_waitcnt lgkmcnt(0)
	v_lshl_add_u64 v[10:11], s[6:7], 0, v[208:209]
	s_mov_b64 s[6:7], 0x780000
	v_lshl_add_u64 v[14:15], v[10:11], 0, s[6:7]
	ds_read_b32 v3, v9
	ds_read_b32 v10, v9 offset:132
	s_waitcnt lgkmcnt(0)
	v_cvt_pk_bf16_f32 v10, v3, v10
	ds_read_b32 v3, v9 offset:264
	ds_read_b32 v11, v9 offset:396
	s_waitcnt lgkmcnt(0)
	v_cvt_pk_bf16_f32 v11, v3, v11
	ds_read_b32 v3, v9 offset:528
	ds_read_b32 v12, v9 offset:660
	s_waitcnt lgkmcnt(0)
	v_cvt_pk_bf16_f32 v12, v3, v12
	ds_read_b32 v3, v9 offset:792
	ds_read_b32 v13, v9 offset:924
	s_waitcnt lgkmcnt(0)
	v_cvt_pk_bf16_f32 v13, v3, v13
	v_or_b32_e32 v3, s3, v7
	v_lshlrev_b32_e32 v208, 11, v3
	v_lshl_add_u64 v[20:21], v[14:15], 0, v[208:209]
	global_store_dwordx4 v[20:21], v[10:13], off
	ds_read_b32 v3, v9 offset:32
	ds_read_b32 v10, v9 offset:164
	s_waitcnt lgkmcnt(0)
	v_cvt_pk_bf16_f32 v10, v3, v10
	ds_read_b32 v3, v9 offset:296
	ds_read_b32 v11, v9 offset:428
	s_waitcnt lgkmcnt(0)
	v_cvt_pk_bf16_f32 v11, v3, v11
	ds_read_b32 v3, v9 offset:560
	ds_read_b32 v12, v9 offset:692
	s_waitcnt lgkmcnt(0)
	v_cvt_pk_bf16_f32 v12, v3, v12
	ds_read_b32 v3, v9 offset:824
	ds_read_b32 v13, v9 offset:956
	s_waitcnt lgkmcnt(0)
	v_cvt_pk_bf16_f32 v13, v3, v13
	v_or_b32_e32 v3, s3, v16
	v_lshlrev_b32_e32 v208, 11, v3
	v_lshl_add_u64 v[20:21], v[14:15], 0, v[208:209]
	global_store_dwordx4 v[20:21], v[10:13], off
	ds_read_b32 v3, v9 offset:64
	ds_read_b32 v10, v9 offset:196
	s_waitcnt lgkmcnt(0)
	v_cvt_pk_bf16_f32 v10, v3, v10
	ds_read_b32 v3, v9 offset:328
	ds_read_b32 v11, v9 offset:460
	s_waitcnt lgkmcnt(0)
	v_cvt_pk_bf16_f32 v11, v3, v11
	ds_read_b32 v3, v9 offset:592
	ds_read_b32 v12, v9 offset:724
	s_waitcnt lgkmcnt(0)
	v_cvt_pk_bf16_f32 v12, v3, v12
	ds_read_b32 v3, v9 offset:856
	ds_read_b32 v13, v9 offset:988
	s_waitcnt lgkmcnt(0)
	v_cvt_pk_bf16_f32 v13, v3, v13
	v_or_b32_e32 v3, s3, v17
	v_lshlrev_b32_e32 v208, 11, v3
	v_lshl_add_u64 v[20:21], v[14:15], 0, v[208:209]
	global_store_dwordx4 v[20:21], v[10:13], off
	ds_read_b32 v3, v9 offset:96
	ds_read_b32 v10, v9 offset:228
	s_waitcnt lgkmcnt(0)
	v_cvt_pk_bf16_f32 v10, v3, v10
	ds_read_b32 v3, v9 offset:360
	ds_read_b32 v11, v9 offset:492
	s_waitcnt lgkmcnt(0)
	v_cvt_pk_bf16_f32 v11, v3, v11
	ds_read_b32 v3, v9 offset:624
	ds_read_b32 v12, v9 offset:756
	s_waitcnt lgkmcnt(0)
	v_cvt_pk_bf16_f32 v12, v3, v12
	ds_read_b32 v3, v9 offset:888
	ds_read_b32 v13, v9 offset:1020
	s_waitcnt lgkmcnt(0)
	v_cvt_pk_bf16_f32 v13, v3, v13
	v_or_b32_e32 v3, s3, v18
	v_lshlrev_b32_e32 v208, 11, v3
	v_lshl_add_u64 v[14:15], v[14:15], 0, v[208:209]
	global_store_dwordx4 v[14:15], v[10:13], off
	s_waitcnt lgkmcnt(0)

;     ...
; #pragma unroll 8
;     for (int i = 0; i < 32; ++i) { const int kk = 2 * i + (lane >> 5); scr[kk * 33 + (lane & 31)] = W[(size_t)(k0 + kk) * N + n0 + (lane & 31)]; }
.LBB0_1195:
	s_lshl_b32 s34, s13, 1
	s_lshl_b32 s23, s11, 1
	v_or_b32_e32 v14, s34, v12
	v_or_b32_e32 v20, s23, v3
	v_mad_i64_i32 v[14:15], s[36:37], v14, s0, v[10:11]
	v_mad_i64_i32 v[20:21], s[36:37], v20, s0, v[10:11]
	global_load_dword v22, v[14:15], off
	global_load_dword v23, v[20:21], off
	v_or_b32_e32 v13, s23, v1
	v_or_b32_e32 v19, s34, v2
	v_mad_u64_u32 v[14:15], s[36:37], v19, s33, v[6:7]
	v_mad_u64_u32 v[20:21], s[36:37], v13, s33, v[6:7]
	s_add_i32 s36, s34, 4
	s_add_i32 s35, s23, 4
	v_or_b32_e32 v19, s36, v2
	v_or_b32_e32 v13, s35, v1
	s_add_i32 s13, s13, 16
	s_add_i32 s11, s11, 16
	s_add_i32 s15, s15, -16
	s_waitcnt vmcnt(0)
	ds_write_b32 v14, v22
	ds_write_b32 v20, v23
	v_or_b32_e32 v14, s36, v12
	v_or_b32_e32 v20, s35, v3
	v_mad_i64_i32 v[14:15], s[36:37], v14, s0, v[10:11]
	v_mad_i64_i32 v[20:21], s[36:37], v20, s0, v[10:11]
	global_load_dword v22, v[14:15], off
	global_load_dword v23, v[20:21], off
	v_mad_u64_u32 v[14:15], s[36:37], v19, s33, v[6:7]
	v_mad_u64_u32 v[20:21], s[36:37], v13, s33, v[6:7]
	s_add_i32 s36, s34, 8
	s_add_i32 s35, s23, 8
	v_or_b32_e32 v19, s36, v2
	v_or_b32_e32 v13, s35, v1
	s_waitcnt vmcnt(1)
	ds_write_b32 v14, v22
	s_waitcnt vmcnt(0)
	ds_write_b32 v20, v23
	v_or_b32_e32 v14, s36, v12
	v_or_b32_e32 v20, s35, v3
	v_mad_i64_i32 v[14:15], s[36:37], v14, s0, v[10:11]
	v_mad_i64_i32 v[20:21], s[36:37], v20, s0, v[10:11]
	global_load_dword v22, v[14:15], off
	global_load_dword v23, v[20:21], off
	v_mad_u64_u32 v[14:15], s[36:37], v19, s33, v[6:7]
	v_mad_u64_u32 v[20:21], s[36:37], v13, s33, v[6:7]
	s_add_i32 s36, s34, 12
	s_add_i32 s35, s23, 12
	v_or_b32_e32 v19, s36, v2
	v_or_b32_e32 v13, s35, v1
	s_waitcnt vmcnt(1)
	ds_write_b32 v14, v22
	s_waitcnt vmcnt(0)
	ds_write_b32 v20, v23
	v_or_b32_e32 v14, s36, v12
	v_or_b32_e32 v20, s35, v3
	v_mad_i64_i32 v[14:15], s[36:37], v14, s0, v[10:11]
	v_mad_i64_i32 v[20:21], s[36:37], v20, s0, v[10:11]
	global_load_dword v22, v[14:15], off
	global_load_dword v23, v[20:21], off
	v_mad_u64_u32 v[14:15], s[36:37], v19, s33, v[6:7]
	v_mad_u64_u32 v[20:21], s[36:37], v13, s33, v[6:7]
	s_add_i32 s36, s34, 16
	s_add_i32 s35, s23, 16
	v_or_b32_e32 v19, s36, v2
	v_or_b32_e32 v13, s35, v1
	s_waitcnt vmcnt(1)
	ds_write_b32 v14, v22
	s_waitcnt vmcnt(0)
	ds_write_b32 v20, v23
	v_or_b32_e32 v14, s36, v12
	v_or_b32_e32 v20, s35, v3
	v_mad_i64_i32 v[14:15], s[36:37], v14, s0, v[10:11]
	v_mad_i64_i32 v[20:21], s[36:37], v20, s0, v[10:11]
	global_load_dword v22, v[14:15], off
	global_load_dword v23, v[20:21], off
	v_mad_u64_u32 v[14:15], s[36:37], v19, s33, v[6:7]
	v_mad_u64_u32 v[20:21], s[36:37], v13, s33, v[6:7]
	s_add_i32 s36, s34, 20
	s_add_i32 s35, s23, 20
	v_or_b32_e32 v19, s36, v2
	v_or_b32_e32 v13, s35, v1
	s_waitcnt vmcnt(1)
	ds_write_b32 v14, v22
	s_waitcnt vmcnt(0)
	ds_write_b32 v20, v23
	v_or_b32_e32 v14, s36, v12
	v_or_b32_e32 v20, s35, v3
	v_mad_i64_i32 v[14:15], s[36:37], v14, s0, v[10:11]
	v_mad_i64_i32 v[20:21], s[36:37], v20, s0, v[10:11]
	global_load_dword v22, v[14:15], off
	global_load_dword v23, v[20:21], off
	v_mad_u64_u32 v[14:15], s[36:37], v19, s33, v[6:7]
	v_mad_u64_u32 v[20:21], s[36:37], v13, s33, v[6:7]
	s_add_i32 s36, s34, 24
	s_add_i32 s35, s23, 24
	v_or_b32_e32 v19, s36, v2
	v_or_b32_e32 v13, s35, v1
	s_add_i32 s34, s34, 28
	s_add_i32 s23, s23, 28
	s_cmp_lg_u32 s15, 0
	s_waitcnt vmcnt(1)
	ds_write_b32 v14, v22
	s_waitcnt vmcnt(0)
	ds_write_b32 v20, v23
	v_or_b32_e32 v14, s36, v12
	v_or_b32_e32 v20, s35, v3
	v_mad_i64_i32 v[14:15], s[36:37], v14, s0, v[10:11]
	v_mad_i64_i32 v[20:21], s[36:37], v20, s0, v[10:11]
	global_load_dword v22, v[14:15], off
	global_load_dword v23, v[20:21], off
	v_mad_u64_u32 v[14:15], s[36:37], v19, s33, v[6:7]
	v_mad_u64_u32 v[20:21], s[36:37], v13, s33, v[6:7]
	v_or_b32_e32 v19, s34, v2
	v_or_b32_e32 v13, s23, v1
	s_waitcnt vmcnt(1)
	ds_write_b32 v14, v22
	s_waitcnt vmcnt(0)
	ds_write_b32 v20, v23
	v_or_b32_e32 v14, s34, v12
	v_or_b32_e32 v20, s23, v3
	v_mad_i64_i32 v[14:15], s[34:35], v14, s0, v[10:11]
	v_mad_i64_i32 v[20:21], s[34:35], v20, s0, v[10:11]
	global_load_dword v22, v[14:15], off
	global_load_dword v23, v[20:21], off
	v_mad_u64_u32 v[14:15], s[34:35], v19, s33, v[6:7]
	v_mad_u64_u32 v[20:21], s[34:35], v13, s33, v[6:7]
	s_waitcnt vmcnt(1)
	ds_write_b32 v14, v22
	s_waitcnt vmcnt(0)
	ds_write_b32 v20, v23
	s_cbranch_scc1 .LBB0_1195
; #define LAS __attribute__((address_space(3)))
; __device__ __forceinline__ unsigned pk2(float lo, float hi) { const f32x2_cv v = {lo, hi}; const bf16x2_cv b = __builtin_convertvector(v, bf16x2_cv); return __builtin_bit_cast(unsigned, b); }
;     ...
;     const int c = lane & 7;
; #pragma unroll
;     for (int j = 0; j < 4; ++j) { const int n = (lane >> 3) + 8 * j; const LAS float* s = scr + (8 * c) * 33 + n;
;         v4u o; o.x = pk2(s[0 * 33], s[1 * 33]); o.y = pk2(s[2 * 33], s[3 * 33]); o.z = pk2(s[4 * 33], s[5 * 33]); o.w = pk2(s[6 * 33], s[7 * 33]);
;         int row = n0 + n; if (PERM_UP == 2) { const int nl = row & 255; row = (row & ~255) + 128 * ((nl >> 5) & 1) + 32 * (nl >> 6) + (nl & 31); }
;         if (PERM_UP == 1) { const bool isv = row >= DFF; const int ch = isv ? row - DFF : row; row = (ch >> 7) * 256 + (isv ? 128 : 0) + (ch & 127); }
;         *(v4u*)(WT + (size_t)row * K + k0 + 8 * c) = o; }
;     asm volatile("s_waitcnt lgkmcnt(0)" ::: "memory");
	s_lshl_b32 s3, s3, 7
	s_and_b32 s11, s12, 0xffffff00
	s_and_b32 s3, s3, 0x80
	s_or_b32 s3, s11, s3
	s_lshr_b32 s11, s12, 1
	s_and_b32 s11, s11, 0x60
	s_or_b32 s3, s3, s11
	s_ashr_i32 s11, s10, 31
	s_lshl_b64 s[10:11], s[10:11], 1
	s_add_u32 s6, s6, s10
	s_addc_u32 s7, s7, s11
	v_lshlrev_b32_e32 v208, 1, v8
	s_waitcnt lgkmcnt(0)
	v_lshl_add_u64 v[10:11], s[6:7], 0, v[208:209]
	s_mov_b64 s[6:7], 0x200000
	v_lshl_add_u64 v[14:15], v[10:11], 0, s[6:7]
	ds_read_b32 v3, v9
	ds_read_b32 v10, v9 offset:132
	v_or_b32_e32 v20, s3, v7
	v_ashrrev_i32_e32 v21, 31, v20
	v_lshlrev_b64 v[20:21], 11, v[20:21]
	v_lshl_add_u64 v[20:21], v[14:15], 0, v[20:21]
	s_waitcnt lgkmcnt(0)
	v_cvt_pk_bf16_f32 v10, v3, v10
	ds_read_b32 v3, v9 offset:264
	ds_read_b32 v11, v9 offset:396
	s_waitcnt lgkmcnt(0)
	v_cvt_pk_bf16_f32 v11, v3, v11
	ds_read_b32 v3, v9 offset:528
	ds_read_b32 v12, v9 offset:660
	s_waitcnt lgkmcnt(0)
	v_cvt_pk_bf16_f32 v12, v3, v12
	ds_read_b32 v3, v9 offset:792
	ds_read_b32 v13, v9 offset:924
	s_waitcnt lgkmcnt(0)
	v_cvt_pk_bf16_f32 v13, v3, v13
	global_store_dwordx4 v[20:21], v[10:13], off
	ds_read_b32 v3, v9 offset:32
	ds_read_b32 v10, v9 offset:164
	v_or_b32_e32 v20, s3, v16
	v_ashrrev_i32_e32 v21, 31, v20
	v_lshlrev_b64 v[20:21], 11, v[20:21]
	v_lshl_add_u64 v[20:21], v[14:15], 0, v[20:21]
	s_waitcnt lgkmcnt(0)
	v_cvt_pk_bf16_f32 v10, v3, v10
	ds_read_b32 v3, v9 offset:296
	ds_read_b32 v11, v9 offset:428
	s_waitcnt lgkmcnt(0)
	v_cvt_pk_bf16_f32 v11, v3, v11
	ds_read_b32 v3, v9 offset:560
	ds_read_b32 v12, v9 offset:692
	s_waitcnt lgkmcnt(0)
	v_cvt_pk_bf16_f32 v12, v3, v12
	ds_read_b32 v3, v9 offset:824
	ds_read_b32 v13, v9 offset:956
	s_waitcnt lgkmcnt(0)
	v_cvt_pk_bf16_f32 v13, v3, v13
	global_store_dwordx4 v[20:21], v[10:13], off
	ds_read_b32 v3, v9 offset:64
	ds_read_b32 v10, v9 offset:196
	v_or_b32_e32 v20, s3, v17
	v_ashrrev_i32_e32 v21, 31, v20
	v_lshlrev_b64 v[20:21], 11, v[20:21]
	v_lshl_add_u64 v[20:21], v[14:15], 0, v[20:21]
	s_waitcnt lgkmcnt(0)
	v_cvt_pk_bf16_f32 v10, v3, v10
	ds_read_b32 v3, v9 offset:328
	ds_read_b32 v11, v9 offset:460
	s_waitcnt lgkmcnt(0)
	v_cvt_pk_bf16_f32 v11, v3, v11
	ds_read_b32 v3, v9 offset:592
	ds_read_b32 v12, v9 offset:724
	s_waitcnt lgkmcnt(0)
	v_cvt_pk_bf16_f32 v12, v3, v12
	ds_read_b32 v3, v9 offset:856
	ds_read_b32 v13, v9 offset:988
	s_waitcnt lgkmcnt(0)
	v_cvt_pk_bf16_f32 v13, v3, v13
	global_store_dwordx4 v[20:21], v[10:13], off
	ds_read_b32 v3, v9 offset:96
	ds_read_b32 v10, v9 offset:228
	v_or_b32_e32 v20, s3, v18
	v_ashrrev_i32_e32 v21, 31, v20
	v_lshlrev_b64 v[20:21], 11, v[20:21]
	v_lshl_add_u64 v[14:15], v[14:15], 0, v[20:21]
	s_waitcnt lgkmcnt(0)
	v_cvt_pk_bf16_f32 v10, v3, v10
	ds_read_b32 v3, v9 offset:360
	ds_read_b32 v11, v9 offset:492
	s_waitcnt lgkmcnt(0)
	v_cvt_pk_bf16_f32 v11, v3, v11
	ds_read_b32 v3, v9 offset:624
	ds_read_b32 v12, v9 offset:756
	s_waitcnt lgkmcnt(0)
	v_cvt_pk_bf16_f32 v12, v3, v12
	ds_read_b32 v3, v9 offset:888
	ds_read_b32 v13, v9 offset:1020
	s_waitcnt lgkmcnt(0)
	v_cvt_pk_bf16_f32 v13, v3, v13
	global_store_dwordx4 v[14:15], v[10:13], off
	s_waitcnt lgkmcnt(0)
	s_branch .LBB0_1182

; #define FILT ((float*)(wsb(a.ws) + WS_FILT))
; #define FILTC ((float*)(wsb(a.ws) + WS_FILTC))
; __device__ __forceinline__ void prep_work(const Args& a, LAS unsigned char* lds, const int lp, const bool needc, const int widx, const int nwg, const bool do_main, const bool do_dn, const int tid, const int lane, const int wave) {
;     ...
;             for (int p = 0; p < npos; ++p) { float s = b3;
; #pragma unroll
;                 for (int e = 0; e < 64; ++e) s += H2[p * 64 + e] * w[e];
;                 const bool isc = p == 32; const int n = isc ? item : item * 32 + p; const float t = (float)n / (isc ? 255.0f : 8191.0f);
;                 float* dst = isc ? FILTC + (size_t)q * 256 : FILT + (size_t)q * 8192;
;                 dst[n] = s * expf(-t * adelta); }
.LBB0_1266:
	s_waitcnt lgkmcnt(0)
	v_fma_f32 v70, v76, v70, v140
	v_fmac_f32_e32 v70, v77, v71
	v_fmac_f32_e32 v70, v78, v62
	v_fmac_f32_e32 v70, v79, v63
	v_fmac_f32_e32 v70, v80, v48
	v_fmac_f32_e32 v70, v81, v49
	v_fmac_f32_e32 v70, v82, v34
	v_fmac_f32_e32 v70, v83, v35
	v_fmac_f32_e32 v70, v84, v68
	v_fmac_f32_e32 v70, v85, v69
	v_fmac_f32_e32 v70, v86, v58
	v_fmac_f32_e32 v70, v87, v59
	v_fmac_f32_e32 v70, v88, v44
	v_fmac_f32_e32 v70, v89, v45
	v_fmac_f32_e32 v70, v90, v30
	v_fmac_f32_e32 v70, v91, v31
	v_fmac_f32_e32 v70, v92, v66
	v_fmac_f32_e32 v70, v93, v67
	v_fmac_f32_e32 v70, v94, v54
	v_fmac_f32_e32 v70, v95, v55
	v_fmac_f32_e32 v70, v96, v40
	v_fmac_f32_e32 v70, v97, v41
	v_fmac_f32_e32 v70, v98, v26
	v_fmac_f32_e32 v70, v99, v27
	v_fmac_f32_e32 v70, v100, v64
	v_fmac_f32_e32 v70, v101, v65
	v_fmac_f32_e32 v70, v102, v50
	v_fmac_f32_e32 v70, v103, v51
	v_fmac_f32_e32 v70, v104, v36
	v_fmac_f32_e32 v70, v105, v37
	v_fmac_f32_e32 v70, v106, v22
	v_fmac_f32_e32 v70, v107, v23
	v_fmac_f32_e32 v70, v108, v60
	v_fmac_f32_e32 v70, v109, v61
	v_fmac_f32_e32 v70, v110, v46
	v_fmac_f32_e32 v70, v111, v47
	s_waitcnt lgkmcnt(13)
	v_fmac_f32_e32 v70, v112, v32
	v_fmac_f32_e32 v70, v113, v33
	s_waitcnt lgkmcnt(12)
	v_fmac_f32_e32 v70, v114, v20
	v_fmac_f32_e32 v70, v115, v21
	s_waitcnt lgkmcnt(11)
	v_fmac_f32_e32 v70, v116, v56
	v_fmac_f32_e32 v70, v117, v57
	s_waitcnt lgkmcnt(10)
	v_fmac_f32_e32 v70, v118, v42
	v_fmac_f32_e32 v70, v119, v43
	s_waitcnt lgkmcnt(9)
	v_fmac_f32_e32 v70, v120, v28
	v_fmac_f32_e32 v70, v121, v29
	s_waitcnt lgkmcnt(8)
	v_fmac_f32_e32 v70, v122, v18
	v_fmac_f32_e32 v70, v123, v19
	s_waitcnt lgkmcnt(7)
	v_fmac_f32_e32 v70, v124, v52
	v_fmac_f32_e32 v70, v125, v53
	s_waitcnt lgkmcnt(6)
	v_fmac_f32_e32 v70, v126, v38
	v_fmac_f32_e32 v70, v127, v39
	s_waitcnt lgkmcnt(5)
	v_fmac_f32_e32 v70, v128, v24
	v_fmac_f32_e32 v70, v129, v25
	s_waitcnt lgkmcnt(4)
	v_fmac_f32_e32 v70, v130, v16
	s_and_b64 s[12:13], s[42:43], exec
	v_fmac_f32_e32 v70, v131, v17
	s_cselect_b32 s12, s60, s14
	s_waitcnt lgkmcnt(3)
	v_fmac_f32_e32 v70, v132, v14
	v_cvt_f32_i32_e32 v14, s12
	v_fmac_f32_e32 v70, v133, v15
	v_cndmask_b32_e64 v15, v230, v231, s[42:43]
	s_waitcnt lgkmcnt(2)
	v_fmac_f32_e32 v70, v134, v12
	v_div_scale_f32 v16, s[36:37], v15, v15, -v14
	v_rcp_f32_e32 v17, v16
	v_fmac_f32_e32 v70, v135, v13
	s_waitcnt lgkmcnt(1)
	v_fmac_f32_e32 v70, v136, v8
	v_fmac_f32_e32 v70, v137, v9
	v_fma_f32 v8, -v16, v17, 1.0
	v_fmac_f32_e32 v17, v8, v17
	v_div_scale_f32 v8, vcc, -v14, v15, -v14
	v_mul_f32_e32 v12, v8, v17
	v_fma_f32 v13, -v16, v12, v8
	v_fmac_f32_e32 v12, v13, v17
	v_fma_f32 v8, -v16, v12, v8
	v_div_fmas_f32 v8, v8, v17, v12
	v_div_fixup_f32 v8, v8, v15, -v14
	v_mul_f32_e32 v8, v1, v8
	v_mul_f32_e32 v12, 0x3fb8aa3b, v8
	v_fma_f32 v13, v8, s28, -v12
	v_rndne_f32_e32 v14, v12
	v_fmac_f32_e32 v13, 0x32a5705f, v8
	v_sub_f32_e32 v12, v12, v14
	v_add_f32_e32 v12, v12, v13
	v_exp_f32_e32 v12, v12
	v_cvt_i32_f32_e32 v13, v14
	s_waitcnt lgkmcnt(0)
	v_fmac_f32_e32 v70, v138, v6
	v_cmp_ngt_f32_e32 vcc, s24, v8
	v_fmac_f32_e32 v70, v139, v7
	v_ldexp_f32 v6, v12, v13
	v_cndmask_b32_e32 v6, 0, v6, vcc
	v_cmp_nlt_f32_e32 vcc, s25, v8
	s_ashr_i32 s13, s12, 31
	s_addk_i32 s15, 0x100
	v_cndmask_b32_e32 v6, v232, v6, vcc
	s_add_i32 s14, s14, 1
	v_mul_f32_e32 v8, v6, v70
	v_lshl_add_u64 v[6:7], s[12:13], 2, v[10:11]
	s_cmp_eq_u32 s34, s15
	global_store_dword v[6:7], v8, off
	s_cbranch_scc1 .LBB0_1264
